# K-loops: LDS-DMA loads with (SGPR base + 32-bit VGPR offset) addresses use the saddr form; 65 v_lshl_add_u64 address adds removed from the load parts
# baseline (speedup 1.0000x reference)
.LBB0_287:
	s_add_u32 s0, s22, 0xfffc0080
	s_addc_u32 s1, s23, -1
	s_add_i32 s72, 0, 0x10000
	s_cmp_eq_u32 s69, 12
	s_cselect_b32 s27, s18, s1
	s_cselect_b32 s26, s19, s0
	s_cselect_b32 s25, s45, s68
	s_cselect_b32 s24, s47, s59
	s_add_i32 m0, s53, 0xc000
	ds_read_b128 v[158:161], v165
	ds_read_b128 v[174:177], v165 offset:1024
	ds_read_b128 v[178:181], v165 offset:2048
	ds_read_b128 v[182:185], v165 offset:3072
	ds_read_b128 v[186:189], v165 offset:4096
	ds_read_b128 v[190:193], v165 offset:5120
	ds_read_b128 v[194:197], v165 offset:6144
	ds_read_b128 v[198:201], v165 offset:7168
	global_load_lds_dwordx4 v154, s[22:23]
	s_add_i32 m0, s53, 0xe000
	s_nop 0
	global_load_lds_dwordx4 v156, s[22:23]
	s_waitcnt vmcnt(10) lgkmcnt(8)
	s_setprio 1
	s_barrier
	s_waitcnt lgkmcnt(0)
	v_mfma_f32_16x16x32_bf16 v[144:147], v[68:71], v[158:161], v[144:147]
	v_mfma_f32_16x16x32_bf16 v[140:143], v[76:79], v[158:161], v[140:143]
	v_mfma_f32_16x16x32_bf16 v[128:131], v[68:71], v[178:181], v[128:131]
	v_mfma_f32_16x16x32_bf16 v[124:127], v[76:79], v[178:181], v[124:127]
	v_mfma_f32_16x16x32_bf16 v[112:115], v[68:71], v[186:189], v[112:115]
	v_mfma_f32_16x16x32_bf16 v[108:111], v[76:79], v[186:189], v[108:111]
	v_mfma_f32_16x16x32_bf16 v[96:99], v[68:71], v[194:197], v[96:99]
	v_mfma_f32_16x16x32_bf16 v[92:95], v[76:79], v[194:197], v[92:95]
	v_mfma_f32_16x16x32_bf16 v[144:147], v[72:75], v[174:177], v[144:147]
	v_mfma_f32_16x16x32_bf16 v[140:143], v[80:83], v[174:177], v[140:143]
	v_mfma_f32_16x16x32_bf16 v[128:131], v[72:75], v[182:185], v[128:131]
	v_mfma_f32_16x16x32_bf16 v[124:127], v[80:83], v[182:185], v[124:127]
	v_mfma_f32_16x16x32_bf16 v[112:115], v[72:75], v[190:193], v[112:115]
	v_mfma_f32_16x16x32_bf16 v[108:111], v[80:83], v[190:193], v[108:111]
	v_mfma_f32_16x16x32_bf16 v[96:99], v[72:75], v[198:201], v[96:99]
	v_mfma_f32_16x16x32_bf16 v[92:95], v[80:83], v[198:201], v[92:95]
	s_barrier
	s_setprio 0
	s_add_i32 s73, 0, 0x14000
	s_add_i32 s0, s72, s52
	v_add_u32_e32 v166, s73, v163
	v_lshl_add_u64 v[218:219], s[24:25], 0, v[26:27]
	s_mov_b32 m0, s0
	ds_read_b128 v[202:205], v166
	ds_read_b128 v[206:209], v166 offset:1024
	ds_read_b128 v[210:213], v166 offset:2048
	ds_read_b128 v[214:217], v166 offset:3072
	global_load_lds_dwordx4 v[218:219], off
	v_lshl_add_u64 v[220:221], s[24:25], 0, v[148:149]
	s_add_i32 m0, s0, 0x2000
	s_nop 0
	global_load_lds_dwordx4 v[220:221], off
	s_waitcnt vmcnt(10)
	s_setprio 1
	s_barrier
	s_waitcnt lgkmcnt(0)
	v_mfma_f32_16x16x32_bf16 v[136:139], v[202:205], v[158:161], v[136:139]
	v_mfma_f32_16x16x32_bf16 v[132:135], v[210:213], v[158:161], v[132:135]
	v_mfma_f32_16x16x32_bf16 v[120:123], v[202:205], v[178:181], v[120:123]
	v_mfma_f32_16x16x32_bf16 v[116:119], v[210:213], v[178:181], v[116:119]
	v_mfma_f32_16x16x32_bf16 v[104:107], v[202:205], v[186:189], v[104:107]
	v_mfma_f32_16x16x32_bf16 v[100:103], v[210:213], v[186:189], v[100:103]
	v_mfma_f32_16x16x32_bf16 v[88:91], v[202:205], v[194:197], v[88:91]
	v_mfma_f32_16x16x32_bf16 v[84:87], v[210:213], v[194:197], v[84:87]
	v_mfma_f32_16x16x32_bf16 v[136:139], v[206:209], v[174:177], v[136:139]
	v_mfma_f32_16x16x32_bf16 v[132:135], v[214:217], v[174:177], v[132:135]
	v_mfma_f32_16x16x32_bf16 v[120:123], v[206:209], v[182:185], v[120:123]
	v_mfma_f32_16x16x32_bf16 v[116:119], v[214:217], v[182:185], v[116:119]
	v_mfma_f32_16x16x32_bf16 v[104:107], v[206:209], v[190:193], v[104:107]
	v_mfma_f32_16x16x32_bf16 v[100:103], v[214:217], v[190:193], v[100:103]
	v_mfma_f32_16x16x32_bf16 v[88:91], v[206:209], v[198:201], v[88:91]
	v_mfma_f32_16x16x32_bf16 v[84:87], v[214:217], v[198:201], v[84:87]
	s_barrier
	s_setprio 0
	s_mov_b32 m0, s53
	v_lshl_add_u64 v[222:223], s[26:27], 0, v[152:153]
	ds_read_b128 v[158:161], v165 offset:16384
	ds_read_b128 v[174:177], v165 offset:17408
	ds_read_b128 v[178:181], v165 offset:18432
	ds_read_b128 v[182:185], v165 offset:19456
	ds_read_b128 v[186:189], v165 offset:20480
	ds_read_b128 v[190:193], v165 offset:21504
	ds_read_b128 v[194:197], v165 offset:22528
	ds_read_b128 v[198:201], v165 offset:23552
	global_load_lds_dwordx4 v[222:223], off
	v_lshl_add_u64 v[224:225], s[26:27], 0, v[150:151]
	s_mov_b32 m0, s54
	s_nop 0
	global_load_lds_dwordx4 v[224:225], off
	s_waitcnt vmcnt(10)
	s_setprio 1
	s_barrier
	s_waitcnt lgkmcnt(0)
	v_mfma_f32_16x16x32_bf16 v[64:67], v[68:71], v[158:161], v[64:67]
	v_mfma_f32_16x16x32_bf16 v[60:63], v[76:79], v[158:161], v[60:63]
	v_mfma_f32_16x16x32_bf16 v[48:51], v[68:71], v[178:181], v[48:51]
	v_mfma_f32_16x16x32_bf16 v[44:47], v[76:79], v[178:181], v[44:47]
	v_mfma_f32_16x16x32_bf16 v[32:35], v[68:71], v[186:189], v[32:35]
	v_mfma_f32_16x16x32_bf16 v[28:31], v[76:79], v[186:189], v[28:31]
	v_mfma_f32_16x16x32_bf16 v[14:17], v[68:71], v[194:197], v[14:17]
	v_mfma_f32_16x16x32_bf16 v[10:13], v[76:79], v[194:197], v[10:13]
	v_mfma_f32_16x16x32_bf16 v[64:67], v[72:75], v[174:177], v[64:67]
	v_mfma_f32_16x16x32_bf16 v[60:63], v[80:83], v[174:177], v[60:63]
	v_mfma_f32_16x16x32_bf16 v[48:51], v[72:75], v[182:185], v[48:51]
	v_mfma_f32_16x16x32_bf16 v[44:47], v[80:83], v[182:185], v[44:47]
	v_mfma_f32_16x16x32_bf16 v[32:35], v[72:75], v[190:193], v[32:35]
	v_mfma_f32_16x16x32_bf16 v[28:31], v[80:83], v[190:193], v[28:31]
	v_mfma_f32_16x16x32_bf16 v[14:17], v[72:75], v[198:201], v[14:17]
	v_mfma_f32_16x16x32_bf16 v[10:13], v[80:83], v[198:201], v[10:13]
	s_barrier
	s_setprio 0
	s_add_u32 s0, s24, 0x40000
	s_addc_u32 s1, s25, 0
	s_add_i32 s72, s73, s52
	s_mov_b32 m0, s72
	s_nop 0
	global_load_lds_dwordx4 v26, s[0:1]
	s_add_i32 m0, s72, 0x2000
	s_nop 0
	global_load_lds_dwordx4 v148, s[0:1]
	v_add_u32_e32 v80, 0x18000, v163
	ds_read_b128 v[68:71], v80
	ds_read_b128 v[72:75], v80 offset:1024
	ds_read_b128 v[76:79], v80 offset:2048
	ds_read_b128 v[80:83], v80 offset:3072
	s_waitcnt vmcnt(10)
	s_setprio 1
	s_barrier
	v_mfma_f32_16x16x32_bf16 v[56:59], v[202:205], v[158:161], v[56:59]
	v_mfma_f32_16x16x32_bf16 v[52:55], v[210:213], v[158:161], v[52:55]
	v_mfma_f32_16x16x32_bf16 v[40:43], v[202:205], v[178:181], v[40:43]
	v_mfma_f32_16x16x32_bf16 v[36:39], v[210:213], v[178:181], v[36:39]
	v_mfma_f32_16x16x32_bf16 v[22:25], v[202:205], v[186:189], v[22:25]
	v_mfma_f32_16x16x32_bf16 v[18:21], v[210:213], v[186:189], v[18:21]
	v_mfma_f32_16x16x32_bf16 v[6:9], v[202:205], v[194:197], v[6:9]
	v_mfma_f32_16x16x32_bf16 v[2:5], v[210:213], v[194:197], v[2:5]
	v_mfma_f32_16x16x32_bf16 v[56:59], v[206:209], v[174:177], v[56:59]
	v_mfma_f32_16x16x32_bf16 v[52:55], v[214:217], v[174:177], v[52:55]
	v_mfma_f32_16x16x32_bf16 v[40:43], v[206:209], v[182:185], v[40:43]
	v_mfma_f32_16x16x32_bf16 v[36:39], v[214:217], v[182:185], v[36:39]
	v_mfma_f32_16x16x32_bf16 v[22:25], v[206:209], v[190:193], v[22:25]
	v_mfma_f32_16x16x32_bf16 v[18:21], v[214:217], v[190:193], v[18:21]
	v_mfma_f32_16x16x32_bf16 v[6:9], v[206:209], v[198:201], v[6:9]
	v_mfma_f32_16x16x32_bf16 v[2:5], v[214:217], v[198:201], v[2:5]
	s_barrier
	s_setprio 0
	s_add_i32 s72, 0, 0x18000
	s_add_u32 s0, s26, 0x40000
	s_addc_u32 s1, s27, 0
	s_mov_b32 m0, s55
	ds_read_b128 v[158:161], v165 offset:32768
	ds_read_b128 v[174:177], v165 offset:33792
	ds_read_b128 v[178:181], v165 offset:34816
	ds_read_b128 v[182:185], v165 offset:35840
	ds_read_b128 v[186:189], v165 offset:36864
	ds_read_b128 v[190:193], v165 offset:37888
	ds_read_b128 v[194:197], v165 offset:38912
	ds_read_b128 v[198:201], v165 offset:39936
	global_load_lds_dwordx4 v152, s[0:1]
	s_mov_b32 m0, s56
	s_nop 0
	global_load_lds_dwordx4 v150, s[0:1]
	s_waitcnt vmcnt(10) lgkmcnt(8)
	s_setprio 1
	s_barrier
	s_waitcnt lgkmcnt(0)
	v_mfma_f32_16x16x32_bf16 v[144:147], v[68:71], v[158:161], v[144:147]
	v_mfma_f32_16x16x32_bf16 v[140:143], v[76:79], v[158:161], v[140:143]
	v_mfma_f32_16x16x32_bf16 v[128:131], v[68:71], v[178:181], v[128:131]
	v_mfma_f32_16x16x32_bf16 v[124:127], v[76:79], v[178:181], v[124:127]
	v_mfma_f32_16x16x32_bf16 v[112:115], v[68:71], v[186:189], v[112:115]
	v_mfma_f32_16x16x32_bf16 v[108:111], v[76:79], v[186:189], v[108:111]
	v_mfma_f32_16x16x32_bf16 v[96:99], v[68:71], v[194:197], v[96:99]
	v_mfma_f32_16x16x32_bf16 v[92:95], v[76:79], v[194:197], v[92:95]
	v_mfma_f32_16x16x32_bf16 v[144:147], v[72:75], v[174:177], v[144:147]
	v_mfma_f32_16x16x32_bf16 v[140:143], v[80:83], v[174:177], v[140:143]
	v_mfma_f32_16x16x32_bf16 v[128:131], v[72:75], v[182:185], v[128:131]
	v_mfma_f32_16x16x32_bf16 v[124:127], v[80:83], v[182:185], v[124:127]
	v_mfma_f32_16x16x32_bf16 v[112:115], v[72:75], v[190:193], v[112:115]
	v_mfma_f32_16x16x32_bf16 v[108:111], v[80:83], v[190:193], v[108:111]
	v_mfma_f32_16x16x32_bf16 v[96:99], v[72:75], v[198:201], v[96:99]
	v_mfma_f32_16x16x32_bf16 v[92:95], v[80:83], v[198:201], v[92:95]
	s_barrier
	s_setprio 0
	s_add_i32 s26, 0, 0x1c000
	s_add_i32 s0, s72, s52
	v_add_u32_e32 v166, s26, v163
	v_lshl_add_u64 v[218:219], v[218:219], 0, s[12:13]
	s_mov_b32 m0, s0
	ds_read_b128 v[202:205], v166
	ds_read_b128 v[206:209], v166 offset:1024
	ds_read_b128 v[210:213], v166 offset:2048
	ds_read_b128 v[214:217], v166 offset:3072
	global_load_lds_dwordx4 v[218:219], off
	v_lshl_add_u64 v[218:219], v[220:221], 0, s[12:13]
	s_add_i32 m0, s0, 0x2000
	s_nop 0
	global_load_lds_dwordx4 v[218:219], off
	s_waitcnt vmcnt(10)
	s_setprio 1
	s_barrier
	s_waitcnt lgkmcnt(0)
	v_mfma_f32_16x16x32_bf16 v[136:139], v[202:205], v[158:161], v[136:139]
	v_mfma_f32_16x16x32_bf16 v[132:135], v[210:213], v[158:161], v[132:135]
	v_mfma_f32_16x16x32_bf16 v[120:123], v[202:205], v[178:181], v[120:123]
	v_mfma_f32_16x16x32_bf16 v[116:119], v[210:213], v[178:181], v[116:119]
	v_mfma_f32_16x16x32_bf16 v[104:107], v[202:205], v[186:189], v[104:107]
	v_mfma_f32_16x16x32_bf16 v[100:103], v[210:213], v[186:189], v[100:103]
	v_mfma_f32_16x16x32_bf16 v[88:91], v[202:205], v[194:197], v[88:91]
	v_mfma_f32_16x16x32_bf16 v[84:87], v[210:213], v[194:197], v[84:87]
	v_mfma_f32_16x16x32_bf16 v[136:139], v[206:209], v[174:177], v[136:139]
	v_mfma_f32_16x16x32_bf16 v[132:135], v[214:217], v[174:177], v[132:135]
	v_mfma_f32_16x16x32_bf16 v[120:123], v[206:209], v[182:185], v[120:123]
	v_mfma_f32_16x16x32_bf16 v[116:119], v[214:217], v[182:185], v[116:119]
	v_mfma_f32_16x16x32_bf16 v[104:107], v[206:209], v[190:193], v[104:107]
	v_mfma_f32_16x16x32_bf16 v[100:103], v[214:217], v[190:193], v[100:103]
	v_mfma_f32_16x16x32_bf16 v[88:91], v[206:209], v[198:201], v[88:91]
	v_mfma_f32_16x16x32_bf16 v[84:87], v[214:217], v[198:201], v[84:87]
	s_barrier
	s_setprio 0
	s_mov_b32 m0, s30
	v_lshl_add_u64 v[218:219], v[222:223], 0, s[12:13]
	ds_read_b128 v[158:161], v165 offset:49152
	ds_read_b128 v[174:177], v165 offset:50176
	ds_read_b128 v[178:181], v165 offset:51200
	ds_read_b128 v[182:185], v165 offset:52224
	ds_read_b128 v[186:189], v165 offset:53248
	ds_read_b128 v[190:193], v165 offset:54272
	ds_read_b128 v[194:197], v165 offset:55296
	ds_read_b128 v[198:201], v165 offset:56320
	global_load_lds_dwordx4 v[218:219], off
	v_lshl_add_u64 v[218:219], v[224:225], 0, s[12:13]
	s_mov_b32 m0, s31
	s_nop 0
	global_load_lds_dwordx4 v[218:219], off
	s_waitcnt vmcnt(10)
	s_setprio 1
	s_barrier
	s_waitcnt lgkmcnt(0)
	v_mfma_f32_16x16x32_bf16 v[64:67], v[68:71], v[158:161], v[64:67]
	v_mfma_f32_16x16x32_bf16 v[60:63], v[76:79], v[158:161], v[60:63]
	v_mfma_f32_16x16x32_bf16 v[48:51], v[68:71], v[178:181], v[48:51]
	v_mfma_f32_16x16x32_bf16 v[44:47], v[76:79], v[178:181], v[44:47]
	v_mfma_f32_16x16x32_bf16 v[32:35], v[68:71], v[186:189], v[32:35]
	v_mfma_f32_16x16x32_bf16 v[28:31], v[76:79], v[186:189], v[28:31]
	v_mfma_f32_16x16x32_bf16 v[14:17], v[68:71], v[194:197], v[14:17]
	v_mfma_f32_16x16x32_bf16 v[10:13], v[76:79], v[194:197], v[10:13]
	v_mfma_f32_16x16x32_bf16 v[64:67], v[72:75], v[174:177], v[64:67]
	v_mfma_f32_16x16x32_bf16 v[60:63], v[80:83], v[174:177], v[60:63]
	v_mfma_f32_16x16x32_bf16 v[48:51], v[72:75], v[182:185], v[48:51]
	v_mfma_f32_16x16x32_bf16 v[44:47], v[80:83], v[182:185], v[44:47]
	v_mfma_f32_16x16x32_bf16 v[32:35], v[72:75], v[190:193], v[32:35]
	v_mfma_f32_16x16x32_bf16 v[28:31], v[80:83], v[190:193], v[28:31]
	v_mfma_f32_16x16x32_bf16 v[14:17], v[72:75], v[198:201], v[14:17]
	v_mfma_f32_16x16x32_bf16 v[10:13], v[80:83], v[198:201], v[10:13]
	s_barrier
	s_setprio 0
	s_add_u32 s0, s24, 0x40080
	s_addc_u32 s1, s25, 0
	s_add_i32 s24, s26, s52
	s_mov_b32 m0, s24
	s_nop 0
	global_load_lds_dwordx4 v26, s[0:1]
	s_add_i32 m0, s24, 0x2000
	s_nop 0
	global_load_lds_dwordx4 v148, s[0:1]
	v_add_u32_e32 v80, 0x10000, v163
	ds_read_b128 v[68:71], v80
	ds_read_b128 v[72:75], v80 offset:1024
	ds_read_b128 v[76:79], v80 offset:2048
	ds_read_b128 v[80:83], v80 offset:3072
	s_waitcnt vmcnt(10)
	s_setprio 1
	s_barrier
	v_mfma_f32_16x16x32_bf16 v[56:59], v[202:205], v[158:161], v[56:59]
	v_mfma_f32_16x16x32_bf16 v[52:55], v[210:213], v[158:161], v[52:55]
	v_mfma_f32_16x16x32_bf16 v[40:43], v[202:205], v[178:181], v[40:43]
	v_mfma_f32_16x16x32_bf16 v[36:39], v[210:213], v[178:181], v[36:39]
	v_mfma_f32_16x16x32_bf16 v[22:25], v[202:205], v[186:189], v[22:25]
	v_mfma_f32_16x16x32_bf16 v[18:21], v[210:213], v[186:189], v[18:21]
	v_mfma_f32_16x16x32_bf16 v[6:9], v[202:205], v[194:197], v[6:9]
	v_mfma_f32_16x16x32_bf16 v[2:5], v[210:213], v[194:197], v[2:5]
	v_mfma_f32_16x16x32_bf16 v[56:59], v[206:209], v[174:177], v[56:59]
	v_mfma_f32_16x16x32_bf16 v[52:55], v[214:217], v[174:177], v[52:55]
	v_mfma_f32_16x16x32_bf16 v[40:43], v[206:209], v[182:185], v[40:43]
	v_mfma_f32_16x16x32_bf16 v[36:39], v[214:217], v[182:185], v[36:39]
	v_mfma_f32_16x16x32_bf16 v[22:25], v[206:209], v[190:193], v[22:25]
	v_mfma_f32_16x16x32_bf16 v[18:21], v[214:217], v[190:193], v[18:21]
	v_mfma_f32_16x16x32_bf16 v[6:9], v[206:209], v[198:201], v[6:9]
	v_mfma_f32_16x16x32_bf16 v[2:5], v[214:217], v[198:201], v[2:5]
	s_barrier
	s_setprio 0
	s_add_i32 s69, s69, 2
	s_add_u32 s22, s22, 0x100
	s_addc_u32 s23, s23, 0
	s_add_u32 s59, s59, 0x100
	s_addc_u32 s68, s68, 0
	s_cmp_gt_u32 s69, 13
	s_cbranch_scc0 .LBB0_287
	s_waitcnt lgkmcnt(0)
	s_cmpk_gt_i32 s58, 0xff
	s_mov_b64 s[18:19], 0xb000
	s_cbranch_scc1 .LBB0_283
	s_ashr_i32 s0, s58, 5
	s_mul_hi_i32 s19, s0, 0x1600
	s_mul_i32 s18, s0, 0x1600
	s_branch .LBB0_283

.LBB0_361:
	s_add_u32 s28, s26, 0x100
	s_addc_u32 s29, s27, 0
	s_add_i32 s0, 0, 0x10000
	s_cmp_eq_u32 s46, 40
	s_cselect_b32 s35, s45, s29
	s_cselect_b32 s34, s44, s28
	s_cselect_b32 s31, s23, s19
	s_cselect_b32 s30, s22, s18
	s_add_i32 m0, s20, 0xc000
	ds_read_b128 v[172:175], v224
	ds_read_b128 v[176:179], v224 offset:1024
	ds_read_b128 v[180:183], v224 offset:2048
	ds_read_b128 v[184:187], v224 offset:3072
	ds_read_b128 v[188:191], v224 offset:4096
	ds_read_b128 v[192:195], v224 offset:5120
	ds_read_b128 v[196:199], v224 offset:6144
	ds_read_b128 v[200:203], v224 offset:7168
	global_load_lds_dwordx4 v152, s[26:27]
	v_lshl_add_u64 v[164:165], s[26:27], 0, v[154:155]
	s_add_i32 m0, s20, 0xe000
	s_nop 0
	global_load_lds_dwordx4 v[164:165], off
	s_waitcnt vmcnt(10) lgkmcnt(8)
	s_setprio 1
	s_barrier
	s_waitcnt lgkmcnt(0)
	v_mfma_f32_16x16x32_bf16 v[128:131], v[132:135], v[172:175], v[128:131]
	v_mfma_f32_16x16x32_bf16 v[124:127], v[156:159], v[172:175], v[124:127]
	v_mfma_f32_16x16x32_bf16 v[120:123], v[132:135], v[180:183], v[120:123]
	v_mfma_f32_16x16x32_bf16 v[116:119], v[156:159], v[180:183], v[116:119]
	v_mfma_f32_16x16x32_bf16 v[112:115], v[132:135], v[188:191], v[112:115]
	v_mfma_f32_16x16x32_bf16 v[108:111], v[156:159], v[188:191], v[108:111]
	v_mfma_f32_16x16x32_bf16 v[104:107], v[132:135], v[196:199], v[104:107]
	v_mfma_f32_16x16x32_bf16 v[100:103], v[156:159], v[196:199], v[100:103]
	v_mfma_f32_16x16x32_bf16 v[128:131], v[136:139], v[176:179], v[128:131]
	v_mfma_f32_16x16x32_bf16 v[124:127], v[160:163], v[176:179], v[124:127]
	v_mfma_f32_16x16x32_bf16 v[120:123], v[136:139], v[184:187], v[120:123]
	v_mfma_f32_16x16x32_bf16 v[116:119], v[160:163], v[184:187], v[116:119]
	v_mfma_f32_16x16x32_bf16 v[112:115], v[136:139], v[192:195], v[112:115]
	v_mfma_f32_16x16x32_bf16 v[108:111], v[160:163], v[192:195], v[108:111]
	v_mfma_f32_16x16x32_bf16 v[104:107], v[136:139], v[200:203], v[104:107]
	v_mfma_f32_16x16x32_bf16 v[100:103], v[160:163], v[200:203], v[100:103]
	s_barrier
	s_setprio 0
	s_add_i32 s26, 0, 0x14000
	v_add_u32_e32 v164, s26, v222
	s_add_i32 s0, s0, s17
	ds_read_b128 v[204:207], v164
	ds_read_b128 v[208:211], v164 offset:1024
	ds_read_b128 v[212:215], v164 offset:2048
	ds_read_b128 v[216:219], v164 offset:3072
	v_lshl_add_u64 v[164:165], s[30:31], 0, v[26:27]
	s_mov_b32 m0, s0
	v_lshl_add_u64 v[166:167], s[30:31], 0, v[140:141]
	global_load_lds_dwordx4 v[164:165], off
	s_add_i32 m0, s0, 0x2000
	s_nop 0
	global_load_lds_dwordx4 v[166:167], off
	s_waitcnt vmcnt(10)
	s_setprio 1
	s_barrier
	s_waitcnt lgkmcnt(0)
	v_mfma_f32_16x16x32_bf16 v[64:67], v[204:207], v[172:175], v[64:67]
	v_mfma_f32_16x16x32_bf16 v[60:63], v[212:215], v[172:175], v[60:63]
	v_mfma_f32_16x16x32_bf16 v[56:59], v[204:207], v[180:183], v[56:59]
	v_mfma_f32_16x16x32_bf16 v[52:55], v[212:215], v[180:183], v[52:55]
	v_mfma_f32_16x16x32_bf16 v[48:51], v[204:207], v[188:191], v[48:51]
	v_mfma_f32_16x16x32_bf16 v[44:47], v[212:215], v[188:191], v[44:47]
	v_mfma_f32_16x16x32_bf16 v[40:43], v[204:207], v[196:199], v[40:43]
	v_mfma_f32_16x16x32_bf16 v[36:39], v[212:215], v[196:199], v[36:39]
	v_mfma_f32_16x16x32_bf16 v[64:67], v[208:211], v[176:179], v[64:67]
	v_mfma_f32_16x16x32_bf16 v[60:63], v[216:219], v[176:179], v[60:63]
	v_mfma_f32_16x16x32_bf16 v[56:59], v[208:211], v[184:187], v[56:59]
	v_mfma_f32_16x16x32_bf16 v[52:55], v[216:219], v[184:187], v[52:55]
	v_mfma_f32_16x16x32_bf16 v[48:51], v[208:211], v[192:195], v[48:51]
	v_mfma_f32_16x16x32_bf16 v[44:47], v[216:219], v[192:195], v[44:47]
	v_mfma_f32_16x16x32_bf16 v[40:43], v[208:211], v[200:203], v[40:43]
	v_mfma_f32_16x16x32_bf16 v[36:39], v[216:219], v[200:203], v[36:39]
	s_barrier
	s_setprio 0
	s_mov_b32 m0, s20
	v_lshl_add_u64 v[168:169], s[34:35], 0, v[144:145]
	ds_read_b128 v[172:175], v224 offset:16384
	ds_read_b128 v[176:179], v224 offset:17408
	ds_read_b128 v[180:183], v224 offset:18432
	ds_read_b128 v[184:187], v224 offset:19456
	ds_read_b128 v[188:191], v224 offset:20480
	ds_read_b128 v[192:195], v224 offset:21504
	ds_read_b128 v[196:199], v224 offset:22528
	ds_read_b128 v[200:203], v224 offset:23552
	global_load_lds_dwordx4 v[168:169], off
	v_lshl_add_u64 v[220:221], s[34:35], 0, v[142:143]
	s_mov_b32 m0, s21
	s_nop 0
	global_load_lds_dwordx4 v[220:221], off
	s_waitcnt vmcnt(10)
	s_setprio 1
	s_barrier
	s_waitcnt lgkmcnt(0)
	v_mfma_f32_16x16x32_bf16 v[96:99], v[132:135], v[172:175], v[96:99]
	v_mfma_f32_16x16x32_bf16 v[92:95], v[156:159], v[172:175], v[92:95]
	v_mfma_f32_16x16x32_bf16 v[88:91], v[132:135], v[180:183], v[88:91]
	v_mfma_f32_16x16x32_bf16 v[84:87], v[156:159], v[180:183], v[84:87]
	v_mfma_f32_16x16x32_bf16 v[80:83], v[132:135], v[188:191], v[80:83]
	v_mfma_f32_16x16x32_bf16 v[76:79], v[156:159], v[188:191], v[76:79]
	v_mfma_f32_16x16x32_bf16 v[72:75], v[132:135], v[196:199], v[72:75]
	v_mfma_f32_16x16x32_bf16 v[68:71], v[156:159], v[196:199], v[68:71]
	v_mfma_f32_16x16x32_bf16 v[96:99], v[136:139], v[176:179], v[96:99]
	v_mfma_f32_16x16x32_bf16 v[92:95], v[160:163], v[176:179], v[92:95]
	v_mfma_f32_16x16x32_bf16 v[88:91], v[136:139], v[184:187], v[88:91]
	v_mfma_f32_16x16x32_bf16 v[84:87], v[160:163], v[184:187], v[84:87]
	v_mfma_f32_16x16x32_bf16 v[80:83], v[136:139], v[192:195], v[80:83]
	v_mfma_f32_16x16x32_bf16 v[76:79], v[160:163], v[192:195], v[76:79]
	v_mfma_f32_16x16x32_bf16 v[72:75], v[136:139], v[200:203], v[72:75]
	v_mfma_f32_16x16x32_bf16 v[68:71], v[160:163], v[200:203], v[68:71]
	s_barrier
	s_setprio 0
	s_add_u32 s0, s30, 0xb0000
	s_addc_u32 s1, s31, 0
	s_add_i32 s26, s26, s17
	s_mov_b32 m0, s26
	s_nop 0
	global_load_lds_dwordx4 v26, s[0:1]
	s_add_i32 m0, s26, 0x2000
	s_nop 0
	global_load_lds_dwordx4 v140, s[0:1]
	v_add_u32_e32 v160, 0x18000, v222
	ds_read_b128 v[132:135], v160
	ds_read_b128 v[136:139], v160 offset:1024
	ds_read_b128 v[156:159], v160 offset:2048
	ds_read_b128 v[160:163], v160 offset:3072
	s_waitcnt vmcnt(10)
	s_setprio 1
	s_barrier
	v_mfma_f32_16x16x32_bf16 v[32:35], v[204:207], v[172:175], v[32:35]
	v_mfma_f32_16x16x32_bf16 v[28:31], v[212:215], v[172:175], v[28:31]
	v_mfma_f32_16x16x32_bf16 v[22:25], v[204:207], v[180:183], v[22:25]
	v_mfma_f32_16x16x32_bf16 v[18:21], v[212:215], v[180:183], v[18:21]
	v_mfma_f32_16x16x32_bf16 v[14:17], v[204:207], v[188:191], v[14:17]
	v_mfma_f32_16x16x32_bf16 v[10:13], v[212:215], v[188:191], v[10:13]
	v_mfma_f32_16x16x32_bf16 v[6:9], v[204:207], v[196:199], v[6:9]
	v_mfma_f32_16x16x32_bf16 v[2:5], v[212:215], v[196:199], v[2:5]
	v_mfma_f32_16x16x32_bf16 v[32:35], v[208:211], v[176:179], v[32:35]
	v_mfma_f32_16x16x32_bf16 v[28:31], v[216:219], v[176:179], v[28:31]
	v_mfma_f32_16x16x32_bf16 v[22:25], v[208:211], v[184:187], v[22:25]
	v_mfma_f32_16x16x32_bf16 v[18:21], v[216:219], v[184:187], v[18:21]
	v_mfma_f32_16x16x32_bf16 v[14:17], v[208:211], v[192:195], v[14:17]
	v_mfma_f32_16x16x32_bf16 v[10:13], v[216:219], v[192:195], v[10:13]
	v_mfma_f32_16x16x32_bf16 v[6:9], v[208:211], v[200:203], v[6:9]
	v_mfma_f32_16x16x32_bf16 v[2:5], v[216:219], v[200:203], v[2:5]
	s_barrier
	s_setprio 0
	s_add_i32 s26, 0, 0x18000
	s_add_u32 s0, s34, 0xb0000
	s_addc_u32 s1, s35, 0
	s_mov_b32 m0, s36
	ds_read_b128 v[172:175], v224 offset:32768
	ds_read_b128 v[176:179], v224 offset:33792
	ds_read_b128 v[180:183], v224 offset:34816
	ds_read_b128 v[184:187], v224 offset:35840
	ds_read_b128 v[188:191], v224 offset:36864
	ds_read_b128 v[192:195], v224 offset:37888
	ds_read_b128 v[196:199], v224 offset:38912
	ds_read_b128 v[200:203], v224 offset:39936
	global_load_lds_dwordx4 v144, s[0:1]
	s_mov_b32 m0, s37
	s_nop 0
	global_load_lds_dwordx4 v142, s[0:1]
	s_waitcnt vmcnt(10) lgkmcnt(8)
	s_setprio 1
	s_barrier
	s_waitcnt lgkmcnt(0)
	v_mfma_f32_16x16x32_bf16 v[128:131], v[132:135], v[172:175], v[128:131]
	v_mfma_f32_16x16x32_bf16 v[124:127], v[156:159], v[172:175], v[124:127]
	v_mfma_f32_16x16x32_bf16 v[120:123], v[132:135], v[180:183], v[120:123]
	v_mfma_f32_16x16x32_bf16 v[116:119], v[156:159], v[180:183], v[116:119]
	v_mfma_f32_16x16x32_bf16 v[112:115], v[132:135], v[188:191], v[112:115]
	v_mfma_f32_16x16x32_bf16 v[108:111], v[156:159], v[188:191], v[108:111]
	v_mfma_f32_16x16x32_bf16 v[104:107], v[132:135], v[196:199], v[104:107]
	v_mfma_f32_16x16x32_bf16 v[100:103], v[156:159], v[196:199], v[100:103]
	v_mfma_f32_16x16x32_bf16 v[128:131], v[136:139], v[176:179], v[128:131]
	v_mfma_f32_16x16x32_bf16 v[124:127], v[160:163], v[176:179], v[124:127]
	v_mfma_f32_16x16x32_bf16 v[120:123], v[136:139], v[184:187], v[120:123]
	v_mfma_f32_16x16x32_bf16 v[116:119], v[160:163], v[184:187], v[116:119]
	v_mfma_f32_16x16x32_bf16 v[112:115], v[136:139], v[192:195], v[112:115]
	v_mfma_f32_16x16x32_bf16 v[108:111], v[160:163], v[192:195], v[108:111]
	v_mfma_f32_16x16x32_bf16 v[104:107], v[136:139], v[200:203], v[104:107]
	v_mfma_f32_16x16x32_bf16 v[100:103], v[160:163], v[200:203], v[100:103]
	s_barrier
	s_setprio 0
	s_add_i32 s27, 0, 0x1c000
	s_add_i32 s0, s26, s17
	v_add_u32_e32 v216, s27, v222
	v_lshl_add_u64 v[164:165], v[164:165], 0, s[12:13]
	s_mov_b32 m0, s0
	ds_read_b128 v[204:207], v216
	ds_read_b128 v[208:211], v216 offset:1024
	ds_read_b128 v[212:215], v216 offset:2048
	ds_read_b128 v[216:219], v216 offset:3072
	global_load_lds_dwordx4 v[164:165], off
	v_lshl_add_u64 v[164:165], v[166:167], 0, s[12:13]
	s_add_i32 m0, s0, 0x2000
	s_nop 0
	global_load_lds_dwordx4 v[164:165], off
	s_waitcnt vmcnt(10)
	s_setprio 1
	s_barrier
	s_waitcnt lgkmcnt(0)
	v_mfma_f32_16x16x32_bf16 v[64:67], v[204:207], v[172:175], v[64:67]
	v_mfma_f32_16x16x32_bf16 v[60:63], v[212:215], v[172:175], v[60:63]
	v_mfma_f32_16x16x32_bf16 v[56:59], v[204:207], v[180:183], v[56:59]
	v_mfma_f32_16x16x32_bf16 v[52:55], v[212:215], v[180:183], v[52:55]
	v_mfma_f32_16x16x32_bf16 v[48:51], v[204:207], v[188:191], v[48:51]
	v_mfma_f32_16x16x32_bf16 v[44:47], v[212:215], v[188:191], v[44:47]
	v_mfma_f32_16x16x32_bf16 v[40:43], v[204:207], v[196:199], v[40:43]
	v_mfma_f32_16x16x32_bf16 v[36:39], v[212:215], v[196:199], v[36:39]
	v_mfma_f32_16x16x32_bf16 v[64:67], v[208:211], v[176:179], v[64:67]
	v_mfma_f32_16x16x32_bf16 v[60:63], v[216:219], v[176:179], v[60:63]
	v_mfma_f32_16x16x32_bf16 v[56:59], v[208:211], v[184:187], v[56:59]
	v_mfma_f32_16x16x32_bf16 v[52:55], v[216:219], v[184:187], v[52:55]
	v_mfma_f32_16x16x32_bf16 v[48:51], v[208:211], v[192:195], v[48:51]
	v_mfma_f32_16x16x32_bf16 v[44:47], v[216:219], v[192:195], v[44:47]
	v_mfma_f32_16x16x32_bf16 v[40:43], v[208:211], v[200:203], v[40:43]
	v_mfma_f32_16x16x32_bf16 v[36:39], v[216:219], v[200:203], v[36:39]
	s_barrier
	s_setprio 0
	s_mov_b32 m0, s59
	v_lshl_add_u64 v[164:165], v[168:169], 0, s[12:13]
	ds_read_b128 v[172:175], v224 offset:49152
	ds_read_b128 v[176:179], v224 offset:50176
	ds_read_b128 v[180:183], v224 offset:51200
	ds_read_b128 v[184:187], v224 offset:52224
	ds_read_b128 v[188:191], v224 offset:53248
	ds_read_b128 v[192:195], v224 offset:54272
	ds_read_b128 v[196:199], v224 offset:55296
	ds_read_b128 v[200:203], v224 offset:56320
	global_load_lds_dwordx4 v[164:165], off
	v_lshl_add_u64 v[164:165], v[220:221], 0, s[12:13]
	s_mov_b32 m0, s68
	s_nop 0
	global_load_lds_dwordx4 v[164:165], off
	s_waitcnt vmcnt(10)
	s_setprio 1
	s_barrier
	s_waitcnt lgkmcnt(0)
	v_mfma_f32_16x16x32_bf16 v[96:99], v[132:135], v[172:175], v[96:99]
	v_mfma_f32_16x16x32_bf16 v[92:95], v[156:159], v[172:175], v[92:95]
	v_mfma_f32_16x16x32_bf16 v[88:91], v[132:135], v[180:183], v[88:91]
	v_mfma_f32_16x16x32_bf16 v[84:87], v[156:159], v[180:183], v[84:87]
	v_mfma_f32_16x16x32_bf16 v[80:83], v[132:135], v[188:191], v[80:83]
	v_mfma_f32_16x16x32_bf16 v[76:79], v[156:159], v[188:191], v[76:79]
	v_mfma_f32_16x16x32_bf16 v[72:75], v[132:135], v[196:199], v[72:75]
	v_mfma_f32_16x16x32_bf16 v[68:71], v[156:159], v[196:199], v[68:71]
	v_mfma_f32_16x16x32_bf16 v[96:99], v[136:139], v[176:179], v[96:99]
	v_mfma_f32_16x16x32_bf16 v[92:95], v[160:163], v[176:179], v[92:95]
	v_mfma_f32_16x16x32_bf16 v[88:91], v[136:139], v[184:187], v[88:91]
	v_mfma_f32_16x16x32_bf16 v[84:87], v[160:163], v[184:187], v[84:87]
	v_mfma_f32_16x16x32_bf16 v[80:83], v[136:139], v[192:195], v[80:83]
	v_mfma_f32_16x16x32_bf16 v[76:79], v[160:163], v[192:195], v[76:79]
	v_mfma_f32_16x16x32_bf16 v[72:75], v[136:139], v[200:203], v[72:75]
	v_mfma_f32_16x16x32_bf16 v[68:71], v[160:163], v[200:203], v[68:71]
	s_barrier
	s_setprio 0
	s_add_u32 s0, s30, 0xb0080
	s_addc_u32 s1, s31, 0
	s_add_i32 s26, s27, s17
	s_mov_b32 m0, s26
	s_nop 0
	global_load_lds_dwordx4 v26, s[0:1]
	s_add_i32 m0, s26, 0x2000
	s_nop 0
	global_load_lds_dwordx4 v140, s[0:1]
	v_add_u32_e32 v160, 0x10000, v222
	ds_read_b128 v[132:135], v160
	ds_read_b128 v[136:139], v160 offset:1024
	ds_read_b128 v[156:159], v160 offset:2048
	ds_read_b128 v[160:163], v160 offset:3072
	s_waitcnt vmcnt(10)
	s_setprio 1
	s_barrier
	v_mfma_f32_16x16x32_bf16 v[32:35], v[204:207], v[172:175], v[32:35]
	v_mfma_f32_16x16x32_bf16 v[28:31], v[212:215], v[172:175], v[28:31]
	v_mfma_f32_16x16x32_bf16 v[22:25], v[204:207], v[180:183], v[22:25]
	v_mfma_f32_16x16x32_bf16 v[18:21], v[212:215], v[180:183], v[18:21]
	v_mfma_f32_16x16x32_bf16 v[14:17], v[204:207], v[188:191], v[14:17]
	v_mfma_f32_16x16x32_bf16 v[10:13], v[212:215], v[188:191], v[10:13]
	v_mfma_f32_16x16x32_bf16 v[6:9], v[204:207], v[196:199], v[6:9]
	v_mfma_f32_16x16x32_bf16 v[2:5], v[212:215], v[196:199], v[2:5]
	v_mfma_f32_16x16x32_bf16 v[32:35], v[208:211], v[176:179], v[32:35]
	v_mfma_f32_16x16x32_bf16 v[28:31], v[216:219], v[176:179], v[28:31]
	v_mfma_f32_16x16x32_bf16 v[22:25], v[208:211], v[184:187], v[22:25]
	v_mfma_f32_16x16x32_bf16 v[18:21], v[216:219], v[184:187], v[18:21]
	v_mfma_f32_16x16x32_bf16 v[14:17], v[208:211], v[192:195], v[14:17]
	v_mfma_f32_16x16x32_bf16 v[10:13], v[216:219], v[192:195], v[10:13]
	v_mfma_f32_16x16x32_bf16 v[6:9], v[208:211], v[200:203], v[6:9]
	v_mfma_f32_16x16x32_bf16 v[2:5], v[216:219], v[200:203], v[2:5]
	s_barrier
	s_setprio 0
	s_add_i32 s46, s46, 2
	s_add_u32 s18, s18, 0x100
	s_addc_u32 s19, s19, 0
	s_cmp_gt_u32 s46, 41
	s_mov_b64 s[26:27], s[28:29]
	s_cbranch_scc0 .LBB0_361
	s_waitcnt lgkmcnt(0)
	s_min_i32 s0, s24, 0x100
	s_ashr_i32 s0, s0, 5
	s_ashr_i32 s1, s0, 31
	s_add_i32 s18, s24, 0xffffff00
	s_cmpk_lt_i32 s24, 0x100
	s_cselect_b32 s18, s24, s18
	s_cselect_b32 s27, 0, s58
	s_cselect_b32 s26, 0, s57
	s_ashr_i32 s19, s18, 31
	s_lshl_b64 s[18:19], s[18:19], 19
	s_add_u32 s26, s50, s26
	v_lshl_or_b32 v178, s25, 8, v223
	s_addc_u32 s27, s51, s27
	s_ashr_i32 s25, s24, 31
	v_lshl_add_u64 v[132:133], s[18:19], 0, v[146:147]
	s_lshl_b64 s[18:19], s[24:25], 19
	v_lshl_add_u64 v[184:185], v[148:149], 0, s[18:19]
	s_lshl_b64 s[24:25], s[24:25], 10
	s_mul_i32 s18, s0, 0x9000
	v_ashrrev_i32_e32 v179, 31, v178
	s_mul_hi_i32 s19, s0, 0x9000
	s_add_u32 s18, s48, s18
	s_addc_u32 s19, s49, s19
	v_lshlrev_b64 v[186:187], 2, v[178:179]
	v_lshl_add_u64 v[156:157], s[18:19], 0, v[186:187]
	v_lshl_add_u64 v[180:181], v[132:133], 0, v[178:179]
	v_lshl_add_u64 v[182:183], v[132:133], 1, s[26:27]
	global_load_dwordx4 v[132:135], v[156:157], off offset:16
	global_load_dwordx4 v[136:139], v[156:157], off
	s_lshl_b64 s[0:1], s[0:1], 12
	s_add_u32 s28, s52, s0
	s_addc_u32 s29, s53, s1
	v_lshl_add_u64 v[196:197], v[180:181], 1, s[26:27]
	v_lshl_add_u64 v[180:181], s[28:29], 0, v[186:187]
	v_add_co_u32_e32 v210, vcc, s65, v196
	v_lshlrev_b64 v[188:189], 1, v[178:179]
	s_nop 0
	v_addc_co_u32_e32 v211, vcc, 0, v197, vcc
	s_mov_b32 s1, 0x20000
	v_lshl_add_u64 v[178:179], v[184:185], 0, v[188:189]
	v_add_co_u32_e32 v184, vcc, s1, v196
	s_mov_b32 s18, 0x30000
	s_nop 0
	v_addc_co_u32_e32 v185, vcc, 0, v197, vcc
	v_lshl_add_u64 v[182:183], v[182:183], 0, v[188:189]
	v_add_co_u32_e32 v188, vcc, s18, v196
	s_mov_b32 s0, 0x8000
	s_nop 0
	v_addc_co_u32_e32 v189, vcc, 0, v197, vcc
	s_mov_b32 s19, 0x80000
	s_mov_b32 s26, 0x90000
	s_waitcnt vmcnt(0)
	v_pk_mul_f32 v[172:173], v[134:135], 0.5 op_sel_hi:[1,0]
	v_pk_mul_f32 v[176:177], v[138:139], 0.5 op_sel_hi:[1,0]
	v_pk_mul_f32 v[174:175], v[136:137], 0.5 op_sel_hi:[1,0]
	v_pk_mul_f32 v[164:165], v[132:133], 0.5 op_sel_hi:[1,0]
	global_load_dwordx4 v[132:135], v[156:157], off offset:528
	global_load_dwordx4 v[136:139], v[156:157], off offset:512
	s_waitcnt vmcnt(0)
	v_pk_mul_f32 v[158:159], v[134:135], 0.5 op_sel_hi:[1,0]
	v_pk_mul_f32 v[162:163], v[138:139], 0.5 op_sel_hi:[1,0]
	v_pk_mul_f32 v[160:161], v[136:137], 0.5 op_sel_hi:[1,0]
	v_pk_mul_f32 v[156:157], v[132:133], 0.5 op_sel_hi:[1,0]
	global_load_dwordx4 v[132:135], v[180:181], off offset:16
	global_load_dwordx4 v[136:139], v[180:181], off
	global_load_dwordx4 v[190:193], v[196:197], off offset:2048
	global_load_dwordx4 v[198:201], v[210:211], off offset:2048
	global_load_dwordx4 v[202:205], v[184:185], off offset:2048
	global_load_dwordx4 v[206:209], v[188:189], off offset:2048
	s_waitcnt vmcnt(0)
	v_lshlrev_b32_e32 v186, 16, v190
	v_and_b32_e32 v187, 0xffff0000, v190
	v_lshlrev_b32_e32 v190, 16, v191
	v_and_b32_e32 v191, 0xffff0000, v191
	v_lshlrev_b32_e32 v194, 16, v192
	v_and_b32_e32 v195, 0xffff0000, v192
	v_lshlrev_b32_e32 v192, 16, v193
	v_and_b32_e32 v193, 0xffff0000, v193
	v_pk_fma_f32 v[130:131], v[130:131], v[176:177], v[190:191]
	v_pk_fma_f32 v[128:129], v[128:129], v[174:175], v[186:187]
	v_pk_fma_f32 v[126:127], v[126:127], v[172:173], v[192:193]
	v_pk_fma_f32 v[124:125], v[124:125], v[164:165], v[194:195]
	v_cvt_pk_bf16_f32 v190, v128, v129
	v_cvt_pk_bf16_f32 v191, v130, v131
	v_cvt_pk_bf16_f32 v192, v124, v125
	v_cvt_pk_bf16_f32 v193, v126, v127
	v_lshlrev_b32_e32 v130, 16, v190
	v_and_b32_e32 v131, 0xffff0000, v190
	v_lshlrev_b32_e32 v128, 16, v191
	v_and_b32_e32 v129, 0xffff0000, v191
	v_lshlrev_b32_e32 v126, 16, v192
	v_and_b32_e32 v127, 0xffff0000, v192
	v_lshlrev_b32_e32 v124, 16, v193
	v_and_b32_e32 v125, 0xffff0000, v193
	v_lshlrev_b32_e32 v212, 16, v198
	v_and_b32_e32 v213, 0xffff0000, v198
	v_lshlrev_b32_e32 v198, 16, v199
	v_and_b32_e32 v199, 0xffff0000, v199
	global_store_dwordx4 v[182:183], v[190:193], off offset:2048
	v_pk_mul_f32 v[186:187], v[138:139], v[128:129]
	v_pk_mul_f32 v[194:195], v[134:135], v[124:125]
	v_pk_mul_f32 v[190:191], v[136:137], v[130:131]
	v_pk_mul_f32 v[192:193], v[132:133], v[126:127]
	v_lshlrev_b32_e32 v214, 16, v200
	v_and_b32_e32 v215, 0xffff0000, v200
	v_lshlrev_b32_e32 v200, 16, v201
	v_and_b32_e32 v201, 0xffff0000, v201
	v_cvt_pk_bf16_f32 v190, v190, v191
	v_cvt_pk_bf16_f32 v191, v186, v187
	v_cvt_pk_bf16_f32 v192, v192, v193
	v_cvt_pk_bf16_f32 v193, v194, v195
	v_pk_fma_f32 v[122:123], v[122:123], v[176:177], v[198:199]
	v_pk_fma_f32 v[120:121], v[120:121], v[174:175], v[212:213]
	global_store_dwordx4 v[178:179], v[190:193], off
	v_pk_fma_f32 v[118:119], v[118:119], v[172:173], v[200:201]
	v_pk_fma_f32 v[116:117], v[116:117], v[164:165], v[214:215]
	v_cvt_pk_bf16_f32 v190, v120, v121
	v_cvt_pk_bf16_f32 v191, v122, v123
	v_add_co_u32_e32 v186, vcc, s65, v182
	v_cvt_pk_bf16_f32 v192, v116, v117
	v_cvt_pk_bf16_f32 v193, v118, v119
	v_addc_co_u32_e32 v187, vcc, 0, v183, vcc
	v_lshlrev_b32_e32 v122, 16, v190
	v_and_b32_e32 v123, 0xffff0000, v190
	v_lshlrev_b32_e32 v120, 16, v191
	v_and_b32_e32 v121, 0xffff0000, v191
	global_store_dwordx4 v[186:187], v[190:193], off offset:2048
	v_lshlrev_b32_e32 v118, 16, v192
	v_and_b32_e32 v119, 0xffff0000, v192
	v_lshlrev_b32_e32 v116, 16, v193
	v_and_b32_e32 v117, 0xffff0000, v193
	v_pk_mul_f32 v[190:191], v[138:139], v[120:121]
	v_pk_mul_f32 v[192:193], v[136:137], v[122:123]
	v_pk_mul_f32 v[198:199], v[134:135], v[116:117]
	v_pk_mul_f32 v[194:195], v[132:133], v[118:119]
	v_cvt_pk_bf16_f32 v192, v192, v193
	v_cvt_pk_bf16_f32 v193, v190, v191
	v_add_co_u32_e32 v190, vcc, s0, v178
	v_cvt_pk_bf16_f32 v194, v194, v195
	v_cvt_pk_bf16_f32 v195, v198, v199
	v_addc_co_u32_e32 v191, vcc, 0, v179, vcc
	global_store_dwordx4 v[190:191], v[192:195], off
	v_lshlrev_b32_e32 v198, 16, v202
	v_and_b32_e32 v199, 0xffff0000, v202
	v_add_co_u32_e32 v192, vcc, s19, v196
	v_lshlrev_b32_e32 v200, 16, v203
	s_nop 0
	v_addc_co_u32_e32 v193, vcc, 0, v197, vcc
	v_add_co_u32_e32 v194, vcc, s26, v196
	v_and_b32_e32 v201, 0xffff0000, v203
	global_load_dwordx4 v[212:215], v[192:193], off offset:2048
	v_addc_co_u32_e32 v195, vcc, 0, v197, vcc
	v_lshlrev_b32_e32 v202, 16, v204
	v_and_b32_e32 v203, 0xffff0000, v204
	v_lshlrev_b32_e32 v204, 16, v205
	v_and_b32_e32 v205, 0xffff0000, v205
	v_pk_fma_f32 v[114:115], v[114:115], v[176:177], v[200:201]
	v_pk_fma_f32 v[112:113], v[112:113], v[174:175], v[198:199]
	v_pk_fma_f32 v[110:111], v[110:111], v[172:173], v[204:205]
	v_pk_fma_f32 v[108:109], v[108:109], v[164:165], v[202:203]
	v_cvt_pk_bf16_f32 v200, v112, v113
	v_cvt_pk_bf16_f32 v201, v114, v115
	v_add_co_u32_e32 v198, vcc, s1, v182
	v_cvt_pk_bf16_f32 v202, v108, v109
	v_cvt_pk_bf16_f32 v203, v110, v111
	v_addc_co_u32_e32 v199, vcc, 0, v183, vcc
	v_lshlrev_b32_e32 v114, 16, v200
	v_and_b32_e32 v115, 0xffff0000, v200
	v_lshlrev_b32_e32 v112, 16, v201
	v_and_b32_e32 v113, 0xffff0000, v201
	global_load_dwordx4 v[216:219], v[194:195], off offset:2048
	v_lshlrev_b32_e32 v110, 16, v202
	global_store_dwordx4 v[198:199], v[200:203], off offset:2048
	v_and_b32_e32 v111, 0xffff0000, v202
	v_lshlrev_b32_e32 v108, 16, v203
	v_and_b32_e32 v109, 0xffff0000, v203
	v_pk_mul_f32 v[200:201], v[138:139], v[112:113]
	v_pk_mul_f32 v[202:203], v[136:137], v[114:115]
	v_lshlrev_b32_e32 v220, 16, v206
	v_and_b32_e32 v221, 0xffff0000, v206
	v_lshlrev_b32_e32 v206, 16, v207
	v_and_b32_e32 v207, 0xffff0000, v207
	v_pk_mul_f32 v[238:239], v[134:135], v[108:109]
	v_pk_mul_f32 v[204:205], v[132:133], v[110:111]
	v_cvt_pk_bf16_f32 v202, v202, v203
	v_cvt_pk_bf16_f32 v203, v200, v201
	v_add_co_u32_e32 v200, vcc, s65, v178
	v_lshlrev_b32_e32 v234, 16, v208
	v_and_b32_e32 v235, 0xffff0000, v208
	v_lshlrev_b32_e32 v208, 16, v209
	v_and_b32_e32 v209, 0xffff0000, v209
	v_cvt_pk_bf16_f32 v204, v204, v205
	v_cvt_pk_bf16_f32 v205, v238, v239
	v_addc_co_u32_e32 v201, vcc, 0, v179, vcc
	v_pk_fma_f32 v[106:107], v[106:107], v[176:177], v[206:207]
	v_pk_fma_f32 v[104:105], v[104:105], v[174:175], v[220:221]
	global_store_dwordx4 v[200:201], v[202:205], off
	v_pk_fma_f32 v[102:103], v[102:103], v[172:173], v[208:209]
	v_pk_fma_f32 v[100:101], v[100:101], v[164:165], v[234:235]
	v_cvt_pk_bf16_f32 v204, v104, v105
	v_cvt_pk_bf16_f32 v205, v106, v107
	v_add_co_u32_e32 v202, vcc, s18, v182
	v_cvt_pk_bf16_f32 v206, v100, v101
	v_cvt_pk_bf16_f32 v207, v102, v103
	v_addc_co_u32_e32 v203, vcc, 0, v183, vcc
	v_lshlrev_b32_e32 v106, 16, v204
	v_and_b32_e32 v107, 0xffff0000, v204
	v_lshlrev_b32_e32 v104, 16, v205
	v_and_b32_e32 v105, 0xffff0000, v205
	global_store_dwordx4 v[202:203], v[204:207], off offset:2048
	v_lshlrev_b32_e32 v102, 16, v206
	v_and_b32_e32 v103, 0xffff0000, v206
	v_lshlrev_b32_e32 v100, 16, v207
	v_and_b32_e32 v101, 0xffff0000, v207
	v_pk_mul_f32 v[204:205], v[138:139], v[104:105]
	v_pk_mul_f32 v[206:207], v[136:137], v[106:107]
	s_mov_b32 s0, 0x18000
	v_pk_mul_f32 v[220:221], v[134:135], v[100:101]
	v_pk_mul_f32 v[208:209], v[132:133], v[102:103]
	v_cvt_pk_bf16_f32 v206, v206, v207
	v_cvt_pk_bf16_f32 v207, v204, v205
	v_add_co_u32_e32 v204, vcc, s0, v178
	v_cvt_pk_bf16_f32 v208, v208, v209
	v_cvt_pk_bf16_f32 v209, v220, v221
	v_addc_co_u32_e32 v205, vcc, 0, v179, vcc
	global_store_dwordx4 v[204:205], v[206:209], off
	s_mov_b32 s0, 0xb0000
	s_waitcnt vmcnt(0)
	v_lshlrev_b32_e32 v220, 16, v212
	v_add_co_u32_e32 v206, vcc, s76, v196
	v_and_b32_e32 v221, 0xffff0000, v212
	s_nop 0
	v_addc_co_u32_e32 v207, vcc, 0, v197, vcc
	global_load_dwordx4 v[238:241], v[206:207], off offset:2048
	v_add_co_u32_e32 v208, vcc, s0, v196
	v_lshlrev_b32_e32 v212, 16, v213
	s_nop 0
	v_addc_co_u32_e32 v209, vcc, 0, v197, vcc
	global_load_dwordx4 v[242:245], v[208:209], off offset:2048
	v_and_b32_e32 v213, 0xffff0000, v213
	v_lshlrev_b32_e32 v234, 16, v214
	v_and_b32_e32 v235, 0xffff0000, v214
	v_lshlrev_b32_e32 v214, 16, v215
	v_and_b32_e32 v215, 0xffff0000, v215
	v_pk_fma_f32 v[98:99], v[98:99], v[176:177], v[212:213]
	v_pk_fma_f32 v[96:97], v[96:97], v[174:175], v[220:221]
	v_pk_fma_f32 v[94:95], v[94:95], v[172:173], v[214:215]
	v_pk_fma_f32 v[92:93], v[92:93], v[164:165], v[234:235]
	v_cvt_pk_bf16_f32 v214, v96, v97
	v_cvt_pk_bf16_f32 v215, v98, v99
	v_add_co_u32_e32 v212, vcc, s19, v182
	v_lshlrev_b32_e32 v246, 16, v216
	v_and_b32_e32 v247, 0xffff0000, v216
	v_lshlrev_b32_e32 v248, 16, v217
	v_and_b32_e32 v249, 0xffff0000, v217
	v_cvt_pk_bf16_f32 v216, v92, v93
	v_cvt_pk_bf16_f32 v217, v94, v95
	v_addc_co_u32_e32 v213, vcc, 0, v183, vcc
	v_lshlrev_b32_e32 v98, 16, v214
	v_and_b32_e32 v99, 0xffff0000, v214
	v_lshlrev_b32_e32 v96, 16, v215
	v_and_b32_e32 v97, 0xffff0000, v215
	global_store_dwordx4 v[212:213], v[214:217], off offset:2048
	v_lshlrev_b32_e32 v94, 16, v216
	v_and_b32_e32 v95, 0xffff0000, v216
	v_lshlrev_b32_e32 v92, 16, v217
	v_and_b32_e32 v93, 0xffff0000, v217
	v_pk_mul_f32 v[214:215], v[138:139], v[96:97]
	v_pk_mul_f32 v[216:217], v[136:137], v[98:99]
	s_mov_b32 s1, 0x40000
	v_lshlrev_b32_e32 v250, 16, v218
	v_and_b32_e32 v251, 0xffff0000, v218
	v_lshlrev_b32_e32 v252, 16, v219
	v_and_b32_e32 v253, 0xffff0000, v219
	v_pk_mul_f32 v[220:221], v[134:135], v[92:93]
	v_pk_mul_f32 v[218:219], v[132:133], v[94:95]
	v_cvt_pk_bf16_f32 v216, v216, v217
	v_cvt_pk_bf16_f32 v217, v214, v215
	v_add_co_u32_e32 v214, vcc, s1, v178
	v_cvt_pk_bf16_f32 v218, v218, v219
	v_cvt_pk_bf16_f32 v219, v220, v221
	v_addc_co_u32_e32 v215, vcc, 0, v179, vcc
	v_pk_fma_f32 v[90:91], v[90:91], v[176:177], v[248:249]
	global_store_dwordx4 v[214:215], v[216:219], off
	v_pk_fma_f32 v[88:89], v[88:89], v[174:175], v[246:247]
	v_pk_fma_f32 v[86:87], v[86:87], v[172:173], v[252:253]
	v_pk_fma_f32 v[84:85], v[84:85], v[164:165], v[250:251]
	v_cvt_pk_bf16_f32 v219, v90, v91
	v_add_co_u32_e32 v216, vcc, s26, v182
	v_cvt_pk_bf16_f32 v218, v88, v89
	v_cvt_pk_bf16_f32 v220, v84, v85
	v_cvt_pk_bf16_f32 v221, v86, v87
	v_addc_co_u32_e32 v217, vcc, 0, v183, vcc
	v_lshlrev_b32_e32 v88, 16, v219
	v_and_b32_e32 v89, 0xffff0000, v219
	global_store_dwordx4 v[216:217], v[218:221], off offset:2048
	v_lshlrev_b32_e32 v90, 16, v218
	v_and_b32_e32 v91, 0xffff0000, v218
	v_lshlrev_b32_e32 v86, 16, v220
	v_and_b32_e32 v87, 0xffff0000, v220
	v_lshlrev_b32_e32 v84, 16, v221
	v_and_b32_e32 v85, 0xffff0000, v221
	v_pk_mul_f32 v[218:219], v[138:139], v[88:89]
	s_mov_b32 s1, 0x48000
	v_pk_mul_f32 v[220:221], v[136:137], v[90:91]
	v_pk_mul_f32 v[234:235], v[134:135], v[84:85]
	v_pk_mul_f32 v[248:249], v[132:133], v[86:87]
	v_cvt_pk_bf16_f32 v247, v218, v219
	v_add_co_u32_e32 v218, vcc, s1, v178
	v_cvt_pk_bf16_f32 v246, v220, v221
	v_cvt_pk_bf16_f32 v248, v248, v249
	v_cvt_pk_bf16_f32 v249, v234, v235
	v_addc_co_u32_e32 v219, vcc, 0, v179, vcc
	global_store_dwordx4 v[218:219], v[246:249], off
	global_load_dwordx4 v[246:249], v[196:197], off offset:2304
	s_nop 0
	global_load_dwordx4 v[250:253], v[210:211], off offset:2304
	s_waitcnt vmcnt(0)
	v_lshlrev_b32_e32 v210, 16, v239
	v_and_b32_e32 v211, 0xffff0000, v239
	v_lshlrev_b32_e32 v196, 16, v238
	v_and_b32_e32 v197, 0xffff0000, v238
	v_pk_fma_f32 v[82:83], v[82:83], v[176:177], v[210:211]
	v_lshlrev_b32_e32 v220, 16, v240
	v_and_b32_e32 v221, 0xffff0000, v240
	v_lshlrev_b32_e32 v234, 16, v241
	v_and_b32_e32 v235, 0xffff0000, v241
	v_pk_fma_f32 v[80:81], v[80:81], v[174:175], v[196:197]
	v_cvt_pk_bf16_f32 v239, v82, v83
	v_pk_fma_f32 v[78:79], v[78:79], v[172:173], v[234:235]
	v_pk_fma_f32 v[76:77], v[76:77], v[164:165], v[220:221]
	v_cvt_pk_bf16_f32 v238, v80, v81
	v_add_co_u32_e32 v196, vcc, s76, v182
	v_lshlrev_b32_e32 v80, 16, v239
	v_and_b32_e32 v81, 0xffff0000, v239
	v_cvt_pk_bf16_f32 v240, v76, v77
	v_cvt_pk_bf16_f32 v241, v78, v79
	v_addc_co_u32_e32 v197, vcc, 0, v183, vcc
	v_pk_mul_f32 v[210:211], v[138:139], v[80:81]
	v_lshlrev_b32_e32 v166, 16, v242
	v_and_b32_e32 v167, 0xffff0000, v242
	v_lshlrev_b32_e32 v242, 16, v243
	v_and_b32_e32 v243, 0xffff0000, v243
	v_lshlrev_b32_e32 v168, 16, v244
	v_and_b32_e32 v169, 0xffff0000, v244
	v_lshlrev_b32_e32 v244, 16, v245
	v_and_b32_e32 v245, 0xffff0000, v245
	global_store_dwordx4 v[196:197], v[238:241], off offset:2048
	v_lshlrev_b32_e32 v82, 16, v238
	v_and_b32_e32 v83, 0xffff0000, v238
	v_cvt_pk_bf16_f32 v239, v210, v211
	v_add_co_u32_e32 v210, vcc, s77, v178
	v_lshlrev_b32_e32 v78, 16, v240
	v_and_b32_e32 v79, 0xffff0000, v240
	v_lshlrev_b32_e32 v76, 16, v241
	v_and_b32_e32 v77, 0xffff0000, v241
	v_pk_mul_f32 v[220:221], v[136:137], v[82:83]
	v_addc_co_u32_e32 v211, vcc, 0, v179, vcc
	v_pk_fma_f32 v[74:75], v[74:75], v[176:177], v[242:243]
	v_pk_fma_f32 v[72:73], v[72:73], v[174:175], v[166:167]
	v_pk_fma_f32 v[166:167], v[70:71], v[172:173], v[244:245]
	v_pk_fma_f32 v[70:71], v[68:69], v[164:165], v[168:169]
	v_pk_mul_f32 v[234:235], v[134:135], v[76:77]
	v_pk_mul_f32 v[240:241], v[132:133], v[78:79]
	v_cvt_pk_bf16_f32 v238, v220, v221
	v_cvt_pk_bf16_f32 v68, v72, v73
	v_cvt_pk_bf16_f32 v69, v74, v75
	v_cvt_pk_bf16_f32 v70, v70, v71
	v_cvt_pk_bf16_f32 v71, v166, v167
	v_add_co_u32_e32 v220, vcc, s0, v182
	v_cvt_pk_bf16_f32 v240, v240, v241
	v_cvt_pk_bf16_f32 v241, v234, v235
	v_addc_co_u32_e32 v221, vcc, 0, v183, vcc
	v_lshlrev_b32_e32 v176, 16, v68
	v_and_b32_e32 v177, 0xffff0000, v68
	v_lshlrev_b32_e32 v174, 16, v69
	v_and_b32_e32 v175, 0xffff0000, v69
	v_lshlrev_b32_e32 v172, 16, v70
	v_and_b32_e32 v173, 0xffff0000, v70
	v_lshlrev_b32_e32 v164, 16, v71
	v_and_b32_e32 v165, 0xffff0000, v71
	s_mov_b32 s0, 0x58000
	global_store_dwordx4 v[210:211], v[238:241], off
	global_store_dwordx4 v[220:221], v[68:71], off offset:2048
	v_pk_mul_f32 v[72:73], v[134:135], v[164:165]
	v_pk_mul_f32 v[74:75], v[132:133], v[172:173]
	v_pk_mul_f32 v[70:71], v[138:139], v[174:175]
	v_pk_mul_f32 v[68:69], v[136:137], v[176:177]
	v_add_co_u32_e32 v132, vcc, s0, v178
	v_cvt_pk_bf16_f32 v68, v68, v69
	v_cvt_pk_bf16_f32 v69, v70, v71
	v_cvt_pk_bf16_f32 v70, v74, v75
	v_cvt_pk_bf16_f32 v71, v72, v73
	v_addc_co_u32_e32 v133, vcc, 0, v179, vcc
	global_store_dwordx4 v[132:133], v[68:71], off
	global_load_dwordx4 v[134:137], v[184:185], off offset:2304
	global_load_dwordx4 v[238:241], v[188:189], off offset:2304
	s_nop 0
	global_load_dwordx4 v[68:71], v[180:181], off offset:528
	global_load_dwordx4 v[72:75], v[180:181], off offset:512
	v_lshlrev_b32_e32 v138, 16, v246
	v_and_b32_e32 v139, 0xffff0000, v246
	v_lshlrev_b32_e32 v166, 16, v247
	v_and_b32_e32 v167, 0xffff0000, v247
	v_lshlrev_b32_e32 v168, 16, v248
	v_and_b32_e32 v169, 0xffff0000, v248
	v_lshlrev_b32_e32 v180, 16, v249
	v_and_b32_e32 v181, 0xffff0000, v249
	v_pk_fma_f32 v[66:67], v[66:67], v[162:163], v[166:167]
	v_pk_fma_f32 v[64:65], v[64:65], v[160:161], v[138:139]
	v_pk_fma_f32 v[62:63], v[62:63], v[158:159], v[180:181]
	v_pk_fma_f32 v[60:61], v[60:61], v[156:157], v[168:169]
	v_cvt_pk_bf16_f32 v242, v64, v65
	v_cvt_pk_bf16_f32 v243, v66, v67
	v_cvt_pk_bf16_f32 v244, v60, v61
	v_cvt_pk_bf16_f32 v245, v62, v63
	v_lshlrev_b32_e32 v66, 16, v242
	v_and_b32_e32 v67, 0xffff0000, v242
	v_lshlrev_b32_e32 v64, 16, v243
	v_and_b32_e32 v65, 0xffff0000, v243
	v_lshlrev_b32_e32 v62, 16, v244
	v_and_b32_e32 v63, 0xffff0000, v244
	v_lshlrev_b32_e32 v60, 16, v245
	v_and_b32_e32 v61, 0xffff0000, v245
	v_lshlrev_b32_e32 v184, 16, v250
	v_and_b32_e32 v185, 0xffff0000, v250
	v_lshlrev_b32_e32 v188, 16, v251
	v_and_b32_e32 v189, 0xffff0000, v251
	v_lshlrev_b32_e32 v234, 16, v252
	v_and_b32_e32 v235, 0xffff0000, v252
	v_lshlrev_b32_e32 v246, 16, v253
	v_and_b32_e32 v247, 0xffff0000, v253
	global_store_dwordx4 v[182:183], v[242:245], off offset:2304
	v_pk_fma_f32 v[58:59], v[58:59], v[162:163], v[188:189]
	v_pk_fma_f32 v[56:57], v[56:57], v[160:161], v[184:185]
	v_pk_fma_f32 v[54:55], v[54:55], v[158:159], v[246:247]
	v_pk_fma_f32 v[52:53], v[52:53], v[156:157], v[234:235]
	s_waitcnt vmcnt(0)
	v_lshlrev_b32_e32 v188, 16, v240
	v_pk_mul_f32 v[168:169], v[70:71], v[60:61]
	v_pk_mul_f32 v[138:139], v[74:75], v[64:65]
	v_pk_mul_f32 v[166:167], v[72:73], v[66:67]
	v_pk_mul_f32 v[182:183], v[68:69], v[62:63]
	v_cvt_pk_bf16_f32 v180, v166, v167
	v_cvt_pk_bf16_f32 v181, v138, v139
	v_cvt_pk_bf16_f32 v182, v182, v183
	v_cvt_pk_bf16_f32 v183, v168, v169
	global_store_dwordx4 v[178:179], v[180:183], off offset:256
	v_cvt_pk_bf16_f32 v178, v56, v57
	v_cvt_pk_bf16_f32 v179, v58, v59
	v_cvt_pk_bf16_f32 v180, v52, v53
	v_cvt_pk_bf16_f32 v181, v54, v55
	v_lshlrev_b32_e32 v58, 16, v178
	v_and_b32_e32 v59, 0xffff0000, v178
	v_lshlrev_b32_e32 v56, 16, v179
	v_and_b32_e32 v57, 0xffff0000, v179
	v_lshlrev_b32_e32 v54, 16, v180
	v_and_b32_e32 v55, 0xffff0000, v180
	v_lshlrev_b32_e32 v52, 16, v181
	v_and_b32_e32 v53, 0xffff0000, v181
	global_store_dwordx4 v[186:187], v[178:181], off offset:2304
	v_pk_mul_f32 v[138:139], v[74:75], v[56:57]
	v_pk_mul_f32 v[166:167], v[72:73], v[58:59]
	v_pk_mul_f32 v[168:169], v[70:71], v[52:53]
	v_pk_mul_f32 v[180:181], v[68:69], v[54:55]
	v_cvt_pk_bf16_f32 v178, v166, v167
	v_cvt_pk_bf16_f32 v179, v138, v139
	v_cvt_pk_bf16_f32 v180, v180, v181
	v_cvt_pk_bf16_f32 v181, v168, v169
	v_lshlrev_b32_e32 v138, 16, v134
	v_and_b32_e32 v139, 0xffff0000, v134
	v_lshlrev_b32_e32 v134, 16, v135
	v_and_b32_e32 v135, 0xffff0000, v135
	v_lshlrev_b32_e32 v166, 16, v136
	v_and_b32_e32 v167, 0xffff0000, v136
	v_lshlrev_b32_e32 v136, 16, v137
	v_and_b32_e32 v137, 0xffff0000, v137
	global_store_dwordx4 v[190:191], v[178:181], off offset:256
	v_pk_fma_f32 v[50:51], v[50:51], v[162:163], v[134:135]
	v_pk_fma_f32 v[48:49], v[48:49], v[160:161], v[138:139]
	v_pk_fma_f32 v[46:47], v[46:47], v[158:159], v[136:137]
	v_pk_fma_f32 v[44:45], v[44:45], v[156:157], v[166:167]
	global_load_dwordx4 v[178:181], v[192:193], off offset:2304
	global_load_dwordx4 v[182:185], v[194:195], off offset:2304
	v_cvt_pk_bf16_f32 v134, v48, v49
	v_cvt_pk_bf16_f32 v135, v50, v51
	v_cvt_pk_bf16_f32 v136, v44, v45
	v_cvt_pk_bf16_f32 v137, v46, v47
	v_lshlrev_b32_e32 v50, 16, v134
	v_and_b32_e32 v51, 0xffff0000, v134
	v_lshlrev_b32_e32 v48, 16, v135
	v_and_b32_e32 v49, 0xffff0000, v135
	v_lshlrev_b32_e32 v46, 16, v136
	v_and_b32_e32 v47, 0xffff0000, v136
	v_lshlrev_b32_e32 v44, 16, v137
	v_and_b32_e32 v45, 0xffff0000, v137
	v_lshlrev_b32_e32 v168, 16, v238
	v_and_b32_e32 v169, 0xffff0000, v238
	v_lshlrev_b32_e32 v186, 16, v239
	v_and_b32_e32 v187, 0xffff0000, v239
	v_and_b32_e32 v189, 0xffff0000, v240
	v_lshlrev_b32_e32 v190, 16, v241
	v_and_b32_e32 v191, 0xffff0000, v241
	global_store_dwordx4 v[198:199], v[134:137], off offset:2304
	v_pk_mul_f32 v[138:139], v[70:71], v[44:45]
	v_pk_mul_f32 v[166:167], v[68:69], v[46:47]
	v_pk_mul_f32 v[136:137], v[74:75], v[48:49]
	v_pk_mul_f32 v[134:135], v[72:73], v[50:51]
	v_pk_fma_f32 v[42:43], v[42:43], v[162:163], v[186:187]
	v_cvt_pk_bf16_f32 v134, v134, v135
	v_cvt_pk_bf16_f32 v135, v136, v137
	v_cvt_pk_bf16_f32 v136, v166, v167
	v_cvt_pk_bf16_f32 v137, v138, v139
	v_pk_fma_f32 v[40:41], v[40:41], v[160:161], v[168:169]
	v_pk_fma_f32 v[38:39], v[38:39], v[158:159], v[190:191]
	v_pk_fma_f32 v[36:37], v[36:37], v[156:157], v[188:189]
	global_store_dwordx4 v[200:201], v[134:137], off offset:256
	v_mul_f32_e32 v67, v67, v67
	v_mul_f32_e32 v65, v65, v65
	v_cvt_pk_bf16_f32 v134, v40, v41
	v_cvt_pk_bf16_f32 v135, v42, v43
	v_cvt_pk_bf16_f32 v136, v36, v37
	v_cvt_pk_bf16_f32 v137, v38, v39
	v_lshlrev_b32_e32 v42, 16, v134
	v_and_b32_e32 v43, 0xffff0000, v134
	v_lshlrev_b32_e32 v40, 16, v135
	v_and_b32_e32 v41, 0xffff0000, v135
	v_lshlrev_b32_e32 v38, 16, v136
	v_and_b32_e32 v39, 0xffff0000, v136
	v_lshlrev_b32_e32 v36, 16, v137
	v_and_b32_e32 v37, 0xffff0000, v137
	global_store_dwordx4 v[202:203], v[134:137], off offset:2304
	v_pk_mul_f32 v[138:139], v[70:71], v[36:37]
	v_pk_mul_f32 v[166:167], v[68:69], v[38:39]
	v_pk_mul_f32 v[136:137], v[74:75], v[40:41]
	v_pk_mul_f32 v[134:135], v[72:73], v[42:43]
	v_fmac_f32_e32 v67, v66, v66
	v_cvt_pk_bf16_f32 v134, v134, v135
	v_cvt_pk_bf16_f32 v135, v136, v137
	v_cvt_pk_bf16_f32 v136, v166, v167
	v_cvt_pk_bf16_f32 v137, v138, v139
	global_store_dwordx4 v[204:205], v[134:137], off offset:256
	global_load_dwordx4 v[134:137], v[206:207], off offset:2304
	s_nop 0
	global_load_dwordx4 v[186:189], v[208:209], off offset:2304
	v_fmac_f32_e32 v65, v64, v64
	v_mul_f32_e32 v63, v63, v63
	v_mul_f32_e32 v61, v61, v61
	v_add_f32_e32 v64, v67, v65
	v_fmac_f32_e32 v63, v62, v62
	v_fmac_f32_e32 v61, v60, v60
	v_add_f32_e32 v60, v63, v61
	s_waitcnt vmcnt(0)
	v_lshlrev_b32_e32 v138, 16, v178
	v_and_b32_e32 v139, 0xffff0000, v178
	v_lshlrev_b32_e32 v166, 16, v179
	v_and_b32_e32 v167, 0xffff0000, v179
	v_lshlrev_b32_e32 v168, 16, v180
	v_and_b32_e32 v169, 0xffff0000, v180
	v_lshlrev_b32_e32 v178, 16, v181
	v_and_b32_e32 v179, 0xffff0000, v181
	v_pk_fma_f32 v[34:35], v[34:35], v[162:163], v[166:167]
	v_pk_fma_f32 v[32:33], v[32:33], v[160:161], v[138:139]
	v_pk_fma_f32 v[30:31], v[30:31], v[158:159], v[178:179]
	v_pk_fma_f32 v[28:29], v[28:29], v[156:157], v[168:169]
	v_cvt_pk_bf16_f32 v178, v32, v33
	v_cvt_pk_bf16_f32 v179, v34, v35
	v_cvt_pk_bf16_f32 v180, v28, v29
	v_cvt_pk_bf16_f32 v181, v30, v31
	v_lshlrev_b32_e32 v34, 16, v178
	v_and_b32_e32 v35, 0xffff0000, v178
	v_lshlrev_b32_e32 v32, 16, v179
	v_and_b32_e32 v33, 0xffff0000, v179
	v_lshlrev_b32_e32 v30, 16, v180
	v_and_b32_e32 v31, 0xffff0000, v180
	v_lshlrev_b32_e32 v28, 16, v181
	v_and_b32_e32 v29, 0xffff0000, v181
	v_lshlrev_b32_e32 v190, 16, v182
	v_and_b32_e32 v191, 0xffff0000, v182
	v_lshlrev_b32_e32 v182, 16, v183
	v_and_b32_e32 v183, 0xffff0000, v183
	global_store_dwordx4 v[212:213], v[178:181], off offset:2304
	v_pk_mul_f32 v[138:139], v[74:75], v[32:33]
	v_pk_mul_f32 v[166:167], v[72:73], v[34:35]
	v_pk_mul_f32 v[168:169], v[70:71], v[28:29]
	v_pk_mul_f32 v[180:181], v[68:69], v[30:31]
	v_cvt_pk_bf16_f32 v178, v166, v167
	v_cvt_pk_bf16_f32 v179, v138, v139
	v_cvt_pk_bf16_f32 v180, v180, v181
	v_cvt_pk_bf16_f32 v181, v168, v169
	v_pk_fma_f32 v[24:25], v[24:25], v[162:163], v[182:183]
	v_pk_fma_f32 v[22:23], v[22:23], v[160:161], v[190:191]
	v_lshlrev_b32_e32 v192, 16, v184
	v_and_b32_e32 v193, 0xffff0000, v184
	v_lshlrev_b32_e32 v184, 16, v185
	v_and_b32_e32 v185, 0xffff0000, v185
	global_store_dwordx4 v[214:215], v[178:181], off offset:256
	v_pk_fma_f32 v[20:21], v[20:21], v[158:159], v[184:185]
	v_pk_fma_f32 v[18:19], v[18:19], v[156:157], v[192:193]
	v_cvt_pk_bf16_f32 v178, v22, v23
	v_cvt_pk_bf16_f32 v179, v24, v25
	v_lshlrev_b32_e32 v24, 16, v178
	v_and_b32_e32 v25, 0xffff0000, v178
	v_lshlrev_b32_e32 v22, 16, v179
	v_and_b32_e32 v23, 0xffff0000, v179
	v_cvt_pk_bf16_f32 v180, v18, v19
	v_cvt_pk_bf16_f32 v181, v20, v21
	v_pk_mul_f32 v[138:139], v[74:75], v[22:23]
	v_pk_mul_f32 v[166:167], v[72:73], v[24:25]
	global_store_dwordx4 v[216:217], v[178:181], off offset:2304
	v_lshlrev_b32_e32 v20, 16, v180
	v_and_b32_e32 v21, 0xffff0000, v180
	v_cvt_pk_bf16_f32 v178, v166, v167
	v_cvt_pk_bf16_f32 v179, v138, v139
	v_lshlrev_b32_e32 v138, 16, v134
	v_and_b32_e32 v139, 0xffff0000, v134
	v_lshlrev_b32_e32 v134, 16, v135
	v_and_b32_e32 v135, 0xffff0000, v135
	v_lshlrev_b32_e32 v166, 16, v136
	v_and_b32_e32 v167, 0xffff0000, v136
	v_lshlrev_b32_e32 v136, 16, v137
	v_and_b32_e32 v137, 0xffff0000, v137
	v_lshlrev_b32_e32 v18, 16, v181
	v_and_b32_e32 v19, 0xffff0000, v181
	v_pk_fma_f32 v[16:17], v[16:17], v[162:163], v[134:135]
	v_pk_fma_f32 v[14:15], v[14:15], v[160:161], v[138:139]
	v_pk_fma_f32 v[12:13], v[12:13], v[158:159], v[136:137]
	v_pk_fma_f32 v[10:11], v[10:11], v[156:157], v[166:167]
	v_pk_mul_f32 v[168:169], v[70:71], v[18:19]
	v_pk_mul_f32 v[180:181], v[68:69], v[20:21]
	v_cvt_pk_bf16_f32 v134, v14, v15
	v_cvt_pk_bf16_f32 v135, v16, v17
	v_cvt_pk_bf16_f32 v136, v10, v11
	v_cvt_pk_bf16_f32 v137, v12, v13
	v_cvt_pk_bf16_f32 v180, v180, v181
	v_cvt_pk_bf16_f32 v181, v168, v169
	v_lshlrev_b32_e32 v16, 16, v134
	v_and_b32_e32 v17, 0xffff0000, v134
	v_lshlrev_b32_e32 v14, 16, v135
	v_and_b32_e32 v15, 0xffff0000, v135
	v_lshlrev_b32_e32 v12, 16, v136
	v_and_b32_e32 v13, 0xffff0000, v136
	v_lshlrev_b32_e32 v10, 16, v137
	v_and_b32_e32 v11, 0xffff0000, v137
	global_store_dwordx4 v[218:219], v[178:181], off offset:256
	v_lshlrev_b32_e32 v168, 16, v186
	v_and_b32_e32 v169, 0xffff0000, v186
	v_lshlrev_b32_e32 v178, 16, v187
	v_and_b32_e32 v179, 0xffff0000, v187
	v_lshlrev_b32_e32 v180, 16, v188
	v_and_b32_e32 v181, 0xffff0000, v188
	v_lshlrev_b32_e32 v182, 16, v189
	v_and_b32_e32 v183, 0xffff0000, v189
	global_store_dwordx4 v[196:197], v[134:137], off offset:2304
	v_pk_mul_f32 v[138:139], v[70:71], v[10:11]
	v_pk_mul_f32 v[166:167], v[68:69], v[12:13]
	v_pk_mul_f32 v[136:137], v[74:75], v[14:15]
	v_pk_mul_f32 v[134:135], v[72:73], v[16:17]
	v_pk_fma_f32 v[8:9], v[8:9], v[162:163], v[178:179]
	v_cvt_pk_bf16_f32 v134, v134, v135
	v_cvt_pk_bf16_f32 v135, v136, v137
	v_cvt_pk_bf16_f32 v136, v166, v167
	v_cvt_pk_bf16_f32 v137, v138, v139
	v_pk_fma_f32 v[6:7], v[6:7], v[160:161], v[168:169]
	v_pk_fma_f32 v[4:5], v[4:5], v[158:159], v[182:183]
	v_pk_fma_f32 v[2:3], v[2:3], v[156:157], v[180:181]
	global_store_dwordx4 v[210:211], v[134:137], off offset:256
	s_nop 1
	v_cvt_pk_bf16_f32 v134, v6, v7
	v_cvt_pk_bf16_f32 v135, v8, v9
	v_cvt_pk_bf16_f32 v136, v2, v3
	v_cvt_pk_bf16_f32 v137, v4, v5
	v_lshlrev_b32_e32 v8, 16, v134
	v_and_b32_e32 v9, 0xffff0000, v134
	v_lshlrev_b32_e32 v6, 16, v135
	v_and_b32_e32 v7, 0xffff0000, v135
	v_lshlrev_b32_e32 v4, 16, v136
	v_and_b32_e32 v5, 0xffff0000, v136
	v_lshlrev_b32_e32 v2, 16, v137
	v_and_b32_e32 v3, 0xffff0000, v137
	global_store_dwordx4 v[220:221], v[134:137], off offset:2304
	v_pk_mul_f32 v[74:75], v[74:75], v[6:7]
	v_pk_mul_f32 v[72:73], v[72:73], v[8:9]
	v_pk_mul_f32 v[134:135], v[70:71], v[2:3]
	v_pk_mul_f32 v[70:71], v[68:69], v[4:5]
	v_cvt_pk_bf16_f32 v68, v72, v73
	v_cvt_pk_bf16_f32 v69, v74, v75
	v_cvt_pk_bf16_f32 v70, v70, v71
	v_cvt_pk_bf16_f32 v71, v134, v135
	global_store_dwordx4 v[132:133], v[68:71], off offset:256
	v_xor_b32_e32 v72, 32, v227
	v_mul_f32_e32 v73, v129, v129
	v_and_b32_e32 v71, 64, v227
	v_xor_b32_e32 v70, 16, v227
	v_add_u32_e32 v71, 64, v71
	v_cmp_lt_i32_e32 vcc, v70, v71
	v_fmac_f32_e32 v73, v128, v128
	v_mul_f32_e32 v74, v125, v125
	v_cndmask_b32_e32 v70, v227, v70, vcc
	v_cmp_lt_i32_e32 vcc, v72, v71
	v_fmac_f32_e32 v74, v124, v124
	v_lshlrev_b32_e32 v70, 2, v70
	v_cndmask_b32_e32 v71, v227, v72, vcc
	v_mul_f32_e32 v72, v131, v131
	v_fmac_f32_e32 v72, v130, v130
	v_add_f32_e32 v72, v72, v73
	v_mul_f32_e32 v73, v127, v127
	v_fmac_f32_e32 v73, v126, v126
	v_add_f32_e32 v73, v73, v74
	v_add_f32_e32 v72, v72, v73
	v_add_f32_e32 v64, v72, v64
	v_add_f32_e32 v60, v60, v64
	ds_bpermute_b32 v61, v70, v60
	v_lshlrev_b32_e32 v71, 2, v71
	v_lshl_add_u64 v[68:69], v[150:151], 0, s[24:25]
	s_waitcnt lgkmcnt(0)
	v_add_f32_e32 v60, v60, v61
	ds_bpermute_b32 v61, v71, v60
	s_and_saveexec_b64 s[18:19], s[40:41]
	s_cbranch_execz .LBB0_364
	s_waitcnt lgkmcnt(0)
	v_add_f32_e32 v60, v60, v61
	global_atomic_add_f32 v[68:69], v60, off

.LBB0_395:
	s_add_u32 s26, s24, 0x100
	s_addc_u32 s27, s25, 0
	s_add_i32 s0, 0, 0x10000
	s_cmp_eq_u32 s52, 40
	s_cselect_b32 s31, s43, s27
	s_cselect_b32 s30, s42, s26
	s_cselect_b32 s29, s45, s19
	s_cselect_b32 s28, s44, s18
	s_add_i32 m0, s69, 0xc000
	ds_read_b128 v[172:175], v235
	ds_read_b128 v[176:179], v235 offset:1024
	ds_read_b128 v[180:183], v235 offset:2048
	ds_read_b128 v[184:187], v235 offset:3072
	ds_read_b128 v[188:191], v235 offset:4096
	ds_read_b128 v[192:195], v235 offset:5120
	ds_read_b128 v[196:199], v235 offset:6144
	ds_read_b128 v[200:203], v235 offset:7168
	global_load_lds_dwordx4 v152, s[24:25]
	v_lshl_add_u64 v[164:165], s[24:25], 0, v[154:155]
	s_add_i32 m0, s69, 0xe000
	s_nop 0
	global_load_lds_dwordx4 v[164:165], off
	s_waitcnt vmcnt(10) lgkmcnt(8)
	s_setprio 1
	s_barrier
	s_waitcnt lgkmcnt(0)
	v_mfma_f32_16x16x32_bf16 v[136:139], v[100:103], v[172:175], v[136:139]
	v_mfma_f32_16x16x32_bf16 v[132:135], v[156:159], v[172:175], v[132:135]
	v_mfma_f32_16x16x32_bf16 v[128:131], v[100:103], v[180:183], v[128:131]
	v_mfma_f32_16x16x32_bf16 v[124:127], v[156:159], v[180:183], v[124:127]
	v_mfma_f32_16x16x32_bf16 v[120:123], v[100:103], v[188:191], v[120:123]
	v_mfma_f32_16x16x32_bf16 v[116:119], v[156:159], v[188:191], v[116:119]
	v_mfma_f32_16x16x32_bf16 v[112:115], v[100:103], v[196:199], v[112:115]
	v_mfma_f32_16x16x32_bf16 v[108:111], v[156:159], v[196:199], v[108:111]
	v_mfma_f32_16x16x32_bf16 v[136:139], v[104:107], v[176:179], v[136:139]
	v_mfma_f32_16x16x32_bf16 v[132:135], v[160:163], v[176:179], v[132:135]
	v_mfma_f32_16x16x32_bf16 v[128:131], v[104:107], v[184:187], v[128:131]
	v_mfma_f32_16x16x32_bf16 v[124:127], v[160:163], v[184:187], v[124:127]
	v_mfma_f32_16x16x32_bf16 v[120:123], v[104:107], v[192:195], v[120:123]
	v_mfma_f32_16x16x32_bf16 v[116:119], v[160:163], v[192:195], v[116:119]
	v_mfma_f32_16x16x32_bf16 v[112:115], v[104:107], v[200:203], v[112:115]
	v_mfma_f32_16x16x32_bf16 v[108:111], v[160:163], v[200:203], v[108:111]
	s_barrier
	s_setprio 0
	s_add_i32 s24, 0, 0x14000
	v_add_u32_e32 v164, s24, v233
	s_add_i32 s0, s0, s68
	ds_read_b128 v[204:207], v164
	ds_read_b128 v[208:211], v164 offset:1024
	ds_read_b128 v[212:215], v164 offset:2048
	ds_read_b128 v[216:219], v164 offset:3072
	v_lshl_add_u64 v[164:165], s[28:29], 0, v[26:27]
	s_mov_b32 m0, s0
	v_lshl_add_u64 v[220:221], s[28:29], 0, v[140:141]
	global_load_lds_dwordx4 v[164:165], off
	s_add_i32 m0, s0, 0x2000
	s_nop 0
	global_load_lds_dwordx4 v[220:221], off
	s_waitcnt vmcnt(10)
	s_setprio 1
	s_barrier
	s_waitcnt lgkmcnt(0)
	v_mfma_f32_16x16x32_bf16 v[64:67], v[204:207], v[172:175], v[64:67]
	v_mfma_f32_16x16x32_bf16 v[60:63], v[212:215], v[172:175], v[60:63]
	v_mfma_f32_16x16x32_bf16 v[56:59], v[204:207], v[180:183], v[56:59]
	v_mfma_f32_16x16x32_bf16 v[52:55], v[212:215], v[180:183], v[52:55]
	v_mfma_f32_16x16x32_bf16 v[48:51], v[204:207], v[188:191], v[48:51]
	v_mfma_f32_16x16x32_bf16 v[44:47], v[212:215], v[188:191], v[44:47]
	v_mfma_f32_16x16x32_bf16 v[40:43], v[204:207], v[196:199], v[40:43]
	v_mfma_f32_16x16x32_bf16 v[36:39], v[212:215], v[196:199], v[36:39]
	v_mfma_f32_16x16x32_bf16 v[64:67], v[208:211], v[176:179], v[64:67]
	v_mfma_f32_16x16x32_bf16 v[60:63], v[216:219], v[176:179], v[60:63]
	v_mfma_f32_16x16x32_bf16 v[56:59], v[208:211], v[184:187], v[56:59]
	v_mfma_f32_16x16x32_bf16 v[52:55], v[216:219], v[184:187], v[52:55]
	v_mfma_f32_16x16x32_bf16 v[48:51], v[208:211], v[192:195], v[48:51]
	v_mfma_f32_16x16x32_bf16 v[44:47], v[216:219], v[192:195], v[44:47]
	v_mfma_f32_16x16x32_bf16 v[40:43], v[208:211], v[200:203], v[40:43]
	v_mfma_f32_16x16x32_bf16 v[36:39], v[216:219], v[200:203], v[36:39]
	s_barrier
	s_setprio 0
	s_mov_b32 m0, s69
	v_lshl_add_u64 v[222:223], s[30:31], 0, v[144:145]
	ds_read_b128 v[172:175], v235 offset:16384
	ds_read_b128 v[176:179], v235 offset:17408
	ds_read_b128 v[180:183], v235 offset:18432
	ds_read_b128 v[184:187], v235 offset:19456
	ds_read_b128 v[188:191], v235 offset:20480
	ds_read_b128 v[192:195], v235 offset:21504
	ds_read_b128 v[196:199], v235 offset:22528
	ds_read_b128 v[200:203], v235 offset:23552
	global_load_lds_dwordx4 v[222:223], off
	v_lshl_add_u64 v[224:225], s[30:31], 0, v[142:143]
	s_mov_b32 m0, s72
	s_nop 0
	global_load_lds_dwordx4 v[224:225], off
	s_waitcnt vmcnt(10)
	s_setprio 1
	s_barrier
	s_waitcnt lgkmcnt(0)
	v_mfma_f32_16x16x32_bf16 v[96:99], v[100:103], v[172:175], v[96:99]
	v_mfma_f32_16x16x32_bf16 v[92:95], v[156:159], v[172:175], v[92:95]
	v_mfma_f32_16x16x32_bf16 v[88:91], v[100:103], v[180:183], v[88:91]
	v_mfma_f32_16x16x32_bf16 v[84:87], v[156:159], v[180:183], v[84:87]
	v_mfma_f32_16x16x32_bf16 v[80:83], v[100:103], v[188:191], v[80:83]
	v_mfma_f32_16x16x32_bf16 v[76:79], v[156:159], v[188:191], v[76:79]
	v_mfma_f32_16x16x32_bf16 v[72:75], v[100:103], v[196:199], v[72:75]
	v_mfma_f32_16x16x32_bf16 v[68:71], v[156:159], v[196:199], v[68:71]
	v_mfma_f32_16x16x32_bf16 v[96:99], v[104:107], v[176:179], v[96:99]
	v_mfma_f32_16x16x32_bf16 v[92:95], v[160:163], v[176:179], v[92:95]
	v_mfma_f32_16x16x32_bf16 v[88:91], v[104:107], v[184:187], v[88:91]
	v_mfma_f32_16x16x32_bf16 v[84:87], v[160:163], v[184:187], v[84:87]
	v_mfma_f32_16x16x32_bf16 v[80:83], v[104:107], v[192:195], v[80:83]
	v_mfma_f32_16x16x32_bf16 v[76:79], v[160:163], v[192:195], v[76:79]
	v_mfma_f32_16x16x32_bf16 v[72:75], v[104:107], v[200:203], v[72:75]
	v_mfma_f32_16x16x32_bf16 v[68:71], v[160:163], v[200:203], v[68:71]
	s_barrier
	s_setprio 0
	s_add_u32 s0, s28, 0xb0000
	s_addc_u32 s1, s29, 0
	s_add_i32 s24, s24, s68
	s_mov_b32 m0, s24
	s_nop 0
	global_load_lds_dwordx4 v26, s[0:1]
	s_add_i32 m0, s24, 0x2000
	s_nop 0
	global_load_lds_dwordx4 v140, s[0:1]
	v_add_u32_e32 v160, 0x18000, v233
	ds_read_b128 v[100:103], v160
	ds_read_b128 v[104:107], v160 offset:1024
	ds_read_b128 v[156:159], v160 offset:2048
	ds_read_b128 v[160:163], v160 offset:3072
	s_waitcnt vmcnt(10)
	s_setprio 1
	s_barrier
	v_mfma_f32_16x16x32_bf16 v[32:35], v[204:207], v[172:175], v[32:35]
	v_mfma_f32_16x16x32_bf16 v[28:31], v[212:215], v[172:175], v[28:31]
	v_mfma_f32_16x16x32_bf16 v[22:25], v[204:207], v[180:183], v[22:25]
	v_mfma_f32_16x16x32_bf16 v[18:21], v[212:215], v[180:183], v[18:21]
	v_mfma_f32_16x16x32_bf16 v[14:17], v[204:207], v[188:191], v[14:17]
	v_mfma_f32_16x16x32_bf16 v[10:13], v[212:215], v[188:191], v[10:13]
	v_mfma_f32_16x16x32_bf16 v[6:9], v[204:207], v[196:199], v[6:9]
	v_mfma_f32_16x16x32_bf16 v[2:5], v[212:215], v[196:199], v[2:5]
	v_mfma_f32_16x16x32_bf16 v[32:35], v[208:211], v[176:179], v[32:35]
	v_mfma_f32_16x16x32_bf16 v[28:31], v[216:219], v[176:179], v[28:31]
	v_mfma_f32_16x16x32_bf16 v[22:25], v[208:211], v[184:187], v[22:25]
	v_mfma_f32_16x16x32_bf16 v[18:21], v[216:219], v[184:187], v[18:21]
	v_mfma_f32_16x16x32_bf16 v[14:17], v[208:211], v[192:195], v[14:17]
	v_mfma_f32_16x16x32_bf16 v[10:13], v[216:219], v[192:195], v[10:13]
	v_mfma_f32_16x16x32_bf16 v[6:9], v[208:211], v[200:203], v[6:9]
	v_mfma_f32_16x16x32_bf16 v[2:5], v[216:219], v[200:203], v[2:5]
	s_barrier
	s_setprio 0
	s_add_i32 s24, 0, 0x18000
	s_add_u32 s0, s30, 0xb0000
	s_addc_u32 s1, s31, 0
	s_mov_b32 m0, s73
	ds_read_b128 v[172:175], v235 offset:32768
	ds_read_b128 v[176:179], v235 offset:33792
	ds_read_b128 v[180:183], v235 offset:34816
	ds_read_b128 v[184:187], v235 offset:35840
	ds_read_b128 v[188:191], v235 offset:36864
	ds_read_b128 v[192:195], v235 offset:37888
	ds_read_b128 v[196:199], v235 offset:38912
	ds_read_b128 v[200:203], v235 offset:39936
	global_load_lds_dwordx4 v144, s[0:1]
	s_mov_b32 m0, s81
	s_nop 0
	global_load_lds_dwordx4 v142, s[0:1]
	s_waitcnt vmcnt(10) lgkmcnt(8)
	s_setprio 1
	s_barrier
	s_waitcnt lgkmcnt(0)
	v_mfma_f32_16x16x32_bf16 v[136:139], v[100:103], v[172:175], v[136:139]
	v_mfma_f32_16x16x32_bf16 v[132:135], v[156:159], v[172:175], v[132:135]
	v_mfma_f32_16x16x32_bf16 v[128:131], v[100:103], v[180:183], v[128:131]
	v_mfma_f32_16x16x32_bf16 v[124:127], v[156:159], v[180:183], v[124:127]
	v_mfma_f32_16x16x32_bf16 v[120:123], v[100:103], v[188:191], v[120:123]
	v_mfma_f32_16x16x32_bf16 v[116:119], v[156:159], v[188:191], v[116:119]
	v_mfma_f32_16x16x32_bf16 v[112:115], v[100:103], v[196:199], v[112:115]
	v_mfma_f32_16x16x32_bf16 v[108:111], v[156:159], v[196:199], v[108:111]
	v_mfma_f32_16x16x32_bf16 v[136:139], v[104:107], v[176:179], v[136:139]
	v_mfma_f32_16x16x32_bf16 v[132:135], v[160:163], v[176:179], v[132:135]
	v_mfma_f32_16x16x32_bf16 v[128:131], v[104:107], v[184:187], v[128:131]
	v_mfma_f32_16x16x32_bf16 v[124:127], v[160:163], v[184:187], v[124:127]
	v_mfma_f32_16x16x32_bf16 v[120:123], v[104:107], v[192:195], v[120:123]
	v_mfma_f32_16x16x32_bf16 v[116:119], v[160:163], v[192:195], v[116:119]
	v_mfma_f32_16x16x32_bf16 v[112:115], v[104:107], v[200:203], v[112:115]
	v_mfma_f32_16x16x32_bf16 v[108:111], v[160:163], v[200:203], v[108:111]
	s_barrier
	s_setprio 0
	s_add_i32 s25, 0, 0x1c000
	s_add_i32 s0, s24, s68
	v_add_u32_e32 v166, s25, v233
	v_lshl_add_u64 v[164:165], v[164:165], 0, s[12:13]
	s_mov_b32 m0, s0
	ds_read_b128 v[204:207], v166
	ds_read_b128 v[208:211], v166 offset:1024
	ds_read_b128 v[212:215], v166 offset:2048
	ds_read_b128 v[216:219], v166 offset:3072
	global_load_lds_dwordx4 v[164:165], off
	v_lshl_add_u64 v[164:165], v[220:221], 0, s[12:13]
	s_add_i32 m0, s0, 0x2000
	s_nop 0
	global_load_lds_dwordx4 v[164:165], off
	s_waitcnt vmcnt(10)
	s_setprio 1
	s_barrier
	s_waitcnt lgkmcnt(0)
	v_mfma_f32_16x16x32_bf16 v[64:67], v[204:207], v[172:175], v[64:67]
	v_mfma_f32_16x16x32_bf16 v[60:63], v[212:215], v[172:175], v[60:63]
	v_mfma_f32_16x16x32_bf16 v[56:59], v[204:207], v[180:183], v[56:59]
	v_mfma_f32_16x16x32_bf16 v[52:55], v[212:215], v[180:183], v[52:55]
	v_mfma_f32_16x16x32_bf16 v[48:51], v[204:207], v[188:191], v[48:51]
	v_mfma_f32_16x16x32_bf16 v[44:47], v[212:215], v[188:191], v[44:47]
	v_mfma_f32_16x16x32_bf16 v[40:43], v[204:207], v[196:199], v[40:43]
	v_mfma_f32_16x16x32_bf16 v[36:39], v[212:215], v[196:199], v[36:39]
	v_mfma_f32_16x16x32_bf16 v[64:67], v[208:211], v[176:179], v[64:67]
	v_mfma_f32_16x16x32_bf16 v[60:63], v[216:219], v[176:179], v[60:63]
	v_mfma_f32_16x16x32_bf16 v[56:59], v[208:211], v[184:187], v[56:59]
	v_mfma_f32_16x16x32_bf16 v[52:55], v[216:219], v[184:187], v[52:55]
	v_mfma_f32_16x16x32_bf16 v[48:51], v[208:211], v[192:195], v[48:51]
	v_mfma_f32_16x16x32_bf16 v[44:47], v[216:219], v[192:195], v[44:47]
	v_mfma_f32_16x16x32_bf16 v[40:43], v[208:211], v[200:203], v[40:43]
	v_mfma_f32_16x16x32_bf16 v[36:39], v[216:219], v[200:203], v[36:39]
	s_barrier
	s_setprio 0
	s_mov_b32 m0, s21
	v_lshl_add_u64 v[164:165], v[222:223], 0, s[12:13]
	ds_read_b128 v[172:175], v235 offset:49152
	ds_read_b128 v[176:179], v235 offset:50176
	ds_read_b128 v[180:183], v235 offset:51200
	ds_read_b128 v[184:187], v235 offset:52224
	ds_read_b128 v[188:191], v235 offset:53248
	ds_read_b128 v[192:195], v235 offset:54272
	ds_read_b128 v[196:199], v235 offset:55296
	ds_read_b128 v[200:203], v235 offset:56320
	global_load_lds_dwordx4 v[164:165], off
	v_lshl_add_u64 v[164:165], v[224:225], 0, s[12:13]
	s_mov_b32 m0, s48
	s_nop 0
	global_load_lds_dwordx4 v[164:165], off
	s_waitcnt vmcnt(10)
	s_setprio 1
	s_barrier
	s_waitcnt lgkmcnt(0)
	v_mfma_f32_16x16x32_bf16 v[96:99], v[100:103], v[172:175], v[96:99]
	v_mfma_f32_16x16x32_bf16 v[92:95], v[156:159], v[172:175], v[92:95]
	v_mfma_f32_16x16x32_bf16 v[88:91], v[100:103], v[180:183], v[88:91]
	v_mfma_f32_16x16x32_bf16 v[84:87], v[156:159], v[180:183], v[84:87]
	v_mfma_f32_16x16x32_bf16 v[80:83], v[100:103], v[188:191], v[80:83]
	v_mfma_f32_16x16x32_bf16 v[76:79], v[156:159], v[188:191], v[76:79]
	v_mfma_f32_16x16x32_bf16 v[72:75], v[100:103], v[196:199], v[72:75]
	v_mfma_f32_16x16x32_bf16 v[68:71], v[156:159], v[196:199], v[68:71]
	v_mfma_f32_16x16x32_bf16 v[96:99], v[104:107], v[176:179], v[96:99]
	v_mfma_f32_16x16x32_bf16 v[92:95], v[160:163], v[176:179], v[92:95]
	v_mfma_f32_16x16x32_bf16 v[88:91], v[104:107], v[184:187], v[88:91]
	v_mfma_f32_16x16x32_bf16 v[84:87], v[160:163], v[184:187], v[84:87]
	v_mfma_f32_16x16x32_bf16 v[80:83], v[104:107], v[192:195], v[80:83]
	v_mfma_f32_16x16x32_bf16 v[76:79], v[160:163], v[192:195], v[76:79]
	v_mfma_f32_16x16x32_bf16 v[72:75], v[104:107], v[200:203], v[72:75]
	v_mfma_f32_16x16x32_bf16 v[68:71], v[160:163], v[200:203], v[68:71]
	s_barrier
	s_setprio 0
	s_add_u32 s0, s28, 0xb0080
	s_addc_u32 s1, s29, 0
	s_add_i32 s24, s25, s68
	s_mov_b32 m0, s24
	s_nop 0
	global_load_lds_dwordx4 v26, s[0:1]
	s_add_i32 m0, s24, 0x2000
	s_nop 0
	global_load_lds_dwordx4 v140, s[0:1]
	v_add_u32_e32 v160, 0x10000, v233
	ds_read_b128 v[100:103], v160
	ds_read_b128 v[104:107], v160 offset:1024
	ds_read_b128 v[156:159], v160 offset:2048
	ds_read_b128 v[160:163], v160 offset:3072
	s_waitcnt vmcnt(10)
	s_setprio 1
	s_barrier
	v_mfma_f32_16x16x32_bf16 v[32:35], v[204:207], v[172:175], v[32:35]
	v_mfma_f32_16x16x32_bf16 v[28:31], v[212:215], v[172:175], v[28:31]
	v_mfma_f32_16x16x32_bf16 v[22:25], v[204:207], v[180:183], v[22:25]
	v_mfma_f32_16x16x32_bf16 v[18:21], v[212:215], v[180:183], v[18:21]
	v_mfma_f32_16x16x32_bf16 v[14:17], v[204:207], v[188:191], v[14:17]
	v_mfma_f32_16x16x32_bf16 v[10:13], v[212:215], v[188:191], v[10:13]
	v_mfma_f32_16x16x32_bf16 v[6:9], v[204:207], v[196:199], v[6:9]
	v_mfma_f32_16x16x32_bf16 v[2:5], v[212:215], v[196:199], v[2:5]
	v_mfma_f32_16x16x32_bf16 v[32:35], v[208:211], v[176:179], v[32:35]
	v_mfma_f32_16x16x32_bf16 v[28:31], v[216:219], v[176:179], v[28:31]
	v_mfma_f32_16x16x32_bf16 v[22:25], v[208:211], v[184:187], v[22:25]
	v_mfma_f32_16x16x32_bf16 v[18:21], v[216:219], v[184:187], v[18:21]
	v_mfma_f32_16x16x32_bf16 v[14:17], v[208:211], v[192:195], v[14:17]
	v_mfma_f32_16x16x32_bf16 v[10:13], v[216:219], v[192:195], v[10:13]
	v_mfma_f32_16x16x32_bf16 v[6:9], v[208:211], v[200:203], v[6:9]
	v_mfma_f32_16x16x32_bf16 v[2:5], v[216:219], v[200:203], v[2:5]
	s_barrier
	s_setprio 0
	s_add_i32 s52, s52, 2
	s_add_u32 s18, s18, 0x100
	s_addc_u32 s19, s19, 0
	s_cmp_gt_u32 s52, 41
	s_mov_b64 s[24:25], s[26:27]
	s_cbranch_scc0 .LBB0_395
	s_waitcnt lgkmcnt(0)
	s_min_i32 s0, s22, 0x100
	s_ashr_i32 s0, s0, 5
	s_ashr_i32 s1, s0, 31
	s_add_i32 s18, s22, 0xffffff00
	s_cmpk_lt_i32 s22, 0x100
	s_cselect_b32 s18, s22, s18
	s_cselect_b32 s25, 0, s35
	s_cselect_b32 s24, 0, s34
	s_cselect_b32 s26, 0, s57
	s_cselect_b32 s27, 0, s58
	s_ashr_i32 s19, s18, 31
	s_add_u32 s24, s46, s24
	s_addc_u32 s25, s47, s25
	s_lshl_b64 s[18:19], s[18:19], 20
	v_lshl_add_u64 v[100:101], s[18:19], 0, v[146:147]
	s_add_u32 s18, s50, s26
	v_lshl_or_b32 v172, s23, 8, v234
	s_addc_u32 s19, s51, s27
	s_ashr_i32 s23, s22, 31
	v_lshl_add_u64 v[180:181], s[18:19], 0, v[100:101]
	s_lshl_b64 s[18:19], s[22:23], 19
	v_lshl_add_u64 v[184:185], v[148:149], 0, s[18:19]
	s_lshl_b64 s[52:53], s[22:23], 10
	s_mul_i32 s18, s0, 0x9000
	v_ashrrev_i32_e32 v173, 31, v172
	s_mul_hi_i32 s19, s0, 0x9000
	s_add_u32 s18, s36, s18
	s_addc_u32 s19, s37, s19
	v_lshlrev_b64 v[186:187], 2, v[172:173]
	v_lshl_add_u64 v[156:157], s[18:19], 0, v[186:187]
	v_lshl_add_u64 v[164:165], s[24:25], 0, v[100:101]
	global_load_dwordx4 v[100:103], v[156:157], off offset:16
	global_load_dwordx4 v[104:107], v[156:157], off
	s_lshl_b64 s[0:1], s[0:1], 12
	s_add_u32 s0, s59, s0
	s_addc_u32 s1, s20, s1
	v_lshl_add_u64 v[164:165], v[164:165], 0, v[186:187]
	s_mov_b32 s18, 0x20000
	s_waitcnt vmcnt(0)
	v_pk_mul_f32 v[178:179], v[102:103], 0.5 op_sel_hi:[1,0]
	v_pk_mul_f32 v[174:175], v[106:107], 0.5 op_sel_hi:[1,0]
	v_pk_mul_f32 v[176:177], v[104:105], 0.5 op_sel_hi:[1,0]
	v_pk_mul_f32 v[210:211], v[100:101], 0.5 op_sel_hi:[1,0]
	global_load_dwordx4 v[100:103], v[156:157], off offset:528
	global_load_dwordx4 v[104:107], v[156:157], off offset:512
	s_waitcnt vmcnt(0)
	v_pk_mul_f32 v[162:163], v[100:101], 0.5 op_sel_hi:[1,0]
	v_lshlrev_b64 v[100:101], 1, v[172:173]
	v_lshl_add_u64 v[182:183], v[180:181], 0, v[100:101]
	v_lshl_add_u64 v[180:181], v[184:185], 0, v[100:101]
	v_lshl_add_u64 v[184:185], s[0:1], 0, v[186:187]
	v_pk_mul_f32 v[156:157], v[106:107], 0.5 op_sel_hi:[1,0]
	v_pk_mul_f32 v[158:159], v[104:105], 0.5 op_sel_hi:[1,0]
	v_pk_mul_f32 v[160:161], v[102:103], 0.5 op_sel_hi:[1,0]
	global_load_dwordx4 v[100:103], v[184:185], off offset:16
	global_load_dwordx4 v[104:107], v[184:185], off
	global_load_dwordx4 v[188:191], v[164:165], off offset:16
	global_load_dwordx4 v[192:195], v[164:165], off
	v_add_co_u32_e32 v186, vcc, s65, v164
	s_mov_b64 s[0:1], 0x10000
	s_nop 0
	v_addc_co_u32_e32 v187, vcc, 0, v165, vcc
	v_lshl_add_u64 v[172:173], v[164:165], 0, s[0:1]
	global_load_dwordx4 v[196:199], v[186:187], off
	global_load_dwordx4 v[200:203], v[172:173], off offset:16
	s_mov_b32 s0, 0x8000
	s_waitcnt vmcnt(0)
	v_pk_fma_f32 v[134:135], v[134:135], v[178:179], v[190:191]
	v_pk_fma_f32 v[138:139], v[138:139], v[174:175], v[194:195]
	v_pk_fma_f32 v[136:137], v[136:137], v[176:177], v[192:193]
	v_pk_fma_f32 v[132:133], v[132:133], v[210:211], v[188:189]
	v_cvt_pk_bf16_f32 v188, v136, v137
	v_cvt_pk_bf16_f32 v189, v138, v139
	v_cvt_pk_bf16_f32 v190, v132, v133
	v_cvt_pk_bf16_f32 v191, v134, v135
	v_lshlrev_b32_e32 v138, 16, v188
	v_and_b32_e32 v139, 0xffff0000, v188
	v_lshlrev_b32_e32 v136, 16, v189
	v_and_b32_e32 v137, 0xffff0000, v189
	global_store_dwordx4 v[182:183], v[188:191], off offset:2048
	v_lshlrev_b32_e32 v134, 16, v190
	v_and_b32_e32 v135, 0xffff0000, v190
	v_lshlrev_b32_e32 v132, 16, v191
	v_and_b32_e32 v133, 0xffff0000, v191
	v_pk_mul_f32 v[172:173], v[106:107], v[136:137]
	v_pk_mul_f32 v[188:189], v[104:105], v[138:139]
	v_pk_mul_f32 v[192:193], v[102:103], v[132:133]
	v_pk_mul_f32 v[190:191], v[100:101], v[134:135]
	v_cvt_pk_bf16_f32 v188, v188, v189
	v_cvt_pk_bf16_f32 v189, v172, v173
	v_pk_fma_f32 v[130:131], v[130:131], v[174:175], v[198:199]
	v_pk_fma_f32 v[128:129], v[128:129], v[176:177], v[196:197]
	v_pk_fma_f32 v[172:173], v[126:127], v[178:179], v[202:203]
	v_pk_fma_f32 v[126:127], v[124:125], v[210:211], v[200:201]
	v_add_co_u32_e32 v202, vcc, s65, v182
	v_cvt_pk_bf16_f32 v190, v190, v191
	v_cvt_pk_bf16_f32 v191, v192, v193
	v_cvt_pk_bf16_f32 v124, v128, v129
	v_cvt_pk_bf16_f32 v125, v130, v131
	v_cvt_pk_bf16_f32 v126, v126, v127
	v_cvt_pk_bf16_f32 v127, v172, v173
	v_addc_co_u32_e32 v203, vcc, 0, v183, vcc
	global_store_dwordx4 v[180:181], v[188:191], off
	global_store_dwordx4 v[202:203], v[124:127], off offset:2048
	v_lshlrev_b32_e32 v128, 16, v124
	v_and_b32_e32 v129, 0xffff0000, v124
	v_lshlrev_b32_e32 v124, 16, v125
	v_and_b32_e32 v125, 0xffff0000, v125
	v_lshlrev_b32_e32 v130, 16, v126
	v_and_b32_e32 v131, 0xffff0000, v126
	v_lshlrev_b32_e32 v126, 16, v127
	v_and_b32_e32 v127, 0xffff0000, v127
	v_pk_mul_f32 v[172:173], v[106:107], v[124:125]
	v_pk_mul_f32 v[188:189], v[104:105], v[128:129]
	v_pk_mul_f32 v[192:193], v[102:103], v[126:127]
	v_pk_mul_f32 v[190:191], v[100:101], v[130:131]
	v_add_co_u32_e32 v220, vcc, s0, v180
	v_cvt_pk_bf16_f32 v188, v188, v189
	v_cvt_pk_bf16_f32 v189, v172, v173
	v_cvt_pk_bf16_f32 v190, v190, v191
	v_cvt_pk_bf16_f32 v191, v192, v193
	v_addc_co_u32_e32 v221, vcc, 0, v181, vcc
	global_store_dwordx4 v[220:221], v[188:191], off
	s_mov_b64 s[0:1], 0x20000
	v_lshl_add_u64 v[172:173], v[164:165], 0, s[0:1]
	v_add_co_u32_e32 v188, vcc, s18, v164
	s_mov_b64 s[0:1], 0x30000
	s_nop 0
	v_addc_co_u32_e32 v189, vcc, 0, v165, vcc
	global_load_dwordx4 v[192:195], v[188:189], off
	global_load_dwordx4 v[196:199], v[172:173], off offset:16
	v_lshl_add_u64 v[172:173], v[164:165], 0, s[0:1]
	s_mov_b32 s0, 0x30000
	v_add_co_u32_e32 v190, vcc, s0, v164
	s_waitcnt vmcnt(0)
	v_pk_fma_f32 v[120:121], v[120:121], v[176:177], v[192:193]
	v_addc_co_u32_e32 v191, vcc, 0, v165, vcc
	global_load_dwordx4 v[204:207], v[190:191], off
	global_load_dwordx4 v[212:215], v[172:173], off offset:16
	v_pk_fma_f32 v[122:123], v[122:123], v[174:175], v[194:195]
	v_pk_fma_f32 v[118:119], v[118:119], v[178:179], v[198:199]
	v_pk_fma_f32 v[116:117], v[116:117], v[210:211], v[196:197]
	v_cvt_pk_bf16_f32 v194, v120, v121
	v_add_co_u32_e32 v192, vcc, s18, v182
	v_cvt_pk_bf16_f32 v195, v122, v123
	v_cvt_pk_bf16_f32 v196, v116, v117
	v_cvt_pk_bf16_f32 v197, v118, v119
	v_addc_co_u32_e32 v193, vcc, 0, v183, vcc
	v_lshlrev_b32_e32 v122, 16, v194
	v_and_b32_e32 v123, 0xffff0000, v194
	global_store_dwordx4 v[192:193], v[194:197], off offset:2048
	v_lshlrev_b32_e32 v120, 16, v195
	v_and_b32_e32 v121, 0xffff0000, v195
	v_pk_mul_f32 v[194:195], v[104:105], v[122:123]
	v_lshlrev_b32_e32 v118, 16, v196
	v_and_b32_e32 v119, 0xffff0000, v196
	v_cvt_pk_bf16_f32 v196, v194, v195
	v_add_co_u32_e32 v194, vcc, s65, v180
	v_lshlrev_b32_e32 v116, 16, v197
	v_and_b32_e32 v117, 0xffff0000, v197
	v_pk_mul_f32 v[172:173], v[106:107], v[120:121]
	v_addc_co_u32_e32 v195, vcc, 0, v181, vcc
	v_pk_mul_f32 v[200:201], v[102:103], v[116:117]
	v_pk_mul_f32 v[198:199], v[100:101], v[118:119]
	v_cvt_pk_bf16_f32 v197, v172, v173
	v_cvt_pk_bf16_f32 v198, v198, v199
	v_cvt_pk_bf16_f32 v199, v200, v201
	global_store_dwordx4 v[194:195], v[196:199], off
	s_mov_b32 s18, 0x80000
	s_waitcnt vmcnt(0)
	v_pk_fma_f32 v[114:115], v[114:115], v[174:175], v[206:207]
	v_pk_fma_f32 v[112:113], v[112:113], v[176:177], v[204:205]
	v_pk_fma_f32 v[172:173], v[110:111], v[178:179], v[214:215]
	v_pk_fma_f32 v[110:111], v[108:109], v[210:211], v[212:213]
	v_add_co_u32_e32 v212, vcc, s0, v182
	v_cvt_pk_bf16_f32 v108, v112, v113
	v_cvt_pk_bf16_f32 v109, v114, v115
	v_cvt_pk_bf16_f32 v110, v110, v111
	v_cvt_pk_bf16_f32 v111, v172, v173
	v_addc_co_u32_e32 v213, vcc, 0, v183, vcc
	global_store_dwordx4 v[212:213], v[108:111], off offset:2048
	v_lshlrev_b32_e32 v112, 16, v108
	v_and_b32_e32 v113, 0xffff0000, v108
	v_lshlrev_b32_e32 v172, 16, v109
	v_and_b32_e32 v173, 0xffff0000, v109
	v_lshlrev_b32_e32 v114, 16, v110
	v_and_b32_e32 v115, 0xffff0000, v110
	v_lshlrev_b32_e32 v108, 16, v111
	v_and_b32_e32 v109, 0xffff0000, v111
	s_mov_b32 s0, 0x18000
	v_pk_mul_f32 v[110:111], v[106:107], v[172:173]
	v_pk_mul_f32 v[196:197], v[104:105], v[112:113]
	v_pk_mul_f32 v[200:201], v[102:103], v[108:109]
	v_pk_mul_f32 v[198:199], v[100:101], v[114:115]
	v_add_co_u32_e32 v222, vcc, s0, v180
	v_cvt_pk_bf16_f32 v196, v196, v197
	v_cvt_pk_bf16_f32 v197, v110, v111
	v_cvt_pk_bf16_f32 v198, v198, v199
	v_cvt_pk_bf16_f32 v199, v200, v201
	v_addc_co_u32_e32 v223, vcc, 0, v181, vcc
	global_store_dwordx4 v[222:223], v[196:199], off
	s_mov_b64 s[0:1], 0x80000
	v_lshl_add_u64 v[110:111], v[164:165], 0, s[0:1]
	v_add_co_u32_e32 v196, vcc, s18, v164
	s_mov_b64 s[0:1], 0x90000
	s_nop 0
	v_addc_co_u32_e32 v197, vcc, 0, v165, vcc
	global_load_dwordx4 v[204:207], v[196:197], off
	global_load_dwordx4 v[214:217], v[110:111], off offset:16
	v_lshl_add_u64 v[110:111], v[164:165], 0, s[0:1]
	s_mov_b32 s0, 0x90000
	v_add_co_u32_e32 v198, vcc, s0, v164
	s_mov_b32 s1, 0x40000
	s_nop 0
	v_addc_co_u32_e32 v199, vcc, 0, v165, vcc
	global_load_dwordx4 v[238:241], v[198:199], off
	global_load_dwordx4 v[242:245], v[110:111], off offset:16
	v_add_co_u32_e32 v200, vcc, s18, v182
	s_waitcnt vmcnt(0)
	v_pk_fma_f32 v[96:97], v[96:97], v[176:177], v[204:205]
	v_pk_fma_f32 v[98:99], v[98:99], v[174:175], v[206:207]
	v_pk_fma_f32 v[94:95], v[94:95], v[178:179], v[216:217]
	v_pk_fma_f32 v[92:93], v[92:93], v[210:211], v[214:215]
	v_cvt_pk_bf16_f32 v204, v96, v97
	v_cvt_pk_bf16_f32 v205, v98, v99
	v_cvt_pk_bf16_f32 v206, v92, v93
	v_cvt_pk_bf16_f32 v207, v94, v95
	v_addc_co_u32_e32 v201, vcc, 0, v183, vcc
	v_lshlrev_b32_e32 v98, 16, v204
	v_and_b32_e32 v99, 0xffff0000, v204
	global_store_dwordx4 v[200:201], v[204:207], off offset:2048
	v_lshlrev_b32_e32 v96, 16, v205
	v_and_b32_e32 v97, 0xffff0000, v205
	v_pk_mul_f32 v[204:205], v[104:105], v[98:99]
	v_lshlrev_b32_e32 v94, 16, v206
	v_and_b32_e32 v95, 0xffff0000, v206
	v_cvt_pk_bf16_f32 v206, v204, v205
	v_add_co_u32_e32 v204, vcc, s1, v180
	v_lshlrev_b32_e32 v92, 16, v207
	v_and_b32_e32 v93, 0xffff0000, v207
	v_pk_mul_f32 v[110:111], v[106:107], v[96:97]
	v_addc_co_u32_e32 v205, vcc, 0, v181, vcc
	v_pk_mul_f32 v[214:215], v[102:103], v[92:93]
	v_pk_mul_f32 v[208:209], v[100:101], v[94:95]
	v_cvt_pk_bf16_f32 v207, v110, v111
	v_pk_fma_f32 v[90:91], v[90:91], v[174:175], v[240:241]
	v_pk_fma_f32 v[88:89], v[88:89], v[176:177], v[238:239]
	v_pk_fma_f32 v[110:111], v[86:87], v[178:179], v[244:245]
	v_pk_fma_f32 v[86:87], v[84:85], v[210:211], v[242:243]
	v_add_co_u32_e32 v218, vcc, s0, v182
	v_cvt_pk_bf16_f32 v208, v208, v209
	v_cvt_pk_bf16_f32 v209, v214, v215
	v_cvt_pk_bf16_f32 v84, v88, v89
	v_cvt_pk_bf16_f32 v85, v90, v91
	v_cvt_pk_bf16_f32 v86, v86, v87
	v_cvt_pk_bf16_f32 v87, v110, v111
	v_addc_co_u32_e32 v219, vcc, 0, v183, vcc
	global_store_dwordx4 v[204:205], v[206:209], off
	global_store_dwordx4 v[218:219], v[84:87], off offset:2048
	v_lshlrev_b32_e32 v88, 16, v84
	v_and_b32_e32 v89, 0xffff0000, v84
	v_lshlrev_b32_e32 v110, 16, v85
	v_and_b32_e32 v111, 0xffff0000, v85
	v_lshlrev_b32_e32 v90, 16, v86
	v_and_b32_e32 v91, 0xffff0000, v86
	v_lshlrev_b32_e32 v84, 16, v87
	v_and_b32_e32 v85, 0xffff0000, v87
	s_mov_b32 s0, 0x48000
	v_pk_mul_f32 v[86:87], v[106:107], v[110:111]
	v_pk_mul_f32 v[206:207], v[104:105], v[88:89]
	v_pk_mul_f32 v[214:215], v[102:103], v[84:85]
	v_pk_mul_f32 v[208:209], v[100:101], v[90:91]
	v_add_co_u32_e32 v224, vcc, s0, v180
	v_cvt_pk_bf16_f32 v206, v206, v207
	v_cvt_pk_bf16_f32 v207, v86, v87
	v_cvt_pk_bf16_f32 v208, v208, v209
	v_cvt_pk_bf16_f32 v209, v214, v215
	v_addc_co_u32_e32 v225, vcc, 0, v181, vcc
	global_store_dwordx4 v[224:225], v[206:209], off
	s_mov_b64 s[0:1], 0xa0000
	v_lshl_add_u64 v[86:87], v[164:165], 0, s[0:1]
	v_add_co_u32_e32 v206, vcc, s76, v164
	s_mov_b64 s[0:1], 0xb0000
	s_nop 0
	v_addc_co_u32_e32 v207, vcc, 0, v165, vcc
	global_load_dwordx4 v[214:217], v[206:207], off
	global_load_dwordx4 v[238:241], v[86:87], off offset:16
	v_lshl_add_u64 v[86:87], v[164:165], 0, s[0:1]
	s_mov_b32 s0, 0xb0000
	v_add_co_u32_e32 v208, vcc, s0, v164
	s_waitcnt vmcnt(0)
	v_pk_fma_f32 v[80:81], v[80:81], v[176:177], v[214:215]
	v_addc_co_u32_e32 v209, vcc, 0, v165, vcc
	global_load_dwordx4 v[242:245], v[208:209], off
	global_load_dwordx4 v[246:249], v[86:87], off offset:16
	v_pk_fma_f32 v[82:83], v[82:83], v[174:175], v[216:217]
	v_pk_fma_f32 v[76:77], v[76:77], v[210:211], v[238:239]
	v_cvt_pk_bf16_f32 v238, v80, v81
	v_pk_fma_f32 v[78:79], v[78:79], v[178:179], v[240:241]
	v_cvt_pk_bf16_f32 v239, v82, v83
	v_add_co_u32_e32 v214, vcc, s76, v182
	v_lshlrev_b32_e32 v82, 16, v238
	v_and_b32_e32 v83, 0xffff0000, v238
	v_cvt_pk_bf16_f32 v240, v76, v77
	v_cvt_pk_bf16_f32 v241, v78, v79
	v_addc_co_u32_e32 v215, vcc, 0, v183, vcc
	v_lshlrev_b32_e32 v80, 16, v239
	v_and_b32_e32 v81, 0xffff0000, v239
	v_pk_mul_f32 v[216:217], v[104:105], v[82:83]
	global_store_dwordx4 v[214:215], v[238:241], off offset:2048
	v_pk_mul_f32 v[86:87], v[106:107], v[80:81]
	v_lshlrev_b32_e32 v78, 16, v240
	v_cvt_pk_bf16_f32 v238, v216, v217
	v_add_co_u32_e32 v216, vcc, s77, v180
	v_and_b32_e32 v79, 0xffff0000, v240
	v_lshlrev_b32_e32 v76, 16, v241
	v_and_b32_e32 v77, 0xffff0000, v241
	v_cvt_pk_bf16_f32 v239, v86, v87
	v_addc_co_u32_e32 v217, vcc, 0, v181, vcc
	v_pk_mul_f32 v[250:251], v[102:103], v[76:77]
	v_pk_mul_f32 v[240:241], v[100:101], v[78:79]
	s_waitcnt vmcnt(0)
	v_pk_fma_f32 v[74:75], v[74:75], v[174:175], v[244:245]
	v_pk_fma_f32 v[72:73], v[72:73], v[176:177], v[242:243]
	v_pk_fma_f32 v[86:87], v[70:71], v[178:179], v[248:249]
	v_pk_fma_f32 v[70:71], v[68:69], v[210:211], v[246:247]
	v_cvt_pk_bf16_f32 v68, v72, v73
	v_cvt_pk_bf16_f32 v69, v74, v75
	v_cvt_pk_bf16_f32 v70, v70, v71
	v_cvt_pk_bf16_f32 v71, v86, v87
	v_add_co_u32_e32 v210, vcc, s0, v182
	v_cvt_pk_bf16_f32 v240, v240, v241
	v_cvt_pk_bf16_f32 v241, v250, v251
	v_addc_co_u32_e32 v211, vcc, 0, v183, vcc
	v_lshlrev_b32_e32 v86, 16, v68
	v_and_b32_e32 v87, 0xffff0000, v68
	v_lshlrev_b32_e32 v178, 16, v69
	v_and_b32_e32 v179, 0xffff0000, v69
	v_lshlrev_b32_e32 v176, 16, v70
	v_and_b32_e32 v177, 0xffff0000, v70
	v_lshlrev_b32_e32 v174, 16, v71
	v_and_b32_e32 v175, 0xffff0000, v71
	s_mov_b32 s0, 0x58000
	global_store_dwordx4 v[216:217], v[238:241], off
	global_store_dwordx4 v[210:211], v[68:71], off offset:2048
	v_pk_mul_f32 v[72:73], v[102:103], v[174:175]
	v_pk_mul_f32 v[74:75], v[100:101], v[176:177]
	v_pk_mul_f32 v[70:71], v[106:107], v[178:179]
	v_pk_mul_f32 v[68:69], v[104:105], v[86:87]
	v_add_co_u32_e32 v100, vcc, s0, v180
	v_cvt_pk_bf16_f32 v68, v68, v69
	v_cvt_pk_bf16_f32 v69, v70, v71
	v_cvt_pk_bf16_f32 v70, v74, v75
	v_cvt_pk_bf16_f32 v71, v72, v73
	v_addc_co_u32_e32 v101, vcc, 0, v181, vcc
	global_store_dwordx4 v[100:101], v[68:71], off
	global_load_dwordx4 v[68:71], v[184:185], off offset:528
	s_nop 0
	global_load_dwordx4 v[72:75], v[184:185], off offset:512
	global_load_dwordx4 v[102:105], v[164:165], off offset:528
	global_load_dwordx4 v[238:241], v[164:165], off offset:512
	s_mov_b64 s[0:1], 0x10200
	v_lshl_add_u64 v[106:107], v[164:165], 0, s[0:1]
	global_load_dwordx4 v[184:187], v[186:187], off offset:512
	s_nop 0
	global_load_dwordx4 v[242:245], v[106:107], off offset:16
	s_mov_b64 s[0:1], 0x20200
	s_waitcnt vmcnt(0)
	v_pk_fma_f32 v[62:63], v[62:63], v[160:161], v[104:105]
	v_pk_fma_f32 v[66:67], v[66:67], v[156:157], v[240:241]
	v_pk_fma_f32 v[64:65], v[64:65], v[158:159], v[238:239]
	v_pk_fma_f32 v[60:61], v[60:61], v[162:163], v[102:103]
	v_cvt_pk_bf16_f32 v102, v64, v65
	v_cvt_pk_bf16_f32 v103, v66, v67
	v_cvt_pk_bf16_f32 v104, v60, v61
	v_cvt_pk_bf16_f32 v105, v62, v63
	v_lshlrev_b32_e32 v66, 16, v102
	v_and_b32_e32 v67, 0xffff0000, v102
	v_lshlrev_b32_e32 v64, 16, v103
	v_and_b32_e32 v65, 0xffff0000, v103
	v_lshlrev_b32_e32 v62, 16, v104
	v_and_b32_e32 v63, 0xffff0000, v104
	v_lshlrev_b32_e32 v60, 16, v105
	v_and_b32_e32 v61, 0xffff0000, v105
	global_store_dwordx4 v[182:183], v[102:105], off offset:2304
	v_pk_mul_f32 v[106:107], v[70:71], v[60:61]
	v_pk_mul_f32 v[182:183], v[68:69], v[62:63]
	v_pk_mul_f32 v[104:105], v[74:75], v[64:65]
	v_pk_mul_f32 v[102:103], v[72:73], v[66:67]
	v_pk_fma_f32 v[58:59], v[58:59], v[156:157], v[186:187]
	v_cvt_pk_bf16_f32 v102, v102, v103
	v_cvt_pk_bf16_f32 v103, v104, v105
	v_cvt_pk_bf16_f32 v104, v182, v183
	v_cvt_pk_bf16_f32 v105, v106, v107
	v_pk_fma_f32 v[56:57], v[56:57], v[158:159], v[184:185]
	v_pk_fma_f32 v[54:55], v[54:55], v[160:161], v[244:245]
	v_pk_fma_f32 v[52:53], v[52:53], v[162:163], v[242:243]
	global_store_dwordx4 v[180:181], v[102:105], off offset:256
	v_mul_f32_e32 v67, v67, v67
	v_mul_f32_e32 v65, v65, v65
	v_cvt_pk_bf16_f32 v102, v56, v57
	v_cvt_pk_bf16_f32 v103, v58, v59
	v_cvt_pk_bf16_f32 v104, v52, v53
	v_cvt_pk_bf16_f32 v105, v54, v55
	v_lshlrev_b32_e32 v58, 16, v102
	v_and_b32_e32 v59, 0xffff0000, v102
	v_lshlrev_b32_e32 v56, 16, v103
	v_and_b32_e32 v57, 0xffff0000, v103
	v_lshlrev_b32_e32 v54, 16, v104
	v_and_b32_e32 v55, 0xffff0000, v104
	v_lshlrev_b32_e32 v52, 16, v105
	v_and_b32_e32 v53, 0xffff0000, v105
	global_store_dwordx4 v[202:203], v[102:105], off offset:2304
	v_pk_mul_f32 v[106:107], v[70:71], v[52:53]
	v_pk_mul_f32 v[180:181], v[68:69], v[54:55]
	v_pk_mul_f32 v[104:105], v[74:75], v[56:57]
	v_pk_mul_f32 v[102:103], v[72:73], v[58:59]
	v_fmac_f32_e32 v67, v66, v66
	v_cvt_pk_bf16_f32 v102, v102, v103
	v_cvt_pk_bf16_f32 v103, v104, v105
	v_cvt_pk_bf16_f32 v104, v180, v181
	v_cvt_pk_bf16_f32 v105, v106, v107
	global_store_dwordx4 v[220:221], v[102:105], off offset:256
	v_lshl_add_u64 v[106:107], v[164:165], 0, s[0:1]
	global_load_dwordx4 v[102:105], v[188:189], off offset:512
	global_load_dwordx4 v[180:183], v[106:107], off offset:16
	s_mov_b64 s[0:1], 0x30200
	v_lshl_add_u64 v[106:107], v[164:165], 0, s[0:1]
	global_load_dwordx4 v[184:187], v[190:191], off offset:512
	s_nop 0
	global_load_dwordx4 v[188:191], v[106:107], off offset:16
	s_mov_b64 s[0:1], 0x80200
	v_fmac_f32_e32 v65, v64, v64
	v_mul_f32_e32 v63, v63, v63
	v_mul_f32_e32 v61, v61, v61
	v_add_f32_e32 v64, v67, v65
	v_fmac_f32_e32 v63, v62, v62
	v_fmac_f32_e32 v61, v60, v60
	v_add_f32_e32 v60, v63, v61
	s_waitcnt vmcnt(0)
	v_pk_fma_f32 v[50:51], v[50:51], v[156:157], v[104:105]
	v_pk_fma_f32 v[48:49], v[48:49], v[158:159], v[102:103]
	v_pk_fma_f32 v[46:47], v[46:47], v[160:161], v[182:183]
	v_pk_fma_f32 v[44:45], v[44:45], v[162:163], v[180:181]
	v_cvt_pk_bf16_f32 v102, v48, v49
	v_cvt_pk_bf16_f32 v103, v50, v51
	v_cvt_pk_bf16_f32 v104, v44, v45
	v_cvt_pk_bf16_f32 v105, v46, v47
	v_lshlrev_b32_e32 v50, 16, v102
	v_and_b32_e32 v51, 0xffff0000, v102
	v_lshlrev_b32_e32 v48, 16, v103
	v_and_b32_e32 v49, 0xffff0000, v103
	v_lshlrev_b32_e32 v46, 16, v104
	v_and_b32_e32 v47, 0xffff0000, v104
	v_lshlrev_b32_e32 v44, 16, v105
	v_and_b32_e32 v45, 0xffff0000, v105
	global_store_dwordx4 v[192:193], v[102:105], off offset:2304
	v_pk_mul_f32 v[106:107], v[70:71], v[44:45]
	v_pk_mul_f32 v[180:181], v[68:69], v[46:47]
	v_pk_mul_f32 v[104:105], v[74:75], v[48:49]
	v_pk_mul_f32 v[102:103], v[72:73], v[50:51]
	v_pk_fma_f32 v[42:43], v[42:43], v[156:157], v[186:187]
	v_cvt_pk_bf16_f32 v102, v102, v103
	v_cvt_pk_bf16_f32 v103, v104, v105
	v_cvt_pk_bf16_f32 v104, v180, v181
	v_cvt_pk_bf16_f32 v105, v106, v107
	v_pk_fma_f32 v[40:41], v[40:41], v[158:159], v[184:185]
	v_pk_fma_f32 v[38:39], v[38:39], v[160:161], v[190:191]
	v_pk_fma_f32 v[36:37], v[36:37], v[162:163], v[188:189]
	global_store_dwordx4 v[194:195], v[102:105], off offset:256
	s_nop 1
	v_cvt_pk_bf16_f32 v102, v40, v41
	v_cvt_pk_bf16_f32 v103, v42, v43
	v_cvt_pk_bf16_f32 v104, v36, v37
	v_cvt_pk_bf16_f32 v105, v38, v39
	v_lshlrev_b32_e32 v42, 16, v102
	v_and_b32_e32 v43, 0xffff0000, v102
	v_lshlrev_b32_e32 v40, 16, v103
	v_and_b32_e32 v41, 0xffff0000, v103
	v_lshlrev_b32_e32 v38, 16, v104
	v_and_b32_e32 v39, 0xffff0000, v104
	v_lshlrev_b32_e32 v36, 16, v105
	v_and_b32_e32 v37, 0xffff0000, v105
	global_store_dwordx4 v[212:213], v[102:105], off offset:2304
	v_pk_mul_f32 v[106:107], v[70:71], v[36:37]
	v_pk_mul_f32 v[180:181], v[68:69], v[38:39]
	v_pk_mul_f32 v[104:105], v[74:75], v[40:41]
	v_pk_mul_f32 v[102:103], v[72:73], v[42:43]
	s_nop 0
	v_cvt_pk_bf16_f32 v102, v102, v103
	v_cvt_pk_bf16_f32 v103, v104, v105
	v_cvt_pk_bf16_f32 v104, v180, v181
	v_cvt_pk_bf16_f32 v105, v106, v107
	global_store_dwordx4 v[222:223], v[102:105], off offset:256
	v_lshl_add_u64 v[106:107], v[164:165], 0, s[0:1]
	global_load_dwordx4 v[102:105], v[196:197], off offset:512
	global_load_dwordx4 v[180:183], v[106:107], off offset:16
	s_mov_b64 s[0:1], 0x90200
	v_lshl_add_u64 v[106:107], v[164:165], 0, s[0:1]
	global_load_dwordx4 v[184:187], v[198:199], off offset:512
	global_load_dwordx4 v[188:191], v[106:107], off offset:16
	s_mov_b64 s[0:1], 0xa0200
	s_waitcnt vmcnt(0)
	v_pk_fma_f32 v[34:35], v[34:35], v[156:157], v[104:105]
	v_pk_fma_f32 v[32:33], v[32:33], v[158:159], v[102:103]
	v_pk_fma_f32 v[30:31], v[30:31], v[160:161], v[182:183]
	v_pk_fma_f32 v[28:29], v[28:29], v[162:163], v[180:181]
	v_cvt_pk_bf16_f32 v102, v32, v33
	v_cvt_pk_bf16_f32 v103, v34, v35
	v_cvt_pk_bf16_f32 v104, v28, v29
	v_cvt_pk_bf16_f32 v105, v30, v31
	v_lshlrev_b32_e32 v34, 16, v102
	v_and_b32_e32 v35, 0xffff0000, v102
	v_lshlrev_b32_e32 v32, 16, v103
	v_and_b32_e32 v33, 0xffff0000, v103
	v_lshlrev_b32_e32 v30, 16, v104
	v_and_b32_e32 v31, 0xffff0000, v104
	v_lshlrev_b32_e32 v28, 16, v105
	v_and_b32_e32 v29, 0xffff0000, v105
	global_store_dwordx4 v[200:201], v[102:105], off offset:2304
	v_pk_mul_f32 v[106:107], v[70:71], v[28:29]
	v_pk_mul_f32 v[180:181], v[68:69], v[30:31]
	v_pk_mul_f32 v[104:105], v[74:75], v[32:33]
	v_pk_mul_f32 v[102:103], v[72:73], v[34:35]
	v_pk_fma_f32 v[24:25], v[24:25], v[156:157], v[186:187]
	v_cvt_pk_bf16_f32 v102, v102, v103
	v_cvt_pk_bf16_f32 v103, v104, v105
	v_cvt_pk_bf16_f32 v104, v180, v181
	v_cvt_pk_bf16_f32 v105, v106, v107
	v_pk_fma_f32 v[22:23], v[22:23], v[158:159], v[184:185]
	v_pk_fma_f32 v[20:21], v[20:21], v[160:161], v[190:191]
	v_pk_fma_f32 v[18:19], v[18:19], v[162:163], v[188:189]
	global_store_dwordx4 v[204:205], v[102:105], off offset:256
	s_nop 1
	v_cvt_pk_bf16_f32 v102, v22, v23
	v_cvt_pk_bf16_f32 v103, v24, v25
	v_cvt_pk_bf16_f32 v104, v18, v19
	v_cvt_pk_bf16_f32 v105, v20, v21
	v_lshlrev_b32_e32 v24, 16, v102
	v_and_b32_e32 v25, 0xffff0000, v102
	v_lshlrev_b32_e32 v22, 16, v103
	v_and_b32_e32 v23, 0xffff0000, v103
	v_lshlrev_b32_e32 v20, 16, v104
	v_and_b32_e32 v21, 0xffff0000, v104
	v_lshlrev_b32_e32 v18, 16, v105
	v_and_b32_e32 v19, 0xffff0000, v105
	global_store_dwordx4 v[218:219], v[102:105], off offset:2304
	v_pk_mul_f32 v[106:107], v[70:71], v[18:19]
	v_pk_mul_f32 v[180:181], v[68:69], v[20:21]
	v_pk_mul_f32 v[104:105], v[74:75], v[22:23]
	v_pk_mul_f32 v[102:103], v[72:73], v[24:25]
	s_nop 0
	v_cvt_pk_bf16_f32 v102, v102, v103
	v_cvt_pk_bf16_f32 v103, v104, v105
	v_cvt_pk_bf16_f32 v104, v180, v181
	v_cvt_pk_bf16_f32 v105, v106, v107
	global_store_dwordx4 v[224:225], v[102:105], off offset:256
	v_lshl_add_u64 v[106:107], v[164:165], 0, s[0:1]
	global_load_dwordx4 v[102:105], v[206:207], off offset:512
	global_load_dwordx4 v[180:183], v[106:107], off offset:16
	s_mov_b64 s[0:1], 0xb0200
	v_lshl_add_u64 v[106:107], v[164:165], 0, s[0:1]
	global_load_dwordx4 v[184:187], v[208:209], off offset:512
	global_load_dwordx4 v[188:191], v[106:107], off offset:16
	s_waitcnt vmcnt(0)
	v_pk_fma_f32 v[16:17], v[16:17], v[156:157], v[104:105]
	v_pk_fma_f32 v[14:15], v[14:15], v[158:159], v[102:103]
	v_pk_fma_f32 v[102:103], v[12:13], v[160:161], v[182:183]
	v_pk_fma_f32 v[12:13], v[10:11], v[162:163], v[180:181]
	v_cvt_pk_bf16_f32 v10, v14, v15
	v_cvt_pk_bf16_f32 v11, v16, v17
	v_cvt_pk_bf16_f32 v12, v12, v13
	v_cvt_pk_bf16_f32 v13, v102, v103
	v_lshlrev_b32_e32 v102, 16, v10
	v_and_b32_e32 v103, 0xffff0000, v10
	v_lshlrev_b32_e32 v16, 16, v11
	v_and_b32_e32 v17, 0xffff0000, v11
	global_store_dwordx4 v[214:215], v[10:13], off offset:2304
	v_lshlrev_b32_e32 v14, 16, v12
	v_and_b32_e32 v15, 0xffff0000, v12
	v_lshlrev_b32_e32 v12, 16, v13
	v_and_b32_e32 v13, 0xffff0000, v13
	v_pk_mul_f32 v[10:11], v[74:75], v[16:17]
	v_pk_mul_f32 v[104:105], v[72:73], v[102:103]
	v_pk_mul_f32 v[164:165], v[70:71], v[12:13]
	v_pk_mul_f32 v[106:107], v[68:69], v[14:15]
	v_cvt_pk_bf16_f32 v104, v104, v105
	v_cvt_pk_bf16_f32 v105, v10, v11
	v_pk_fma_f32 v[8:9], v[8:9], v[156:157], v[186:187]
	v_pk_fma_f32 v[6:7], v[6:7], v[158:159], v[184:185]
	v_pk_fma_f32 v[10:11], v[4:5], v[160:161], v[190:191]
	v_pk_fma_f32 v[4:5], v[2:3], v[162:163], v[188:189]
	v_cvt_pk_bf16_f32 v106, v106, v107
	v_cvt_pk_bf16_f32 v107, v164, v165
	v_cvt_pk_bf16_f32 v2, v6, v7
	v_cvt_pk_bf16_f32 v3, v8, v9
	v_cvt_pk_bf16_f32 v4, v4, v5
	v_cvt_pk_bf16_f32 v5, v10, v11
	global_store_dwordx4 v[216:217], v[104:107], off offset:256
	global_store_dwordx4 v[210:211], v[2:5], off offset:2304
	v_lshlrev_b32_e32 v10, 16, v2
	v_and_b32_e32 v11, 0xffff0000, v2
	v_lshlrev_b32_e32 v8, 16, v3
	v_and_b32_e32 v9, 0xffff0000, v3
	v_lshlrev_b32_e32 v6, 16, v4
	v_and_b32_e32 v7, 0xffff0000, v4
	v_lshlrev_b32_e32 v4, 16, v5
	v_and_b32_e32 v5, 0xffff0000, v5
	v_pk_mul_f32 v[2:3], v[74:75], v[8:9]
	v_pk_mul_f32 v[72:73], v[72:73], v[10:11]
	v_pk_mul_f32 v[74:75], v[70:71], v[4:5]
	v_pk_mul_f32 v[70:71], v[68:69], v[6:7]
	v_cvt_pk_bf16_f32 v68, v72, v73
	v_cvt_pk_bf16_f32 v69, v2, v3
	v_cvt_pk_bf16_f32 v70, v70, v71
	v_cvt_pk_bf16_f32 v71, v74, v75
	global_store_dwordx4 v[100:101], v[68:71], off offset:256
	v_mul_f32_e32 v72, v133, v133
	v_fmac_f32_e32 v72, v132, v132
	v_and_b32_e32 v69, 64, v227
	v_xor_b32_e32 v68, 16, v227
	v_add_u32_e32 v69, 64, v69
	v_cmp_lt_i32_e32 vcc, v68, v69
	v_xor_b32_e32 v70, 32, v227
	v_mul_f32_e32 v71, v137, v137
	v_cndmask_b32_e32 v68, v227, v68, vcc
	v_cmp_lt_i32_e32 vcc, v70, v69
	v_fmac_f32_e32 v71, v136, v136
	v_lshlrev_b32_e32 v68, 2, v68
	v_cndmask_b32_e32 v69, v227, v70, vcc
	v_mul_f32_e32 v70, v139, v139
	v_fmac_f32_e32 v70, v138, v138
	v_add_f32_e32 v70, v70, v71
	v_mul_f32_e32 v71, v135, v135
	v_fmac_f32_e32 v71, v134, v134
	v_add_f32_e32 v71, v71, v72
	v_add_f32_e32 v70, v70, v71
	v_add_f32_e32 v64, v70, v64
	v_add_f32_e32 v60, v64, v60
	ds_bpermute_b32 v61, v68, v60
	v_lshlrev_b32_e32 v69, 2, v69
	v_lshl_add_u64 v[2:3], v[150:151], 0, s[52:53]
	s_waitcnt lgkmcnt(0)
	v_add_f32_e32 v60, v60, v61
	ds_bpermute_b32 v61, v69, v60
	s_and_saveexec_b64 s[18:19], s[38:39]
	s_cbranch_execz .LBB0_398
	s_waitcnt lgkmcnt(0)
	v_add_f32_e32 v60, v60, v61
	global_atomic_add_f32 v[2:3], v60, off

.LBB0_479:
	s_add_u32 s0, s22, 0xfffc0080
	s_addc_u32 s1, s23, -1
	s_add_i32 s69, 0, 0x10000
	s_cmp_eq_u32 s68, 12
	s_cselect_b32 s27, s35, s1
	s_cselect_b32 s26, s40, s0
	s_cselect_b32 s25, s41, s59
	s_cselect_b32 s24, s49, s51
	s_add_i32 m0, s37, 0xc000
	ds_read_b128 v[158:161], v165
	ds_read_b128 v[172:175], v165 offset:1024
	ds_read_b128 v[176:179], v165 offset:2048
	ds_read_b128 v[180:183], v165 offset:3072
	ds_read_b128 v[184:187], v165 offset:4096
	ds_read_b128 v[188:191], v165 offset:5120
	ds_read_b128 v[192:195], v165 offset:6144
	ds_read_b128 v[196:199], v165 offset:7168
	global_load_lds_dwordx4 v146, s[22:23]
	v_lshl_add_u64 v[166:167], s[22:23], 0, v[148:149]
	s_add_i32 m0, s37, 0xe000
	s_nop 0
	global_load_lds_dwordx4 v[166:167], off
	s_waitcnt vmcnt(10) lgkmcnt(8)
	s_setprio 1
	s_barrier
	s_waitcnt lgkmcnt(0)
	v_mfma_f32_16x16x32_bf16 v[136:139], v[100:103], v[158:161], v[136:139]
	v_mfma_f32_16x16x32_bf16 v[132:135], v[150:153], v[158:161], v[132:135]
	v_mfma_f32_16x16x32_bf16 v[128:131], v[100:103], v[176:179], v[128:131]
	v_mfma_f32_16x16x32_bf16 v[124:127], v[150:153], v[176:179], v[124:127]
	v_mfma_f32_16x16x32_bf16 v[120:123], v[100:103], v[184:187], v[120:123]
	v_mfma_f32_16x16x32_bf16 v[116:119], v[150:153], v[184:187], v[116:119]
	v_mfma_f32_16x16x32_bf16 v[112:115], v[100:103], v[192:195], v[112:115]
	v_mfma_f32_16x16x32_bf16 v[108:111], v[150:153], v[192:195], v[108:111]
	v_mfma_f32_16x16x32_bf16 v[136:139], v[104:107], v[172:175], v[136:139]
	v_mfma_f32_16x16x32_bf16 v[132:135], v[154:157], v[172:175], v[132:135]
	v_mfma_f32_16x16x32_bf16 v[128:131], v[104:107], v[180:183], v[128:131]
	v_mfma_f32_16x16x32_bf16 v[124:127], v[154:157], v[180:183], v[124:127]
	v_mfma_f32_16x16x32_bf16 v[120:123], v[104:107], v[188:191], v[120:123]
	v_mfma_f32_16x16x32_bf16 v[116:119], v[154:157], v[188:191], v[116:119]
	v_mfma_f32_16x16x32_bf16 v[112:115], v[104:107], v[196:199], v[112:115]
	v_mfma_f32_16x16x32_bf16 v[108:111], v[154:157], v[196:199], v[108:111]
	s_barrier
	s_setprio 0
	s_add_i32 s72, 0, 0x14000
	v_add_u32_e32 v166, s72, v163
	s_add_i32 s0, s69, s36
	ds_read_b128 v[200:203], v166
	ds_read_b128 v[204:207], v166 offset:1024
	ds_read_b128 v[208:211], v166 offset:2048
	ds_read_b128 v[212:215], v166 offset:3072
	v_lshl_add_u64 v[166:167], s[24:25], 0, v[26:27]
	s_mov_b32 m0, s0
	v_lshl_add_u64 v[168:169], s[24:25], 0, v[140:141]
	global_load_lds_dwordx4 v[166:167], off
	s_add_i32 m0, s0, 0x2000
	s_nop 0
	global_load_lds_dwordx4 v[168:169], off
	s_waitcnt vmcnt(10)
	s_setprio 1
	s_barrier
	s_waitcnt lgkmcnt(0)
	v_mfma_f32_16x16x32_bf16 v[64:67], v[200:203], v[158:161], v[64:67]
	v_mfma_f32_16x16x32_bf16 v[60:63], v[208:211], v[158:161], v[60:63]
	v_mfma_f32_16x16x32_bf16 v[56:59], v[200:203], v[176:179], v[56:59]
	v_mfma_f32_16x16x32_bf16 v[52:55], v[208:211], v[176:179], v[52:55]
	v_mfma_f32_16x16x32_bf16 v[48:51], v[200:203], v[184:187], v[48:51]
	v_mfma_f32_16x16x32_bf16 v[44:47], v[208:211], v[184:187], v[44:47]
	v_mfma_f32_16x16x32_bf16 v[40:43], v[200:203], v[192:195], v[40:43]
	v_mfma_f32_16x16x32_bf16 v[36:39], v[208:211], v[192:195], v[36:39]
	v_mfma_f32_16x16x32_bf16 v[64:67], v[204:207], v[172:175], v[64:67]
	v_mfma_f32_16x16x32_bf16 v[60:63], v[212:215], v[172:175], v[60:63]
	v_mfma_f32_16x16x32_bf16 v[56:59], v[204:207], v[180:183], v[56:59]
	v_mfma_f32_16x16x32_bf16 v[52:55], v[212:215], v[180:183], v[52:55]
	v_mfma_f32_16x16x32_bf16 v[48:51], v[204:207], v[188:191], v[48:51]
	v_mfma_f32_16x16x32_bf16 v[44:47], v[212:215], v[188:191], v[44:47]
	v_mfma_f32_16x16x32_bf16 v[40:43], v[204:207], v[196:199], v[40:43]
	v_mfma_f32_16x16x32_bf16 v[36:39], v[212:215], v[196:199], v[36:39]
	s_barrier
	s_setprio 0
	s_mov_b32 m0, s37
	v_lshl_add_u64 v[216:217], s[26:27], 0, v[144:145]
	ds_read_b128 v[158:161], v165 offset:16384
	ds_read_b128 v[172:175], v165 offset:17408
	ds_read_b128 v[176:179], v165 offset:18432
	ds_read_b128 v[180:183], v165 offset:19456
	ds_read_b128 v[184:187], v165 offset:20480
	ds_read_b128 v[188:191], v165 offset:21504
	ds_read_b128 v[192:195], v165 offset:22528
	ds_read_b128 v[196:199], v165 offset:23552
	global_load_lds_dwordx4 v[216:217], off
	v_lshl_add_u64 v[218:219], s[26:27], 0, v[142:143]
	s_mov_b32 m0, s56
	s_nop 0
	global_load_lds_dwordx4 v[218:219], off
	s_waitcnt vmcnt(10)
	s_setprio 1
	s_barrier
	s_waitcnt lgkmcnt(0)
	v_mfma_f32_16x16x32_bf16 v[96:99], v[100:103], v[158:161], v[96:99]
	v_mfma_f32_16x16x32_bf16 v[92:95], v[150:153], v[158:161], v[92:95]
	v_mfma_f32_16x16x32_bf16 v[88:91], v[100:103], v[176:179], v[88:91]
	v_mfma_f32_16x16x32_bf16 v[84:87], v[150:153], v[176:179], v[84:87]
	v_mfma_f32_16x16x32_bf16 v[80:83], v[100:103], v[184:187], v[80:83]
	v_mfma_f32_16x16x32_bf16 v[76:79], v[150:153], v[184:187], v[76:79]
	v_mfma_f32_16x16x32_bf16 v[72:75], v[100:103], v[192:195], v[72:75]
	v_mfma_f32_16x16x32_bf16 v[68:71], v[150:153], v[192:195], v[68:71]
	v_mfma_f32_16x16x32_bf16 v[96:99], v[104:107], v[172:175], v[96:99]
	v_mfma_f32_16x16x32_bf16 v[92:95], v[154:157], v[172:175], v[92:95]
	v_mfma_f32_16x16x32_bf16 v[88:91], v[104:107], v[180:183], v[88:91]
	v_mfma_f32_16x16x32_bf16 v[84:87], v[154:157], v[180:183], v[84:87]
	v_mfma_f32_16x16x32_bf16 v[80:83], v[104:107], v[188:191], v[80:83]
	v_mfma_f32_16x16x32_bf16 v[76:79], v[154:157], v[188:191], v[76:79]
	v_mfma_f32_16x16x32_bf16 v[72:75], v[104:107], v[196:199], v[72:75]
	v_mfma_f32_16x16x32_bf16 v[68:71], v[154:157], v[196:199], v[68:71]
	s_barrier
	s_setprio 0
	s_add_u32 s0, s24, 0x40000
	s_addc_u32 s1, s25, 0
	s_add_i32 s69, s72, s36
	s_mov_b32 m0, s69
	s_nop 0
	global_load_lds_dwordx4 v26, s[0:1]
	s_add_i32 m0, s69, 0x2000
	s_nop 0
	global_load_lds_dwordx4 v140, s[0:1]
	v_add_u32_e32 v154, 0x18000, v163
	ds_read_b128 v[100:103], v154
	ds_read_b128 v[104:107], v154 offset:1024
	ds_read_b128 v[150:153], v154 offset:2048
	ds_read_b128 v[154:157], v154 offset:3072
	s_waitcnt vmcnt(10)
	s_setprio 1
	s_barrier
	v_mfma_f32_16x16x32_bf16 v[32:35], v[200:203], v[158:161], v[32:35]
	v_mfma_f32_16x16x32_bf16 v[28:31], v[208:211], v[158:161], v[28:31]
	v_mfma_f32_16x16x32_bf16 v[22:25], v[200:203], v[176:179], v[22:25]
	v_mfma_f32_16x16x32_bf16 v[18:21], v[208:211], v[176:179], v[18:21]
	v_mfma_f32_16x16x32_bf16 v[14:17], v[200:203], v[184:187], v[14:17]
	v_mfma_f32_16x16x32_bf16 v[10:13], v[208:211], v[184:187], v[10:13]
	v_mfma_f32_16x16x32_bf16 v[6:9], v[200:203], v[192:195], v[6:9]
	v_mfma_f32_16x16x32_bf16 v[2:5], v[208:211], v[192:195], v[2:5]
	v_mfma_f32_16x16x32_bf16 v[32:35], v[204:207], v[172:175], v[32:35]
	v_mfma_f32_16x16x32_bf16 v[28:31], v[212:215], v[172:175], v[28:31]
	v_mfma_f32_16x16x32_bf16 v[22:25], v[204:207], v[180:183], v[22:25]
	v_mfma_f32_16x16x32_bf16 v[18:21], v[212:215], v[180:183], v[18:21]
	v_mfma_f32_16x16x32_bf16 v[14:17], v[204:207], v[188:191], v[14:17]
	v_mfma_f32_16x16x32_bf16 v[10:13], v[212:215], v[188:191], v[10:13]
	v_mfma_f32_16x16x32_bf16 v[6:9], v[204:207], v[196:199], v[6:9]
	v_mfma_f32_16x16x32_bf16 v[2:5], v[212:215], v[196:199], v[2:5]
	s_barrier
	s_setprio 0
	s_add_i32 s69, 0, 0x18000
	s_add_u32 s0, s26, 0x40000
	s_addc_u32 s1, s27, 0
	s_mov_b32 m0, s57
	ds_read_b128 v[158:161], v165 offset:32768
	ds_read_b128 v[172:175], v165 offset:33792
	ds_read_b128 v[176:179], v165 offset:34816
	ds_read_b128 v[180:183], v165 offset:35840
	ds_read_b128 v[184:187], v165 offset:36864
	ds_read_b128 v[188:191], v165 offset:37888
	ds_read_b128 v[192:195], v165 offset:38912
	ds_read_b128 v[196:199], v165 offset:39936
	global_load_lds_dwordx4 v144, s[0:1]
	s_mov_b32 m0, s58
	s_nop 0
	global_load_lds_dwordx4 v142, s[0:1]
	s_waitcnt vmcnt(10) lgkmcnt(8)
	s_setprio 1
	s_barrier
	s_waitcnt lgkmcnt(0)
	v_mfma_f32_16x16x32_bf16 v[136:139], v[100:103], v[158:161], v[136:139]
	v_mfma_f32_16x16x32_bf16 v[132:135], v[150:153], v[158:161], v[132:135]
	v_mfma_f32_16x16x32_bf16 v[128:131], v[100:103], v[176:179], v[128:131]
	v_mfma_f32_16x16x32_bf16 v[124:127], v[150:153], v[176:179], v[124:127]
	v_mfma_f32_16x16x32_bf16 v[120:123], v[100:103], v[184:187], v[120:123]
	v_mfma_f32_16x16x32_bf16 v[116:119], v[150:153], v[184:187], v[116:119]
	v_mfma_f32_16x16x32_bf16 v[112:115], v[100:103], v[192:195], v[112:115]
	v_mfma_f32_16x16x32_bf16 v[108:111], v[150:153], v[192:195], v[108:111]
	v_mfma_f32_16x16x32_bf16 v[136:139], v[104:107], v[172:175], v[136:139]
	v_mfma_f32_16x16x32_bf16 v[132:135], v[154:157], v[172:175], v[132:135]
	v_mfma_f32_16x16x32_bf16 v[128:131], v[104:107], v[180:183], v[128:131]
	v_mfma_f32_16x16x32_bf16 v[124:127], v[154:157], v[180:183], v[124:127]
	v_mfma_f32_16x16x32_bf16 v[120:123], v[104:107], v[188:191], v[120:123]
	v_mfma_f32_16x16x32_bf16 v[116:119], v[154:157], v[188:191], v[116:119]
	v_mfma_f32_16x16x32_bf16 v[112:115], v[104:107], v[196:199], v[112:115]
	v_mfma_f32_16x16x32_bf16 v[108:111], v[154:157], v[196:199], v[108:111]
	s_barrier
	s_setprio 0
	s_add_i32 s26, 0, 0x1c000
	s_add_i32 s0, s69, s36
	v_add_u32_e32 v212, s26, v163
	v_lshl_add_u64 v[166:167], v[166:167], 0, s[12:13]
	s_mov_b32 m0, s0
	ds_read_b128 v[200:203], v212
	ds_read_b128 v[204:207], v212 offset:1024
	ds_read_b128 v[208:211], v212 offset:2048
	ds_read_b128 v[212:215], v212 offset:3072
	global_load_lds_dwordx4 v[166:167], off
	v_lshl_add_u64 v[166:167], v[168:169], 0, s[12:13]
	s_add_i32 m0, s0, 0x2000
	s_nop 0
	global_load_lds_dwordx4 v[166:167], off
	s_waitcnt vmcnt(10)
	s_setprio 1
	s_barrier
	s_waitcnt lgkmcnt(0)
	v_mfma_f32_16x16x32_bf16 v[64:67], v[200:203], v[158:161], v[64:67]
	v_mfma_f32_16x16x32_bf16 v[60:63], v[208:211], v[158:161], v[60:63]
	v_mfma_f32_16x16x32_bf16 v[56:59], v[200:203], v[176:179], v[56:59]
	v_mfma_f32_16x16x32_bf16 v[52:55], v[208:211], v[176:179], v[52:55]
	v_mfma_f32_16x16x32_bf16 v[48:51], v[200:203], v[184:187], v[48:51]
	v_mfma_f32_16x16x32_bf16 v[44:47], v[208:211], v[184:187], v[44:47]
	v_mfma_f32_16x16x32_bf16 v[40:43], v[200:203], v[192:195], v[40:43]
	v_mfma_f32_16x16x32_bf16 v[36:39], v[208:211], v[192:195], v[36:39]
	v_mfma_f32_16x16x32_bf16 v[64:67], v[204:207], v[172:175], v[64:67]
	v_mfma_f32_16x16x32_bf16 v[60:63], v[212:215], v[172:175], v[60:63]
	v_mfma_f32_16x16x32_bf16 v[56:59], v[204:207], v[180:183], v[56:59]
	v_mfma_f32_16x16x32_bf16 v[52:55], v[212:215], v[180:183], v[52:55]
	v_mfma_f32_16x16x32_bf16 v[48:51], v[204:207], v[188:191], v[48:51]
	v_mfma_f32_16x16x32_bf16 v[44:47], v[212:215], v[188:191], v[44:47]
	v_mfma_f32_16x16x32_bf16 v[40:43], v[204:207], v[196:199], v[40:43]
	v_mfma_f32_16x16x32_bf16 v[36:39], v[212:215], v[196:199], v[36:39]
	s_barrier
	s_setprio 0
	s_mov_b32 m0, s28
	v_lshl_add_u64 v[166:167], v[216:217], 0, s[12:13]
	ds_read_b128 v[158:161], v165 offset:49152
	ds_read_b128 v[172:175], v165 offset:50176
	ds_read_b128 v[176:179], v165 offset:51200
	ds_read_b128 v[180:183], v165 offset:52224
	ds_read_b128 v[184:187], v165 offset:53248
	ds_read_b128 v[188:191], v165 offset:54272
	ds_read_b128 v[192:195], v165 offset:55296
	ds_read_b128 v[196:199], v165 offset:56320
	global_load_lds_dwordx4 v[166:167], off
	v_lshl_add_u64 v[166:167], v[218:219], 0, s[12:13]
	s_mov_b32 m0, s29
	s_nop 0
	global_load_lds_dwordx4 v[166:167], off
	s_waitcnt vmcnt(10)
	s_setprio 1
	s_barrier
	s_waitcnt lgkmcnt(0)
	v_mfma_f32_16x16x32_bf16 v[96:99], v[100:103], v[158:161], v[96:99]
	v_mfma_f32_16x16x32_bf16 v[92:95], v[150:153], v[158:161], v[92:95]
	v_mfma_f32_16x16x32_bf16 v[88:91], v[100:103], v[176:179], v[88:91]
	v_mfma_f32_16x16x32_bf16 v[84:87], v[150:153], v[176:179], v[84:87]
	v_mfma_f32_16x16x32_bf16 v[80:83], v[100:103], v[184:187], v[80:83]
	v_mfma_f32_16x16x32_bf16 v[76:79], v[150:153], v[184:187], v[76:79]
	v_mfma_f32_16x16x32_bf16 v[72:75], v[100:103], v[192:195], v[72:75]
	v_mfma_f32_16x16x32_bf16 v[68:71], v[150:153], v[192:195], v[68:71]
	v_mfma_f32_16x16x32_bf16 v[96:99], v[104:107], v[172:175], v[96:99]
	v_mfma_f32_16x16x32_bf16 v[92:95], v[154:157], v[172:175], v[92:95]
	v_mfma_f32_16x16x32_bf16 v[88:91], v[104:107], v[180:183], v[88:91]
	v_mfma_f32_16x16x32_bf16 v[84:87], v[154:157], v[180:183], v[84:87]
	v_mfma_f32_16x16x32_bf16 v[80:83], v[104:107], v[188:191], v[80:83]
	v_mfma_f32_16x16x32_bf16 v[76:79], v[154:157], v[188:191], v[76:79]
	v_mfma_f32_16x16x32_bf16 v[72:75], v[104:107], v[196:199], v[72:75]
	v_mfma_f32_16x16x32_bf16 v[68:71], v[154:157], v[196:199], v[68:71]
	s_barrier
	s_setprio 0
	s_add_u32 s0, s24, 0x40080
	s_addc_u32 s1, s25, 0
	s_add_i32 s24, s26, s36
	s_mov_b32 m0, s24
	s_nop 0
	global_load_lds_dwordx4 v26, s[0:1]
	s_add_i32 m0, s24, 0x2000
	s_nop 0
	global_load_lds_dwordx4 v140, s[0:1]
	v_add_u32_e32 v154, 0x10000, v163
	ds_read_b128 v[100:103], v154
	ds_read_b128 v[104:107], v154 offset:1024
	ds_read_b128 v[150:153], v154 offset:2048
	ds_read_b128 v[154:157], v154 offset:3072
	s_waitcnt vmcnt(10)
	s_setprio 1
	s_barrier
	v_mfma_f32_16x16x32_bf16 v[32:35], v[200:203], v[158:161], v[32:35]
	v_mfma_f32_16x16x32_bf16 v[28:31], v[208:211], v[158:161], v[28:31]
	v_mfma_f32_16x16x32_bf16 v[22:25], v[200:203], v[176:179], v[22:25]
	v_mfma_f32_16x16x32_bf16 v[18:21], v[208:211], v[176:179], v[18:21]
	v_mfma_f32_16x16x32_bf16 v[14:17], v[200:203], v[184:187], v[14:17]
	v_mfma_f32_16x16x32_bf16 v[10:13], v[208:211], v[184:187], v[10:13]
	v_mfma_f32_16x16x32_bf16 v[6:9], v[200:203], v[192:195], v[6:9]
	v_mfma_f32_16x16x32_bf16 v[2:5], v[208:211], v[192:195], v[2:5]
	v_mfma_f32_16x16x32_bf16 v[32:35], v[204:207], v[172:175], v[32:35]
	v_mfma_f32_16x16x32_bf16 v[28:31], v[212:215], v[172:175], v[28:31]
	v_mfma_f32_16x16x32_bf16 v[22:25], v[204:207], v[180:183], v[22:25]
	v_mfma_f32_16x16x32_bf16 v[18:21], v[212:215], v[180:183], v[18:21]
	v_mfma_f32_16x16x32_bf16 v[14:17], v[204:207], v[188:191], v[14:17]
	v_mfma_f32_16x16x32_bf16 v[10:13], v[212:215], v[188:191], v[10:13]
	v_mfma_f32_16x16x32_bf16 v[6:9], v[204:207], v[196:199], v[6:9]
	v_mfma_f32_16x16x32_bf16 v[2:5], v[212:215], v[196:199], v[2:5]
	s_barrier
	s_setprio 0
	s_add_i32 s68, s68, 2
	s_add_u32 s22, s22, 0x100
	s_addc_u32 s23, s23, 0
	s_add_u32 s51, s51, 0x100
	s_addc_u32 s59, s59, 0
	s_cmp_gt_u32 s68, 13
	s_cbranch_scc0 .LBB0_479
	s_waitcnt lgkmcnt(0)
	s_cmpk_gt_i32 s34, 0xff
	s_mov_b64 s[22:23], 0xb000
	s_cbranch_scc1 .LBB0_482
	s_ashr_i32 s0, s34, 5
	s_mul_hi_i32 s23, s0, 0x1600
	s_mul_i32 s22, s0, 0x1600

.LBB0_887:
	s_add_u32 s24, s22, 0x100
	s_addc_u32 s25, s23, 0
	s_add_i32 s0, 0, 0x10000
	s_cmp_eq_u32 s51, 4
	s_cselect_b32 s29, s47, s25
	s_cselect_b32 s28, s46, s24
	s_cselect_b32 s27, s18, s50
	s_cselect_b32 s26, s19, s45
	s_add_i32 m0, s58, 0xc000
	ds_read_b128 v[150:153], v193
	ds_read_b128 v[154:157], v193 offset:1024
	ds_read_b128 v[158:161], v193 offset:2048
	ds_read_b128 v[162:165], v193 offset:3072
	ds_read_b128 v[184:187], v193 offset:4096
	ds_read_b128 v[194:197], v193 offset:5120
	ds_read_b128 v[198:201], v193 offset:6144
	ds_read_b128 v[202:205], v193 offset:7168
	global_load_lds_dwordx4 v180, s[22:23]
	s_add_i32 m0, s58, 0xe000
	s_nop 0
	global_load_lds_dwordx4 v182, s[22:23]
	s_waitcnt vmcnt(10) lgkmcnt(8)
	s_setprio 1
	s_barrier
	s_waitcnt lgkmcnt(0)
	v_mfma_f32_16x16x32_bf16 v[130:133], v[134:137], v[150:153], v[130:133]
	v_mfma_f32_16x16x32_bf16 v[126:129], v[142:145], v[150:153], v[126:129]
	v_mfma_f32_16x16x32_bf16 v[122:125], v[134:137], v[158:161], v[122:125]
	v_mfma_f32_16x16x32_bf16 v[118:121], v[142:145], v[158:161], v[118:121]
	v_mfma_f32_16x16x32_bf16 v[114:117], v[134:137], v[184:187], v[114:117]
	v_mfma_f32_16x16x32_bf16 v[110:113], v[142:145], v[184:187], v[110:113]
	v_mfma_f32_16x16x32_bf16 v[106:109], v[134:137], v[198:201], v[106:109]
	v_mfma_f32_16x16x32_bf16 v[102:105], v[142:145], v[198:201], v[102:105]
	v_mfma_f32_16x16x32_bf16 v[130:133], v[138:141], v[154:157], v[130:133]
	v_mfma_f32_16x16x32_bf16 v[126:129], v[146:149], v[154:157], v[126:129]
	v_mfma_f32_16x16x32_bf16 v[122:125], v[138:141], v[162:165], v[122:125]
	v_mfma_f32_16x16x32_bf16 v[118:121], v[146:149], v[162:165], v[118:121]
	v_mfma_f32_16x16x32_bf16 v[114:117], v[138:141], v[194:197], v[114:117]
	v_mfma_f32_16x16x32_bf16 v[110:113], v[146:149], v[194:197], v[110:113]
	v_mfma_f32_16x16x32_bf16 v[106:109], v[138:141], v[202:205], v[106:109]
	v_mfma_f32_16x16x32_bf16 v[102:105], v[146:149], v[202:205], v[102:105]
	s_barrier
	s_setprio 0
	s_add_i32 s22, 0, 0x14000
	s_add_i32 s0, s0, s55
	v_add_u32_e32 v26, s22, v191
	v_lshl_add_u64 v[166:167], s[26:27], 0, v[176:177]
	s_mov_b32 m0, s0
	ds_read_b128 v[206:209], v26
	ds_read_b128 v[210:213], v26 offset:1024
	ds_read_b128 v[214:217], v26 offset:2048
	ds_read_b128 v[218:221], v26 offset:3072
	global_load_lds_dwordx4 v[166:167], off
	v_lshl_add_u64 v[168:169], s[26:27], 0, v[172:173]
	s_add_i32 m0, s0, 0x2000
	s_nop 0
	global_load_lds_dwordx4 v[168:169], off
	s_waitcnt vmcnt(10)
	s_setprio 1
	s_barrier
	s_waitcnt lgkmcnt(0)
	v_mfma_f32_16x16x32_bf16 v[98:101], v[206:209], v[150:153], v[98:101]
	v_mfma_f32_16x16x32_bf16 v[94:97], v[214:217], v[150:153], v[94:97]
	v_mfma_f32_16x16x32_bf16 v[90:93], v[206:209], v[158:161], v[90:93]
	v_mfma_f32_16x16x32_bf16 v[86:89], v[214:217], v[158:161], v[86:89]
	v_mfma_f32_16x16x32_bf16 v[82:85], v[206:209], v[184:187], v[82:85]
	v_mfma_f32_16x16x32_bf16 v[78:81], v[214:217], v[184:187], v[78:81]
	v_mfma_f32_16x16x32_bf16 v[74:77], v[206:209], v[198:201], v[74:77]
	v_mfma_f32_16x16x32_bf16 v[70:73], v[214:217], v[198:201], v[70:73]
	v_mfma_f32_16x16x32_bf16 v[98:101], v[210:213], v[154:157], v[98:101]
	v_mfma_f32_16x16x32_bf16 v[94:97], v[218:221], v[154:157], v[94:97]
	v_mfma_f32_16x16x32_bf16 v[90:93], v[210:213], v[162:165], v[90:93]
	v_mfma_f32_16x16x32_bf16 v[86:89], v[218:221], v[162:165], v[86:89]
	v_mfma_f32_16x16x32_bf16 v[82:85], v[210:213], v[194:197], v[82:85]
	v_mfma_f32_16x16x32_bf16 v[78:81], v[218:221], v[194:197], v[78:81]
	v_mfma_f32_16x16x32_bf16 v[74:77], v[210:213], v[202:205], v[74:77]
	v_mfma_f32_16x16x32_bf16 v[70:73], v[218:221], v[202:205], v[70:73]
	s_barrier
	s_setprio 0
	s_mov_b32 m0, s58
	v_lshl_add_u64 v[188:189], s[28:29], 0, v[178:179]
	ds_read_b128 v[150:153], v193 offset:16384
	ds_read_b128 v[154:157], v193 offset:17408
	ds_read_b128 v[158:161], v193 offset:18432
	ds_read_b128 v[162:165], v193 offset:19456
	ds_read_b128 v[184:187], v193 offset:20480
	ds_read_b128 v[194:197], v193 offset:21504
	ds_read_b128 v[198:201], v193 offset:22528
	ds_read_b128 v[202:205], v193 offset:23552
	global_load_lds_dwordx4 v[188:189], off
	v_lshl_add_u64 v[222:223], s[28:29], 0, v[174:175]
	s_mov_b32 m0, s59
	s_nop 0
	global_load_lds_dwordx4 v[222:223], off
	s_waitcnt vmcnt(10)
	s_setprio 1
	s_barrier
	s_waitcnt lgkmcnt(0)
	v_mfma_f32_16x16x32_bf16 v[66:69], v[134:137], v[150:153], v[66:69]
	v_mfma_f32_16x16x32_bf16 v[62:65], v[142:145], v[150:153], v[62:65]
	v_mfma_f32_16x16x32_bf16 v[58:61], v[134:137], v[158:161], v[58:61]
	v_mfma_f32_16x16x32_bf16 v[54:57], v[142:145], v[158:161], v[54:57]
	v_mfma_f32_16x16x32_bf16 v[50:53], v[134:137], v[184:187], v[50:53]
	v_mfma_f32_16x16x32_bf16 v[46:49], v[142:145], v[184:187], v[46:49]
	v_mfma_f32_16x16x32_bf16 v[42:45], v[134:137], v[198:201], v[42:45]
	v_mfma_f32_16x16x32_bf16 v[38:41], v[142:145], v[198:201], v[38:41]
	v_mfma_f32_16x16x32_bf16 v[66:69], v[138:141], v[154:157], v[66:69]
	v_mfma_f32_16x16x32_bf16 v[62:65], v[146:149], v[154:157], v[62:65]
	v_mfma_f32_16x16x32_bf16 v[58:61], v[138:141], v[162:165], v[58:61]
	v_mfma_f32_16x16x32_bf16 v[54:57], v[146:149], v[162:165], v[54:57]
	v_mfma_f32_16x16x32_bf16 v[50:53], v[138:141], v[194:197], v[50:53]
	v_mfma_f32_16x16x32_bf16 v[46:49], v[146:149], v[194:197], v[46:49]
	v_mfma_f32_16x16x32_bf16 v[42:45], v[138:141], v[202:205], v[42:45]
	v_mfma_f32_16x16x32_bf16 v[38:41], v[146:149], v[202:205], v[38:41]
	s_barrier
	s_setprio 0
	s_add_u32 s0, s26, 0x20000
	s_addc_u32 s1, s27, 0
	s_add_i32 s22, s22, s55
	s_mov_b32 m0, s22
	s_nop 0
	global_load_lds_dwordx4 v176, s[0:1]
	s_add_i32 m0, s22, 0x2000
	s_nop 0
	global_load_lds_dwordx4 v172, s[0:1]
	v_add_u32_e32 v26, 0x18000, v191
	ds_read_b128 v[134:137], v26
	ds_read_b128 v[138:141], v26 offset:1024
	ds_read_b128 v[142:145], v26 offset:2048
	ds_read_b128 v[146:149], v26 offset:3072
	s_waitcnt vmcnt(10)
	s_setprio 1
	s_barrier
	v_mfma_f32_16x16x32_bf16 v[34:37], v[206:209], v[150:153], v[34:37]
	v_mfma_f32_16x16x32_bf16 v[28:31], v[214:217], v[150:153], v[30:33]
	v_mfma_f32_16x16x32_bf16 v[22:25], v[206:209], v[158:161], v[22:25]
	v_mfma_f32_16x16x32_bf16 v[18:21], v[214:217], v[158:161], v[18:21]
	v_mfma_f32_16x16x32_bf16 v[14:17], v[206:209], v[184:187], v[14:17]
	v_mfma_f32_16x16x32_bf16 v[10:13], v[214:217], v[184:187], v[10:13]
	v_mfma_f32_16x16x32_bf16 v[6:9], v[206:209], v[198:201], v[6:9]
	v_mfma_f32_16x16x32_bf16 v[2:5], v[214:217], v[198:201], v[2:5]
	v_mfma_f32_16x16x32_bf16 v[34:37], v[210:213], v[154:157], v[34:37]
	v_mfma_f32_16x16x32_bf16 v[28:31], v[218:221], v[154:157], v[28:31]
	v_mfma_f32_16x16x32_bf16 v[22:25], v[210:213], v[162:165], v[22:25]
	v_mfma_f32_16x16x32_bf16 v[18:21], v[218:221], v[162:165], v[18:21]
	v_mfma_f32_16x16x32_bf16 v[14:17], v[210:213], v[194:197], v[14:17]
	v_mfma_f32_16x16x32_bf16 v[10:13], v[218:221], v[194:197], v[10:13]
	v_mfma_f32_16x16x32_bf16 v[6:9], v[210:213], v[202:205], v[6:9]
	v_mfma_f32_16x16x32_bf16 v[2:5], v[218:221], v[202:205], v[2:5]
	s_barrier
	s_setprio 0
	s_add_i32 s22, 0, 0x18000
	s_add_u32 s0, s28, 0x140000
	s_addc_u32 s1, s29, 0
	s_mov_b32 m0, s68
	ds_read_b128 v[150:153], v193 offset:32768
	ds_read_b128 v[154:157], v193 offset:33792
	ds_read_b128 v[158:161], v193 offset:34816
	ds_read_b128 v[162:165], v193 offset:35840
	ds_read_b128 v[184:187], v193 offset:36864
	ds_read_b128 v[194:197], v193 offset:37888
	ds_read_b128 v[198:201], v193 offset:38912
	ds_read_b128 v[202:205], v193 offset:39936
	global_load_lds_dwordx4 v178, s[0:1]
	s_mov_b32 m0, s69
	s_nop 0
	global_load_lds_dwordx4 v174, s[0:1]
	s_waitcnt vmcnt(10) lgkmcnt(8)
	s_setprio 1
	s_barrier
	s_waitcnt lgkmcnt(0)
	v_mfma_f32_16x16x32_bf16 v[130:133], v[134:137], v[150:153], v[130:133]
	v_mfma_f32_16x16x32_bf16 v[126:129], v[142:145], v[150:153], v[126:129]
	v_mfma_f32_16x16x32_bf16 v[122:125], v[134:137], v[158:161], v[122:125]
	v_mfma_f32_16x16x32_bf16 v[118:121], v[142:145], v[158:161], v[118:121]
	v_mfma_f32_16x16x32_bf16 v[114:117], v[134:137], v[184:187], v[114:117]
	v_mfma_f32_16x16x32_bf16 v[110:113], v[142:145], v[184:187], v[110:113]
	v_mfma_f32_16x16x32_bf16 v[106:109], v[134:137], v[198:201], v[106:109]
	v_mfma_f32_16x16x32_bf16 v[102:105], v[142:145], v[198:201], v[102:105]
	v_mfma_f32_16x16x32_bf16 v[130:133], v[138:141], v[154:157], v[130:133]
	v_mfma_f32_16x16x32_bf16 v[126:129], v[146:149], v[154:157], v[126:129]
	v_mfma_f32_16x16x32_bf16 v[122:125], v[138:141], v[162:165], v[122:125]
	v_mfma_f32_16x16x32_bf16 v[118:121], v[146:149], v[162:165], v[118:121]
	v_mfma_f32_16x16x32_bf16 v[114:117], v[138:141], v[194:197], v[114:117]
	v_mfma_f32_16x16x32_bf16 v[110:113], v[146:149], v[194:197], v[110:113]
	v_mfma_f32_16x16x32_bf16 v[106:109], v[138:141], v[202:205], v[106:109]
	v_mfma_f32_16x16x32_bf16 v[102:105], v[146:149], v[202:205], v[102:105]
	s_barrier
	s_setprio 0
	s_add_i32 s23, 0, 0x1c000
	s_add_i32 s0, s22, s55
	v_add_u32_e32 v26, s23, v191
	v_lshl_add_u64 v[32:33], v[166:167], 0, s[12:13]
	s_mov_b32 m0, s0
	ds_read_b128 v[206:209], v26
	ds_read_b128 v[210:213], v26 offset:1024
	ds_read_b128 v[214:217], v26 offset:2048
	ds_read_b128 v[218:221], v26 offset:3072
	global_load_lds_dwordx4 v[32:33], off
	v_lshl_add_u64 v[32:33], v[168:169], 0, s[12:13]
	s_add_i32 m0, s0, 0x2000
	s_nop 0
	global_load_lds_dwordx4 v[32:33], off
	s_waitcnt vmcnt(10)
	s_setprio 1
	s_barrier
	s_waitcnt lgkmcnt(0)
	v_mfma_f32_16x16x32_bf16 v[98:101], v[206:209], v[150:153], v[98:101]
	v_mfma_f32_16x16x32_bf16 v[94:97], v[214:217], v[150:153], v[94:97]
	v_mfma_f32_16x16x32_bf16 v[90:93], v[206:209], v[158:161], v[90:93]
	v_mfma_f32_16x16x32_bf16 v[86:89], v[214:217], v[158:161], v[86:89]
	v_mfma_f32_16x16x32_bf16 v[82:85], v[206:209], v[184:187], v[82:85]
	v_mfma_f32_16x16x32_bf16 v[78:81], v[214:217], v[184:187], v[78:81]
	v_mfma_f32_16x16x32_bf16 v[74:77], v[206:209], v[198:201], v[74:77]
	v_mfma_f32_16x16x32_bf16 v[70:73], v[214:217], v[198:201], v[70:73]
	v_mfma_f32_16x16x32_bf16 v[98:101], v[210:213], v[154:157], v[98:101]
	v_mfma_f32_16x16x32_bf16 v[94:97], v[218:221], v[154:157], v[94:97]
	v_mfma_f32_16x16x32_bf16 v[90:93], v[210:213], v[162:165], v[90:93]
	v_mfma_f32_16x16x32_bf16 v[86:89], v[218:221], v[162:165], v[86:89]
	v_mfma_f32_16x16x32_bf16 v[82:85], v[210:213], v[194:197], v[82:85]
	v_mfma_f32_16x16x32_bf16 v[78:81], v[218:221], v[194:197], v[78:81]
	v_mfma_f32_16x16x32_bf16 v[74:77], v[210:213], v[202:205], v[74:77]
	v_mfma_f32_16x16x32_bf16 v[70:73], v[218:221], v[202:205], v[70:73]
	s_barrier
	s_setprio 0
	s_mov_b32 m0, s30
	v_lshl_add_u64 v[32:33], v[188:189], 0, s[12:13]
	ds_read_b128 v[150:153], v193 offset:49152
	ds_read_b128 v[154:157], v193 offset:50176
	ds_read_b128 v[158:161], v193 offset:51200
	ds_read_b128 v[162:165], v193 offset:52224
	ds_read_b128 v[184:187], v193 offset:53248
	ds_read_b128 v[194:197], v193 offset:54272
	ds_read_b128 v[198:201], v193 offset:55296
	ds_read_b128 v[202:205], v193 offset:56320
	global_load_lds_dwordx4 v[32:33], off
	v_lshl_add_u64 v[32:33], v[222:223], 0, s[12:13]
	s_mov_b32 m0, s34
	s_nop 0
	global_load_lds_dwordx4 v[32:33], off
	s_waitcnt vmcnt(10)
	s_setprio 1
	s_barrier
	s_waitcnt lgkmcnt(0)
	v_mfma_f32_16x16x32_bf16 v[66:69], v[134:137], v[150:153], v[66:69]
	v_mfma_f32_16x16x32_bf16 v[62:65], v[142:145], v[150:153], v[62:65]
	v_mfma_f32_16x16x32_bf16 v[58:61], v[134:137], v[158:161], v[58:61]
	v_mfma_f32_16x16x32_bf16 v[54:57], v[142:145], v[158:161], v[54:57]
	v_mfma_f32_16x16x32_bf16 v[50:53], v[134:137], v[184:187], v[50:53]
	v_mfma_f32_16x16x32_bf16 v[46:49], v[142:145], v[184:187], v[46:49]
	v_mfma_f32_16x16x32_bf16 v[42:45], v[134:137], v[198:201], v[42:45]
	v_mfma_f32_16x16x32_bf16 v[38:41], v[142:145], v[198:201], v[38:41]
	v_mfma_f32_16x16x32_bf16 v[66:69], v[138:141], v[154:157], v[66:69]
	v_mfma_f32_16x16x32_bf16 v[62:65], v[146:149], v[154:157], v[62:65]
	v_mfma_f32_16x16x32_bf16 v[58:61], v[138:141], v[162:165], v[58:61]
	v_mfma_f32_16x16x32_bf16 v[54:57], v[146:149], v[162:165], v[54:57]
	v_mfma_f32_16x16x32_bf16 v[50:53], v[138:141], v[194:197], v[50:53]
	v_mfma_f32_16x16x32_bf16 v[46:49], v[146:149], v[194:197], v[46:49]
	v_mfma_f32_16x16x32_bf16 v[42:45], v[138:141], v[202:205], v[42:45]
	v_mfma_f32_16x16x32_bf16 v[38:41], v[146:149], v[202:205], v[38:41]
	s_barrier
	s_setprio 0
	s_add_u32 s0, s26, 0x20080
	s_addc_u32 s1, s27, 0
	s_add_i32 s22, s23, s55
	s_mov_b32 m0, s22
	s_nop 0
	global_load_lds_dwordx4 v176, s[0:1]
	s_add_i32 m0, s22, 0x2000
	s_nop 0
	global_load_lds_dwordx4 v172, s[0:1]
	v_add_u32_e32 v26, 0x10000, v191
	ds_read_b128 v[134:137], v26
	ds_read_b128 v[138:141], v26 offset:1024
	ds_read_b128 v[142:145], v26 offset:2048
	ds_read_b128 v[146:149], v26 offset:3072
	s_waitcnt vmcnt(10)
	s_setprio 1
	s_barrier
	v_mfma_f32_16x16x32_bf16 v[32:35], v[206:209], v[150:153], v[34:37]
	v_mfma_f32_16x16x32_bf16 v[28:31], v[214:217], v[150:153], v[28:31]
	v_mfma_f32_16x16x32_bf16 v[22:25], v[206:209], v[158:161], v[22:25]
	v_mfma_f32_16x16x32_bf16 v[18:21], v[214:217], v[158:161], v[18:21]
	v_mfma_f32_16x16x32_bf16 v[14:17], v[206:209], v[184:187], v[14:17]
	v_mfma_f32_16x16x32_bf16 v[10:13], v[214:217], v[184:187], v[10:13]
	v_mfma_f32_16x16x32_bf16 v[6:9], v[206:209], v[198:201], v[6:9]
	v_mfma_f32_16x16x32_bf16 v[2:5], v[214:217], v[198:201], v[2:5]
	v_mfma_f32_16x16x32_bf16 v[34:37], v[210:213], v[154:157], v[32:35]
	v_mfma_f32_16x16x32_bf16 v[30:33], v[218:221], v[154:157], v[28:31]
	v_mfma_f32_16x16x32_bf16 v[22:25], v[210:213], v[162:165], v[22:25]
	v_mfma_f32_16x16x32_bf16 v[18:21], v[218:221], v[162:165], v[18:21]
	v_mfma_f32_16x16x32_bf16 v[14:17], v[210:213], v[194:197], v[14:17]
	v_mfma_f32_16x16x32_bf16 v[10:13], v[218:221], v[194:197], v[10:13]
	v_mfma_f32_16x16x32_bf16 v[6:9], v[210:213], v[202:205], v[6:9]
	v_mfma_f32_16x16x32_bf16 v[2:5], v[218:221], v[202:205], v[2:5]
	s_barrier
	s_setprio 0
	s_add_i32 s51, s51, 2
	s_add_u32 s45, s45, 0x100
	s_addc_u32 s50, s50, 0
	s_cmp_gt_u32 s51, 5
	s_mov_b64 s[22:23], s[24:25]
	s_cbranch_scc0 .LBB0_887
	s_waitcnt lgkmcnt(0)
	v_lshl_or_b32 v186, s17, 8, v192
	v_ashrrev_i32_e32 v187, 31, v186
	v_lshl_add_u32 v26, s16, 8, v190
	s_cmp_lg_u32 s81, 0
	v_lshl_add_u64 v[28:29], v[186:187], 1, s[40:41]
	s_cselect_b64 s[50:51], -1, 0
	s_cmp_eq_u32 s81, 0
	v_mad_i64_i32 v[184:185], s[0:1], v26, s78, v[28:29]
	v_or_b32_e32 v198, 16, v26
	v_or_b32_e32 v197, 32, v26
	v_or_b32_e32 v196, 48, v26
	v_add_u32_e32 v195, 0x80, v26
	v_add_u32_e32 v194, 0x90, v26
	s_cbranch_scc1 .LBB0_894
	v_add_co_u32_e32 v134, vcc, 0x2000, v184
	v_mad_i64_i32 v[166:167], s[0:1], v26, s78, 0
	s_nop 0
	v_addc_co_u32_e32 v135, vcc, 0, v185, vcc
	global_load_dwordx4 v[162:165], v[134:135], off
	global_load_dwordx4 v[158:161], v[134:135], off offset:256
	v_mad_i64_i32 v[134:135], s[0:1], v198, s78, v[28:29]
	v_add_co_u32_e32 v134, vcc, 0x2000, v134
	v_lshlrev_b64 v[186:187], 1, v[186:187]
	s_nop 0
	v_addc_co_u32_e32 v135, vcc, 0, v135, vcc
	global_load_dwordx4 v[154:157], v[134:135], off
	global_load_dwordx4 v[150:153], v[134:135], off offset:256
	v_mad_i64_i32 v[134:135], s[0:1], v197, s78, v[28:29]
	v_add_co_u32_e32 v134, vcc, 0x2000, v134
	s_movk_i32 s16, 0x2000
	s_nop 0
	v_addc_co_u32_e32 v135, vcc, 0, v135, vcc
	global_load_dwordx4 v[146:149], v[134:135], off
	global_load_dwordx4 v[142:145], v[134:135], off offset:256
	v_mad_i64_i32 v[134:135], s[0:1], v196, s78, v[28:29]
	v_add_co_u32_e32 v134, vcc, 0x2000, v134
	s_nop 1
	v_addc_co_u32_e32 v135, vcc, 0, v135, vcc
	global_load_dwordx4 v[138:141], v[134:135], off
	s_nop 0
	global_load_dwordx4 v[134:137], v[134:135], off offset:256
	s_waitcnt vmcnt(0)
	v_lshlrev_b32_e32 v168, 16, v162
	v_and_b32_e32 v162, 0xffff0000, v162
	v_mul_f32_e32 v162, 0xbfb8aa3b, v162
	v_exp_f32_e32 v162, v162
	v_mul_f32_e32 v168, 0xbfb8aa3b, v168
	v_exp_f32_e32 v168, v168
	v_add_f32_e32 v162, 1.0, v162
	v_rcp_f32_e32 v169, v162
	v_lshlrev_b32_e32 v162, 16, v163
	v_and_b32_e32 v163, 0xffff0000, v163
	v_mul_f32_e32 v162, 0xbfb8aa3b, v162
	v_mul_f32_e32 v163, 0xbfb8aa3b, v163
	v_exp_f32_e32 v162, v162
	v_exp_f32_e32 v163, v163
	v_add_f32_e32 v168, 1.0, v168
	v_rcp_f32_e32 v168, v168
	v_add_f32_e32 v162, 1.0, v162
	v_add_f32_e32 v163, 1.0, v163
	v_rcp_f32_e32 v162, v162
	v_rcp_f32_e32 v163, v163
	v_pk_mul_f32 v[168:169], v[130:131], v[168:169]
	v_pk_mul_f32 v[188:189], v[132:133], v[162:163]
	v_lshlrev_b32_e32 v162, 16, v164
	v_and_b32_e32 v163, 0xffff0000, v164
	v_mul_f32_e32 v162, 0xbfb8aa3b, v162
	v_mul_f32_e32 v163, 0xbfb8aa3b, v163
	v_exp_f32_e32 v162, v162
	v_exp_f32_e32 v163, v163
	v_add_f32_e32 v162, 1.0, v162
	v_add_f32_e32 v163, 1.0, v163
	v_rcp_f32_e32 v162, v162
	v_rcp_f32_e32 v163, v163
	s_nop 0
	v_pk_mul_f32 v[200:201], v[126:127], v[162:163]
	v_lshlrev_b32_e32 v162, 16, v165
	v_and_b32_e32 v163, 0xffff0000, v165
	v_mul_f32_e32 v162, 0xbfb8aa3b, v162
	v_mul_f32_e32 v163, 0xbfb8aa3b, v163
	v_exp_f32_e32 v162, v162
	v_exp_f32_e32 v163, v163
	v_cvt_pk_bf16_f32 v164, v200, v201
	v_add_f32_e32 v162, 1.0, v162
	v_add_f32_e32 v163, 1.0, v163
	v_rcp_f32_e32 v162, v162
	v_rcp_f32_e32 v163, v163
	s_nop 0
	v_pk_mul_f32 v[202:203], v[128:129], v[162:163]
	v_cvt_pk_bf16_f32 v163, v188, v189
	v_lshl_add_u64 v[188:189], s[42:43], 0, v[166:167]
	v_cvt_pk_bf16_f32 v162, v168, v169
	v_cvt_pk_bf16_f32 v165, v202, v203
	v_lshl_add_u64 v[188:189], v[188:189], 0, v[186:187]
	global_store_dwordx4 v[188:189], v[162:165], off
	s_nop 1
	v_lshlrev_b32_e32 v162, 16, v158
	v_and_b32_e32 v158, 0xffff0000, v158
	v_mul_f32_e32 v158, 0xbfb8aa3b, v158
	v_exp_f32_e32 v158, v158
	v_mul_f32_e32 v162, 0xbfb8aa3b, v162
	v_exp_f32_e32 v162, v162
	v_add_f32_e32 v158, 1.0, v158
	v_rcp_f32_e32 v163, v158
	v_lshlrev_b32_e32 v158, 16, v159
	v_and_b32_e32 v159, 0xffff0000, v159
	v_mul_f32_e32 v158, 0xbfb8aa3b, v158
	v_mul_f32_e32 v159, 0xbfb8aa3b, v159
	v_exp_f32_e32 v158, v158
	v_exp_f32_e32 v159, v159
	v_add_f32_e32 v162, 1.0, v162
	v_rcp_f32_e32 v162, v162
	v_add_f32_e32 v158, 1.0, v158
	v_add_f32_e32 v159, 1.0, v159
	v_rcp_f32_e32 v158, v158
	v_rcp_f32_e32 v159, v159
	v_pk_mul_f32 v[162:163], v[98:99], v[162:163]
	v_pk_mul_f32 v[164:165], v[100:101], v[158:159]
	v_lshlrev_b32_e32 v158, 16, v160
	v_and_b32_e32 v159, 0xffff0000, v160
	v_mul_f32_e32 v158, 0xbfb8aa3b, v158
	v_mul_f32_e32 v159, 0xbfb8aa3b, v159
	v_exp_f32_e32 v158, v158
	v_exp_f32_e32 v159, v159
	v_add_f32_e32 v158, 1.0, v158
	v_add_f32_e32 v159, 1.0, v159
	v_rcp_f32_e32 v158, v158
	v_rcp_f32_e32 v159, v159
	s_nop 0
	v_pk_mul_f32 v[166:167], v[94:95], v[158:159]
	v_lshlrev_b32_e32 v158, 16, v161
	v_and_b32_e32 v159, 0xffff0000, v161
	v_mul_f32_e32 v158, 0xbfb8aa3b, v158
	v_mul_f32_e32 v159, 0xbfb8aa3b, v159
	v_exp_f32_e32 v158, v158
	v_exp_f32_e32 v159, v159
	v_cvt_pk_bf16_f32 v160, v166, v167
	v_add_f32_e32 v158, 1.0, v158
	v_add_f32_e32 v159, 1.0, v159
	v_rcp_f32_e32 v158, v158
	v_rcp_f32_e32 v159, v159
	s_nop 0
	v_pk_mul_f32 v[168:169], v[96:97], v[158:159]
	v_cvt_pk_bf16_f32 v158, v162, v163
	v_cvt_pk_bf16_f32 v159, v164, v165
	v_cvt_pk_bf16_f32 v161, v168, v169
	global_store_dwordx4 v[188:189], v[158:161], off offset:256
	s_nop 1
	v_lshlrev_b32_e32 v158, 16, v154
	v_and_b32_e32 v154, 0xffff0000, v154
	v_mul_f32_e32 v154, 0xbfb8aa3b, v154
	v_exp_f32_e32 v154, v154
	v_mul_f32_e32 v158, 0xbfb8aa3b, v158
	v_exp_f32_e32 v158, v158
	v_add_f32_e32 v154, 1.0, v154
	v_rcp_f32_e32 v159, v154
	v_lshlrev_b32_e32 v154, 16, v155
	v_and_b32_e32 v155, 0xffff0000, v155
	v_mul_f32_e32 v154, 0xbfb8aa3b, v154
	v_mul_f32_e32 v155, 0xbfb8aa3b, v155
	v_exp_f32_e32 v154, v154
	v_exp_f32_e32 v155, v155
	v_add_f32_e32 v158, 1.0, v158
	v_rcp_f32_e32 v158, v158
	v_add_f32_e32 v154, 1.0, v154
	v_add_f32_e32 v155, 1.0, v155
	v_rcp_f32_e32 v154, v154
	v_rcp_f32_e32 v155, v155
	v_pk_mul_f32 v[158:159], v[122:123], v[158:159]
	v_pk_mul_f32 v[160:161], v[124:125], v[154:155]
	v_lshlrev_b32_e32 v154, 16, v156
	v_and_b32_e32 v155, 0xffff0000, v156
	v_mul_f32_e32 v154, 0xbfb8aa3b, v154
	v_mul_f32_e32 v155, 0xbfb8aa3b, v155
	v_exp_f32_e32 v154, v154
	v_exp_f32_e32 v155, v155
	v_add_f32_e32 v154, 1.0, v154
	v_add_f32_e32 v155, 1.0, v155
	v_rcp_f32_e32 v154, v154
	v_rcp_f32_e32 v155, v155
	s_nop 0
	v_pk_mul_f32 v[162:163], v[118:119], v[154:155]
	v_lshlrev_b32_e32 v154, 16, v157
	v_and_b32_e32 v155, 0xffff0000, v157
	v_mul_f32_e32 v154, 0xbfb8aa3b, v154
	v_mul_f32_e32 v155, 0xbfb8aa3b, v155
	v_exp_f32_e32 v154, v154
	v_exp_f32_e32 v155, v155
	v_cvt_pk_bf16_f32 v156, v162, v163
	v_mov_b64_e32 v[162:163], s[42:43]
	v_add_f32_e32 v154, 1.0, v154
	v_add_f32_e32 v155, 1.0, v155
	v_rcp_f32_e32 v154, v154
	v_rcp_f32_e32 v155, v155
	s_nop 0
	v_pk_mul_f32 v[164:165], v[120:121], v[154:155]
	v_cvt_pk_bf16_f32 v154, v158, v159
	v_mad_i64_i32 v[158:159], s[0:1], v198, s78, v[162:163]
	v_cvt_pk_bf16_f32 v155, v160, v161
	v_cvt_pk_bf16_f32 v157, v164, v165
	v_lshl_add_u64 v[158:159], v[158:159], 0, v[186:187]
	global_store_dwordx4 v[158:159], v[154:157], off
	s_nop 1
	v_lshlrev_b32_e32 v154, 16, v150
	v_and_b32_e32 v150, 0xffff0000, v150
	v_mul_f32_e32 v150, 0xbfb8aa3b, v150
	v_exp_f32_e32 v150, v150
	v_mul_f32_e32 v154, 0xbfb8aa3b, v154
	v_exp_f32_e32 v154, v154
	v_add_f32_e32 v150, 1.0, v150
	v_rcp_f32_e32 v155, v150
	v_lshlrev_b32_e32 v150, 16, v151
	v_and_b32_e32 v151, 0xffff0000, v151
	v_mul_f32_e32 v150, 0xbfb8aa3b, v150
	v_mul_f32_e32 v151, 0xbfb8aa3b, v151
	v_exp_f32_e32 v150, v150
	v_exp_f32_e32 v151, v151
	v_add_f32_e32 v154, 1.0, v154
	v_rcp_f32_e32 v154, v154
	v_add_f32_e32 v150, 1.0, v150
	v_add_f32_e32 v151, 1.0, v151
	v_rcp_f32_e32 v150, v150
	v_rcp_f32_e32 v151, v151
	v_pk_mul_f32 v[154:155], v[90:91], v[154:155]
	v_pk_mul_f32 v[156:157], v[92:93], v[150:151]
	v_lshlrev_b32_e32 v150, 16, v152
	v_and_b32_e32 v151, 0xffff0000, v152
	v_mul_f32_e32 v150, 0xbfb8aa3b, v150
	v_mul_f32_e32 v151, 0xbfb8aa3b, v151
	v_exp_f32_e32 v150, v150
	v_exp_f32_e32 v151, v151
	v_add_f32_e32 v150, 1.0, v150
	v_add_f32_e32 v151, 1.0, v151
	v_rcp_f32_e32 v150, v150
	v_rcp_f32_e32 v151, v151
	s_nop 0
	v_pk_mul_f32 v[160:161], v[86:87], v[150:151]
	v_lshlrev_b32_e32 v150, 16, v153
	v_and_b32_e32 v151, 0xffff0000, v153
	v_mul_f32_e32 v150, 0xbfb8aa3b, v150
	v_mul_f32_e32 v151, 0xbfb8aa3b, v151
	v_exp_f32_e32 v150, v150
	v_exp_f32_e32 v151, v151
	v_cvt_pk_bf16_f32 v152, v160, v161
	v_add_f32_e32 v150, 1.0, v150
	v_add_f32_e32 v151, 1.0, v151
	v_rcp_f32_e32 v150, v150
	v_rcp_f32_e32 v151, v151
	s_nop 0
	v_pk_mul_f32 v[164:165], v[88:89], v[150:151]
	v_cvt_pk_bf16_f32 v150, v154, v155
	v_cvt_pk_bf16_f32 v151, v156, v157
	v_cvt_pk_bf16_f32 v153, v164, v165
	global_store_dwordx4 v[158:159], v[150:153], off offset:256
	v_add_u32_e32 v165, 0xa0, v26
	v_add_u32_e32 v164, 0xb0, v26
	v_lshlrev_b32_e32 v150, 16, v146
	v_and_b32_e32 v146, 0xffff0000, v146
	v_mul_f32_e32 v146, 0xbfb8aa3b, v146
	v_exp_f32_e32 v146, v146
	v_mul_f32_e32 v150, 0xbfb8aa3b, v150
	v_exp_f32_e32 v150, v150
	v_add_f32_e32 v146, 1.0, v146
	v_rcp_f32_e32 v151, v146
	v_lshlrev_b32_e32 v146, 16, v147
	v_and_b32_e32 v147, 0xffff0000, v147
	v_mul_f32_e32 v146, 0xbfb8aa3b, v146
	v_mul_f32_e32 v147, 0xbfb8aa3b, v147
	v_exp_f32_e32 v146, v146
	v_exp_f32_e32 v147, v147
	v_add_f32_e32 v150, 1.0, v150
	v_rcp_f32_e32 v150, v150
	v_add_f32_e32 v146, 1.0, v146
	v_add_f32_e32 v147, 1.0, v147
	v_rcp_f32_e32 v146, v146
	v_rcp_f32_e32 v147, v147
	v_pk_mul_f32 v[150:151], v[114:115], v[150:151]
	v_pk_mul_f32 v[152:153], v[116:117], v[146:147]
	v_lshlrev_b32_e32 v146, 16, v148
	v_and_b32_e32 v147, 0xffff0000, v148
	v_mul_f32_e32 v146, 0xbfb8aa3b, v146
	v_mul_f32_e32 v147, 0xbfb8aa3b, v147
	v_exp_f32_e32 v146, v146
	v_exp_f32_e32 v147, v147
	v_add_f32_e32 v146, 1.0, v146
	v_add_f32_e32 v147, 1.0, v147
	v_rcp_f32_e32 v146, v146
	v_rcp_f32_e32 v147, v147
	s_nop 0
	v_pk_mul_f32 v[154:155], v[110:111], v[146:147]
	v_lshlrev_b32_e32 v146, 16, v149
	v_and_b32_e32 v147, 0xffff0000, v149
	v_mul_f32_e32 v146, 0xbfb8aa3b, v146
	v_mul_f32_e32 v147, 0xbfb8aa3b, v147
	v_exp_f32_e32 v146, v146
	v_exp_f32_e32 v147, v147
	v_cvt_pk_bf16_f32 v148, v154, v155
	v_add_f32_e32 v146, 1.0, v146
	v_add_f32_e32 v147, 1.0, v147
	v_rcp_f32_e32 v146, v146
	v_rcp_f32_e32 v147, v147
	s_nop 0
	v_pk_mul_f32 v[156:157], v[112:113], v[146:147]
	v_cvt_pk_bf16_f32 v146, v150, v151
	v_mad_i64_i32 v[150:151], s[0:1], v197, s78, v[162:163]
	v_cvt_pk_bf16_f32 v147, v152, v153
	v_cvt_pk_bf16_f32 v149, v156, v157
	v_lshl_add_u64 v[150:151], v[150:151], 0, v[186:187]
	global_store_dwordx4 v[150:151], v[146:149], off
	s_nop 1
	v_lshlrev_b32_e32 v146, 16, v142
	v_and_b32_e32 v142, 0xffff0000, v142
	v_mul_f32_e32 v142, 0xbfb8aa3b, v142
	v_exp_f32_e32 v142, v142
	v_mul_f32_e32 v146, 0xbfb8aa3b, v146
	v_exp_f32_e32 v146, v146
	v_add_f32_e32 v142, 1.0, v142
	v_rcp_f32_e32 v147, v142
	v_lshlrev_b32_e32 v142, 16, v143
	v_and_b32_e32 v143, 0xffff0000, v143
	v_mul_f32_e32 v142, 0xbfb8aa3b, v142
	v_mul_f32_e32 v143, 0xbfb8aa3b, v143
	v_exp_f32_e32 v142, v142
	v_exp_f32_e32 v143, v143
	v_add_f32_e32 v146, 1.0, v146
	v_rcp_f32_e32 v146, v146
	v_add_f32_e32 v142, 1.0, v142
	v_add_f32_e32 v143, 1.0, v143
	v_rcp_f32_e32 v142, v142
	v_rcp_f32_e32 v143, v143
	v_pk_mul_f32 v[146:147], v[82:83], v[146:147]
	v_pk_mul_f32 v[148:149], v[84:85], v[142:143]
	v_lshlrev_b32_e32 v142, 16, v144
	v_and_b32_e32 v143, 0xffff0000, v144
	v_mul_f32_e32 v142, 0xbfb8aa3b, v142
	v_mul_f32_e32 v143, 0xbfb8aa3b, v143
	v_exp_f32_e32 v142, v142
	v_exp_f32_e32 v143, v143
	v_add_f32_e32 v142, 1.0, v142
	v_add_f32_e32 v143, 1.0, v143
	v_rcp_f32_e32 v142, v142
	v_rcp_f32_e32 v143, v143
	s_nop 0
	v_pk_mul_f32 v[152:153], v[78:79], v[142:143]
	v_lshlrev_b32_e32 v142, 16, v145
	v_and_b32_e32 v143, 0xffff0000, v145
	v_mul_f32_e32 v142, 0xbfb8aa3b, v142
	v_mul_f32_e32 v143, 0xbfb8aa3b, v143
	v_exp_f32_e32 v142, v142
	v_exp_f32_e32 v143, v143
	v_cvt_pk_bf16_f32 v144, v152, v153
	v_add_f32_e32 v142, 1.0, v142
	v_add_f32_e32 v143, 1.0, v143
	v_rcp_f32_e32 v142, v142
	v_rcp_f32_e32 v143, v143
	s_nop 0
	v_pk_mul_f32 v[154:155], v[80:81], v[142:143]
	v_cvt_pk_bf16_f32 v142, v146, v147
	v_cvt_pk_bf16_f32 v143, v148, v149
	v_cvt_pk_bf16_f32 v145, v154, v155
	global_store_dwordx4 v[150:151], v[142:145], off offset:256
	s_nop 1
	v_lshlrev_b32_e32 v142, 16, v138
	v_and_b32_e32 v138, 0xffff0000, v138
	v_mul_f32_e32 v138, 0xbfb8aa3b, v138
	v_exp_f32_e32 v138, v138
	v_mul_f32_e32 v142, 0xbfb8aa3b, v142
	v_exp_f32_e32 v142, v142
	v_add_f32_e32 v138, 1.0, v138
	v_rcp_f32_e32 v143, v138
	v_lshlrev_b32_e32 v138, 16, v139
	v_and_b32_e32 v139, 0xffff0000, v139
	v_mul_f32_e32 v138, 0xbfb8aa3b, v138
	v_mul_f32_e32 v139, 0xbfb8aa3b, v139
	v_exp_f32_e32 v138, v138
	v_exp_f32_e32 v139, v139
	v_add_f32_e32 v142, 1.0, v142
	v_rcp_f32_e32 v142, v142
	v_add_f32_e32 v138, 1.0, v138
	v_add_f32_e32 v139, 1.0, v139
	v_rcp_f32_e32 v138, v138
	v_rcp_f32_e32 v139, v139
	v_pk_mul_f32 v[142:143], v[106:107], v[142:143]
	v_pk_mul_f32 v[144:145], v[108:109], v[138:139]
	v_lshlrev_b32_e32 v138, 16, v140
	v_and_b32_e32 v139, 0xffff0000, v140
	v_mul_f32_e32 v138, 0xbfb8aa3b, v138
	v_mul_f32_e32 v139, 0xbfb8aa3b, v139
	v_exp_f32_e32 v138, v138
	v_exp_f32_e32 v139, v139
	v_add_f32_e32 v138, 1.0, v138
	v_add_f32_e32 v139, 1.0, v139
	v_rcp_f32_e32 v138, v138
	v_rcp_f32_e32 v139, v139
	s_nop 0
	v_pk_mul_f32 v[146:147], v[102:103], v[138:139]
	v_lshlrev_b32_e32 v138, 16, v141
	v_and_b32_e32 v139, 0xffff0000, v141
	v_mul_f32_e32 v138, 0xbfb8aa3b, v138
	v_mul_f32_e32 v139, 0xbfb8aa3b, v139
	v_exp_f32_e32 v138, v138
	v_exp_f32_e32 v139, v139
	v_cvt_pk_bf16_f32 v140, v146, v147
	v_add_f32_e32 v138, 1.0, v138
	v_add_f32_e32 v139, 1.0, v139
	v_rcp_f32_e32 v138, v138
	v_rcp_f32_e32 v139, v139
	s_nop 0
	v_pk_mul_f32 v[148:149], v[104:105], v[138:139]
	v_cvt_pk_bf16_f32 v138, v142, v143
	v_mad_i64_i32 v[142:143], s[0:1], v196, s78, v[162:163]
	v_cvt_pk_bf16_f32 v139, v144, v145
	v_cvt_pk_bf16_f32 v141, v148, v149
	v_lshl_add_u64 v[142:143], v[142:143], 0, v[186:187]
	global_store_dwordx4 v[142:143], v[138:141], off
	s_nop 1
	v_lshlrev_b32_e32 v138, 16, v134
	v_and_b32_e32 v134, 0xffff0000, v134
	v_mul_f32_e32 v134, 0xbfb8aa3b, v134
	v_exp_f32_e32 v134, v134
	v_mul_f32_e32 v138, 0xbfb8aa3b, v138
	v_exp_f32_e32 v138, v138
	v_add_f32_e32 v134, 1.0, v134
	v_rcp_f32_e32 v139, v134
	v_lshlrev_b32_e32 v134, 16, v135
	v_and_b32_e32 v135, 0xffff0000, v135
	v_mul_f32_e32 v134, 0xbfb8aa3b, v134
	v_mul_f32_e32 v135, 0xbfb8aa3b, v135
	v_exp_f32_e32 v134, v134
	v_exp_f32_e32 v135, v135
	v_add_f32_e32 v138, 1.0, v138
	v_rcp_f32_e32 v138, v138
	v_add_f32_e32 v134, 1.0, v134
	v_add_f32_e32 v135, 1.0, v135
	v_rcp_f32_e32 v134, v134
	v_rcp_f32_e32 v135, v135
	v_pk_mul_f32 v[138:139], v[74:75], v[138:139]
	v_pk_mul_f32 v[140:141], v[76:77], v[134:135]
	v_lshlrev_b32_e32 v134, 16, v136
	v_and_b32_e32 v135, 0xffff0000, v136
	v_mul_f32_e32 v134, 0xbfb8aa3b, v134
	v_mul_f32_e32 v135, 0xbfb8aa3b, v135
	v_exp_f32_e32 v134, v134
	v_exp_f32_e32 v135, v135
	v_add_f32_e32 v134, 1.0, v134
	v_add_f32_e32 v135, 1.0, v135
	v_rcp_f32_e32 v134, v134
	v_rcp_f32_e32 v135, v135
	s_nop 0
	v_pk_mul_f32 v[144:145], v[70:71], v[134:135]
	v_lshlrev_b32_e32 v134, 16, v137
	v_and_b32_e32 v135, 0xffff0000, v137
	v_mul_f32_e32 v134, 0xbfb8aa3b, v134
	v_mul_f32_e32 v135, 0xbfb8aa3b, v135
	v_exp_f32_e32 v134, v134
	v_exp_f32_e32 v135, v135
	v_cvt_pk_bf16_f32 v136, v144, v145
	v_add_f32_e32 v134, 1.0, v134
	v_add_f32_e32 v135, 1.0, v135
	v_rcp_f32_e32 v134, v134
	v_rcp_f32_e32 v135, v135
	s_nop 0
	v_pk_mul_f32 v[146:147], v[72:73], v[134:135]
	v_cvt_pk_bf16_f32 v134, v138, v139
	v_cvt_pk_bf16_f32 v135, v140, v141
	v_cvt_pk_bf16_f32 v137, v146, v147
	global_store_dwordx4 v[142:143], v[134:137], off offset:256
	s_nop 1
	v_mad_i64_i32 v[134:135], s[0:1], v195, s78, v[28:29]
	v_add_co_u32_e32 v134, vcc, s16, v134
	s_nop 1
	v_addc_co_u32_e32 v135, vcc, 0, v135, vcc
	global_load_dwordx4 v[200:203], v[134:135], off
	global_load_dwordx4 v[158:161], v[134:135], off offset:256
	v_mad_i64_i32 v[134:135], s[0:1], v194, s78, v[28:29]
	v_add_co_u32_e32 v134, vcc, s16, v134
	s_waitcnt vmcnt(0)
	v_lshlrev_b32_e32 v199, 16, v203
	v_addc_co_u32_e32 v135, vcc, 0, v135, vcc
	global_load_dwordx4 v[154:157], v[134:135], off
	global_load_dwordx4 v[150:153], v[134:135], off offset:256
	v_mul_f32_e32 v199, 0xbfb8aa3b, v199
	v_exp_f32_e32 v199, v199
	v_lshlrev_b32_e32 v168, 16, v201
	v_and_b32_e32 v169, 0xffff0000, v201
	v_lshlrev_b32_e32 v166, 16, v200
	v_add_f32_e32 v199, 1.0, v199
	v_and_b32_e32 v167, 0xffff0000, v200
	v_mul_f32_e32 v168, 0xbfb8aa3b, v168
	v_mul_f32_e32 v169, 0xbfb8aa3b, v169
	v_rcp_f32_e32 v200, v199
	v_and_b32_e32 v199, 0xffff0000, v203
	v_exp_f32_e32 v168, v168
	v_exp_f32_e32 v169, v169
	v_mul_f32_e32 v199, 0xbfb8aa3b, v199
	v_exp_f32_e32 v199, v199
	v_add_f32_e32 v168, 1.0, v168
	v_add_f32_e32 v169, 1.0, v169
	v_rcp_f32_e32 v168, v168
	v_rcp_f32_e32 v169, v169
	v_add_f32_e32 v199, 1.0, v199
	v_rcp_f32_e32 v201, v199
	v_lshlrev_b32_e32 v188, 16, v202
	v_pk_mul_f32 v[168:169], v[68:69], v[168:169]
	v_and_b32_e32 v189, 0xffff0000, v202
	v_pk_mul_f32 v[204:205], v[64:65], v[200:201]
	v_cvt_pk_bf16_f32 v201, v168, v169
	v_lshlrev_b32_e32 v168, 16, v158
	v_and_b32_e32 v158, 0xffff0000, v158
	v_mul_f32_e32 v158, 0xbfb8aa3b, v158
	v_exp_f32_e32 v158, v158
	v_mul_f32_e32 v188, 0xbfb8aa3b, v188
	v_mul_f32_e32 v189, 0xbfb8aa3b, v189
	v_exp_f32_e32 v188, v188
	v_add_f32_e32 v158, 1.0, v158
	v_rcp_f32_e32 v169, v158
	v_lshlrev_b32_e32 v158, 16, v159
	v_and_b32_e32 v159, 0xffff0000, v159
	v_exp_f32_e32 v189, v189
	v_mul_f32_e32 v158, 0xbfb8aa3b, v158
	v_mul_f32_e32 v159, 0xbfb8aa3b, v159
	v_exp_f32_e32 v158, v158
	v_exp_f32_e32 v159, v159
	v_add_f32_e32 v188, 1.0, v188
	v_add_f32_e32 v189, 1.0, v189
	v_rcp_f32_e32 v188, v188
	v_rcp_f32_e32 v189, v189
	v_add_f32_e32 v158, 1.0, v158
	v_add_f32_e32 v159, 1.0, v159
	v_rcp_f32_e32 v158, v158
	v_rcp_f32_e32 v159, v159
	v_mul_f32_e32 v166, 0xbfb8aa3b, v166
	v_mul_f32_e32 v167, 0xbfb8aa3b, v167
	v_exp_f32_e32 v166, v166
	v_exp_f32_e32 v167, v167
	v_pk_mul_f32 v[188:189], v[62:63], v[188:189]
	v_mad_i64_i32 v[134:135], s[0:1], v165, s78, v[28:29]
	v_cvt_pk_bf16_f32 v202, v188, v189
	v_pk_mul_f32 v[188:189], v[36:37], v[158:159]
	v_lshlrev_b32_e32 v158, 16, v160
	v_and_b32_e32 v159, 0xffff0000, v160
	v_mul_f32_e32 v158, 0xbfb8aa3b, v158
	v_mul_f32_e32 v159, 0xbfb8aa3b, v159
	v_exp_f32_e32 v158, v158
	v_exp_f32_e32 v159, v159
	v_add_f32_e32 v166, 1.0, v166
	v_add_f32_e32 v167, 1.0, v167
	v_rcp_f32_e32 v166, v166
	v_rcp_f32_e32 v167, v167
	v_add_co_u32_e32 v134, vcc, s16, v134
	v_add_f32_e32 v158, 1.0, v158
	v_add_f32_e32 v159, 1.0, v159
	v_addc_co_u32_e32 v135, vcc, 0, v135, vcc
	v_rcp_f32_e32 v158, v158
	v_rcp_f32_e32 v159, v159
	global_load_dwordx4 v[146:149], v[134:135], off
	global_load_dwordx4 v[142:145], v[134:135], off offset:256
	v_mad_i64_i32 v[134:135], s[0:1], v164, s78, v[28:29]
	v_pk_mul_f32 v[166:167], v[66:67], v[166:167]
	v_add_co_u32_e32 v134, vcc, s16, v134
	v_cvt_pk_bf16_f32 v200, v166, v167
	v_mad_i64_i32 v[166:167], s[0:1], v195, s78, v[162:163]
	v_addc_co_u32_e32 v135, vcc, 0, v135, vcc
	v_cvt_pk_bf16_f32 v203, v204, v205
	v_lshl_add_u64 v[166:167], v[166:167], 0, v[186:187]
	global_load_dwordx4 v[138:141], v[134:135], off
	s_nop 0
	global_load_dwordx4 v[134:137], v[134:135], off offset:256
	v_mul_f32_e32 v168, 0xbfb8aa3b, v168
	global_store_dwordx4 v[166:167], v[200:203], off
	v_exp_f32_e32 v168, v168
	s_nop 0
	v_pk_mul_f32 v[200:201], v[30:31], v[158:159]
	v_lshlrev_b32_e32 v158, 16, v161
	v_and_b32_e32 v159, 0xffff0000, v161
	v_mul_f32_e32 v158, 0xbfb8aa3b, v158
	v_mul_f32_e32 v159, 0xbfb8aa3b, v159
	v_exp_f32_e32 v158, v158
	v_exp_f32_e32 v159, v159
	v_add_f32_e32 v168, 1.0, v168
	v_rcp_f32_e32 v168, v168
	v_add_f32_e32 v158, 1.0, v158
	v_add_f32_e32 v159, 1.0, v159
	v_rcp_f32_e32 v158, v158
	v_rcp_f32_e32 v159, v159
	v_pk_mul_f32 v[168:169], v[34:35], v[168:169]
	v_cvt_pk_bf16_f32 v160, v200, v201
	v_pk_mul_f32 v[202:203], v[32:33], v[158:159]
	v_cvt_pk_bf16_f32 v158, v168, v169
	v_cvt_pk_bf16_f32 v159, v188, v189
	v_cvt_pk_bf16_f32 v161, v202, v203
	global_store_dwordx4 v[166:167], v[158:161], off offset:256
	s_waitcnt vmcnt(0)
	s_nop 0
	v_lshlrev_b32_e32 v158, 16, v154
	v_and_b32_e32 v154, 0xffff0000, v154
	v_mul_f32_e32 v154, 0xbfb8aa3b, v154
	v_exp_f32_e32 v154, v154
	v_mul_f32_e32 v158, 0xbfb8aa3b, v158
	v_exp_f32_e32 v158, v158
	v_add_f32_e32 v154, 1.0, v154
	v_rcp_f32_e32 v159, v154
	v_lshlrev_b32_e32 v154, 16, v155
	v_and_b32_e32 v155, 0xffff0000, v155
	v_mul_f32_e32 v154, 0xbfb8aa3b, v154
	v_mul_f32_e32 v155, 0xbfb8aa3b, v155
	v_exp_f32_e32 v154, v154
	v_exp_f32_e32 v155, v155
	v_add_f32_e32 v158, 1.0, v158
	v_rcp_f32_e32 v158, v158
	v_add_f32_e32 v154, 1.0, v154
	v_add_f32_e32 v155, 1.0, v155
	v_rcp_f32_e32 v154, v154
	v_rcp_f32_e32 v155, v155
	v_pk_mul_f32 v[158:159], v[58:59], v[158:159]
	v_pk_mul_f32 v[160:161], v[60:61], v[154:155]
	v_lshlrev_b32_e32 v154, 16, v156
	v_and_b32_e32 v155, 0xffff0000, v156
	v_mul_f32_e32 v154, 0xbfb8aa3b, v154
	v_mul_f32_e32 v155, 0xbfb8aa3b, v155
	v_exp_f32_e32 v154, v154
	v_exp_f32_e32 v155, v155
	v_add_f32_e32 v154, 1.0, v154
	v_add_f32_e32 v155, 1.0, v155
	v_rcp_f32_e32 v154, v154
	v_rcp_f32_e32 v155, v155
	s_nop 0
	v_pk_mul_f32 v[166:167], v[54:55], v[154:155]
	v_lshlrev_b32_e32 v154, 16, v157
	v_and_b32_e32 v155, 0xffff0000, v157
	v_mul_f32_e32 v154, 0xbfb8aa3b, v154
	v_mul_f32_e32 v155, 0xbfb8aa3b, v155
	v_exp_f32_e32 v154, v154
	v_exp_f32_e32 v155, v155
	v_cvt_pk_bf16_f32 v156, v166, v167
	v_add_f32_e32 v154, 1.0, v154
	v_add_f32_e32 v155, 1.0, v155
	v_rcp_f32_e32 v154, v154
	v_rcp_f32_e32 v155, v155
	s_nop 0
	v_pk_mul_f32 v[168:169], v[56:57], v[154:155]
	v_cvt_pk_bf16_f32 v154, v158, v159
	v_mad_i64_i32 v[158:159], s[0:1], v194, s78, v[162:163]
	v_cvt_pk_bf16_f32 v155, v160, v161
	v_cvt_pk_bf16_f32 v157, v168, v169
	v_lshl_add_u64 v[158:159], v[158:159], 0, v[186:187]
	global_store_dwordx4 v[158:159], v[154:157], off
	s_nop 1
	v_lshlrev_b32_e32 v154, 16, v150
	v_and_b32_e32 v150, 0xffff0000, v150
	v_mul_f32_e32 v150, 0xbfb8aa3b, v150
	v_exp_f32_e32 v150, v150
	v_mul_f32_e32 v154, 0xbfb8aa3b, v154
	v_exp_f32_e32 v154, v154
	v_add_f32_e32 v150, 1.0, v150
	v_rcp_f32_e32 v155, v150
	v_lshlrev_b32_e32 v150, 16, v151
	v_and_b32_e32 v151, 0xffff0000, v151
	v_mul_f32_e32 v150, 0xbfb8aa3b, v150
	v_mul_f32_e32 v151, 0xbfb8aa3b, v151
	v_exp_f32_e32 v150, v150
	v_exp_f32_e32 v151, v151
	v_add_f32_e32 v154, 1.0, v154
	v_rcp_f32_e32 v154, v154
	v_add_f32_e32 v150, 1.0, v150
	v_add_f32_e32 v151, 1.0, v151
	v_rcp_f32_e32 v150, v150
	v_rcp_f32_e32 v151, v151
	v_pk_mul_f32 v[154:155], v[22:23], v[154:155]
	v_pk_mul_f32 v[156:157], v[24:25], v[150:151]
	v_lshlrev_b32_e32 v150, 16, v152
	v_and_b32_e32 v151, 0xffff0000, v152
	v_mul_f32_e32 v150, 0xbfb8aa3b, v150
	v_mul_f32_e32 v151, 0xbfb8aa3b, v151
	v_exp_f32_e32 v150, v150
	v_exp_f32_e32 v151, v151
	v_add_f32_e32 v150, 1.0, v150
	v_add_f32_e32 v151, 1.0, v151
	v_rcp_f32_e32 v150, v150
	v_rcp_f32_e32 v151, v151
	s_nop 0
	v_pk_mul_f32 v[160:161], v[18:19], v[150:151]
	v_lshlrev_b32_e32 v150, 16, v153
	v_and_b32_e32 v151, 0xffff0000, v153
	v_mul_f32_e32 v150, 0xbfb8aa3b, v150
	v_mul_f32_e32 v151, 0xbfb8aa3b, v151
	v_exp_f32_e32 v150, v150
	v_exp_f32_e32 v151, v151
	v_cvt_pk_bf16_f32 v152, v160, v161
	v_add_f32_e32 v150, 1.0, v150
	v_add_f32_e32 v151, 1.0, v151
	v_rcp_f32_e32 v150, v150
	v_rcp_f32_e32 v151, v151
	s_nop 0
	v_pk_mul_f32 v[166:167], v[20:21], v[150:151]
	v_cvt_pk_bf16_f32 v150, v154, v155
	v_cvt_pk_bf16_f32 v151, v156, v157
	v_cvt_pk_bf16_f32 v153, v166, v167
	global_store_dwordx4 v[158:159], v[150:153], off offset:256
	s_nop 1
	v_lshlrev_b32_e32 v150, 16, v146
	v_and_b32_e32 v146, 0xffff0000, v146
	v_mul_f32_e32 v146, 0xbfb8aa3b, v146
	v_exp_f32_e32 v146, v146
	v_mul_f32_e32 v150, 0xbfb8aa3b, v150
	v_exp_f32_e32 v150, v150
	v_add_f32_e32 v146, 1.0, v146
	v_rcp_f32_e32 v151, v146
	v_lshlrev_b32_e32 v146, 16, v147
	v_and_b32_e32 v147, 0xffff0000, v147
	v_mul_f32_e32 v146, 0xbfb8aa3b, v146
	v_mul_f32_e32 v147, 0xbfb8aa3b, v147
	v_exp_f32_e32 v146, v146
	v_exp_f32_e32 v147, v147
	v_add_f32_e32 v150, 1.0, v150
	v_rcp_f32_e32 v150, v150
	v_add_f32_e32 v146, 1.0, v146
	v_add_f32_e32 v147, 1.0, v147
	v_rcp_f32_e32 v146, v146
	v_rcp_f32_e32 v147, v147
	v_pk_mul_f32 v[150:151], v[50:51], v[150:151]
	v_pk_mul_f32 v[152:153], v[52:53], v[146:147]
	v_lshlrev_b32_e32 v146, 16, v148
	v_and_b32_e32 v147, 0xffff0000, v148
	v_mul_f32_e32 v146, 0xbfb8aa3b, v146
	v_mul_f32_e32 v147, 0xbfb8aa3b, v147
	v_exp_f32_e32 v146, v146
	v_exp_f32_e32 v147, v147
	v_add_f32_e32 v146, 1.0, v146
	v_add_f32_e32 v147, 1.0, v147
	v_rcp_f32_e32 v146, v146
	v_rcp_f32_e32 v147, v147
	s_nop 0
	v_pk_mul_f32 v[154:155], v[46:47], v[146:147]
	v_lshlrev_b32_e32 v146, 16, v149
	v_and_b32_e32 v147, 0xffff0000, v149
	v_mul_f32_e32 v146, 0xbfb8aa3b, v146
	v_mul_f32_e32 v147, 0xbfb8aa3b, v147
	v_exp_f32_e32 v146, v146
	v_exp_f32_e32 v147, v147
	v_cvt_pk_bf16_f32 v148, v154, v155
	v_add_f32_e32 v146, 1.0, v146
	v_add_f32_e32 v147, 1.0, v147
	v_rcp_f32_e32 v146, v146
	v_rcp_f32_e32 v147, v147
	s_nop 0
	v_pk_mul_f32 v[156:157], v[48:49], v[146:147]
	v_cvt_pk_bf16_f32 v146, v150, v151
	v_mad_i64_i32 v[150:151], s[0:1], v165, s78, v[162:163]
	v_cvt_pk_bf16_f32 v147, v152, v153
	v_cvt_pk_bf16_f32 v149, v156, v157
	v_lshl_add_u64 v[150:151], v[150:151], 0, v[186:187]
	global_store_dwordx4 v[150:151], v[146:149], off
	s_nop 1
	v_lshlrev_b32_e32 v146, 16, v142
	v_and_b32_e32 v142, 0xffff0000, v142
	v_mul_f32_e32 v142, 0xbfb8aa3b, v142
	v_exp_f32_e32 v142, v142
	v_mul_f32_e32 v146, 0xbfb8aa3b, v146
	v_exp_f32_e32 v146, v146
	v_add_f32_e32 v142, 1.0, v142
	v_rcp_f32_e32 v147, v142
	v_lshlrev_b32_e32 v142, 16, v143
	v_and_b32_e32 v143, 0xffff0000, v143
	v_mul_f32_e32 v142, 0xbfb8aa3b, v142
	v_mul_f32_e32 v143, 0xbfb8aa3b, v143
	v_exp_f32_e32 v142, v142
	v_exp_f32_e32 v143, v143
	v_add_f32_e32 v146, 1.0, v146
	v_rcp_f32_e32 v146, v146
	v_add_f32_e32 v142, 1.0, v142
	v_add_f32_e32 v143, 1.0, v143
	v_rcp_f32_e32 v142, v142
	v_rcp_f32_e32 v143, v143
	v_pk_mul_f32 v[146:147], v[14:15], v[146:147]
	v_pk_mul_f32 v[148:149], v[16:17], v[142:143]
	v_lshlrev_b32_e32 v142, 16, v144
	v_and_b32_e32 v143, 0xffff0000, v144
	v_mul_f32_e32 v142, 0xbfb8aa3b, v142
	v_mul_f32_e32 v143, 0xbfb8aa3b, v143
	v_exp_f32_e32 v142, v142
	v_exp_f32_e32 v143, v143
	v_add_f32_e32 v142, 1.0, v142
	v_add_f32_e32 v143, 1.0, v143
	v_rcp_f32_e32 v142, v142
	v_rcp_f32_e32 v143, v143
	s_nop 0
	v_pk_mul_f32 v[152:153], v[10:11], v[142:143]
	v_lshlrev_b32_e32 v142, 16, v145
	v_and_b32_e32 v143, 0xffff0000, v145
	v_mul_f32_e32 v142, 0xbfb8aa3b, v142
	v_mul_f32_e32 v143, 0xbfb8aa3b, v143
	v_exp_f32_e32 v142, v142
	v_exp_f32_e32 v143, v143
	v_cvt_pk_bf16_f32 v144, v152, v153
	v_add_f32_e32 v142, 1.0, v142
	v_add_f32_e32 v143, 1.0, v143
	v_rcp_f32_e32 v142, v142
	v_rcp_f32_e32 v143, v143
	s_nop 0
	v_pk_mul_f32 v[154:155], v[12:13], v[142:143]
	v_cvt_pk_bf16_f32 v142, v146, v147
	v_cvt_pk_bf16_f32 v143, v148, v149
	v_cvt_pk_bf16_f32 v145, v154, v155
	global_store_dwordx4 v[150:151], v[142:145], off offset:256
	s_nop 1
	v_lshlrev_b32_e32 v142, 16, v138
	v_and_b32_e32 v138, 0xffff0000, v138
	v_mul_f32_e32 v138, 0xbfb8aa3b, v138
	v_exp_f32_e32 v138, v138
	v_mul_f32_e32 v142, 0xbfb8aa3b, v142
	v_exp_f32_e32 v142, v142
	v_add_f32_e32 v138, 1.0, v138
	v_rcp_f32_e32 v143, v138
	v_lshlrev_b32_e32 v138, 16, v139
	v_and_b32_e32 v139, 0xffff0000, v139
	v_mul_f32_e32 v138, 0xbfb8aa3b, v138
	v_mul_f32_e32 v139, 0xbfb8aa3b, v139
	v_exp_f32_e32 v138, v138
	v_exp_f32_e32 v139, v139
	v_add_f32_e32 v142, 1.0, v142
	v_rcp_f32_e32 v142, v142
	v_add_f32_e32 v138, 1.0, v138
	v_add_f32_e32 v139, 1.0, v139
	v_rcp_f32_e32 v138, v138
	v_rcp_f32_e32 v139, v139
	v_pk_mul_f32 v[142:143], v[42:43], v[142:143]
	v_pk_mul_f32 v[144:145], v[44:45], v[138:139]
	v_lshlrev_b32_e32 v138, 16, v140
	v_and_b32_e32 v139, 0xffff0000, v140
	v_mul_f32_e32 v138, 0xbfb8aa3b, v138
	v_mul_f32_e32 v139, 0xbfb8aa3b, v139
	v_exp_f32_e32 v138, v138
	v_exp_f32_e32 v139, v139
	v_add_f32_e32 v138, 1.0, v138
	v_add_f32_e32 v139, 1.0, v139
	v_rcp_f32_e32 v138, v138
	v_rcp_f32_e32 v139, v139
	s_nop 0
	v_pk_mul_f32 v[146:147], v[38:39], v[138:139]
	v_lshlrev_b32_e32 v138, 16, v141
	v_and_b32_e32 v139, 0xffff0000, v141
	v_mul_f32_e32 v138, 0xbfb8aa3b, v138
	v_mul_f32_e32 v139, 0xbfb8aa3b, v139
	v_exp_f32_e32 v138, v138
	v_exp_f32_e32 v139, v139
	v_cvt_pk_bf16_f32 v140, v146, v147
	v_add_f32_e32 v138, 1.0, v138
	v_add_f32_e32 v139, 1.0, v139
	v_rcp_f32_e32 v138, v138
	v_rcp_f32_e32 v139, v139
	s_nop 0
	v_pk_mul_f32 v[148:149], v[40:41], v[138:139]
	v_cvt_pk_bf16_f32 v138, v142, v143
	v_mad_i64_i32 v[142:143], s[0:1], v164, s78, v[162:163]
	v_cvt_pk_bf16_f32 v139, v144, v145
	v_cvt_pk_bf16_f32 v141, v148, v149
	v_lshl_add_u64 v[142:143], v[142:143], 0, v[186:187]
	global_store_dwordx4 v[142:143], v[138:141], off
	s_nop 1
	v_lshlrev_b32_e32 v138, 16, v134
	v_and_b32_e32 v134, 0xffff0000, v134
	v_mul_f32_e32 v134, 0xbfb8aa3b, v134
	v_exp_f32_e32 v134, v134
	v_mul_f32_e32 v138, 0xbfb8aa3b, v138
	v_exp_f32_e32 v138, v138
	v_add_f32_e32 v134, 1.0, v134
	v_rcp_f32_e32 v139, v134
	v_lshlrev_b32_e32 v134, 16, v135
	v_and_b32_e32 v135, 0xffff0000, v135
	v_mul_f32_e32 v134, 0xbfb8aa3b, v134
	v_mul_f32_e32 v135, 0xbfb8aa3b, v135
	v_exp_f32_e32 v134, v134
	v_exp_f32_e32 v135, v135
	v_add_f32_e32 v138, 1.0, v138
	v_rcp_f32_e32 v138, v138
	v_add_f32_e32 v134, 1.0, v134
	v_add_f32_e32 v135, 1.0, v135
	v_rcp_f32_e32 v134, v134
	v_rcp_f32_e32 v135, v135
	v_pk_mul_f32 v[138:139], v[6:7], v[138:139]
	v_pk_mul_f32 v[140:141], v[8:9], v[134:135]
	v_lshlrev_b32_e32 v134, 16, v136
	v_and_b32_e32 v135, 0xffff0000, v136
	v_mul_f32_e32 v134, 0xbfb8aa3b, v134
	v_mul_f32_e32 v135, 0xbfb8aa3b, v135
	v_exp_f32_e32 v134, v134
	v_exp_f32_e32 v135, v135
	v_add_f32_e32 v134, 1.0, v134
	v_add_f32_e32 v135, 1.0, v135
	v_rcp_f32_e32 v134, v134
	v_rcp_f32_e32 v135, v135
	s_nop 0
	v_pk_mul_f32 v[144:145], v[2:3], v[134:135]
	v_lshlrev_b32_e32 v134, 16, v137
	v_and_b32_e32 v135, 0xffff0000, v137
	v_mul_f32_e32 v134, 0xbfb8aa3b, v134
	v_mul_f32_e32 v135, 0xbfb8aa3b, v135
	v_exp_f32_e32 v134, v134
	v_exp_f32_e32 v135, v135
	v_cvt_pk_bf16_f32 v136, v144, v145
	v_add_f32_e32 v134, 1.0, v134
	v_add_f32_e32 v135, 1.0, v135
	v_rcp_f32_e32 v134, v134
	v_rcp_f32_e32 v135, v135
	s_nop 0
	v_pk_mul_f32 v[146:147], v[4:5], v[134:135]
	v_cvt_pk_bf16_f32 v134, v138, v139
	v_cvt_pk_bf16_f32 v135, v140, v141
	v_cvt_pk_bf16_f32 v137, v146, v147
	global_store_dwordx4 v[142:143], v[134:137], off offset:256
	s_cbranch_execnz .LBB0_891

.LBB0_965:
	s_add_u32 s36, s34, 0x100
	s_addc_u32 s37, s35, 0
	s_add_i32 s0, 0, 0x10000
	s_cmp_eq_u32 s31, 12
	s_cselect_b32 s47, s25, s37
	s_cselect_b32 s46, s24, s36
	s_cselect_b32 s43, s18, s29
	s_cselect_b32 s42, s19, s23
	s_add_i32 m0, s54, 0xc000
	ds_read_b128 v[148:151], v224
	ds_read_b128 v[152:155], v224 offset:1024
	ds_read_b128 v[178:181], v224 offset:2048
	ds_read_b128 v[182:185], v224 offset:3072
	ds_read_b128 v[186:189], v224 offset:4096
	ds_read_b128 v[190:193], v224 offset:5120
	ds_read_b128 v[194:197], v224 offset:6144
	ds_read_b128 v[198:201], v224 offset:7168
	global_load_lds_dwordx4 v174, s[34:35]
	v_lshl_add_u64 v[166:167], s[34:35], 0, v[176:177]
	s_add_i32 m0, s54, 0xe000
	s_nop 0
	global_load_lds_dwordx4 v[166:167], off
	s_waitcnt vmcnt(10) lgkmcnt(8)
	s_setprio 1
	s_barrier
	s_waitcnt lgkmcnt(0)
	v_mfma_f32_16x16x32_bf16 v[136:139], v[100:103], v[148:151], v[136:139]
	v_mfma_f32_16x16x32_bf16 v[132:135], v[140:143], v[148:151], v[132:135]
	v_mfma_f32_16x16x32_bf16 v[128:131], v[100:103], v[178:181], v[128:131]
	v_mfma_f32_16x16x32_bf16 v[124:127], v[140:143], v[178:181], v[124:127]
	v_mfma_f32_16x16x32_bf16 v[120:123], v[100:103], v[186:189], v[120:123]
	v_mfma_f32_16x16x32_bf16 v[116:119], v[140:143], v[186:189], v[116:119]
	v_mfma_f32_16x16x32_bf16 v[112:115], v[100:103], v[194:197], v[112:115]
	v_mfma_f32_16x16x32_bf16 v[108:111], v[140:143], v[194:197], v[108:111]
	v_mfma_f32_16x16x32_bf16 v[136:139], v[104:107], v[152:155], v[136:139]
	v_mfma_f32_16x16x32_bf16 v[132:135], v[144:147], v[152:155], v[132:135]
	v_mfma_f32_16x16x32_bf16 v[128:131], v[104:107], v[182:185], v[128:131]
	v_mfma_f32_16x16x32_bf16 v[124:127], v[144:147], v[182:185], v[124:127]
	v_mfma_f32_16x16x32_bf16 v[120:123], v[104:107], v[190:193], v[120:123]
	v_mfma_f32_16x16x32_bf16 v[116:119], v[144:147], v[190:193], v[116:119]
	v_mfma_f32_16x16x32_bf16 v[112:115], v[104:107], v[198:201], v[112:115]
	v_mfma_f32_16x16x32_bf16 v[108:111], v[144:147], v[198:201], v[108:111]
	s_barrier
	s_setprio 0
	s_add_i32 s34, 0, 0x14000
	v_add_u32_e32 v166, s34, v222
	s_add_i32 s0, s0, s53
	ds_read_b128 v[202:205], v166
	ds_read_b128 v[206:209], v166 offset:1024
	ds_read_b128 v[210:213], v166 offset:2048
	ds_read_b128 v[214:217], v166 offset:3072
	v_lshl_add_u64 v[166:167], s[42:43], 0, v[26:27]
	s_mov_b32 m0, s0
	v_lshl_add_u64 v[168:169], s[42:43], 0, v[160:161]
	global_load_lds_dwordx4 v[166:167], off
	s_add_i32 m0, s0, 0x2000
	s_nop 0
	global_load_lds_dwordx4 v[168:169], off
	s_waitcnt vmcnt(10)
	s_setprio 1
	s_barrier
	s_waitcnt lgkmcnt(0)
	v_mfma_f32_16x16x32_bf16 v[64:67], v[202:205], v[148:151], v[64:67]
	v_mfma_f32_16x16x32_bf16 v[60:63], v[210:213], v[148:151], v[60:63]
	v_mfma_f32_16x16x32_bf16 v[56:59], v[202:205], v[178:181], v[56:59]
	v_mfma_f32_16x16x32_bf16 v[52:55], v[210:213], v[178:181], v[52:55]
	v_mfma_f32_16x16x32_bf16 v[48:51], v[202:205], v[186:189], v[48:51]
	v_mfma_f32_16x16x32_bf16 v[44:47], v[210:213], v[186:189], v[44:47]
	v_mfma_f32_16x16x32_bf16 v[40:43], v[202:205], v[194:197], v[40:43]
	v_mfma_f32_16x16x32_bf16 v[36:39], v[210:213], v[194:197], v[36:39]
	v_mfma_f32_16x16x32_bf16 v[64:67], v[206:209], v[152:155], v[64:67]
	v_mfma_f32_16x16x32_bf16 v[60:63], v[214:217], v[152:155], v[60:63]
	v_mfma_f32_16x16x32_bf16 v[56:59], v[206:209], v[182:185], v[56:59]
	v_mfma_f32_16x16x32_bf16 v[52:55], v[214:217], v[182:185], v[52:55]
	v_mfma_f32_16x16x32_bf16 v[48:51], v[206:209], v[190:193], v[48:51]
	v_mfma_f32_16x16x32_bf16 v[44:47], v[214:217], v[190:193], v[44:47]
	v_mfma_f32_16x16x32_bf16 v[40:43], v[206:209], v[198:201], v[40:43]
	v_mfma_f32_16x16x32_bf16 v[36:39], v[214:217], v[198:201], v[36:39]
	s_barrier
	s_setprio 0
	s_mov_b32 m0, s54
	v_lshl_add_u64 v[218:219], s[46:47], 0, v[156:157]
	ds_read_b128 v[148:151], v224 offset:16384
	ds_read_b128 v[152:155], v224 offset:17408
	ds_read_b128 v[178:181], v224 offset:18432
	ds_read_b128 v[182:185], v224 offset:19456
	ds_read_b128 v[186:189], v224 offset:20480
	ds_read_b128 v[190:193], v224 offset:21504
	ds_read_b128 v[194:197], v224 offset:22528
	ds_read_b128 v[198:201], v224 offset:23552
	global_load_lds_dwordx4 v[218:219], off
	v_lshl_add_u64 v[220:221], s[46:47], 0, v[158:159]
	s_mov_b32 m0, s55
	s_nop 0
	global_load_lds_dwordx4 v[220:221], off
	s_waitcnt vmcnt(10)
	s_setprio 1
	s_barrier
	s_waitcnt lgkmcnt(0)
	v_mfma_f32_16x16x32_bf16 v[96:99], v[100:103], v[148:151], v[96:99]
	v_mfma_f32_16x16x32_bf16 v[92:95], v[140:143], v[148:151], v[92:95]
	v_mfma_f32_16x16x32_bf16 v[88:91], v[100:103], v[178:181], v[88:91]
	v_mfma_f32_16x16x32_bf16 v[84:87], v[140:143], v[178:181], v[84:87]
	v_mfma_f32_16x16x32_bf16 v[80:83], v[100:103], v[186:189], v[80:83]
	v_mfma_f32_16x16x32_bf16 v[76:79], v[140:143], v[186:189], v[76:79]
	v_mfma_f32_16x16x32_bf16 v[72:75], v[100:103], v[194:197], v[72:75]
	v_mfma_f32_16x16x32_bf16 v[68:71], v[140:143], v[194:197], v[68:71]
	v_mfma_f32_16x16x32_bf16 v[96:99], v[104:107], v[152:155], v[96:99]
	v_mfma_f32_16x16x32_bf16 v[92:95], v[144:147], v[152:155], v[92:95]
	v_mfma_f32_16x16x32_bf16 v[88:91], v[104:107], v[182:185], v[88:91]
	v_mfma_f32_16x16x32_bf16 v[84:87], v[144:147], v[182:185], v[84:87]
	v_mfma_f32_16x16x32_bf16 v[80:83], v[104:107], v[190:193], v[80:83]
	v_mfma_f32_16x16x32_bf16 v[76:79], v[144:147], v[190:193], v[76:79]
	v_mfma_f32_16x16x32_bf16 v[72:75], v[104:107], v[198:201], v[72:75]
	v_mfma_f32_16x16x32_bf16 v[68:71], v[144:147], v[198:201], v[68:71]
	s_barrier
	s_setprio 0
	s_add_u32 s0, s42, 0x40000
	s_addc_u32 s1, s43, 0
	s_add_i32 s34, s34, s53
	s_mov_b32 m0, s34
	s_nop 0
	global_load_lds_dwordx4 v26, s[0:1]
	s_add_i32 m0, s34, 0x2000
	s_nop 0
	global_load_lds_dwordx4 v160, s[0:1]
	v_add_u32_e32 v144, 0x18000, v222
	ds_read_b128 v[100:103], v144
	ds_read_b128 v[104:107], v144 offset:1024
	ds_read_b128 v[140:143], v144 offset:2048
	ds_read_b128 v[144:147], v144 offset:3072
	s_waitcnt vmcnt(10)
	s_setprio 1
	s_barrier
	v_mfma_f32_16x16x32_bf16 v[32:35], v[202:205], v[148:151], v[32:35]
	v_mfma_f32_16x16x32_bf16 v[28:31], v[210:213], v[148:151], v[28:31]
	v_mfma_f32_16x16x32_bf16 v[22:25], v[202:205], v[178:181], v[22:25]
	v_mfma_f32_16x16x32_bf16 v[18:21], v[210:213], v[178:181], v[18:21]
	v_mfma_f32_16x16x32_bf16 v[14:17], v[202:205], v[186:189], v[14:17]
	v_mfma_f32_16x16x32_bf16 v[10:13], v[210:213], v[186:189], v[10:13]
	v_mfma_f32_16x16x32_bf16 v[6:9], v[202:205], v[194:197], v[6:9]
	v_mfma_f32_16x16x32_bf16 v[2:5], v[210:213], v[194:197], v[2:5]
	v_mfma_f32_16x16x32_bf16 v[32:35], v[206:209], v[152:155], v[32:35]
	v_mfma_f32_16x16x32_bf16 v[28:31], v[214:217], v[152:155], v[28:31]
	v_mfma_f32_16x16x32_bf16 v[22:25], v[206:209], v[182:185], v[22:25]
	v_mfma_f32_16x16x32_bf16 v[18:21], v[214:217], v[182:185], v[18:21]
	v_mfma_f32_16x16x32_bf16 v[14:17], v[206:209], v[190:193], v[14:17]
	v_mfma_f32_16x16x32_bf16 v[10:13], v[214:217], v[190:193], v[10:13]
	v_mfma_f32_16x16x32_bf16 v[6:9], v[206:209], v[198:201], v[6:9]
	v_mfma_f32_16x16x32_bf16 v[2:5], v[214:217], v[198:201], v[2:5]
	s_barrier
	s_setprio 0
	s_add_i32 s34, 0, 0x18000
	s_add_u32 s0, s46, 0x140000
	s_addc_u32 s1, s47, 0
	s_mov_b32 m0, s56
	ds_read_b128 v[148:151], v224 offset:32768
	ds_read_b128 v[152:155], v224 offset:33792
	ds_read_b128 v[178:181], v224 offset:34816
	ds_read_b128 v[182:185], v224 offset:35840
	ds_read_b128 v[186:189], v224 offset:36864
	ds_read_b128 v[190:193], v224 offset:37888
	ds_read_b128 v[194:197], v224 offset:38912
	ds_read_b128 v[198:201], v224 offset:39936
	global_load_lds_dwordx4 v156, s[0:1]
	s_mov_b32 m0, s57
	s_nop 0
	global_load_lds_dwordx4 v158, s[0:1]
	s_waitcnt vmcnt(10) lgkmcnt(8)
	s_setprio 1
	s_barrier
	s_waitcnt lgkmcnt(0)
	v_mfma_f32_16x16x32_bf16 v[136:139], v[100:103], v[148:151], v[136:139]
	v_mfma_f32_16x16x32_bf16 v[132:135], v[140:143], v[148:151], v[132:135]
	v_mfma_f32_16x16x32_bf16 v[128:131], v[100:103], v[178:181], v[128:131]
	v_mfma_f32_16x16x32_bf16 v[124:127], v[140:143], v[178:181], v[124:127]
	v_mfma_f32_16x16x32_bf16 v[120:123], v[100:103], v[186:189], v[120:123]
	v_mfma_f32_16x16x32_bf16 v[116:119], v[140:143], v[186:189], v[116:119]
	v_mfma_f32_16x16x32_bf16 v[112:115], v[100:103], v[194:197], v[112:115]
	v_mfma_f32_16x16x32_bf16 v[108:111], v[140:143], v[194:197], v[108:111]
	v_mfma_f32_16x16x32_bf16 v[136:139], v[104:107], v[152:155], v[136:139]
	v_mfma_f32_16x16x32_bf16 v[132:135], v[144:147], v[152:155], v[132:135]
	v_mfma_f32_16x16x32_bf16 v[128:131], v[104:107], v[182:185], v[128:131]
	v_mfma_f32_16x16x32_bf16 v[124:127], v[144:147], v[182:185], v[124:127]
	v_mfma_f32_16x16x32_bf16 v[120:123], v[104:107], v[190:193], v[120:123]
	v_mfma_f32_16x16x32_bf16 v[116:119], v[144:147], v[190:193], v[116:119]
	v_mfma_f32_16x16x32_bf16 v[112:115], v[104:107], v[198:201], v[112:115]
	v_mfma_f32_16x16x32_bf16 v[108:111], v[144:147], v[198:201], v[108:111]
	s_barrier
	s_setprio 0
	s_add_i32 s35, 0, 0x1c000
	s_add_i32 s0, s34, s53
	v_add_u32_e32 v214, s35, v222
	v_lshl_add_u64 v[166:167], v[166:167], 0, s[12:13]
	s_mov_b32 m0, s0
	ds_read_b128 v[202:205], v214
	ds_read_b128 v[206:209], v214 offset:1024
	ds_read_b128 v[210:213], v214 offset:2048
	ds_read_b128 v[214:217], v214 offset:3072
	global_load_lds_dwordx4 v[166:167], off
	v_lshl_add_u64 v[166:167], v[168:169], 0, s[12:13]
	s_add_i32 m0, s0, 0x2000
	s_nop 0
	global_load_lds_dwordx4 v[166:167], off
	s_waitcnt vmcnt(10)
	s_setprio 1
	s_barrier
	s_waitcnt lgkmcnt(0)
	v_mfma_f32_16x16x32_bf16 v[64:67], v[202:205], v[148:151], v[64:67]
	v_mfma_f32_16x16x32_bf16 v[60:63], v[210:213], v[148:151], v[60:63]
	v_mfma_f32_16x16x32_bf16 v[56:59], v[202:205], v[178:181], v[56:59]
	v_mfma_f32_16x16x32_bf16 v[52:55], v[210:213], v[178:181], v[52:55]
	v_mfma_f32_16x16x32_bf16 v[48:51], v[202:205], v[186:189], v[48:51]
	v_mfma_f32_16x16x32_bf16 v[44:47], v[210:213], v[186:189], v[44:47]
	v_mfma_f32_16x16x32_bf16 v[40:43], v[202:205], v[194:197], v[40:43]
	v_mfma_f32_16x16x32_bf16 v[36:39], v[210:213], v[194:197], v[36:39]
	v_mfma_f32_16x16x32_bf16 v[64:67], v[206:209], v[152:155], v[64:67]
	v_mfma_f32_16x16x32_bf16 v[60:63], v[214:217], v[152:155], v[60:63]
	v_mfma_f32_16x16x32_bf16 v[56:59], v[206:209], v[182:185], v[56:59]
	v_mfma_f32_16x16x32_bf16 v[52:55], v[214:217], v[182:185], v[52:55]
	v_mfma_f32_16x16x32_bf16 v[48:51], v[206:209], v[190:193], v[48:51]
	v_mfma_f32_16x16x32_bf16 v[44:47], v[214:217], v[190:193], v[44:47]
	v_mfma_f32_16x16x32_bf16 v[40:43], v[206:209], v[198:201], v[40:43]
	v_mfma_f32_16x16x32_bf16 v[36:39], v[214:217], v[198:201], v[36:39]
	s_barrier
	s_setprio 0
	s_mov_b32 m0, s81
	v_lshl_add_u64 v[166:167], v[218:219], 0, s[12:13]
	ds_read_b128 v[148:151], v224 offset:49152
	ds_read_b128 v[152:155], v224 offset:50176
	ds_read_b128 v[178:181], v224 offset:51200
	ds_read_b128 v[182:185], v224 offset:52224
	ds_read_b128 v[186:189], v224 offset:53248
	ds_read_b128 v[190:193], v224 offset:54272
	ds_read_b128 v[194:197], v224 offset:55296
	ds_read_b128 v[198:201], v224 offset:56320
	global_load_lds_dwordx4 v[166:167], off
	v_lshl_add_u64 v[166:167], v[220:221], 0, s[12:13]
	s_mov_b32 m0, s17
	s_nop 0
	global_load_lds_dwordx4 v[166:167], off
	s_waitcnt vmcnt(10)
	s_setprio 1
	s_barrier
	s_waitcnt lgkmcnt(0)
	v_mfma_f32_16x16x32_bf16 v[96:99], v[100:103], v[148:151], v[96:99]
	v_mfma_f32_16x16x32_bf16 v[92:95], v[140:143], v[148:151], v[92:95]
	v_mfma_f32_16x16x32_bf16 v[88:91], v[100:103], v[178:181], v[88:91]
	v_mfma_f32_16x16x32_bf16 v[84:87], v[140:143], v[178:181], v[84:87]
	v_mfma_f32_16x16x32_bf16 v[80:83], v[100:103], v[186:189], v[80:83]
	v_mfma_f32_16x16x32_bf16 v[76:79], v[140:143], v[186:189], v[76:79]
	v_mfma_f32_16x16x32_bf16 v[72:75], v[100:103], v[194:197], v[72:75]
	v_mfma_f32_16x16x32_bf16 v[68:71], v[140:143], v[194:197], v[68:71]
	v_mfma_f32_16x16x32_bf16 v[96:99], v[104:107], v[152:155], v[96:99]
	v_mfma_f32_16x16x32_bf16 v[92:95], v[144:147], v[152:155], v[92:95]
	v_mfma_f32_16x16x32_bf16 v[88:91], v[104:107], v[182:185], v[88:91]
	v_mfma_f32_16x16x32_bf16 v[84:87], v[144:147], v[182:185], v[84:87]
	v_mfma_f32_16x16x32_bf16 v[80:83], v[104:107], v[190:193], v[80:83]
	v_mfma_f32_16x16x32_bf16 v[76:79], v[144:147], v[190:193], v[76:79]
	v_mfma_f32_16x16x32_bf16 v[72:75], v[104:107], v[198:201], v[72:75]
	v_mfma_f32_16x16x32_bf16 v[68:71], v[144:147], v[198:201], v[68:71]
	s_barrier
	s_setprio 0
	s_add_u32 s0, s42, 0x40080
	s_addc_u32 s1, s43, 0
	s_add_i32 s34, s35, s53
	s_mov_b32 m0, s34
	s_nop 0
	global_load_lds_dwordx4 v26, s[0:1]
	s_add_i32 m0, s34, 0x2000
	s_nop 0
	global_load_lds_dwordx4 v160, s[0:1]
	v_add_u32_e32 v144, 0x10000, v222
	ds_read_b128 v[100:103], v144
	ds_read_b128 v[104:107], v144 offset:1024
	ds_read_b128 v[140:143], v144 offset:2048
	ds_read_b128 v[144:147], v144 offset:3072
	s_waitcnt vmcnt(10)
	s_setprio 1
	s_barrier
	v_mfma_f32_16x16x32_bf16 v[32:35], v[202:205], v[148:151], v[32:35]
	v_mfma_f32_16x16x32_bf16 v[28:31], v[210:213], v[148:151], v[28:31]
	v_mfma_f32_16x16x32_bf16 v[22:25], v[202:205], v[178:181], v[22:25]
	v_mfma_f32_16x16x32_bf16 v[18:21], v[210:213], v[178:181], v[18:21]
	v_mfma_f32_16x16x32_bf16 v[14:17], v[202:205], v[186:189], v[14:17]
	v_mfma_f32_16x16x32_bf16 v[10:13], v[210:213], v[186:189], v[10:13]
	v_mfma_f32_16x16x32_bf16 v[6:9], v[202:205], v[194:197], v[6:9]
	v_mfma_f32_16x16x32_bf16 v[2:5], v[210:213], v[194:197], v[2:5]
	v_mfma_f32_16x16x32_bf16 v[32:35], v[206:209], v[152:155], v[32:35]
	v_mfma_f32_16x16x32_bf16 v[28:31], v[214:217], v[152:155], v[28:31]
	v_mfma_f32_16x16x32_bf16 v[22:25], v[206:209], v[182:185], v[22:25]
	v_mfma_f32_16x16x32_bf16 v[18:21], v[214:217], v[182:185], v[18:21]
	v_mfma_f32_16x16x32_bf16 v[14:17], v[206:209], v[190:193], v[14:17]
	v_mfma_f32_16x16x32_bf16 v[10:13], v[214:217], v[190:193], v[10:13]
	v_mfma_f32_16x16x32_bf16 v[6:9], v[206:209], v[198:201], v[6:9]
	v_mfma_f32_16x16x32_bf16 v[2:5], v[214:217], v[198:201], v[2:5]
	s_barrier
	s_setprio 0
	s_add_i32 s31, s31, 2
	s_add_u32 s23, s23, 0x100
	s_addc_u32 s29, s29, 0
	s_cmp_gt_u32 s31, 13
	s_mov_b64 s[34:35], s[36:37]
	s_cbranch_scc0 .LBB0_965
	s_waitcnt lgkmcnt(0)
	s_min_i32 s0, s28, 0x100
	s_ashr_i32 s0, s0, 5
	s_ashr_i32 s1, s0, 31
	s_add_i32 s18, s28, 0xffffff00
	s_cmpk_lt_i32 s28, 0x100
	s_cselect_b32 s18, s28, s18
	s_cselect_b32 s23, 0, s59
	s_cselect_b32 s29, 0, s58
	s_ashr_i32 s19, s18, 31
	s_lshl_b64 s[18:19], s[18:19], 19
	v_lshl_or_b32 v148, s30, 8, v223
	s_add_u32 s30, s44, s29
	s_addc_u32 s31, s45, s23
	s_ashr_i32 s29, s28, 31
	v_lshl_add_u64 v[100:101], s[18:19], 0, v[162:163]
	s_lshl_b64 s[18:19], s[28:29], 19
	v_lshl_add_u64 v[152:153], v[164:165], 0, s[18:19]
	s_lshl_b64 s[28:29], s[28:29], 10
	s_mul_i32 s18, s0, 0x9000
	s_mul_hi_i32 s19, s0, 0x9000
	s_add_u32 s18, s68, s18
	s_addc_u32 s19, s69, s19
	s_lshl_b64 s[0:1], s[0:1], 12
	v_ashrrev_i32_e32 v149, 31, v148
	s_add_u32 s0, s72, s0
	v_lshlrev_b64 v[154:155], 2, v[148:149]
	s_addc_u32 s1, s73, s1
	v_lshl_add_u64 v[150:151], v[100:101], 0, v[148:149]
	v_lshl_add_u64 v[104:105], s[18:19], 0, v[154:155]
	v_lshlrev_b64 v[168:169], 1, v[148:149]
	v_lshl_add_u64 v[180:181], s[0:1], 0, v[154:155]
	v_lshl_add_u64 v[166:167], v[100:101], 1, s[30:31]
	global_load_dwordx4 v[140:143], v[104:105], off offset:16
	global_load_dwordx4 v[144:147], v[104:105], off
	global_load_dwordx4 v[100:103], v[104:105], off offset:528
	s_nop 0
	global_load_dwordx4 v[104:107], v[104:105], off offset:512
	v_lshl_add_u64 v[196:197], v[150:151], 1, s[30:31]
	v_lshl_add_u64 v[178:179], v[152:153], 0, v[168:169]
	global_load_dwordx4 v[148:151], v[180:181], off offset:16
	global_load_dwordx4 v[152:155], v[180:181], off
	global_load_dwordx4 v[190:193], v[196:197], off offset:2048
	v_add_co_u32_e32 v210, vcc, s65, v196
	s_mov_b32 s1, 0x20000
	s_nop 0
	v_addc_co_u32_e32 v211, vcc, 0, v197, vcc
	global_load_dwordx4 v[198:201], v[210:211], off offset:2048
	v_add_co_u32_e32 v184, vcc, s1, v196
	s_mov_b32 s18, 0x30000
	s_nop 0
	v_addc_co_u32_e32 v185, vcc, 0, v197, vcc
	global_load_dwordx4 v[202:205], v[184:185], off offset:2048
	v_add_co_u32_e32 v188, vcc, s18, v196
	v_lshl_add_u64 v[182:183], v[166:167], 0, v[168:169]
	s_nop 0
	v_addc_co_u32_e32 v189, vcc, 0, v197, vcc
	global_load_dwordx4 v[206:209], v[188:189], off offset:2048
	s_mov_b32 s0, 0x8000
	s_mov_b32 s19, 0x80000
	s_mov_b32 s23, 0x90000
	s_waitcnt vmcnt(0)
	v_lshlrev_b32_e32 v166, 16, v190
	v_and_b32_e32 v167, 0xffff0000, v190
	v_lshlrev_b32_e32 v168, 16, v191
	v_and_b32_e32 v169, 0xffff0000, v191
	v_lshlrev_b32_e32 v186, 16, v192
	v_and_b32_e32 v187, 0xffff0000, v192
	v_lshlrev_b32_e32 v190, 16, v193
	v_and_b32_e32 v191, 0xffff0000, v193
	v_pk_fma_f32 v[138:139], v[138:139], v[146:147], v[168:169]
	v_pk_fma_f32 v[136:137], v[136:137], v[144:145], v[166:167]
	v_pk_fma_f32 v[134:135], v[134:135], v[142:143], v[190:191]
	v_pk_fma_f32 v[132:133], v[132:133], v[140:141], v[186:187]
	v_cvt_pk_bf16_f32 v190, v136, v137
	v_cvt_pk_bf16_f32 v191, v138, v139
	v_cvt_pk_bf16_f32 v192, v132, v133
	v_cvt_pk_bf16_f32 v193, v134, v135
	v_lshlrev_b32_e32 v138, 16, v190
	v_and_b32_e32 v139, 0xffff0000, v190
	v_lshlrev_b32_e32 v136, 16, v191
	v_and_b32_e32 v137, 0xffff0000, v191
	v_lshlrev_b32_e32 v134, 16, v192
	v_and_b32_e32 v135, 0xffff0000, v192
	v_lshlrev_b32_e32 v132, 16, v193
	v_and_b32_e32 v133, 0xffff0000, v193
	v_lshlrev_b32_e32 v212, 16, v200
	v_and_b32_e32 v213, 0xffff0000, v200
	v_lshlrev_b32_e32 v200, 16, v201
	v_and_b32_e32 v201, 0xffff0000, v201
	global_store_dwordx4 v[182:183], v[190:193], off offset:2048
	v_pk_mul_f32 v[166:167], v[154:155], v[136:137]
	v_pk_mul_f32 v[168:169], v[152:153], v[138:139]
	v_pk_mul_f32 v[186:187], v[150:151], v[132:133]
	v_pk_mul_f32 v[192:193], v[148:149], v[134:135]
	v_lshlrev_b32_e32 v194, 16, v198
	v_and_b32_e32 v195, 0xffff0000, v198
	v_lshlrev_b32_e32 v198, 16, v199
	v_and_b32_e32 v199, 0xffff0000, v199
	v_cvt_pk_bf16_f32 v190, v168, v169
	v_cvt_pk_bf16_f32 v191, v166, v167
	v_cvt_pk_bf16_f32 v192, v192, v193
	v_cvt_pk_bf16_f32 v193, v186, v187
	v_pk_fma_f32 v[126:127], v[126:127], v[142:143], v[200:201]
	v_pk_fma_f32 v[124:125], v[124:125], v[140:141], v[212:213]
	global_store_dwordx4 v[178:179], v[190:193], off
	v_pk_fma_f32 v[130:131], v[130:131], v[146:147], v[198:199]
	v_pk_fma_f32 v[128:129], v[128:129], v[144:145], v[194:195]
	v_cvt_pk_bf16_f32 v192, v124, v125
	v_cvt_pk_bf16_f32 v193, v126, v127
	v_add_co_u32_e32 v186, vcc, s65, v182
	v_cvt_pk_bf16_f32 v190, v128, v129
	v_cvt_pk_bf16_f32 v191, v130, v131
	v_addc_co_u32_e32 v187, vcc, 0, v183, vcc
	v_lshlrev_b32_e32 v126, 16, v192
	v_and_b32_e32 v127, 0xffff0000, v192
	v_lshlrev_b32_e32 v124, 16, v193
	v_and_b32_e32 v125, 0xffff0000, v193
	global_store_dwordx4 v[186:187], v[190:193], off offset:2048
	v_lshlrev_b32_e32 v130, 16, v190
	v_and_b32_e32 v131, 0xffff0000, v190
	v_lshlrev_b32_e32 v128, 16, v191
	v_and_b32_e32 v129, 0xffff0000, v191
	v_pk_mul_f32 v[190:191], v[150:151], v[124:125]
	v_pk_mul_f32 v[194:195], v[148:149], v[126:127]
	v_pk_mul_f32 v[166:167], v[154:155], v[128:129]
	v_pk_mul_f32 v[168:169], v[152:153], v[130:131]
	v_cvt_pk_bf16_f32 v194, v194, v195
	v_cvt_pk_bf16_f32 v195, v190, v191
	v_add_co_u32_e32 v190, vcc, s0, v178
	v_cvt_pk_bf16_f32 v192, v168, v169
	v_cvt_pk_bf16_f32 v193, v166, v167
	v_addc_co_u32_e32 v191, vcc, 0, v179, vcc
	global_store_dwordx4 v[190:191], v[192:195], off
	v_lshlrev_b32_e32 v198, 16, v204
	v_and_b32_e32 v199, 0xffff0000, v204
	v_add_co_u32_e32 v192, vcc, s19, v196
	v_lshlrev_b32_e32 v200, 16, v205
	s_nop 0
	v_addc_co_u32_e32 v193, vcc, 0, v197, vcc
	v_add_co_u32_e32 v194, vcc, s23, v196
	v_and_b32_e32 v201, 0xffff0000, v205
	global_load_dwordx4 v[212:215], v[192:193], off offset:2048
	v_addc_co_u32_e32 v195, vcc, 0, v197, vcc
	v_lshlrev_b32_e32 v166, 16, v202
	v_and_b32_e32 v167, 0xffff0000, v202
	v_lshlrev_b32_e32 v168, 16, v203
	v_and_b32_e32 v169, 0xffff0000, v203
	v_pk_fma_f32 v[118:119], v[118:119], v[142:143], v[200:201]
	v_pk_fma_f32 v[116:117], v[116:117], v[140:141], v[198:199]
	v_pk_fma_f32 v[122:123], v[122:123], v[146:147], v[168:169]
	v_pk_fma_f32 v[120:121], v[120:121], v[144:145], v[166:167]
	v_cvt_pk_bf16_f32 v202, v116, v117
	v_cvt_pk_bf16_f32 v203, v118, v119
	v_add_co_u32_e32 v198, vcc, s1, v182
	global_load_dwordx4 v[216:219], v[194:195], off offset:2048
	v_cvt_pk_bf16_f32 v200, v120, v121
	v_cvt_pk_bf16_f32 v201, v122, v123
	v_addc_co_u32_e32 v199, vcc, 0, v183, vcc
	v_lshlrev_b32_e32 v118, 16, v202
	v_and_b32_e32 v119, 0xffff0000, v202
	v_lshlrev_b32_e32 v116, 16, v203
	v_and_b32_e32 v117, 0xffff0000, v203
	global_store_dwordx4 v[198:199], v[200:203], off offset:2048
	v_lshlrev_b32_e32 v122, 16, v200
	v_and_b32_e32 v123, 0xffff0000, v200
	v_lshlrev_b32_e32 v120, 16, v201
	v_and_b32_e32 v121, 0xffff0000, v201
	v_pk_mul_f32 v[200:201], v[150:151], v[116:117]
	v_pk_mul_f32 v[204:205], v[148:149], v[118:119]
	v_lshlrev_b32_e32 v234, 16, v208
	v_and_b32_e32 v235, 0xffff0000, v208
	v_lshlrev_b32_e32 v208, 16, v209
	v_and_b32_e32 v209, 0xffff0000, v209
	v_pk_mul_f32 v[166:167], v[154:155], v[120:121]
	v_pk_mul_f32 v[168:169], v[152:153], v[122:123]
	v_cvt_pk_bf16_f32 v204, v204, v205
	v_cvt_pk_bf16_f32 v205, v200, v201
	v_add_co_u32_e32 v200, vcc, s65, v178
	v_lshlrev_b32_e32 v220, 16, v206
	v_and_b32_e32 v221, 0xffff0000, v206
	v_lshlrev_b32_e32 v206, 16, v207
	v_and_b32_e32 v207, 0xffff0000, v207
	v_cvt_pk_bf16_f32 v202, v168, v169
	v_cvt_pk_bf16_f32 v203, v166, v167
	v_addc_co_u32_e32 v201, vcc, 0, v179, vcc
	v_pk_fma_f32 v[110:111], v[110:111], v[142:143], v[208:209]
	v_pk_fma_f32 v[108:109], v[108:109], v[140:141], v[234:235]
	global_store_dwordx4 v[200:201], v[202:205], off
	v_pk_fma_f32 v[114:115], v[114:115], v[146:147], v[206:207]
	v_pk_fma_f32 v[112:113], v[112:113], v[144:145], v[220:221]
	v_cvt_pk_bf16_f32 v206, v108, v109
	v_cvt_pk_bf16_f32 v207, v110, v111
	v_add_co_u32_e32 v202, vcc, s18, v182
	v_cvt_pk_bf16_f32 v204, v112, v113
	v_cvt_pk_bf16_f32 v205, v114, v115
	v_addc_co_u32_e32 v203, vcc, 0, v183, vcc
	v_lshlrev_b32_e32 v110, 16, v206
	v_and_b32_e32 v111, 0xffff0000, v206
	v_lshlrev_b32_e32 v108, 16, v207
	v_and_b32_e32 v109, 0xffff0000, v207
	global_store_dwordx4 v[202:203], v[204:207], off offset:2048
	v_lshlrev_b32_e32 v114, 16, v204
	v_and_b32_e32 v115, 0xffff0000, v204
	v_lshlrev_b32_e32 v112, 16, v205
	v_and_b32_e32 v113, 0xffff0000, v205
	v_pk_mul_f32 v[204:205], v[150:151], v[108:109]
	v_pk_mul_f32 v[208:209], v[148:149], v[110:111]
	s_mov_b32 s0, 0x18000
	v_pk_mul_f32 v[166:167], v[154:155], v[112:113]
	v_pk_mul_f32 v[168:169], v[152:153], v[114:115]
	v_cvt_pk_bf16_f32 v208, v208, v209
	v_cvt_pk_bf16_f32 v209, v204, v205
	v_add_co_u32_e32 v204, vcc, s0, v178
	v_cvt_pk_bf16_f32 v206, v168, v169
	v_cvt_pk_bf16_f32 v207, v166, v167
	v_addc_co_u32_e32 v205, vcc, 0, v179, vcc
	global_store_dwordx4 v[204:205], v[206:209], off
	s_mov_b32 s0, 0xb0000
	s_waitcnt vmcnt(0)
	v_lshlrev_b32_e32 v166, 16, v212
	v_add_co_u32_e32 v206, vcc, s76, v196
	v_and_b32_e32 v167, 0xffff0000, v212
	s_nop 0
	v_addc_co_u32_e32 v207, vcc, 0, v197, vcc
	global_load_dwordx4 v[238:241], v[206:207], off offset:2048
	v_add_co_u32_e32 v208, vcc, s0, v196
	v_lshlrev_b32_e32 v168, 16, v213
	s_nop 0
	v_addc_co_u32_e32 v209, vcc, 0, v197, vcc
	global_load_dwordx4 v[242:245], v[208:209], off offset:2048
	v_and_b32_e32 v169, 0xffff0000, v213
	v_lshlrev_b32_e32 v212, 16, v214
	v_and_b32_e32 v213, 0xffff0000, v214
	v_lshlrev_b32_e32 v214, 16, v215
	v_and_b32_e32 v215, 0xffff0000, v215
	v_pk_fma_f32 v[94:95], v[94:95], v[142:143], v[214:215]
	v_pk_fma_f32 v[92:93], v[92:93], v[140:141], v[212:213]
	v_lshlrev_b32_e32 v220, 16, v216
	v_and_b32_e32 v221, 0xffff0000, v216
	v_lshlrev_b32_e32 v234, 16, v217
	v_and_b32_e32 v235, 0xffff0000, v217
	v_pk_fma_f32 v[98:99], v[98:99], v[146:147], v[168:169]
	v_pk_fma_f32 v[96:97], v[96:97], v[144:145], v[166:167]
	v_cvt_pk_bf16_f32 v216, v92, v93
	v_cvt_pk_bf16_f32 v217, v94, v95
	v_add_co_u32_e32 v212, vcc, s19, v182
	v_cvt_pk_bf16_f32 v214, v96, v97
	v_cvt_pk_bf16_f32 v215, v98, v99
	v_addc_co_u32_e32 v213, vcc, 0, v183, vcc
	v_lshlrev_b32_e32 v94, 16, v216
	v_and_b32_e32 v95, 0xffff0000, v216
	v_lshlrev_b32_e32 v92, 16, v217
	v_and_b32_e32 v93, 0xffff0000, v217
	v_lshlrev_b32_e32 v246, 16, v218
	v_and_b32_e32 v247, 0xffff0000, v218
	v_lshlrev_b32_e32 v248, 16, v219
	v_and_b32_e32 v249, 0xffff0000, v219
	global_store_dwordx4 v[212:213], v[214:217], off offset:2048
	v_lshlrev_b32_e32 v98, 16, v214
	v_and_b32_e32 v99, 0xffff0000, v214
	v_lshlrev_b32_e32 v96, 16, v215
	v_and_b32_e32 v97, 0xffff0000, v215
	v_pk_mul_f32 v[214:215], v[150:151], v[92:93]
	v_pk_mul_f32 v[218:219], v[148:149], v[94:95]
	s_mov_b32 s1, 0x40000
	v_pk_mul_f32 v[166:167], v[154:155], v[96:97]
	v_pk_mul_f32 v[168:169], v[152:153], v[98:99]
	v_cvt_pk_bf16_f32 v218, v218, v219
	v_cvt_pk_bf16_f32 v219, v214, v215
	v_add_co_u32_e32 v214, vcc, s1, v178
	v_cvt_pk_bf16_f32 v216, v168, v169
	v_cvt_pk_bf16_f32 v217, v166, v167
	v_addc_co_u32_e32 v215, vcc, 0, v179, vcc
	v_pk_fma_f32 v[86:87], v[86:87], v[142:143], v[248:249]
	global_store_dwordx4 v[214:215], v[216:219], off
	v_pk_fma_f32 v[90:91], v[90:91], v[146:147], v[234:235]
	v_pk_fma_f32 v[88:89], v[88:89], v[144:145], v[220:221]
	v_pk_fma_f32 v[84:85], v[84:85], v[140:141], v[246:247]
	v_cvt_pk_bf16_f32 v221, v86, v87
	v_add_co_u32_e32 v216, vcc, s23, v182
	v_cvt_pk_bf16_f32 v218, v88, v89
	v_cvt_pk_bf16_f32 v219, v90, v91
	v_cvt_pk_bf16_f32 v220, v84, v85
	v_addc_co_u32_e32 v217, vcc, 0, v183, vcc
	v_lshlrev_b32_e32 v84, 16, v221
	v_and_b32_e32 v85, 0xffff0000, v221
	global_store_dwordx4 v[216:217], v[218:221], off offset:2048
	v_lshlrev_b32_e32 v90, 16, v218
	v_and_b32_e32 v91, 0xffff0000, v218
	v_lshlrev_b32_e32 v88, 16, v219
	v_and_b32_e32 v89, 0xffff0000, v219
	v_lshlrev_b32_e32 v86, 16, v220
	v_and_b32_e32 v87, 0xffff0000, v220
	v_pk_mul_f32 v[218:219], v[150:151], v[84:85]
	s_mov_b32 s1, 0x48000
	v_pk_mul_f32 v[166:167], v[154:155], v[88:89]
	v_pk_mul_f32 v[168:169], v[152:153], v[90:91]
	v_pk_mul_f32 v[220:221], v[148:149], v[86:87]
	v_cvt_pk_bf16_f32 v249, v218, v219
	v_add_co_u32_e32 v218, vcc, s1, v178
	v_cvt_pk_bf16_f32 v246, v168, v169
	v_cvt_pk_bf16_f32 v247, v166, v167
	v_cvt_pk_bf16_f32 v248, v220, v221
	v_addc_co_u32_e32 v219, vcc, 0, v179, vcc
	global_store_dwordx4 v[218:219], v[246:249], off
	global_load_dwordx4 v[246:249], v[196:197], off offset:2304
	s_nop 0
	global_load_dwordx4 v[250:253], v[210:211], off offset:2304
	s_waitcnt vmcnt(0)
	v_lshlrev_b32_e32 v196, 16, v240
	v_and_b32_e32 v197, 0xffff0000, v240
	v_lshlrev_b32_e32 v210, 16, v241
	v_and_b32_e32 v211, 0xffff0000, v241
	v_lshlrev_b32_e32 v166, 16, v238
	v_and_b32_e32 v167, 0xffff0000, v238
	v_lshlrev_b32_e32 v168, 16, v239
	v_and_b32_e32 v169, 0xffff0000, v239
	v_pk_fma_f32 v[78:79], v[78:79], v[142:143], v[210:211]
	v_pk_fma_f32 v[76:77], v[76:77], v[140:141], v[196:197]
	v_pk_fma_f32 v[82:83], v[82:83], v[146:147], v[168:169]
	v_pk_fma_f32 v[80:81], v[80:81], v[144:145], v[166:167]
	v_cvt_pk_bf16_f32 v240, v76, v77
	v_cvt_pk_bf16_f32 v241, v78, v79
	v_add_co_u32_e32 v196, vcc, s76, v182
	v_cvt_pk_bf16_f32 v238, v80, v81
	v_cvt_pk_bf16_f32 v239, v82, v83
	v_addc_co_u32_e32 v197, vcc, 0, v183, vcc
	v_lshlrev_b32_e32 v78, 16, v240
	v_and_b32_e32 v79, 0xffff0000, v240
	v_lshlrev_b32_e32 v76, 16, v241
	v_and_b32_e32 v77, 0xffff0000, v241
	global_store_dwordx4 v[196:197], v[238:241], off offset:2048
	v_pk_mul_f32 v[210:211], v[150:151], v[76:77]
	v_lshlrev_b32_e32 v220, 16, v242
	v_pk_mul_f32 v[240:241], v[148:149], v[78:79]
	v_and_b32_e32 v221, 0xffff0000, v242
	v_lshlrev_b32_e32 v234, 16, v243
	v_and_b32_e32 v235, 0xffff0000, v243
	v_lshlrev_b32_e32 v242, 16, v244
	v_and_b32_e32 v243, 0xffff0000, v244
	v_lshlrev_b32_e32 v244, 16, v245
	v_and_b32_e32 v245, 0xffff0000, v245
	v_cvt_pk_bf16_f32 v240, v240, v241
	v_cvt_pk_bf16_f32 v241, v210, v211
	v_add_co_u32_e32 v210, vcc, s77, v178
	v_lshlrev_b32_e32 v82, 16, v238
	v_and_b32_e32 v83, 0xffff0000, v238
	v_lshlrev_b32_e32 v80, 16, v239
	v_and_b32_e32 v81, 0xffff0000, v239
	v_addc_co_u32_e32 v211, vcc, 0, v179, vcc
	v_pk_fma_f32 v[74:75], v[74:75], v[146:147], v[234:235]
	v_pk_fma_f32 v[72:73], v[72:73], v[144:145], v[220:221]
	v_pk_fma_f32 v[142:143], v[70:71], v[142:143], v[244:245]
	v_pk_fma_f32 v[70:71], v[68:69], v[140:141], v[242:243]
	v_pk_mul_f32 v[166:167], v[154:155], v[80:81]
	v_pk_mul_f32 v[168:169], v[152:153], v[82:83]
	v_cvt_pk_bf16_f32 v68, v72, v73
	v_cvt_pk_bf16_f32 v69, v74, v75
	v_cvt_pk_bf16_f32 v70, v70, v71
	v_cvt_pk_bf16_f32 v71, v142, v143
	v_add_co_u32_e32 v220, vcc, s0, v182
	v_cvt_pk_bf16_f32 v238, v168, v169
	v_cvt_pk_bf16_f32 v239, v166, v167
	v_addc_co_u32_e32 v221, vcc, 0, v183, vcc
	v_lshlrev_b32_e32 v146, 16, v68
	v_and_b32_e32 v147, 0xffff0000, v68
	v_lshlrev_b32_e32 v144, 16, v69
	v_and_b32_e32 v145, 0xffff0000, v69
	v_lshlrev_b32_e32 v142, 16, v70
	v_and_b32_e32 v143, 0xffff0000, v70
	v_lshlrev_b32_e32 v140, 16, v71
	v_and_b32_e32 v141, 0xffff0000, v71
	s_mov_b32 s0, 0x58000
	global_store_dwordx4 v[210:211], v[238:241], off
	global_store_dwordx4 v[220:221], v[68:71], off offset:2048
	v_pk_mul_f32 v[72:73], v[150:151], v[140:141]
	v_pk_mul_f32 v[74:75], v[148:149], v[142:143]
	v_pk_mul_f32 v[70:71], v[154:155], v[144:145]
	v_pk_mul_f32 v[68:69], v[152:153], v[146:147]
	v_add_co_u32_e32 v148, vcc, s0, v178
	v_cvt_pk_bf16_f32 v68, v68, v69
	v_cvt_pk_bf16_f32 v69, v70, v71
	v_cvt_pk_bf16_f32 v70, v74, v75
	v_cvt_pk_bf16_f32 v71, v72, v73
	v_addc_co_u32_e32 v149, vcc, 0, v179, vcc
	global_store_dwordx4 v[148:149], v[68:71], off
	global_load_dwordx4 v[150:153], v[184:185], off offset:2304
	global_load_dwordx4 v[238:241], v[188:189], off offset:2304
	s_nop 0
	global_load_dwordx4 v[68:71], v[180:181], off offset:528
	global_load_dwordx4 v[72:75], v[180:181], off offset:512
	v_lshlrev_b32_e32 v154, 16, v246
	v_and_b32_e32 v155, 0xffff0000, v246
	v_lshlrev_b32_e32 v166, 16, v247
	v_and_b32_e32 v167, 0xffff0000, v247
	v_lshlrev_b32_e32 v168, 16, v248
	v_and_b32_e32 v169, 0xffff0000, v248
	v_lshlrev_b32_e32 v180, 16, v249
	v_and_b32_e32 v181, 0xffff0000, v249
	v_pk_fma_f32 v[66:67], v[66:67], v[106:107], v[166:167]
	v_pk_fma_f32 v[64:65], v[64:65], v[104:105], v[154:155]
	v_pk_fma_f32 v[62:63], v[62:63], v[102:103], v[180:181]
	v_pk_fma_f32 v[60:61], v[60:61], v[100:101], v[168:169]
	v_cvt_pk_bf16_f32 v242, v64, v65
	v_cvt_pk_bf16_f32 v243, v66, v67
	v_cvt_pk_bf16_f32 v244, v60, v61
	v_cvt_pk_bf16_f32 v245, v62, v63
	v_lshlrev_b32_e32 v66, 16, v242
	v_and_b32_e32 v67, 0xffff0000, v242
	v_lshlrev_b32_e32 v64, 16, v243
	v_and_b32_e32 v65, 0xffff0000, v243
	v_lshlrev_b32_e32 v62, 16, v244
	v_and_b32_e32 v63, 0xffff0000, v244
	v_lshlrev_b32_e32 v60, 16, v245
	v_and_b32_e32 v61, 0xffff0000, v245
	v_lshlrev_b32_e32 v184, 16, v250
	v_and_b32_e32 v185, 0xffff0000, v250
	v_lshlrev_b32_e32 v188, 16, v251
	v_and_b32_e32 v189, 0xffff0000, v251
	v_lshlrev_b32_e32 v234, 16, v252
	v_and_b32_e32 v235, 0xffff0000, v252
	v_lshlrev_b32_e32 v246, 16, v253
	v_and_b32_e32 v247, 0xffff0000, v253
	global_store_dwordx4 v[182:183], v[242:245], off offset:2304
	v_pk_fma_f32 v[58:59], v[58:59], v[106:107], v[188:189]
	v_pk_fma_f32 v[56:57], v[56:57], v[104:105], v[184:185]
	v_pk_fma_f32 v[54:55], v[54:55], v[102:103], v[246:247]
	v_pk_fma_f32 v[52:53], v[52:53], v[100:101], v[234:235]
	s_waitcnt vmcnt(0)
	v_lshlrev_b32_e32 v188, 16, v240
	v_pk_mul_f32 v[168:169], v[70:71], v[60:61]
	v_pk_mul_f32 v[154:155], v[74:75], v[64:65]
	v_pk_mul_f32 v[166:167], v[72:73], v[66:67]
	v_pk_mul_f32 v[182:183], v[68:69], v[62:63]
	v_cvt_pk_bf16_f32 v180, v166, v167
	v_cvt_pk_bf16_f32 v181, v154, v155
	v_cvt_pk_bf16_f32 v182, v182, v183
	v_cvt_pk_bf16_f32 v183, v168, v169
	global_store_dwordx4 v[178:179], v[180:183], off offset:256
	v_cvt_pk_bf16_f32 v178, v56, v57
	v_cvt_pk_bf16_f32 v179, v58, v59
	v_cvt_pk_bf16_f32 v180, v52, v53
	v_cvt_pk_bf16_f32 v181, v54, v55
	v_lshlrev_b32_e32 v58, 16, v178
	v_and_b32_e32 v59, 0xffff0000, v178
	v_lshlrev_b32_e32 v56, 16, v179
	v_and_b32_e32 v57, 0xffff0000, v179
	v_lshlrev_b32_e32 v54, 16, v180
	v_and_b32_e32 v55, 0xffff0000, v180
	v_lshlrev_b32_e32 v52, 16, v181
	v_and_b32_e32 v53, 0xffff0000, v181
	global_store_dwordx4 v[186:187], v[178:181], off offset:2304
	v_pk_mul_f32 v[154:155], v[74:75], v[56:57]
	v_pk_mul_f32 v[166:167], v[72:73], v[58:59]
	v_pk_mul_f32 v[168:169], v[70:71], v[52:53]
	v_pk_mul_f32 v[180:181], v[68:69], v[54:55]
	v_cvt_pk_bf16_f32 v178, v166, v167
	v_cvt_pk_bf16_f32 v179, v154, v155
	v_cvt_pk_bf16_f32 v180, v180, v181
	v_cvt_pk_bf16_f32 v181, v168, v169
	v_lshlrev_b32_e32 v154, 16, v150
	v_and_b32_e32 v155, 0xffff0000, v150
	v_lshlrev_b32_e32 v150, 16, v151
	v_and_b32_e32 v151, 0xffff0000, v151
	v_lshlrev_b32_e32 v166, 16, v152
	v_and_b32_e32 v167, 0xffff0000, v152
	v_lshlrev_b32_e32 v152, 16, v153
	v_and_b32_e32 v153, 0xffff0000, v153
	global_store_dwordx4 v[190:191], v[178:181], off offset:256
	v_pk_fma_f32 v[50:51], v[50:51], v[106:107], v[150:151]
	v_pk_fma_f32 v[48:49], v[48:49], v[104:105], v[154:155]
	v_pk_fma_f32 v[46:47], v[46:47], v[102:103], v[152:153]
	v_pk_fma_f32 v[44:45], v[44:45], v[100:101], v[166:167]
	global_load_dwordx4 v[178:181], v[192:193], off offset:2304
	global_load_dwordx4 v[182:185], v[194:195], off offset:2304
	v_cvt_pk_bf16_f32 v150, v48, v49
	v_cvt_pk_bf16_f32 v151, v50, v51
	v_cvt_pk_bf16_f32 v152, v44, v45
	v_cvt_pk_bf16_f32 v153, v46, v47
	v_lshlrev_b32_e32 v50, 16, v150
	v_and_b32_e32 v51, 0xffff0000, v150
	v_lshlrev_b32_e32 v48, 16, v151
	v_and_b32_e32 v49, 0xffff0000, v151
	v_lshlrev_b32_e32 v46, 16, v152
	v_and_b32_e32 v47, 0xffff0000, v152
	v_lshlrev_b32_e32 v44, 16, v153
	v_and_b32_e32 v45, 0xffff0000, v153
	v_lshlrev_b32_e32 v168, 16, v238
	v_and_b32_e32 v169, 0xffff0000, v238
	v_lshlrev_b32_e32 v186, 16, v239
	v_and_b32_e32 v187, 0xffff0000, v239
	v_and_b32_e32 v189, 0xffff0000, v240
	v_lshlrev_b32_e32 v190, 16, v241
	v_and_b32_e32 v191, 0xffff0000, v241
	global_store_dwordx4 v[198:199], v[150:153], off offset:2304
	v_pk_mul_f32 v[154:155], v[70:71], v[44:45]
	v_pk_mul_f32 v[166:167], v[68:69], v[46:47]
	v_pk_mul_f32 v[152:153], v[74:75], v[48:49]
	v_pk_mul_f32 v[150:151], v[72:73], v[50:51]
	v_pk_fma_f32 v[42:43], v[42:43], v[106:107], v[186:187]
	v_cvt_pk_bf16_f32 v150, v150, v151
	v_cvt_pk_bf16_f32 v151, v152, v153
	v_cvt_pk_bf16_f32 v152, v166, v167
	v_cvt_pk_bf16_f32 v153, v154, v155
	v_pk_fma_f32 v[40:41], v[40:41], v[104:105], v[168:169]
	v_pk_fma_f32 v[38:39], v[38:39], v[102:103], v[190:191]
	v_pk_fma_f32 v[36:37], v[36:37], v[100:101], v[188:189]
	global_store_dwordx4 v[200:201], v[150:153], off offset:256
	v_mul_f32_e32 v67, v67, v67
	v_mul_f32_e32 v65, v65, v65
	v_cvt_pk_bf16_f32 v150, v40, v41
	v_cvt_pk_bf16_f32 v151, v42, v43
	v_cvt_pk_bf16_f32 v152, v36, v37
	v_cvt_pk_bf16_f32 v153, v38, v39
	v_lshlrev_b32_e32 v42, 16, v150
	v_and_b32_e32 v43, 0xffff0000, v150
	v_lshlrev_b32_e32 v40, 16, v151
	v_and_b32_e32 v41, 0xffff0000, v151
	v_lshlrev_b32_e32 v38, 16, v152
	v_and_b32_e32 v39, 0xffff0000, v152
	v_lshlrev_b32_e32 v36, 16, v153
	v_and_b32_e32 v37, 0xffff0000, v153
	global_store_dwordx4 v[202:203], v[150:153], off offset:2304
	v_pk_mul_f32 v[154:155], v[70:71], v[36:37]
	v_pk_mul_f32 v[166:167], v[68:69], v[38:39]
	v_pk_mul_f32 v[152:153], v[74:75], v[40:41]
	v_pk_mul_f32 v[150:151], v[72:73], v[42:43]
	v_fmac_f32_e32 v67, v66, v66
	v_cvt_pk_bf16_f32 v150, v150, v151
	v_cvt_pk_bf16_f32 v151, v152, v153
	v_cvt_pk_bf16_f32 v152, v166, v167
	v_cvt_pk_bf16_f32 v153, v154, v155
	global_store_dwordx4 v[204:205], v[150:153], off offset:256
	global_load_dwordx4 v[150:153], v[206:207], off offset:2304
	s_nop 0
	global_load_dwordx4 v[186:189], v[208:209], off offset:2304
	v_fmac_f32_e32 v65, v64, v64
	v_mul_f32_e32 v63, v63, v63
	v_mul_f32_e32 v61, v61, v61
	v_add_f32_e32 v64, v67, v65
	v_fmac_f32_e32 v63, v62, v62
	v_fmac_f32_e32 v61, v60, v60
	v_add_f32_e32 v60, v63, v61
	s_waitcnt vmcnt(0)
	v_lshlrev_b32_e32 v154, 16, v178
	v_and_b32_e32 v155, 0xffff0000, v178
	v_lshlrev_b32_e32 v166, 16, v179
	v_and_b32_e32 v167, 0xffff0000, v179
	v_lshlrev_b32_e32 v168, 16, v180
	v_and_b32_e32 v169, 0xffff0000, v180
	v_lshlrev_b32_e32 v178, 16, v181
	v_and_b32_e32 v179, 0xffff0000, v181
	v_pk_fma_f32 v[34:35], v[34:35], v[106:107], v[166:167]
	v_pk_fma_f32 v[32:33], v[32:33], v[104:105], v[154:155]
	v_pk_fma_f32 v[30:31], v[30:31], v[102:103], v[178:179]
	v_pk_fma_f32 v[28:29], v[28:29], v[100:101], v[168:169]
	v_cvt_pk_bf16_f32 v178, v32, v33
	v_cvt_pk_bf16_f32 v179, v34, v35
	v_cvt_pk_bf16_f32 v180, v28, v29
	v_cvt_pk_bf16_f32 v181, v30, v31
	v_lshlrev_b32_e32 v34, 16, v178
	v_and_b32_e32 v35, 0xffff0000, v178
	v_lshlrev_b32_e32 v32, 16, v179
	v_and_b32_e32 v33, 0xffff0000, v179
	v_lshlrev_b32_e32 v30, 16, v180
	v_and_b32_e32 v31, 0xffff0000, v180
	v_lshlrev_b32_e32 v28, 16, v181
	v_and_b32_e32 v29, 0xffff0000, v181
	v_lshlrev_b32_e32 v190, 16, v182
	v_and_b32_e32 v191, 0xffff0000, v182
	v_lshlrev_b32_e32 v182, 16, v183
	v_and_b32_e32 v183, 0xffff0000, v183
	global_store_dwordx4 v[212:213], v[178:181], off offset:2304
	v_pk_mul_f32 v[154:155], v[74:75], v[32:33]
	v_pk_mul_f32 v[166:167], v[72:73], v[34:35]
	v_pk_mul_f32 v[168:169], v[70:71], v[28:29]
	v_pk_mul_f32 v[180:181], v[68:69], v[30:31]
	v_lshlrev_b32_e32 v192, 16, v184
	v_and_b32_e32 v193, 0xffff0000, v184
	v_lshlrev_b32_e32 v184, 16, v185
	v_and_b32_e32 v185, 0xffff0000, v185
	v_cvt_pk_bf16_f32 v178, v166, v167
	v_cvt_pk_bf16_f32 v179, v154, v155
	v_cvt_pk_bf16_f32 v180, v180, v181
	v_cvt_pk_bf16_f32 v181, v168, v169
	v_pk_fma_f32 v[24:25], v[24:25], v[106:107], v[182:183]
	v_pk_fma_f32 v[22:23], v[22:23], v[104:105], v[190:191]
	global_store_dwordx4 v[214:215], v[178:181], off offset:256
	v_pk_fma_f32 v[20:21], v[20:21], v[102:103], v[184:185]
	v_pk_fma_f32 v[18:19], v[18:19], v[100:101], v[192:193]
	v_cvt_pk_bf16_f32 v178, v22, v23
	v_cvt_pk_bf16_f32 v179, v24, v25
	v_cvt_pk_bf16_f32 v180, v18, v19
	v_cvt_pk_bf16_f32 v181, v20, v21
	v_lshlrev_b32_e32 v24, 16, v178
	v_and_b32_e32 v25, 0xffff0000, v178
	v_lshlrev_b32_e32 v22, 16, v179
	v_and_b32_e32 v23, 0xffff0000, v179
	v_lshlrev_b32_e32 v20, 16, v180
	v_and_b32_e32 v21, 0xffff0000, v180
	v_lshlrev_b32_e32 v18, 16, v181
	v_and_b32_e32 v19, 0xffff0000, v181
	v_pk_mul_f32 v[154:155], v[74:75], v[22:23]
	v_pk_mul_f32 v[166:167], v[72:73], v[24:25]
	global_store_dwordx4 v[216:217], v[178:181], off offset:2304
	v_pk_mul_f32 v[168:169], v[70:71], v[18:19]
	v_lshlrev_b32_e32 v182, 16, v189
	v_pk_mul_f32 v[180:181], v[68:69], v[20:21]
	v_cvt_pk_bf16_f32 v178, v166, v167
	v_cvt_pk_bf16_f32 v179, v154, v155
	v_lshlrev_b32_e32 v154, 16, v150
	v_and_b32_e32 v155, 0xffff0000, v150
	v_lshlrev_b32_e32 v150, 16, v151
	v_and_b32_e32 v151, 0xffff0000, v151
	v_lshlrev_b32_e32 v166, 16, v152
	v_and_b32_e32 v167, 0xffff0000, v152
	v_lshlrev_b32_e32 v152, 16, v153
	v_and_b32_e32 v153, 0xffff0000, v153
	v_cvt_pk_bf16_f32 v180, v180, v181
	v_cvt_pk_bf16_f32 v181, v168, v169
	v_pk_fma_f32 v[16:17], v[16:17], v[106:107], v[150:151]
	v_pk_fma_f32 v[14:15], v[14:15], v[104:105], v[154:155]
	v_pk_fma_f32 v[12:13], v[12:13], v[102:103], v[152:153]
	v_pk_fma_f32 v[10:11], v[10:11], v[100:101], v[166:167]
	global_store_dwordx4 v[218:219], v[178:181], off offset:256
	v_lshlrev_b32_e32 v168, 16, v186
	v_and_b32_e32 v169, 0xffff0000, v186
	v_lshlrev_b32_e32 v178, 16, v187
	v_and_b32_e32 v179, 0xffff0000, v187
	v_lshlrev_b32_e32 v180, 16, v188
	v_and_b32_e32 v181, 0xffff0000, v188
	v_and_b32_e32 v183, 0xffff0000, v189
	v_cvt_pk_bf16_f32 v150, v14, v15
	v_cvt_pk_bf16_f32 v151, v16, v17
	v_cvt_pk_bf16_f32 v152, v10, v11
	v_cvt_pk_bf16_f32 v153, v12, v13
	v_lshlrev_b32_e32 v16, 16, v150
	v_and_b32_e32 v17, 0xffff0000, v150
	v_lshlrev_b32_e32 v14, 16, v151
	v_and_b32_e32 v15, 0xffff0000, v151
	v_lshlrev_b32_e32 v12, 16, v152
	v_and_b32_e32 v13, 0xffff0000, v152
	v_lshlrev_b32_e32 v10, 16, v153
	v_and_b32_e32 v11, 0xffff0000, v153
	v_pk_fma_f32 v[8:9], v[8:9], v[106:107], v[178:179]
	v_pk_fma_f32 v[6:7], v[6:7], v[104:105], v[168:169]
	v_pk_fma_f32 v[4:5], v[4:5], v[102:103], v[182:183]
	v_pk_fma_f32 v[2:3], v[2:3], v[100:101], v[180:181]
	global_store_dwordx4 v[196:197], v[150:153], off offset:2304
	v_pk_mul_f32 v[154:155], v[70:71], v[10:11]
	v_pk_mul_f32 v[166:167], v[68:69], v[12:13]
	v_pk_mul_f32 v[152:153], v[74:75], v[14:15]
	v_pk_mul_f32 v[150:151], v[72:73], v[16:17]
	v_cvt_pk_bf16_f32 v100, v6, v7
	v_cvt_pk_bf16_f32 v101, v8, v9
	v_cvt_pk_bf16_f32 v102, v2, v3
	v_cvt_pk_bf16_f32 v103, v4, v5
	v_cvt_pk_bf16_f32 v150, v150, v151
	v_cvt_pk_bf16_f32 v151, v152, v153
	v_cvt_pk_bf16_f32 v152, v166, v167
	v_cvt_pk_bf16_f32 v153, v154, v155
	v_lshlrev_b32_e32 v8, 16, v100
	v_and_b32_e32 v9, 0xffff0000, v100
	v_lshlrev_b32_e32 v6, 16, v101
	v_and_b32_e32 v7, 0xffff0000, v101
	v_lshlrev_b32_e32 v4, 16, v102
	v_and_b32_e32 v5, 0xffff0000, v102
	v_lshlrev_b32_e32 v2, 16, v103
	v_and_b32_e32 v3, 0xffff0000, v103
	global_store_dwordx4 v[210:211], v[150:153], off offset:256
	global_store_dwordx4 v[220:221], v[100:103], off offset:2304
	v_pk_mul_f32 v[74:75], v[74:75], v[6:7]
	v_pk_mul_f32 v[72:73], v[72:73], v[8:9]
	v_pk_mul_f32 v[100:101], v[70:71], v[2:3]
	v_pk_mul_f32 v[70:71], v[68:69], v[4:5]
	v_cvt_pk_bf16_f32 v68, v72, v73
	v_cvt_pk_bf16_f32 v69, v74, v75
	v_cvt_pk_bf16_f32 v70, v70, v71
	v_cvt_pk_bf16_f32 v71, v100, v101
	global_store_dwordx4 v[148:149], v[68:71], off offset:256
	v_xor_b32_e32 v72, 32, v227
	v_mul_f32_e32 v73, v137, v137
	v_and_b32_e32 v71, 64, v227
	v_xor_b32_e32 v70, 16, v227
	v_add_u32_e32 v71, 64, v71
	v_cmp_lt_i32_e32 vcc, v70, v71
	v_fmac_f32_e32 v73, v136, v136
	v_mul_f32_e32 v74, v133, v133
	v_cndmask_b32_e32 v70, v227, v70, vcc
	v_cmp_lt_i32_e32 vcc, v72, v71
	v_fmac_f32_e32 v74, v132, v132
	v_lshlrev_b32_e32 v70, 2, v70
	v_cndmask_b32_e32 v71, v227, v72, vcc
	v_mul_f32_e32 v72, v139, v139
	v_fmac_f32_e32 v72, v138, v138
	v_add_f32_e32 v72, v72, v73
	v_mul_f32_e32 v73, v135, v135
	v_fmac_f32_e32 v73, v134, v134
	v_add_f32_e32 v73, v73, v74
	v_add_f32_e32 v72, v72, v73
	v_add_f32_e32 v64, v72, v64
	v_add_f32_e32 v60, v60, v64
	ds_bpermute_b32 v61, v70, v60
	v_lshlrev_b32_e32 v71, 2, v71
	v_lshl_add_u64 v[68:69], v[172:173], 0, s[28:29]
	s_waitcnt lgkmcnt(0)
	v_add_f32_e32 v60, v60, v61
	ds_bpermute_b32 v61, v71, v60
	s_and_saveexec_b64 s[18:19], s[38:39]
	s_cbranch_execz .LBB0_968
	s_waitcnt lgkmcnt(0)
	v_add_f32_e32 v60, v60, v61
	global_atomic_add_f32 v[68:69], v60, off

.LBB0_1048:
	s_add_u32 s0, s24, 0xfffc0080
	s_addc_u32 s1, s25, -1
	s_add_i32 s83, 0, 0x10000
	s_cmp_eq_u32 s82, 12
	s_cselect_b32 s29, s43, s1
	s_cselect_b32 s28, s69, s0
	s_cselect_b32 s27, s45, s81
	s_cselect_b32 s26, s72, s73
	s_add_i32 m0, s23, 0xc000
	ds_read_b128 v[158:161], v165
	ds_read_b128 v[174:177], v165 offset:1024
	ds_read_b128 v[178:181], v165 offset:2048
	ds_read_b128 v[182:185], v165 offset:3072
	ds_read_b128 v[186:189], v165 offset:4096
	ds_read_b128 v[190:193], v165 offset:5120
	ds_read_b128 v[194:197], v165 offset:6144
	ds_read_b128 v[198:201], v165 offset:7168
	global_load_lds_dwordx4 v154, s[24:25]
	v_lshl_add_u64 v[166:167], s[24:25], 0, v[156:157]
	s_add_i32 m0, s23, 0xe000
	s_nop 0
	global_load_lds_dwordx4 v[166:167], off
	s_waitcnt vmcnt(10) lgkmcnt(8)
	s_setprio 1
	s_barrier
	s_waitcnt lgkmcnt(0)
	v_mfma_f32_16x16x32_bf16 v[144:147], v[68:71], v[158:161], v[144:147]
	v_mfma_f32_16x16x32_bf16 v[140:143], v[76:79], v[158:161], v[140:143]
	v_mfma_f32_16x16x32_bf16 v[128:131], v[68:71], v[178:181], v[128:131]
	v_mfma_f32_16x16x32_bf16 v[124:127], v[76:79], v[178:181], v[124:127]
	v_mfma_f32_16x16x32_bf16 v[112:115], v[68:71], v[186:189], v[112:115]
	v_mfma_f32_16x16x32_bf16 v[108:111], v[76:79], v[186:189], v[108:111]
	v_mfma_f32_16x16x32_bf16 v[96:99], v[68:71], v[194:197], v[96:99]
	v_mfma_f32_16x16x32_bf16 v[92:95], v[76:79], v[194:197], v[92:95]
	v_mfma_f32_16x16x32_bf16 v[144:147], v[72:75], v[174:177], v[144:147]
	v_mfma_f32_16x16x32_bf16 v[140:143], v[80:83], v[174:177], v[140:143]
	v_mfma_f32_16x16x32_bf16 v[128:131], v[72:75], v[182:185], v[128:131]
	v_mfma_f32_16x16x32_bf16 v[124:127], v[80:83], v[182:185], v[124:127]
	v_mfma_f32_16x16x32_bf16 v[112:115], v[72:75], v[190:193], v[112:115]
	v_mfma_f32_16x16x32_bf16 v[108:111], v[80:83], v[190:193], v[108:111]
	v_mfma_f32_16x16x32_bf16 v[96:99], v[72:75], v[198:201], v[96:99]
	v_mfma_f32_16x16x32_bf16 v[92:95], v[80:83], v[198:201], v[92:95]
	s_barrier
	s_setprio 0
	s_add_i32 s84, 0, 0x14000
	v_add_u32_e32 v166, s84, v163
	s_add_i32 s0, s83, s54
	ds_read_b128 v[202:205], v166
	ds_read_b128 v[206:209], v166 offset:1024
	ds_read_b128 v[210:213], v166 offset:2048
	ds_read_b128 v[214:217], v166 offset:3072
	v_lshl_add_u64 v[166:167], s[26:27], 0, v[26:27]
	s_mov_b32 m0, s0
	v_lshl_add_u64 v[168:169], s[26:27], 0, v[148:149]
	global_load_lds_dwordx4 v[166:167], off
	s_add_i32 m0, s0, 0x2000
	s_nop 0
	global_load_lds_dwordx4 v[168:169], off
	s_waitcnt vmcnt(10)
	s_setprio 1
	s_barrier
	s_waitcnt lgkmcnt(0)
	v_mfma_f32_16x16x32_bf16 v[136:139], v[202:205], v[158:161], v[136:139]
	v_mfma_f32_16x16x32_bf16 v[132:135], v[210:213], v[158:161], v[132:135]
	v_mfma_f32_16x16x32_bf16 v[120:123], v[202:205], v[178:181], v[120:123]
	v_mfma_f32_16x16x32_bf16 v[116:119], v[210:213], v[178:181], v[116:119]
	v_mfma_f32_16x16x32_bf16 v[104:107], v[202:205], v[186:189], v[104:107]
	v_mfma_f32_16x16x32_bf16 v[100:103], v[210:213], v[186:189], v[100:103]
	v_mfma_f32_16x16x32_bf16 v[88:91], v[202:205], v[194:197], v[88:91]
	v_mfma_f32_16x16x32_bf16 v[84:87], v[210:213], v[194:197], v[84:87]
	v_mfma_f32_16x16x32_bf16 v[136:139], v[206:209], v[174:177], v[136:139]
	v_mfma_f32_16x16x32_bf16 v[132:135], v[214:217], v[174:177], v[132:135]
	v_mfma_f32_16x16x32_bf16 v[120:123], v[206:209], v[182:185], v[120:123]
	v_mfma_f32_16x16x32_bf16 v[116:119], v[214:217], v[182:185], v[116:119]
	v_mfma_f32_16x16x32_bf16 v[104:107], v[206:209], v[190:193], v[104:107]
	v_mfma_f32_16x16x32_bf16 v[100:103], v[214:217], v[190:193], v[100:103]
	v_mfma_f32_16x16x32_bf16 v[88:91], v[206:209], v[198:201], v[88:91]
	v_mfma_f32_16x16x32_bf16 v[84:87], v[214:217], v[198:201], v[84:87]
	s_barrier
	s_setprio 0
	s_mov_b32 m0, s23
	v_lshl_add_u64 v[218:219], s[28:29], 0, v[152:153]
	ds_read_b128 v[158:161], v165 offset:16384
	ds_read_b128 v[174:177], v165 offset:17408
	ds_read_b128 v[178:181], v165 offset:18432
	ds_read_b128 v[182:185], v165 offset:19456
	ds_read_b128 v[186:189], v165 offset:20480
	ds_read_b128 v[190:193], v165 offset:21504
	ds_read_b128 v[194:197], v165 offset:22528
	ds_read_b128 v[198:201], v165 offset:23552
	global_load_lds_dwordx4 v[218:219], off
	v_lshl_add_u64 v[220:221], s[28:29], 0, v[150:151]
	s_mov_b32 m0, s57
	s_nop 0
	global_load_lds_dwordx4 v[220:221], off
	s_waitcnt vmcnt(10)
	s_setprio 1
	s_barrier
	s_waitcnt lgkmcnt(0)
	v_mfma_f32_16x16x32_bf16 v[64:67], v[68:71], v[158:161], v[64:67]
	v_mfma_f32_16x16x32_bf16 v[60:63], v[76:79], v[158:161], v[60:63]
	v_mfma_f32_16x16x32_bf16 v[48:51], v[68:71], v[178:181], v[48:51]
	v_mfma_f32_16x16x32_bf16 v[44:47], v[76:79], v[178:181], v[44:47]
	v_mfma_f32_16x16x32_bf16 v[32:35], v[68:71], v[186:189], v[32:35]
	v_mfma_f32_16x16x32_bf16 v[28:31], v[76:79], v[186:189], v[28:31]
	v_mfma_f32_16x16x32_bf16 v[14:17], v[68:71], v[194:197], v[14:17]
	v_mfma_f32_16x16x32_bf16 v[10:13], v[76:79], v[194:197], v[10:13]
	v_mfma_f32_16x16x32_bf16 v[64:67], v[72:75], v[174:177], v[64:67]
	v_mfma_f32_16x16x32_bf16 v[60:63], v[80:83], v[174:177], v[60:63]
	v_mfma_f32_16x16x32_bf16 v[48:51], v[72:75], v[182:185], v[48:51]
	v_mfma_f32_16x16x32_bf16 v[44:47], v[80:83], v[182:185], v[44:47]
	v_mfma_f32_16x16x32_bf16 v[32:35], v[72:75], v[190:193], v[32:35]
	v_mfma_f32_16x16x32_bf16 v[28:31], v[80:83], v[190:193], v[28:31]
	v_mfma_f32_16x16x32_bf16 v[14:17], v[72:75], v[198:201], v[14:17]
	v_mfma_f32_16x16x32_bf16 v[10:13], v[80:83], v[198:201], v[10:13]
	s_barrier
	s_setprio 0
	s_add_u32 s0, s26, 0x40000
	s_addc_u32 s1, s27, 0
	s_add_i32 s83, s84, s54
	s_mov_b32 m0, s83
	s_nop 0
	global_load_lds_dwordx4 v26, s[0:1]
	s_add_i32 m0, s83, 0x2000
	s_nop 0
	global_load_lds_dwordx4 v148, s[0:1]
	v_add_u32_e32 v80, 0x18000, v163
	ds_read_b128 v[68:71], v80
	ds_read_b128 v[72:75], v80 offset:1024
	ds_read_b128 v[76:79], v80 offset:2048
	ds_read_b128 v[80:83], v80 offset:3072
	s_waitcnt vmcnt(10)
	s_setprio 1
	s_barrier
	v_mfma_f32_16x16x32_bf16 v[56:59], v[202:205], v[158:161], v[56:59]
	v_mfma_f32_16x16x32_bf16 v[52:55], v[210:213], v[158:161], v[52:55]
	v_mfma_f32_16x16x32_bf16 v[40:43], v[202:205], v[178:181], v[40:43]
	v_mfma_f32_16x16x32_bf16 v[36:39], v[210:213], v[178:181], v[36:39]
	v_mfma_f32_16x16x32_bf16 v[22:25], v[202:205], v[186:189], v[22:25]
	v_mfma_f32_16x16x32_bf16 v[18:21], v[210:213], v[186:189], v[18:21]
	v_mfma_f32_16x16x32_bf16 v[6:9], v[202:205], v[194:197], v[6:9]
	v_mfma_f32_16x16x32_bf16 v[2:5], v[210:213], v[194:197], v[2:5]
	v_mfma_f32_16x16x32_bf16 v[56:59], v[206:209], v[174:177], v[56:59]
	v_mfma_f32_16x16x32_bf16 v[52:55], v[214:217], v[174:177], v[52:55]
	v_mfma_f32_16x16x32_bf16 v[40:43], v[206:209], v[182:185], v[40:43]
	v_mfma_f32_16x16x32_bf16 v[36:39], v[214:217], v[182:185], v[36:39]
	v_mfma_f32_16x16x32_bf16 v[22:25], v[206:209], v[190:193], v[22:25]
	v_mfma_f32_16x16x32_bf16 v[18:21], v[214:217], v[190:193], v[18:21]
	v_mfma_f32_16x16x32_bf16 v[6:9], v[206:209], v[198:201], v[6:9]
	v_mfma_f32_16x16x32_bf16 v[2:5], v[214:217], v[198:201], v[2:5]
	s_barrier
	s_setprio 0
	s_add_i32 s83, 0, 0x18000
	s_add_u32 s0, s28, 0x40000
	s_addc_u32 s1, s29, 0
	s_mov_b32 m0, s58
	ds_read_b128 v[158:161], v165 offset:32768
	ds_read_b128 v[174:177], v165 offset:33792
	ds_read_b128 v[178:181], v165 offset:34816
	ds_read_b128 v[182:185], v165 offset:35840
	ds_read_b128 v[186:189], v165 offset:36864
	ds_read_b128 v[190:193], v165 offset:37888
	ds_read_b128 v[194:197], v165 offset:38912
	ds_read_b128 v[198:201], v165 offset:39936
	global_load_lds_dwordx4 v152, s[0:1]
	s_mov_b32 m0, s59
	s_nop 0
	global_load_lds_dwordx4 v150, s[0:1]
	s_waitcnt vmcnt(10) lgkmcnt(8)
	s_setprio 1
	s_barrier
	s_waitcnt lgkmcnt(0)
	v_mfma_f32_16x16x32_bf16 v[144:147], v[68:71], v[158:161], v[144:147]
	v_mfma_f32_16x16x32_bf16 v[140:143], v[76:79], v[158:161], v[140:143]
	v_mfma_f32_16x16x32_bf16 v[128:131], v[68:71], v[178:181], v[128:131]
	v_mfma_f32_16x16x32_bf16 v[124:127], v[76:79], v[178:181], v[124:127]
	v_mfma_f32_16x16x32_bf16 v[112:115], v[68:71], v[186:189], v[112:115]
	v_mfma_f32_16x16x32_bf16 v[108:111], v[76:79], v[186:189], v[108:111]
	v_mfma_f32_16x16x32_bf16 v[96:99], v[68:71], v[194:197], v[96:99]
	v_mfma_f32_16x16x32_bf16 v[92:95], v[76:79], v[194:197], v[92:95]
	v_mfma_f32_16x16x32_bf16 v[144:147], v[72:75], v[174:177], v[144:147]
	v_mfma_f32_16x16x32_bf16 v[140:143], v[80:83], v[174:177], v[140:143]
	v_mfma_f32_16x16x32_bf16 v[128:131], v[72:75], v[182:185], v[128:131]
	v_mfma_f32_16x16x32_bf16 v[124:127], v[80:83], v[182:185], v[124:127]
	v_mfma_f32_16x16x32_bf16 v[112:115], v[72:75], v[190:193], v[112:115]
	v_mfma_f32_16x16x32_bf16 v[108:111], v[80:83], v[190:193], v[108:111]
	v_mfma_f32_16x16x32_bf16 v[96:99], v[72:75], v[198:201], v[96:99]
	v_mfma_f32_16x16x32_bf16 v[92:95], v[80:83], v[198:201], v[92:95]
	s_barrier
	s_setprio 0
	s_add_i32 s28, 0, 0x1c000
	s_add_i32 s0, s83, s54
	v_add_u32_e32 v173, s28, v163
	v_lshl_add_u64 v[166:167], v[166:167], 0, s[12:13]
	s_mov_b32 m0, s0
	ds_read_b128 v[202:205], v173
	ds_read_b128 v[206:209], v173 offset:1024
	ds_read_b128 v[210:213], v173 offset:2048
	ds_read_b128 v[214:217], v173 offset:3072
	global_load_lds_dwordx4 v[166:167], off
	v_lshl_add_u64 v[166:167], v[168:169], 0, s[12:13]
	s_add_i32 m0, s0, 0x2000
	s_nop 0
	global_load_lds_dwordx4 v[166:167], off
	s_waitcnt vmcnt(10)
	s_setprio 1
	s_barrier
	s_waitcnt lgkmcnt(0)
	v_mfma_f32_16x16x32_bf16 v[136:139], v[202:205], v[158:161], v[136:139]
	v_mfma_f32_16x16x32_bf16 v[132:135], v[210:213], v[158:161], v[132:135]
	v_mfma_f32_16x16x32_bf16 v[120:123], v[202:205], v[178:181], v[120:123]
	v_mfma_f32_16x16x32_bf16 v[116:119], v[210:213], v[178:181], v[116:119]
	v_mfma_f32_16x16x32_bf16 v[104:107], v[202:205], v[186:189], v[104:107]
	v_mfma_f32_16x16x32_bf16 v[100:103], v[210:213], v[186:189], v[100:103]
	v_mfma_f32_16x16x32_bf16 v[88:91], v[202:205], v[194:197], v[88:91]
	v_mfma_f32_16x16x32_bf16 v[84:87], v[210:213], v[194:197], v[84:87]
	v_mfma_f32_16x16x32_bf16 v[136:139], v[206:209], v[174:177], v[136:139]
	v_mfma_f32_16x16x32_bf16 v[132:135], v[214:217], v[174:177], v[132:135]
	v_mfma_f32_16x16x32_bf16 v[120:123], v[206:209], v[182:185], v[120:123]
	v_mfma_f32_16x16x32_bf16 v[116:119], v[214:217], v[182:185], v[116:119]
	v_mfma_f32_16x16x32_bf16 v[104:107], v[206:209], v[190:193], v[104:107]
	v_mfma_f32_16x16x32_bf16 v[100:103], v[214:217], v[190:193], v[100:103]
	v_mfma_f32_16x16x32_bf16 v[88:91], v[206:209], v[198:201], v[88:91]
	v_mfma_f32_16x16x32_bf16 v[84:87], v[214:217], v[198:201], v[84:87]
	s_barrier
	s_setprio 0
	s_mov_b32 m0, s34
	v_lshl_add_u64 v[166:167], v[218:219], 0, s[12:13]
	ds_read_b128 v[158:161], v165 offset:49152
	ds_read_b128 v[174:177], v165 offset:50176
	ds_read_b128 v[178:181], v165 offset:51200
	ds_read_b128 v[182:185], v165 offset:52224
	ds_read_b128 v[186:189], v165 offset:53248
	ds_read_b128 v[190:193], v165 offset:54272
	ds_read_b128 v[194:197], v165 offset:55296
	ds_read_b128 v[198:201], v165 offset:56320
	global_load_lds_dwordx4 v[166:167], off
	v_lshl_add_u64 v[166:167], v[220:221], 0, s[12:13]
	s_mov_b32 m0, s35
	s_nop 0
	global_load_lds_dwordx4 v[166:167], off
	s_waitcnt vmcnt(10)
	s_setprio 1
	s_barrier
	s_waitcnt lgkmcnt(0)
	v_mfma_f32_16x16x32_bf16 v[64:67], v[68:71], v[158:161], v[64:67]
	v_mfma_f32_16x16x32_bf16 v[60:63], v[76:79], v[158:161], v[60:63]
	v_mfma_f32_16x16x32_bf16 v[48:51], v[68:71], v[178:181], v[48:51]
	v_mfma_f32_16x16x32_bf16 v[44:47], v[76:79], v[178:181], v[44:47]
	v_mfma_f32_16x16x32_bf16 v[32:35], v[68:71], v[186:189], v[32:35]
	v_mfma_f32_16x16x32_bf16 v[28:31], v[76:79], v[186:189], v[28:31]
	v_mfma_f32_16x16x32_bf16 v[14:17], v[68:71], v[194:197], v[14:17]
	v_mfma_f32_16x16x32_bf16 v[10:13], v[76:79], v[194:197], v[10:13]
	v_mfma_f32_16x16x32_bf16 v[64:67], v[72:75], v[174:177], v[64:67]
	v_mfma_f32_16x16x32_bf16 v[60:63], v[80:83], v[174:177], v[60:63]
	v_mfma_f32_16x16x32_bf16 v[48:51], v[72:75], v[182:185], v[48:51]
	v_mfma_f32_16x16x32_bf16 v[44:47], v[80:83], v[182:185], v[44:47]
	v_mfma_f32_16x16x32_bf16 v[32:35], v[72:75], v[190:193], v[32:35]
	v_mfma_f32_16x16x32_bf16 v[28:31], v[80:83], v[190:193], v[28:31]
	v_mfma_f32_16x16x32_bf16 v[14:17], v[72:75], v[198:201], v[14:17]
	v_mfma_f32_16x16x32_bf16 v[10:13], v[80:83], v[198:201], v[10:13]
	s_barrier
	s_setprio 0
	s_add_u32 s0, s26, 0x40080
	s_addc_u32 s1, s27, 0
	s_add_i32 s26, s28, s54
	s_mov_b32 m0, s26
	s_nop 0
	global_load_lds_dwordx4 v26, s[0:1]
	s_add_i32 m0, s26, 0x2000
	s_nop 0
	global_load_lds_dwordx4 v148, s[0:1]
	v_add_u32_e32 v80, 0x10000, v163
	ds_read_b128 v[68:71], v80
	ds_read_b128 v[72:75], v80 offset:1024
	ds_read_b128 v[76:79], v80 offset:2048
	ds_read_b128 v[80:83], v80 offset:3072
	s_waitcnt vmcnt(10)
	s_setprio 1
	s_barrier
	v_mfma_f32_16x16x32_bf16 v[56:59], v[202:205], v[158:161], v[56:59]
	v_mfma_f32_16x16x32_bf16 v[52:55], v[210:213], v[158:161], v[52:55]
	v_mfma_f32_16x16x32_bf16 v[40:43], v[202:205], v[178:181], v[40:43]
	v_mfma_f32_16x16x32_bf16 v[36:39], v[210:213], v[178:181], v[36:39]
	v_mfma_f32_16x16x32_bf16 v[22:25], v[202:205], v[186:189], v[22:25]
	v_mfma_f32_16x16x32_bf16 v[18:21], v[210:213], v[186:189], v[18:21]
	v_mfma_f32_16x16x32_bf16 v[6:9], v[202:205], v[194:197], v[6:9]
	v_mfma_f32_16x16x32_bf16 v[2:5], v[210:213], v[194:197], v[2:5]
	v_mfma_f32_16x16x32_bf16 v[56:59], v[206:209], v[174:177], v[56:59]
	v_mfma_f32_16x16x32_bf16 v[52:55], v[214:217], v[174:177], v[52:55]
	v_mfma_f32_16x16x32_bf16 v[40:43], v[206:209], v[182:185], v[40:43]
	v_mfma_f32_16x16x32_bf16 v[36:39], v[214:217], v[182:185], v[36:39]
	v_mfma_f32_16x16x32_bf16 v[22:25], v[206:209], v[190:193], v[22:25]
	v_mfma_f32_16x16x32_bf16 v[18:21], v[214:217], v[190:193], v[18:21]
	v_mfma_f32_16x16x32_bf16 v[6:9], v[206:209], v[198:201], v[6:9]
	v_mfma_f32_16x16x32_bf16 v[2:5], v[214:217], v[198:201], v[2:5]
	s_barrier
	s_setprio 0
	s_add_i32 s82, s82, 2
	s_add_u32 s24, s24, 0x100
	s_addc_u32 s25, s25, 0
	s_add_u32 s73, s73, 0x100
	s_addc_u32 s81, s81, 0
	s_cmp_gt_u32 s82, 13
	s_cbranch_scc0 .LBB0_1048
	s_waitcnt lgkmcnt(0)
	v_readlane_b32 s82, v255, 51
	s_cmpk_gt_i32 s22, 0xff
	s_mov_b64 s[24:25], 0xb000
	v_readlane_b32 s83, v255, 52
	s_cbranch_scc1 .LBB0_1044
	s_ashr_i32 s0, s22, 5
	s_mul_hi_i32 s25, s0, 0x1600
	s_mul_i32 s24, s0, 0x1600
	s_branch .LBB0_1044

.LBB0_1122:
	s_add_u32 s26, s24, 0x100
	s_addc_u32 s27, s25, 0
	s_add_i32 s0, 0, 0x10000
	s_cmp_eq_u32 s72, 40
	s_cselect_b32 s31, s43, s27
	s_cselect_b32 s30, s42, s26
	s_cselect_b32 s29, s45, s69
	s_cselect_b32 s28, s44, s68
	s_add_i32 m0, s36, 0xc000
	ds_read_b128 v[162:165], v188
	ds_read_b128 v[172:175], v188 offset:1024
	ds_read_b128 v[176:179], v188 offset:2048
	ds_read_b128 v[180:183], v188 offset:3072
	ds_read_b128 v[190:193], v188 offset:4096
	ds_read_b128 v[194:197], v188 offset:5120
	ds_read_b128 v[198:201], v188 offset:6144
	ds_read_b128 v[202:205], v188 offset:7168
	global_load_lds_dwordx4 v150, s[24:25]
	v_lshl_add_u64 v[166:167], s[24:25], 0, v[152:153]
	s_add_i32 m0, s36, 0xe000
	s_nop 0
	global_load_lds_dwordx4 v[166:167], off
	s_waitcnt vmcnt(10) lgkmcnt(8)
	s_setprio 1
	s_barrier
	s_waitcnt lgkmcnt(0)
	v_mfma_f32_16x16x32_bf16 v[128:131], v[132:135], v[162:165], v[128:131]
	v_mfma_f32_16x16x32_bf16 v[124:127], v[154:157], v[162:165], v[124:127]
	v_mfma_f32_16x16x32_bf16 v[120:123], v[132:135], v[176:179], v[120:123]
	v_mfma_f32_16x16x32_bf16 v[116:119], v[154:157], v[176:179], v[116:119]
	v_mfma_f32_16x16x32_bf16 v[112:115], v[132:135], v[190:193], v[112:115]
	v_mfma_f32_16x16x32_bf16 v[108:111], v[154:157], v[190:193], v[108:111]
	v_mfma_f32_16x16x32_bf16 v[104:107], v[132:135], v[198:201], v[104:107]
	v_mfma_f32_16x16x32_bf16 v[100:103], v[154:157], v[198:201], v[100:103]
	v_mfma_f32_16x16x32_bf16 v[128:131], v[136:139], v[172:175], v[128:131]
	v_mfma_f32_16x16x32_bf16 v[124:127], v[158:161], v[172:175], v[124:127]
	v_mfma_f32_16x16x32_bf16 v[120:123], v[136:139], v[180:183], v[120:123]
	v_mfma_f32_16x16x32_bf16 v[116:119], v[158:161], v[180:183], v[116:119]
	v_mfma_f32_16x16x32_bf16 v[112:115], v[136:139], v[194:197], v[112:115]
	v_mfma_f32_16x16x32_bf16 v[108:111], v[158:161], v[194:197], v[108:111]
	v_mfma_f32_16x16x32_bf16 v[104:107], v[136:139], v[202:205], v[104:107]
	v_mfma_f32_16x16x32_bf16 v[100:103], v[158:161], v[202:205], v[100:103]
	s_barrier
	s_setprio 0
	s_add_i32 s24, 0, 0x14000
	v_add_u32_e32 v166, s24, v186
	s_add_i32 s0, s0, s17
	ds_read_b128 v[206:209], v166
	ds_read_b128 v[210:213], v166 offset:1024
	ds_read_b128 v[214:217], v166 offset:2048
	ds_read_b128 v[218:221], v166 offset:3072
	v_lshl_add_u64 v[166:167], s[28:29], 0, v[26:27]
	s_mov_b32 m0, s0
	v_lshl_add_u64 v[168:169], s[28:29], 0, v[144:145]
	global_load_lds_dwordx4 v[166:167], off
	s_add_i32 m0, s0, 0x2000
	s_nop 0
	global_load_lds_dwordx4 v[168:169], off
	s_waitcnt vmcnt(10)
	s_setprio 1
	s_barrier
	s_waitcnt lgkmcnt(0)
	v_mfma_f32_16x16x32_bf16 v[68:71], v[206:209], v[162:165], v[68:71]
	v_mfma_f32_16x16x32_bf16 v[60:63], v[214:217], v[162:165], v[60:63]
	v_mfma_f32_16x16x32_bf16 v[56:59], v[206:209], v[176:179], v[56:59]
	v_mfma_f32_16x16x32_bf16 v[52:55], v[214:217], v[176:179], v[52:55]
	v_mfma_f32_16x16x32_bf16 v[48:51], v[206:209], v[190:193], v[48:51]
	v_mfma_f32_16x16x32_bf16 v[44:47], v[214:217], v[190:193], v[44:47]
	v_mfma_f32_16x16x32_bf16 v[40:43], v[206:209], v[198:201], v[40:43]
	v_mfma_f32_16x16x32_bf16 v[36:39], v[214:217], v[198:201], v[36:39]
	v_mfma_f32_16x16x32_bf16 v[68:71], v[210:213], v[172:175], v[68:71]
	v_mfma_f32_16x16x32_bf16 v[60:63], v[218:221], v[172:175], v[60:63]
	v_mfma_f32_16x16x32_bf16 v[56:59], v[210:213], v[180:183], v[56:59]
	v_mfma_f32_16x16x32_bf16 v[52:55], v[218:221], v[180:183], v[52:55]
	v_mfma_f32_16x16x32_bf16 v[48:51], v[210:213], v[194:197], v[48:51]
	v_mfma_f32_16x16x32_bf16 v[44:47], v[218:221], v[194:197], v[44:47]
	v_mfma_f32_16x16x32_bf16 v[40:43], v[210:213], v[202:205], v[40:43]
	v_mfma_f32_16x16x32_bf16 v[36:39], v[218:221], v[202:205], v[36:39]
	s_barrier
	s_setprio 0
	s_mov_b32 m0, s36
	v_lshl_add_u64 v[184:185], s[30:31], 0, v[140:141]
	ds_read_b128 v[162:165], v188 offset:16384
	ds_read_b128 v[172:175], v188 offset:17408
	ds_read_b128 v[176:179], v188 offset:18432
	ds_read_b128 v[180:183], v188 offset:19456
	ds_read_b128 v[190:193], v188 offset:20480
	ds_read_b128 v[194:197], v188 offset:21504
	ds_read_b128 v[198:201], v188 offset:22528
	ds_read_b128 v[202:205], v188 offset:23552
	global_load_lds_dwordx4 v[184:185], off
	v_lshl_add_u64 v[222:223], s[30:31], 0, v[142:143]
	s_mov_b32 m0, s37
	s_nop 0
	global_load_lds_dwordx4 v[222:223], off
	s_waitcnt vmcnt(10)
	s_setprio 1
	s_barrier
	s_waitcnt lgkmcnt(0)
	v_mfma_f32_16x16x32_bf16 v[96:99], v[132:135], v[162:165], v[96:99]
	v_mfma_f32_16x16x32_bf16 v[92:95], v[154:157], v[162:165], v[92:95]
	v_mfma_f32_16x16x32_bf16 v[88:91], v[132:135], v[176:179], v[88:91]
	v_mfma_f32_16x16x32_bf16 v[84:87], v[154:157], v[176:179], v[84:87]
	v_mfma_f32_16x16x32_bf16 v[80:83], v[132:135], v[190:193], v[80:83]
	v_mfma_f32_16x16x32_bf16 v[76:79], v[154:157], v[190:193], v[76:79]
	v_mfma_f32_16x16x32_bf16 v[72:75], v[132:135], v[198:201], v[72:75]
	v_mfma_f32_16x16x32_bf16 v[64:67], v[154:157], v[198:201], v[64:67]
	v_mfma_f32_16x16x32_bf16 v[96:99], v[136:139], v[172:175], v[96:99]
	v_mfma_f32_16x16x32_bf16 v[92:95], v[158:161], v[172:175], v[92:95]
	v_mfma_f32_16x16x32_bf16 v[88:91], v[136:139], v[180:183], v[88:91]
	v_mfma_f32_16x16x32_bf16 v[84:87], v[158:161], v[180:183], v[84:87]
	v_mfma_f32_16x16x32_bf16 v[80:83], v[136:139], v[194:197], v[80:83]
	v_mfma_f32_16x16x32_bf16 v[76:79], v[158:161], v[194:197], v[76:79]
	v_mfma_f32_16x16x32_bf16 v[72:75], v[136:139], v[202:205], v[72:75]
	v_mfma_f32_16x16x32_bf16 v[64:67], v[158:161], v[202:205], v[64:67]
	s_barrier
	s_setprio 0
	s_add_u32 s0, s28, 0xb0000
	s_addc_u32 s1, s29, 0
	s_add_i32 s24, s24, s17
	s_mov_b32 m0, s24
	s_nop 0
	global_load_lds_dwordx4 v26, s[0:1]
	s_add_i32 m0, s24, 0x2000
	s_nop 0
	global_load_lds_dwordx4 v144, s[0:1]
	v_add_u32_e32 v158, 0x18000, v186
	ds_read_b128 v[132:135], v158
	ds_read_b128 v[136:139], v158 offset:1024
	ds_read_b128 v[154:157], v158 offset:2048
	ds_read_b128 v[158:161], v158 offset:3072
	s_waitcnt vmcnt(10)
	s_setprio 1
	s_barrier
	v_mfma_f32_16x16x32_bf16 v[32:35], v[206:209], v[162:165], v[32:35]
	v_mfma_f32_16x16x32_bf16 v[28:31], v[214:217], v[162:165], v[28:31]
	v_mfma_f32_16x16x32_bf16 v[22:25], v[206:209], v[176:179], v[22:25]
	v_mfma_f32_16x16x32_bf16 v[18:21], v[214:217], v[176:179], v[18:21]
	v_mfma_f32_16x16x32_bf16 v[14:17], v[206:209], v[190:193], v[14:17]
	v_mfma_f32_16x16x32_bf16 v[10:13], v[214:217], v[190:193], v[10:13]
	v_mfma_f32_16x16x32_bf16 v[6:9], v[206:209], v[198:201], v[6:9]
	v_mfma_f32_16x16x32_bf16 v[2:5], v[214:217], v[198:201], v[2:5]
	v_mfma_f32_16x16x32_bf16 v[32:35], v[210:213], v[172:175], v[32:35]
	v_mfma_f32_16x16x32_bf16 v[28:31], v[218:221], v[172:175], v[28:31]
	v_mfma_f32_16x16x32_bf16 v[22:25], v[210:213], v[180:183], v[22:25]
	v_mfma_f32_16x16x32_bf16 v[18:21], v[218:221], v[180:183], v[18:21]
	v_mfma_f32_16x16x32_bf16 v[14:17], v[210:213], v[194:197], v[14:17]
	v_mfma_f32_16x16x32_bf16 v[10:13], v[218:221], v[194:197], v[10:13]
	v_mfma_f32_16x16x32_bf16 v[6:9], v[210:213], v[202:205], v[6:9]
	v_mfma_f32_16x16x32_bf16 v[2:5], v[218:221], v[202:205], v[2:5]
	s_barrier
	s_setprio 0
	s_add_i32 s24, 0, 0x18000
	s_add_u32 s0, s30, 0xb0000
	s_addc_u32 s1, s31, 0
	s_mov_b32 m0, s52
	ds_read_b128 v[162:165], v188 offset:32768
	ds_read_b128 v[172:175], v188 offset:33792
	ds_read_b128 v[176:179], v188 offset:34816
	ds_read_b128 v[180:183], v188 offset:35840
	ds_read_b128 v[190:193], v188 offset:36864
	ds_read_b128 v[194:197], v188 offset:37888
	ds_read_b128 v[198:201], v188 offset:38912
	ds_read_b128 v[202:205], v188 offset:39936
	global_load_lds_dwordx4 v140, s[0:1]
	s_mov_b32 m0, s54
	s_nop 0
	global_load_lds_dwordx4 v142, s[0:1]
	s_waitcnt vmcnt(10) lgkmcnt(8)
	s_setprio 1
	s_barrier
	s_waitcnt lgkmcnt(0)
	v_mfma_f32_16x16x32_bf16 v[128:131], v[132:135], v[162:165], v[128:131]
	v_mfma_f32_16x16x32_bf16 v[124:127], v[154:157], v[162:165], v[124:127]
	v_mfma_f32_16x16x32_bf16 v[120:123], v[132:135], v[176:179], v[120:123]
	v_mfma_f32_16x16x32_bf16 v[116:119], v[154:157], v[176:179], v[116:119]
	v_mfma_f32_16x16x32_bf16 v[112:115], v[132:135], v[190:193], v[112:115]
	v_mfma_f32_16x16x32_bf16 v[108:111], v[154:157], v[190:193], v[108:111]
	v_mfma_f32_16x16x32_bf16 v[104:107], v[132:135], v[198:201], v[104:107]
	v_mfma_f32_16x16x32_bf16 v[100:103], v[154:157], v[198:201], v[100:103]
	v_mfma_f32_16x16x32_bf16 v[128:131], v[136:139], v[172:175], v[128:131]
	v_mfma_f32_16x16x32_bf16 v[124:127], v[158:161], v[172:175], v[124:127]
	v_mfma_f32_16x16x32_bf16 v[120:123], v[136:139], v[180:183], v[120:123]
	v_mfma_f32_16x16x32_bf16 v[116:119], v[158:161], v[180:183], v[116:119]
	v_mfma_f32_16x16x32_bf16 v[112:115], v[136:139], v[194:197], v[112:115]
	v_mfma_f32_16x16x32_bf16 v[108:111], v[158:161], v[194:197], v[108:111]
	v_mfma_f32_16x16x32_bf16 v[104:107], v[136:139], v[202:205], v[104:107]
	v_mfma_f32_16x16x32_bf16 v[100:103], v[158:161], v[202:205], v[100:103]
	s_barrier
	s_setprio 0
	s_add_i32 s25, 0, 0x1c000
	s_add_i32 s0, s24, s17
	v_add_u32_e32 v189, s25, v186
	v_lshl_add_u64 v[166:167], v[166:167], 0, s[12:13]
	s_mov_b32 m0, s0
	ds_read_b128 v[206:209], v189
	ds_read_b128 v[210:213], v189 offset:1024
	ds_read_b128 v[214:217], v189 offset:2048
	ds_read_b128 v[218:221], v189 offset:3072
	global_load_lds_dwordx4 v[166:167], off
	v_lshl_add_u64 v[166:167], v[168:169], 0, s[12:13]
	s_add_i32 m0, s0, 0x2000
	s_nop 0
	global_load_lds_dwordx4 v[166:167], off
	s_waitcnt vmcnt(10)
	s_setprio 1
	s_barrier
	s_waitcnt lgkmcnt(0)
	v_mfma_f32_16x16x32_bf16 v[68:71], v[206:209], v[162:165], v[68:71]
	v_mfma_f32_16x16x32_bf16 v[60:63], v[214:217], v[162:165], v[60:63]
	v_mfma_f32_16x16x32_bf16 v[56:59], v[206:209], v[176:179], v[56:59]
	v_mfma_f32_16x16x32_bf16 v[52:55], v[214:217], v[176:179], v[52:55]
	v_mfma_f32_16x16x32_bf16 v[48:51], v[206:209], v[190:193], v[48:51]
	v_mfma_f32_16x16x32_bf16 v[44:47], v[214:217], v[190:193], v[44:47]
	v_mfma_f32_16x16x32_bf16 v[40:43], v[206:209], v[198:201], v[40:43]
	v_mfma_f32_16x16x32_bf16 v[36:39], v[214:217], v[198:201], v[36:39]
	v_mfma_f32_16x16x32_bf16 v[68:71], v[210:213], v[172:175], v[68:71]
	v_mfma_f32_16x16x32_bf16 v[60:63], v[218:221], v[172:175], v[60:63]
	v_mfma_f32_16x16x32_bf16 v[56:59], v[210:213], v[180:183], v[56:59]
	v_mfma_f32_16x16x32_bf16 v[52:55], v[218:221], v[180:183], v[52:55]
	v_mfma_f32_16x16x32_bf16 v[48:51], v[210:213], v[194:197], v[48:51]
	v_mfma_f32_16x16x32_bf16 v[44:47], v[218:221], v[194:197], v[44:47]
	v_mfma_f32_16x16x32_bf16 v[40:43], v[210:213], v[202:205], v[40:43]
	v_mfma_f32_16x16x32_bf16 v[36:39], v[218:221], v[202:205], v[36:39]
	s_barrier
	s_setprio 0
	s_mov_b32 m0, s55
	v_lshl_add_u64 v[166:167], v[184:185], 0, s[12:13]
	ds_read_b128 v[162:165], v188 offset:49152
	ds_read_b128 v[172:175], v188 offset:50176
	ds_read_b128 v[176:179], v188 offset:51200
	ds_read_b128 v[180:183], v188 offset:52224
	ds_read_b128 v[190:193], v188 offset:53248
	ds_read_b128 v[194:197], v188 offset:54272
	ds_read_b128 v[198:201], v188 offset:55296
	ds_read_b128 v[202:205], v188 offset:56320
	global_load_lds_dwordx4 v[166:167], off
	v_lshl_add_u64 v[166:167], v[222:223], 0, s[12:13]
	s_mov_b32 m0, s56
	s_nop 0
	global_load_lds_dwordx4 v[166:167], off
	s_waitcnt vmcnt(10)
	s_setprio 1
	s_barrier
	s_waitcnt lgkmcnt(0)
	v_mfma_f32_16x16x32_bf16 v[96:99], v[132:135], v[162:165], v[96:99]
	v_mfma_f32_16x16x32_bf16 v[92:95], v[154:157], v[162:165], v[92:95]
	v_mfma_f32_16x16x32_bf16 v[88:91], v[132:135], v[176:179], v[88:91]
	v_mfma_f32_16x16x32_bf16 v[84:87], v[154:157], v[176:179], v[84:87]
	v_mfma_f32_16x16x32_bf16 v[80:83], v[132:135], v[190:193], v[80:83]
	v_mfma_f32_16x16x32_bf16 v[76:79], v[154:157], v[190:193], v[76:79]
	v_mfma_f32_16x16x32_bf16 v[72:75], v[132:135], v[198:201], v[72:75]
	v_mfma_f32_16x16x32_bf16 v[64:67], v[154:157], v[198:201], v[64:67]
	v_mfma_f32_16x16x32_bf16 v[96:99], v[136:139], v[172:175], v[96:99]
	v_mfma_f32_16x16x32_bf16 v[92:95], v[158:161], v[172:175], v[92:95]
	v_mfma_f32_16x16x32_bf16 v[88:91], v[136:139], v[180:183], v[88:91]
	v_mfma_f32_16x16x32_bf16 v[84:87], v[158:161], v[180:183], v[84:87]
	v_mfma_f32_16x16x32_bf16 v[80:83], v[136:139], v[194:197], v[80:83]
	v_mfma_f32_16x16x32_bf16 v[76:79], v[158:161], v[194:197], v[76:79]
	v_mfma_f32_16x16x32_bf16 v[72:75], v[136:139], v[202:205], v[72:75]
	v_mfma_f32_16x16x32_bf16 v[64:67], v[158:161], v[202:205], v[64:67]
	s_barrier
	s_setprio 0
	s_add_u32 s0, s28, 0xb0080
	s_addc_u32 s1, s29, 0
	s_add_i32 s24, s25, s17
	s_mov_b32 m0, s24
	s_nop 0
	global_load_lds_dwordx4 v26, s[0:1]
	s_add_i32 m0, s24, 0x2000
	s_nop 0
	global_load_lds_dwordx4 v144, s[0:1]
	v_add_u32_e32 v158, 0x10000, v186
	ds_read_b128 v[132:135], v158
	ds_read_b128 v[136:139], v158 offset:1024
	ds_read_b128 v[154:157], v158 offset:2048
	ds_read_b128 v[158:161], v158 offset:3072
	s_waitcnt vmcnt(10)
	s_setprio 1
	s_barrier
	v_mfma_f32_16x16x32_bf16 v[32:35], v[206:209], v[162:165], v[32:35]
	v_mfma_f32_16x16x32_bf16 v[28:31], v[214:217], v[162:165], v[28:31]
	v_mfma_f32_16x16x32_bf16 v[22:25], v[206:209], v[176:179], v[22:25]
	v_mfma_f32_16x16x32_bf16 v[18:21], v[214:217], v[176:179], v[18:21]
	v_mfma_f32_16x16x32_bf16 v[14:17], v[206:209], v[190:193], v[14:17]
	v_mfma_f32_16x16x32_bf16 v[10:13], v[214:217], v[190:193], v[10:13]
	v_mfma_f32_16x16x32_bf16 v[6:9], v[206:209], v[198:201], v[6:9]
	v_mfma_f32_16x16x32_bf16 v[2:5], v[214:217], v[198:201], v[2:5]
	v_mfma_f32_16x16x32_bf16 v[32:35], v[210:213], v[172:175], v[32:35]
	v_mfma_f32_16x16x32_bf16 v[28:31], v[218:221], v[172:175], v[28:31]
	v_mfma_f32_16x16x32_bf16 v[22:25], v[210:213], v[180:183], v[22:25]
	v_mfma_f32_16x16x32_bf16 v[18:21], v[218:221], v[180:183], v[18:21]
	v_mfma_f32_16x16x32_bf16 v[14:17], v[210:213], v[194:197], v[14:17]
	v_mfma_f32_16x16x32_bf16 v[10:13], v[218:221], v[194:197], v[10:13]
	v_mfma_f32_16x16x32_bf16 v[6:9], v[210:213], v[202:205], v[6:9]
	v_mfma_f32_16x16x32_bf16 v[2:5], v[218:221], v[202:205], v[2:5]
	s_barrier
	s_setprio 0
	s_add_i32 s72, s72, 2
	s_add_u32 s68, s68, 0x100
	s_addc_u32 s69, s69, 0
	s_cmp_gt_u32 s72, 41
	s_mov_b64 s[24:25], s[26:27]
	s_cbranch_scc0 .LBB0_1122
	s_waitcnt lgkmcnt(0)
	s_min_i32 s0, s22, 0x100
	s_ashr_i32 s26, s0, 5
	s_add_i32 s0, s22, 0xffffff00
	s_cmpk_lt_i32 s22, 0x100
	s_cselect_b32 s0, s22, s0
	s_cselect_b32 s25, 0, s51
	s_cselect_b32 s24, 0, s50
	s_ashr_i32 s1, s0, 31
	s_lshl_b64 s[0:1], s[0:1], 19
	s_add_u32 s24, s20, s24
	v_lshl_or_b32 v166, s23, 8, v187
	s_addc_u32 s25, s21, s25
	s_ashr_i32 s23, s22, 31
	v_lshl_add_u64 v[132:133], s[0:1], 0, v[146:147]
	s_lshl_b64 s[22:23], s[22:23], 10
	s_mul_hi_i32 s1, s26, 0x9000
	s_mul_i32 s26, s26, 0x9000
	s_add_u32 s0, s34, s26
	v_ashrrev_i32_e32 v167, 31, v166
	s_addc_u32 s1, s35, s1
	v_lshl_add_u64 v[154:155], v[166:167], 2, s[0:1]
	v_lshl_add_u64 v[168:169], v[132:133], 0, v[166:167]
	v_lshl_add_u64 v[176:177], v[132:133], 1, s[24:25]
	global_load_dwordx4 v[132:135], v[154:155], off offset:16
	global_load_dwordx4 v[136:139], v[154:155], off
	v_lshl_add_u64 v[182:183], v[168:169], 1, s[24:25]
	v_add_co_u32_e32 v184, vcc, s65, v182
	s_mov_b32 s0, 0x20000
	s_nop 0
	v_addc_co_u32_e32 v185, vcc, 0, v183, vcc
	v_add_co_u32_e32 v178, vcc, s0, v182
	s_mov_b32 s1, 0x30000
	s_nop 0
	v_addc_co_u32_e32 v179, vcc, 0, v183, vcc
	v_add_co_u32_e32 v180, vcc, s1, v182
	v_lshl_add_u64 v[176:177], v[166:167], 1, v[176:177]
	s_nop 0
	v_addc_co_u32_e32 v181, vcc, 0, v183, vcc
	s_mov_b32 s24, 0x80000
	s_mov_b32 s25, 0x90000
	s_waitcnt vmcnt(0)
	v_pk_mul_f32 v[164:165], v[134:135], 0.5 op_sel_hi:[1,0]
	v_pk_mul_f32 v[174:175], v[138:139], 0.5 op_sel_hi:[1,0]
	v_pk_mul_f32 v[172:173], v[136:137], 0.5 op_sel_hi:[1,0]
	v_pk_mul_f32 v[162:163], v[132:133], 0.5 op_sel_hi:[1,0]
	global_load_dwordx4 v[132:135], v[154:155], off offset:528
	global_load_dwordx4 v[136:139], v[154:155], off offset:512
	global_load_dwordx4 v[190:193], v[182:183], off offset:2048
	global_load_dwordx4 v[194:197], v[184:185], off offset:2048
	s_waitcnt vmcnt(0)
	v_pk_mul_f32 v[156:157], v[134:135], 0.5 op_sel_hi:[1,0]
	v_pk_mul_f32 v[160:161], v[138:139], 0.5 op_sel_hi:[1,0]
	v_pk_mul_f32 v[158:159], v[136:137], 0.5 op_sel_hi:[1,0]
	global_load_dwordx4 v[136:139], v[178:179], off offset:2048
	v_pk_mul_f32 v[154:155], v[132:133], 0.5 op_sel_hi:[1,0]
	global_load_dwordx4 v[132:135], v[180:181], off offset:2048
	v_lshlrev_b32_e32 v166, 16, v190
	v_and_b32_e32 v167, 0xffff0000, v190
	v_lshlrev_b32_e32 v168, 16, v191
	v_and_b32_e32 v169, 0xffff0000, v191
	v_lshlrev_b32_e32 v190, 16, v192
	v_and_b32_e32 v191, 0xffff0000, v192
	v_lshlrev_b32_e32 v192, 16, v193
	v_and_b32_e32 v193, 0xffff0000, v193
	v_pk_fma_f32 v[130:131], v[130:131], v[174:175], v[168:169]
	v_pk_fma_f32 v[128:129], v[128:129], v[172:173], v[166:167]
	v_pk_fma_f32 v[166:167], v[126:127], v[164:165], v[192:193]
	v_pk_fma_f32 v[126:127], v[124:125], v[162:163], v[190:191]
	v_lshlrev_b32_e32 v202, 16, v196
	v_and_b32_e32 v203, 0xffff0000, v196
	v_lshlrev_b32_e32 v204, 16, v197
	v_and_b32_e32 v205, 0xffff0000, v197
	v_cvt_pk_bf16_f32 v124, v128, v129
	v_cvt_pk_bf16_f32 v125, v130, v131
	v_cvt_pk_bf16_f32 v126, v126, v127
	v_cvt_pk_bf16_f32 v127, v166, v167
	v_lshlrev_b32_e32 v200, 16, v195
	v_and_b32_e32 v201, 0xffff0000, v195
	global_store_dwordx4 v[176:177], v[124:127], off offset:2048
	v_lshlrev_b32_e32 v193, 16, v124
	v_and_b32_e32 v196, 0xffff0000, v124
	v_lshlrev_b32_e32 v191, 16, v125
	v_and_b32_e32 v195, 0xffff0000, v125
	v_pk_fma_f32 v[124:125], v[118:119], v[164:165], v[204:205]
	v_pk_fma_f32 v[118:119], v[116:117], v[162:163], v[202:203]
	v_lshlrev_b32_e32 v198, 16, v194
	v_cvt_pk_bf16_f32 v118, v118, v119
	v_cvt_pk_bf16_f32 v119, v124, v125
	v_add_co_u32_e32 v124, vcc, s65, v176
	v_and_b32_e32 v199, 0xffff0000, v194
	s_nop 0
	v_addc_co_u32_e32 v125, vcc, 0, v177, vcc
	v_lshlrev_b32_e32 v190, 16, v126
	v_and_b32_e32 v194, 0xffff0000, v126
	v_add_co_u32_e32 v126, vcc, s24, v182
	v_lshlrev_b32_e32 v189, 16, v127
	v_and_b32_e32 v192, 0xffff0000, v127
	v_addc_co_u32_e32 v127, vcc, 0, v183, vcc
	v_add_co_u32_e32 v128, vcc, s25, v182
	v_pk_fma_f32 v[122:123], v[122:123], v[174:175], v[200:201]
	v_pk_fma_f32 v[120:121], v[120:121], v[172:173], v[198:199]
	v_addc_co_u32_e32 v129, vcc, 0, v183, vcc
	v_cvt_pk_bf16_f32 v116, v120, v121
	v_cvt_pk_bf16_f32 v117, v122, v123
	global_store_dwordx4 v[124:125], v[116:119], off offset:2048
	global_load_dwordx4 v[120:123], v[126:127], off offset:2048
	global_load_dwordx4 v[198:201], v[128:129], off offset:2048
	s_waitcnt vmcnt(0)
	v_lshlrev_b32_e32 v130, 16, v136
	v_and_b32_e32 v131, 0xffff0000, v136
	v_lshlrev_b32_e32 v166, 16, v138
	v_and_b32_e32 v167, 0xffff0000, v138
	v_lshlrev_b32_e32 v138, 16, v139
	v_and_b32_e32 v139, 0xffff0000, v139
	v_pk_fma_f32 v[112:113], v[112:113], v[172:173], v[130:131]
	v_pk_fma_f32 v[130:131], v[110:111], v[164:165], v[138:139]
	v_pk_fma_f32 v[110:111], v[108:109], v[162:163], v[166:167]
	v_lshlrev_b32_e32 v168, 16, v132
	v_cvt_pk_bf16_f32 v110, v110, v111
	v_cvt_pk_bf16_f32 v111, v130, v131
	v_add_co_u32_e32 v130, vcc, s0, v176
	v_and_b32_e32 v169, 0xffff0000, v132
	v_lshlrev_b32_e32 v132, 16, v133
	v_and_b32_e32 v133, 0xffff0000, v133
	v_addc_co_u32_e32 v131, vcc, 0, v177, vcc
	v_lshlrev_b32_e32 v136, 16, v137
	v_and_b32_e32 v137, 0xffff0000, v137
	v_lshlrev_b32_e32 v202, 16, v134
	v_and_b32_e32 v203, 0xffff0000, v134
	v_lshlrev_b32_e32 v134, 16, v135
	v_and_b32_e32 v135, 0xffff0000, v135
	v_pk_fma_f32 v[106:107], v[106:107], v[174:175], v[132:133]
	v_add_co_u32_e32 v132, vcc, s1, v176
	v_pk_fma_f32 v[114:115], v[114:115], v[174:175], v[136:137]
	v_cvt_pk_bf16_f32 v108, v112, v113
	v_pk_fma_f32 v[104:105], v[104:105], v[172:173], v[168:169]
	v_pk_fma_f32 v[112:113], v[102:103], v[164:165], v[134:135]
	v_pk_fma_f32 v[102:103], v[100:101], v[162:163], v[202:203]
	v_addc_co_u32_e32 v133, vcc, 0, v177, vcc
	v_cvt_pk_bf16_f32 v109, v114, v115
	v_cvt_pk_bf16_f32 v100, v104, v105
	v_cvt_pk_bf16_f32 v101, v106, v107
	v_cvt_pk_bf16_f32 v102, v102, v103
	v_cvt_pk_bf16_f32 v103, v112, v113
	v_add_co_u32_e32 v134, vcc, s76, v182
	global_store_dwordx4 v[130:131], v[108:111], off offset:2048
	global_store_dwordx4 v[132:133], v[100:103], off offset:2048
	v_addc_co_u32_e32 v135, vcc, 0, v183, vcc
	s_mov_b32 s0, 0xb0000
	global_load_dwordx4 v[112:115], v[134:135], off offset:2048
	v_add_co_u32_e32 v136, vcc, s0, v182
	v_lshlrev_b32_e32 v138, 16, v120
	s_nop 0
	v_addc_co_u32_e32 v137, vcc, 0, v183, vcc
	global_load_dwordx4 v[104:107], v[136:137], off offset:2048
	v_and_b32_e32 v139, 0xffff0000, v120
	v_lshlrev_b32_e32 v120, 16, v121
	v_and_b32_e32 v121, 0xffff0000, v121
	v_lshlrev_b32_e32 v166, 16, v122
	v_and_b32_e32 v167, 0xffff0000, v122
	v_lshlrev_b32_e32 v122, 16, v123
	v_and_b32_e32 v123, 0xffff0000, v123
	v_pk_fma_f32 v[96:97], v[96:97], v[172:173], v[138:139]
	v_lshlrev_b32_e32 v168, 16, v198
	v_and_b32_e32 v169, 0xffff0000, v198
	v_lshlrev_b32_e32 v198, 16, v199
	v_and_b32_e32 v199, 0xffff0000, v199
	v_pk_fma_f32 v[98:99], v[98:99], v[174:175], v[120:121]
	v_pk_fma_f32 v[120:121], v[94:95], v[164:165], v[122:123]
	v_pk_fma_f32 v[94:95], v[92:93], v[162:163], v[166:167]
	v_cvt_pk_bf16_f32 v92, v96, v97
	v_add_co_u32_e32 v96, vcc, s24, v176
	v_lshlrev_b32_e32 v202, 16, v200
	v_and_b32_e32 v203, 0xffff0000, v200
	v_lshlrev_b32_e32 v200, 16, v201
	v_and_b32_e32 v201, 0xffff0000, v201
	v_addc_co_u32_e32 v97, vcc, 0, v177, vcc
	v_pk_fma_f32 v[90:91], v[90:91], v[174:175], v[198:199]
	v_pk_fma_f32 v[88:89], v[88:89], v[172:173], v[168:169]
	v_cvt_pk_bf16_f32 v93, v98, v99
	v_pk_fma_f32 v[98:99], v[86:87], v[164:165], v[200:201]
	v_pk_fma_f32 v[86:87], v[84:85], v[162:163], v[202:203]
	v_cvt_pk_bf16_f32 v84, v88, v89
	v_cvt_pk_bf16_f32 v85, v90, v91
	v_add_co_u32_e32 v88, vcc, s25, v176
	v_cvt_pk_bf16_f32 v86, v86, v87
	v_cvt_pk_bf16_f32 v87, v98, v99
	v_addc_co_u32_e32 v89, vcc, 0, v177, vcc
	v_cvt_pk_bf16_f32 v94, v94, v95
	v_cvt_pk_bf16_f32 v95, v120, v121
	global_store_dwordx4 v[96:97], v[92:95], off offset:2048
	global_store_dwordx4 v[88:89], v[84:87], off offset:2048
	global_load_dwordx4 v[120:123], v[182:183], off offset:2304
	s_nop 0
	global_load_dwordx4 v[182:185], v[184:185], off offset:2304
	s_waitcnt vmcnt(0)
	v_lshlrev_b32_e32 v90, 16, v112
	v_and_b32_e32 v91, 0xffff0000, v112
	v_lshlrev_b32_e32 v98, 16, v113
	v_and_b32_e32 v99, 0xffff0000, v113
	v_lshlrev_b32_e32 v112, 16, v114
	v_and_b32_e32 v113, 0xffff0000, v114
	v_lshlrev_b32_e32 v114, 16, v115
	v_and_b32_e32 v115, 0xffff0000, v115
	v_pk_fma_f32 v[80:81], v[80:81], v[172:173], v[90:91]
	v_pk_fma_f32 v[90:91], v[78:79], v[164:165], v[114:115]
	v_pk_fma_f32 v[78:79], v[76:77], v[162:163], v[112:113]
	v_cvt_pk_bf16_f32 v76, v80, v81
	v_add_co_u32_e32 v80, vcc, s76, v176
	v_lshlrev_b32_e32 v138, 16, v104
	v_and_b32_e32 v139, 0xffff0000, v104
	v_lshlrev_b32_e32 v104, 16, v105
	v_and_b32_e32 v105, 0xffff0000, v105
	v_lshlrev_b32_e32 v166, 16, v106
	v_and_b32_e32 v167, 0xffff0000, v106
	v_lshlrev_b32_e32 v106, 16, v107
	v_and_b32_e32 v107, 0xffff0000, v107
	v_pk_fma_f32 v[82:83], v[82:83], v[174:175], v[98:99]
	v_addc_co_u32_e32 v81, vcc, 0, v177, vcc
	v_pk_fma_f32 v[72:73], v[72:73], v[172:173], v[138:139]
	v_cvt_pk_bf16_f32 v77, v82, v83
	v_pk_fma_f32 v[74:75], v[74:75], v[174:175], v[104:105]
	v_pk_fma_f32 v[82:83], v[66:67], v[164:165], v[106:107]
	v_pk_fma_f32 v[66:67], v[64:65], v[162:163], v[166:167]
	v_cvt_pk_bf16_f32 v64, v72, v73
	v_add_co_u32_e32 v72, vcc, s0, v176
	v_cvt_pk_bf16_f32 v78, v78, v79
	v_cvt_pk_bf16_f32 v79, v90, v91
	v_cvt_pk_bf16_f32 v65, v74, v75
	v_cvt_pk_bf16_f32 v66, v66, v67
	v_cvt_pk_bf16_f32 v67, v82, v83
	v_addc_co_u32_e32 v73, vcc, 0, v177, vcc
	global_store_dwordx4 v[80:81], v[76:79], off offset:2048
	global_store_dwordx4 v[72:73], v[64:67], off offset:2048
	global_load_dwordx4 v[104:107], v[178:179], off offset:2304
	global_load_dwordx4 v[112:115], v[180:181], off offset:2304
	v_lshlrev_b32_e32 v74, 16, v120
	v_and_b32_e32 v75, 0xffff0000, v120
	v_lshlrev_b32_e32 v82, 16, v121
	v_and_b32_e32 v83, 0xffff0000, v121
	v_lshlrev_b32_e32 v90, 16, v122
	v_and_b32_e32 v91, 0xffff0000, v122
	v_lshlrev_b32_e32 v98, 16, v123
	v_and_b32_e32 v99, 0xffff0000, v123
	v_pk_fma_f32 v[70:71], v[70:71], v[160:161], v[82:83]
	v_pk_fma_f32 v[68:69], v[68:69], v[158:159], v[74:75]
	v_pk_fma_f32 v[74:75], v[62:63], v[156:157], v[98:99]
	v_pk_fma_f32 v[62:63], v[60:61], v[154:155], v[90:91]
	v_lshlrev_b32_e32 v120, 16, v182
	v_and_b32_e32 v121, 0xffff0000, v182
	v_lshlrev_b32_e32 v122, 16, v183
	v_and_b32_e32 v123, 0xffff0000, v183
	v_lshlrev_b32_e32 v138, 16, v184
	v_and_b32_e32 v139, 0xffff0000, v184
	v_lshlrev_b32_e32 v162, 16, v185
	v_and_b32_e32 v163, 0xffff0000, v185
	v_cvt_pk_bf16_f32 v60, v68, v69
	v_cvt_pk_bf16_f32 v61, v70, v71
	v_cvt_pk_bf16_f32 v62, v62, v63
	v_cvt_pk_bf16_f32 v63, v74, v75
	global_store_dwordx4 v[176:177], v[60:63], off offset:2304
	v_lshlrev_b32_e32 v164, 16, v60
	v_and_b32_e32 v165, 0xffff0000, v60
	v_lshlrev_b32_e32 v166, 16, v61
	v_and_b32_e32 v167, 0xffff0000, v61
	v_pk_fma_f32 v[58:59], v[58:59], v[160:161], v[122:123]
	v_pk_fma_f32 v[56:57], v[56:57], v[158:159], v[120:121]
	v_pk_fma_f32 v[60:61], v[54:55], v[156:157], v[162:163]
	v_pk_fma_f32 v[54:55], v[52:53], v[154:155], v[138:139]
	v_cvt_pk_bf16_f32 v52, v56, v57
	v_cvt_pk_bf16_f32 v53, v58, v59
	v_cvt_pk_bf16_f32 v54, v54, v55
	v_cvt_pk_bf16_f32 v55, v60, v61
	global_store_dwordx4 v[124:125], v[52:55], off offset:2304
	v_lshlrev_b32_e32 v168, 16, v62
	v_and_b32_e32 v169, 0xffff0000, v62
	v_lshlrev_b32_e32 v172, 16, v63
	v_and_b32_e32 v173, 0xffff0000, v63
	global_load_dwordx4 v[56:59], v[126:127], off offset:2304
	global_load_dwordx4 v[60:63], v[128:129], off offset:2304
	s_waitcnt vmcnt(0)
	v_lshlrev_b32_e32 v68, 16, v104
	v_and_b32_e32 v69, 0xffff0000, v104
	v_lshlrev_b32_e32 v70, 16, v105
	v_and_b32_e32 v71, 0xffff0000, v105
	v_lshlrev_b32_e32 v74, 16, v106
	v_and_b32_e32 v75, 0xffff0000, v106
	v_lshlrev_b32_e32 v82, 16, v107
	v_and_b32_e32 v83, 0xffff0000, v107
	v_lshlrev_b32_e32 v90, 16, v112
	v_and_b32_e32 v91, 0xffff0000, v112
	v_lshlrev_b32_e32 v98, 16, v113
	v_and_b32_e32 v99, 0xffff0000, v113
	v_lshlrev_b32_e32 v104, 16, v114
	v_and_b32_e32 v105, 0xffff0000, v114
	v_lshlrev_b32_e32 v106, 16, v115
	v_and_b32_e32 v107, 0xffff0000, v115
	v_pk_fma_f32 v[48:49], v[48:49], v[158:159], v[68:69]
	v_pk_fma_f32 v[50:51], v[50:51], v[160:161], v[70:71]
	v_pk_fma_f32 v[68:69], v[46:47], v[156:157], v[82:83]
	v_pk_fma_f32 v[46:47], v[44:45], v[154:155], v[74:75]
	v_cvt_pk_bf16_f32 v44, v48, v49
	v_pk_fma_f32 v[42:43], v[42:43], v[160:161], v[98:99]
	v_pk_fma_f32 v[40:41], v[40:41], v[158:159], v[90:91]
	v_pk_fma_f32 v[48:49], v[38:39], v[156:157], v[106:107]
	v_pk_fma_f32 v[38:39], v[36:37], v[154:155], v[104:105]
	v_cvt_pk_bf16_f32 v45, v50, v51
	v_cvt_pk_bf16_f32 v46, v46, v47
	v_cvt_pk_bf16_f32 v47, v68, v69
	v_cvt_pk_bf16_f32 v36, v40, v41
	v_cvt_pk_bf16_f32 v37, v42, v43
	v_cvt_pk_bf16_f32 v38, v38, v39
	v_cvt_pk_bf16_f32 v39, v48, v49
	global_store_dwordx4 v[130:131], v[44:47], off offset:2304
	global_store_dwordx4 v[132:133], v[36:39], off offset:2304
	global_load_dwordx4 v[40:43], v[134:135], off offset:2304
	global_load_dwordx4 v[48:51], v[136:137], off offset:2304
	v_lshlrev_b32_e32 v68, 16, v56
	v_and_b32_e32 v69, 0xffff0000, v56
	v_lshlrev_b32_e32 v56, 16, v57
	v_and_b32_e32 v57, 0xffff0000, v57
	v_lshlrev_b32_e32 v70, 16, v58
	v_and_b32_e32 v71, 0xffff0000, v58
	v_lshlrev_b32_e32 v58, 16, v59
	v_and_b32_e32 v59, 0xffff0000, v59
	v_lshlrev_b32_e32 v74, 16, v60
	v_and_b32_e32 v75, 0xffff0000, v60
	v_lshlrev_b32_e32 v82, 16, v62
	v_and_b32_e32 v83, 0xffff0000, v62
	v_lshlrev_b32_e32 v62, 16, v63
	v_and_b32_e32 v63, 0xffff0000, v63
	v_pk_fma_f32 v[32:33], v[32:33], v[158:159], v[68:69]
	v_lshlrev_b32_e32 v60, 16, v61
	v_and_b32_e32 v61, 0xffff0000, v61
	v_pk_fma_f32 v[34:35], v[34:35], v[160:161], v[56:57]
	v_pk_fma_f32 v[56:57], v[30:31], v[156:157], v[58:59]
	v_pk_fma_f32 v[30:31], v[28:29], v[154:155], v[70:71]
	v_cvt_pk_bf16_f32 v28, v32, v33
	v_pk_fma_f32 v[22:23], v[22:23], v[158:159], v[74:75]
	v_pk_fma_f32 v[32:33], v[20:21], v[156:157], v[62:63]
	v_pk_fma_f32 v[20:21], v[18:19], v[154:155], v[82:83]
	v_cvt_pk_bf16_f32 v29, v34, v35
	v_pk_fma_f32 v[24:25], v[24:25], v[160:161], v[60:61]
	v_cvt_pk_bf16_f32 v18, v22, v23
	v_cvt_pk_bf16_f32 v20, v20, v21
	v_cvt_pk_bf16_f32 v21, v32, v33
	v_cvt_pk_bf16_f32 v19, v24, v25
	v_cvt_pk_bf16_f32 v30, v30, v31
	v_cvt_pk_bf16_f32 v31, v56, v57
	global_store_dwordx4 v[96:97], v[28:31], off offset:2304
	global_store_dwordx4 v[88:89], v[18:21], off offset:2304
	s_waitcnt vmcnt(0)
	v_lshlrev_b32_e32 v22, 16, v40
	v_and_b32_e32 v23, 0xffff0000, v40
	v_lshlrev_b32_e32 v32, 16, v42
	v_and_b32_e32 v33, 0xffff0000, v42
	v_lshlrev_b32_e32 v34, 16, v43
	v_and_b32_e32 v35, 0xffff0000, v43
	v_lshlrev_b32_e32 v42, 16, v49
	v_and_b32_e32 v43, 0xffff0000, v49
	v_lshlrev_b32_e32 v24, 16, v41
	v_and_b32_e32 v25, 0xffff0000, v41
	v_lshlrev_b32_e32 v40, 16, v48
	v_and_b32_e32 v41, 0xffff0000, v48
	v_lshlrev_b32_e32 v48, 16, v50
	v_and_b32_e32 v49, 0xffff0000, v50
	v_lshlrev_b32_e32 v50, 16, v51
	v_and_b32_e32 v51, 0xffff0000, v51
	v_pk_fma_f32 v[14:15], v[14:15], v[158:159], v[22:23]
	v_pk_fma_f32 v[8:9], v[8:9], v[160:161], v[42:43]
	v_pk_fma_f32 v[22:23], v[12:13], v[156:157], v[34:35]
	v_pk_fma_f32 v[12:13], v[10:11], v[154:155], v[32:33]
	v_cvt_pk_bf16_f32 v10, v14, v15
	v_pk_fma_f32 v[14:15], v[4:5], v[156:157], v[50:51]
	v_pk_fma_f32 v[4:5], v[2:3], v[154:155], v[48:49]
	v_cvt_pk_bf16_f32 v3, v8, v9
	v_and_b32_e32 v9, 64, v227
	v_xor_b32_e32 v8, 16, v227
	v_add_u32_e32 v9, 64, v9
	v_cvt_pk_bf16_f32 v4, v4, v5
	v_cvt_pk_bf16_f32 v5, v14, v15
	v_cmp_lt_i32_e32 vcc, v8, v9
	v_xor_b32_e32 v14, 32, v227
	v_mul_f32_e32 v15, v195, v195
	v_cndmask_b32_e32 v8, v227, v8, vcc
	v_cmp_lt_i32_e32 vcc, v14, v9
	v_pk_fma_f32 v[16:17], v[16:17], v[160:161], v[24:25]
	v_fmac_f32_e32 v15, v191, v191
	v_cndmask_b32_e32 v9, v227, v14, vcc
	v_mul_f32_e32 v14, v196, v196
	v_fmac_f32_e32 v14, v193, v193
	v_cvt_pk_bf16_f32 v11, v16, v17
	v_add_f32_e32 v14, v14, v15
	v_mul_f32_e32 v15, v194, v194
	v_mul_f32_e32 v16, v192, v192
	v_fmac_f32_e32 v15, v190, v190
	v_fmac_f32_e32 v16, v189, v189
	v_add_f32_e32 v15, v15, v16
	v_add_f32_e32 v14, v14, v15
	v_mul_f32_e32 v15, v165, v165
	v_mul_f32_e32 v16, v167, v167
	v_fmac_f32_e32 v15, v164, v164
	v_fmac_f32_e32 v16, v166, v166
	v_add_f32_e32 v15, v15, v16
	v_add_f32_e32 v14, v14, v15
	v_mul_f32_e32 v15, v169, v169
	v_mul_f32_e32 v16, v173, v173
	v_fmac_f32_e32 v15, v168, v168
	v_fmac_f32_e32 v16, v172, v172
	v_add_f32_e32 v15, v15, v16
	v_lshlrev_b32_e32 v8, 2, v8
	v_add_f32_e32 v14, v15, v14
	ds_bpermute_b32 v15, v8, v14
	v_lshlrev_b32_e32 v9, 2, v9
	v_pk_fma_f32 v[6:7], v[6:7], v[158:159], v[40:41]
	v_cvt_pk_bf16_f32 v12, v12, v13
	v_cvt_pk_bf16_f32 v13, v22, v23
	s_waitcnt lgkmcnt(0)
	v_add_f32_e32 v14, v14, v15
	ds_bpermute_b32 v15, v9, v14
	v_cvt_pk_bf16_f32 v2, v6, v7
	v_lshl_add_u64 v[6:7], v[148:149], 0, s[22:23]
	global_store_dwordx4 v[80:81], v[10:13], off offset:2304
	global_store_dwordx4 v[72:73], v[2:5], off offset:2304
	s_and_saveexec_b64 s[22:23], s[38:39]
	s_cbranch_execz .LBB0_1125
	s_waitcnt lgkmcnt(0)
	v_add_f32_e32 v14, v14, v15
	global_atomic_add_f32 v[6:7], v14, off

.LBB0_1156:
	s_add_u32 s28, s26, 0x100
	s_addc_u32 s29, s27, 0
	s_add_i32 s0, 0, 0x10000
	s_cmp_eq_u32 s81, 40
	s_cselect_b32 s35, s43, s29
	s_cselect_b32 s34, s42, s28
	s_cselect_b32 s31, s23, s45
	s_cselect_b32 s30, s22, s44
	s_add_i32 m0, s52, 0xc000
	ds_read_b128 v[172:175], v224
	ds_read_b128 v[176:179], v224 offset:1024
	ds_read_b128 v[180:183], v224 offset:2048
	ds_read_b128 v[184:187], v224 offset:3072
	ds_read_b128 v[188:191], v224 offset:4096
	ds_read_b128 v[192:195], v224 offset:5120
	ds_read_b128 v[196:199], v224 offset:6144
	ds_read_b128 v[200:203], v224 offset:7168
	global_load_lds_dwordx4 v152, s[26:27]
	v_lshl_add_u64 v[164:165], s[26:27], 0, v[154:155]
	s_add_i32 m0, s52, 0xe000
	s_nop 0
	global_load_lds_dwordx4 v[164:165], off
	s_waitcnt vmcnt(10) lgkmcnt(8)
	s_setprio 1
	s_barrier
	s_waitcnt lgkmcnt(0)
	v_mfma_f32_16x16x32_bf16 v[128:131], v[132:135], v[172:175], v[128:131]
	v_mfma_f32_16x16x32_bf16 v[124:127], v[156:159], v[172:175], v[124:127]
	v_mfma_f32_16x16x32_bf16 v[120:123], v[132:135], v[180:183], v[120:123]
	v_mfma_f32_16x16x32_bf16 v[116:119], v[156:159], v[180:183], v[116:119]
	v_mfma_f32_16x16x32_bf16 v[112:115], v[132:135], v[188:191], v[112:115]
	v_mfma_f32_16x16x32_bf16 v[108:111], v[156:159], v[188:191], v[108:111]
	v_mfma_f32_16x16x32_bf16 v[104:107], v[132:135], v[196:199], v[104:107]
	v_mfma_f32_16x16x32_bf16 v[100:103], v[156:159], v[196:199], v[100:103]
	v_mfma_f32_16x16x32_bf16 v[128:131], v[136:139], v[176:179], v[128:131]
	v_mfma_f32_16x16x32_bf16 v[124:127], v[160:163], v[176:179], v[124:127]
	v_mfma_f32_16x16x32_bf16 v[120:123], v[136:139], v[184:187], v[120:123]
	v_mfma_f32_16x16x32_bf16 v[116:119], v[160:163], v[184:187], v[116:119]
	v_mfma_f32_16x16x32_bf16 v[112:115], v[136:139], v[192:195], v[112:115]
	v_mfma_f32_16x16x32_bf16 v[108:111], v[160:163], v[192:195], v[108:111]
	v_mfma_f32_16x16x32_bf16 v[104:107], v[136:139], v[200:203], v[104:107]
	v_mfma_f32_16x16x32_bf16 v[100:103], v[160:163], v[200:203], v[100:103]
	s_barrier
	s_setprio 0
	s_add_i32 s26, 0, 0x14000
	v_add_u32_e32 v164, s26, v222
	s_add_i32 s0, s0, s17
	ds_read_b128 v[204:207], v164
	ds_read_b128 v[208:211], v164 offset:1024
	ds_read_b128 v[212:215], v164 offset:2048
	ds_read_b128 v[216:219], v164 offset:3072
	v_lshl_add_u64 v[164:165], s[30:31], 0, v[26:27]
	s_mov_b32 m0, s0
	v_lshl_add_u64 v[166:167], s[30:31], 0, v[144:145]
	global_load_lds_dwordx4 v[164:165], off
	s_add_i32 m0, s0, 0x2000
	s_nop 0
	global_load_lds_dwordx4 v[166:167], off
	s_waitcnt vmcnt(10)
	s_setprio 1
	s_barrier
	s_waitcnt lgkmcnt(0)
	v_mfma_f32_16x16x32_bf16 v[64:67], v[204:207], v[172:175], v[64:67]
	v_mfma_f32_16x16x32_bf16 v[60:63], v[212:215], v[172:175], v[60:63]
	v_mfma_f32_16x16x32_bf16 v[56:59], v[204:207], v[180:183], v[56:59]
	v_mfma_f32_16x16x32_bf16 v[52:55], v[212:215], v[180:183], v[52:55]
	v_mfma_f32_16x16x32_bf16 v[48:51], v[204:207], v[188:191], v[48:51]
	v_mfma_f32_16x16x32_bf16 v[44:47], v[212:215], v[188:191], v[44:47]
	v_mfma_f32_16x16x32_bf16 v[40:43], v[204:207], v[196:199], v[40:43]
	v_mfma_f32_16x16x32_bf16 v[36:39], v[212:215], v[196:199], v[36:39]
	v_mfma_f32_16x16x32_bf16 v[64:67], v[208:211], v[176:179], v[64:67]
	v_mfma_f32_16x16x32_bf16 v[60:63], v[216:219], v[176:179], v[60:63]
	v_mfma_f32_16x16x32_bf16 v[56:59], v[208:211], v[184:187], v[56:59]
	v_mfma_f32_16x16x32_bf16 v[52:55], v[216:219], v[184:187], v[52:55]
	v_mfma_f32_16x16x32_bf16 v[48:51], v[208:211], v[192:195], v[48:51]
	v_mfma_f32_16x16x32_bf16 v[44:47], v[216:219], v[192:195], v[44:47]
	v_mfma_f32_16x16x32_bf16 v[40:43], v[208:211], v[200:203], v[40:43]
	v_mfma_f32_16x16x32_bf16 v[36:39], v[216:219], v[200:203], v[36:39]
	s_barrier
	s_setprio 0
	s_mov_b32 m0, s52
	v_lshl_add_u64 v[168:169], s[34:35], 0, v[140:141]
	ds_read_b128 v[172:175], v224 offset:16384
	ds_read_b128 v[176:179], v224 offset:17408
	ds_read_b128 v[180:183], v224 offset:18432
	ds_read_b128 v[184:187], v224 offset:19456
	ds_read_b128 v[188:191], v224 offset:20480
	ds_read_b128 v[192:195], v224 offset:21504
	ds_read_b128 v[196:199], v224 offset:22528
	ds_read_b128 v[200:203], v224 offset:23552
	global_load_lds_dwordx4 v[168:169], off
	v_lshl_add_u64 v[220:221], s[34:35], 0, v[142:143]
	s_mov_b32 m0, s54
	s_nop 0
	global_load_lds_dwordx4 v[220:221], off
	s_waitcnt vmcnt(10)
	s_setprio 1
	s_barrier
	s_waitcnt lgkmcnt(0)
	v_mfma_f32_16x16x32_bf16 v[96:99], v[132:135], v[172:175], v[96:99]
	v_mfma_f32_16x16x32_bf16 v[92:95], v[156:159], v[172:175], v[92:95]
	v_mfma_f32_16x16x32_bf16 v[88:91], v[132:135], v[180:183], v[88:91]
	v_mfma_f32_16x16x32_bf16 v[84:87], v[156:159], v[180:183], v[84:87]
	v_mfma_f32_16x16x32_bf16 v[80:83], v[132:135], v[188:191], v[80:83]
	v_mfma_f32_16x16x32_bf16 v[76:79], v[156:159], v[188:191], v[76:79]
	v_mfma_f32_16x16x32_bf16 v[72:75], v[132:135], v[196:199], v[72:75]
	v_mfma_f32_16x16x32_bf16 v[68:71], v[156:159], v[196:199], v[68:71]
	v_mfma_f32_16x16x32_bf16 v[96:99], v[136:139], v[176:179], v[96:99]
	v_mfma_f32_16x16x32_bf16 v[92:95], v[160:163], v[176:179], v[92:95]
	v_mfma_f32_16x16x32_bf16 v[88:91], v[136:139], v[184:187], v[88:91]
	v_mfma_f32_16x16x32_bf16 v[84:87], v[160:163], v[184:187], v[84:87]
	v_mfma_f32_16x16x32_bf16 v[80:83], v[136:139], v[192:195], v[80:83]
	v_mfma_f32_16x16x32_bf16 v[76:79], v[160:163], v[192:195], v[76:79]
	v_mfma_f32_16x16x32_bf16 v[72:75], v[136:139], v[200:203], v[72:75]
	v_mfma_f32_16x16x32_bf16 v[68:71], v[160:163], v[200:203], v[68:71]
	s_barrier
	s_setprio 0
	s_add_u32 s0, s30, 0xb0000
	s_addc_u32 s1, s31, 0
	s_add_i32 s26, s26, s17
	s_mov_b32 m0, s26
	s_nop 0
	global_load_lds_dwordx4 v26, s[0:1]
	s_add_i32 m0, s26, 0x2000
	s_nop 0
	global_load_lds_dwordx4 v144, s[0:1]
	v_add_u32_e32 v160, 0x18000, v222
	ds_read_b128 v[132:135], v160
	ds_read_b128 v[136:139], v160 offset:1024
	ds_read_b128 v[156:159], v160 offset:2048
	ds_read_b128 v[160:163], v160 offset:3072
	s_waitcnt vmcnt(10)
	s_setprio 1
	s_barrier
	v_mfma_f32_16x16x32_bf16 v[32:35], v[204:207], v[172:175], v[32:35]
	v_mfma_f32_16x16x32_bf16 v[28:31], v[212:215], v[172:175], v[28:31]
	v_mfma_f32_16x16x32_bf16 v[22:25], v[204:207], v[180:183], v[22:25]
	v_mfma_f32_16x16x32_bf16 v[18:21], v[212:215], v[180:183], v[18:21]
	v_mfma_f32_16x16x32_bf16 v[14:17], v[204:207], v[188:191], v[14:17]
	v_mfma_f32_16x16x32_bf16 v[10:13], v[212:215], v[188:191], v[10:13]
	v_mfma_f32_16x16x32_bf16 v[6:9], v[204:207], v[196:199], v[6:9]
	v_mfma_f32_16x16x32_bf16 v[2:5], v[212:215], v[196:199], v[2:5]
	v_mfma_f32_16x16x32_bf16 v[32:35], v[208:211], v[176:179], v[32:35]
	v_mfma_f32_16x16x32_bf16 v[28:31], v[216:219], v[176:179], v[28:31]
	v_mfma_f32_16x16x32_bf16 v[22:25], v[208:211], v[184:187], v[22:25]
	v_mfma_f32_16x16x32_bf16 v[18:21], v[216:219], v[184:187], v[18:21]
	v_mfma_f32_16x16x32_bf16 v[14:17], v[208:211], v[192:195], v[14:17]
	v_mfma_f32_16x16x32_bf16 v[10:13], v[216:219], v[192:195], v[10:13]
	v_mfma_f32_16x16x32_bf16 v[6:9], v[208:211], v[200:203], v[6:9]
	v_mfma_f32_16x16x32_bf16 v[2:5], v[216:219], v[200:203], v[2:5]
	s_barrier
	s_setprio 0
	s_add_i32 s26, 0, 0x18000
	s_add_u32 s0, s34, 0xb0000
	s_addc_u32 s1, s35, 0
	s_mov_b32 m0, s55
	ds_read_b128 v[172:175], v224 offset:32768
	ds_read_b128 v[176:179], v224 offset:33792
	ds_read_b128 v[180:183], v224 offset:34816
	ds_read_b128 v[184:187], v224 offset:35840
	ds_read_b128 v[188:191], v224 offset:36864
	ds_read_b128 v[192:195], v224 offset:37888
	ds_read_b128 v[196:199], v224 offset:38912
	ds_read_b128 v[200:203], v224 offset:39936
	global_load_lds_dwordx4 v140, s[0:1]
	s_mov_b32 m0, s56
	s_nop 0
	global_load_lds_dwordx4 v142, s[0:1]
	s_waitcnt vmcnt(10) lgkmcnt(8)
	s_setprio 1
	s_barrier
	s_waitcnt lgkmcnt(0)
	v_mfma_f32_16x16x32_bf16 v[128:131], v[132:135], v[172:175], v[128:131]
	v_mfma_f32_16x16x32_bf16 v[124:127], v[156:159], v[172:175], v[124:127]
	v_mfma_f32_16x16x32_bf16 v[120:123], v[132:135], v[180:183], v[120:123]
	v_mfma_f32_16x16x32_bf16 v[116:119], v[156:159], v[180:183], v[116:119]
	v_mfma_f32_16x16x32_bf16 v[112:115], v[132:135], v[188:191], v[112:115]
	v_mfma_f32_16x16x32_bf16 v[108:111], v[156:159], v[188:191], v[108:111]
	v_mfma_f32_16x16x32_bf16 v[104:107], v[132:135], v[196:199], v[104:107]
	v_mfma_f32_16x16x32_bf16 v[100:103], v[156:159], v[196:199], v[100:103]
	v_mfma_f32_16x16x32_bf16 v[128:131], v[136:139], v[176:179], v[128:131]
	v_mfma_f32_16x16x32_bf16 v[124:127], v[160:163], v[176:179], v[124:127]
	v_mfma_f32_16x16x32_bf16 v[120:123], v[136:139], v[184:187], v[120:123]
	v_mfma_f32_16x16x32_bf16 v[116:119], v[160:163], v[184:187], v[116:119]
	v_mfma_f32_16x16x32_bf16 v[112:115], v[136:139], v[192:195], v[112:115]
	v_mfma_f32_16x16x32_bf16 v[108:111], v[160:163], v[192:195], v[108:111]
	v_mfma_f32_16x16x32_bf16 v[104:107], v[136:139], v[200:203], v[104:107]
	v_mfma_f32_16x16x32_bf16 v[100:103], v[160:163], v[200:203], v[100:103]
	s_barrier
	s_setprio 0
	s_add_i32 s27, 0, 0x1c000
	s_add_i32 s0, s26, s17
	v_add_u32_e32 v216, s27, v222
	v_lshl_add_u64 v[164:165], v[164:165], 0, s[12:13]
	s_mov_b32 m0, s0
	ds_read_b128 v[204:207], v216
	ds_read_b128 v[208:211], v216 offset:1024
	ds_read_b128 v[212:215], v216 offset:2048
	ds_read_b128 v[216:219], v216 offset:3072
	global_load_lds_dwordx4 v[164:165], off
	v_lshl_add_u64 v[164:165], v[166:167], 0, s[12:13]
	s_add_i32 m0, s0, 0x2000
	s_nop 0
	global_load_lds_dwordx4 v[164:165], off
	s_waitcnt vmcnt(10)
	s_setprio 1
	s_barrier
	s_waitcnt lgkmcnt(0)
	v_mfma_f32_16x16x32_bf16 v[64:67], v[204:207], v[172:175], v[64:67]
	v_mfma_f32_16x16x32_bf16 v[60:63], v[212:215], v[172:175], v[60:63]
	v_mfma_f32_16x16x32_bf16 v[56:59], v[204:207], v[180:183], v[56:59]
	v_mfma_f32_16x16x32_bf16 v[52:55], v[212:215], v[180:183], v[52:55]
	v_mfma_f32_16x16x32_bf16 v[48:51], v[204:207], v[188:191], v[48:51]
	v_mfma_f32_16x16x32_bf16 v[44:47], v[212:215], v[188:191], v[44:47]
	v_mfma_f32_16x16x32_bf16 v[40:43], v[204:207], v[196:199], v[40:43]
	v_mfma_f32_16x16x32_bf16 v[36:39], v[212:215], v[196:199], v[36:39]
	v_mfma_f32_16x16x32_bf16 v[64:67], v[208:211], v[176:179], v[64:67]
	v_mfma_f32_16x16x32_bf16 v[60:63], v[216:219], v[176:179], v[60:63]
	v_mfma_f32_16x16x32_bf16 v[56:59], v[208:211], v[184:187], v[56:59]
	v_mfma_f32_16x16x32_bf16 v[52:55], v[216:219], v[184:187], v[52:55]
	v_mfma_f32_16x16x32_bf16 v[48:51], v[208:211], v[192:195], v[48:51]
	v_mfma_f32_16x16x32_bf16 v[44:47], v[216:219], v[192:195], v[44:47]
	v_mfma_f32_16x16x32_bf16 v[40:43], v[208:211], v[200:203], v[40:43]
	v_mfma_f32_16x16x32_bf16 v[36:39], v[216:219], v[200:203], v[36:39]
	s_barrier
	s_setprio 0
	s_mov_b32 m0, s59
	v_lshl_add_u64 v[164:165], v[168:169], 0, s[12:13]
	ds_read_b128 v[172:175], v224 offset:49152
	ds_read_b128 v[176:179], v224 offset:50176
	ds_read_b128 v[180:183], v224 offset:51200
	ds_read_b128 v[184:187], v224 offset:52224
	ds_read_b128 v[188:191], v224 offset:53248
	ds_read_b128 v[192:195], v224 offset:54272
	ds_read_b128 v[196:199], v224 offset:55296
	ds_read_b128 v[200:203], v224 offset:56320
	global_load_lds_dwordx4 v[164:165], off
	v_lshl_add_u64 v[164:165], v[220:221], 0, s[12:13]
	s_mov_b32 m0, s68
	s_nop 0
	global_load_lds_dwordx4 v[164:165], off
	s_waitcnt vmcnt(10)
	s_setprio 1
	s_barrier
	s_waitcnt lgkmcnt(0)
	v_mfma_f32_16x16x32_bf16 v[96:99], v[132:135], v[172:175], v[96:99]
	v_mfma_f32_16x16x32_bf16 v[92:95], v[156:159], v[172:175], v[92:95]
	v_mfma_f32_16x16x32_bf16 v[88:91], v[132:135], v[180:183], v[88:91]
	v_mfma_f32_16x16x32_bf16 v[84:87], v[156:159], v[180:183], v[84:87]
	v_mfma_f32_16x16x32_bf16 v[80:83], v[132:135], v[188:191], v[80:83]
	v_mfma_f32_16x16x32_bf16 v[76:79], v[156:159], v[188:191], v[76:79]
	v_mfma_f32_16x16x32_bf16 v[72:75], v[132:135], v[196:199], v[72:75]
	v_mfma_f32_16x16x32_bf16 v[68:71], v[156:159], v[196:199], v[68:71]
	v_mfma_f32_16x16x32_bf16 v[96:99], v[136:139], v[176:179], v[96:99]
	v_mfma_f32_16x16x32_bf16 v[92:95], v[160:163], v[176:179], v[92:95]
	v_mfma_f32_16x16x32_bf16 v[88:91], v[136:139], v[184:187], v[88:91]
	v_mfma_f32_16x16x32_bf16 v[84:87], v[160:163], v[184:187], v[84:87]
	v_mfma_f32_16x16x32_bf16 v[80:83], v[136:139], v[192:195], v[80:83]
	v_mfma_f32_16x16x32_bf16 v[76:79], v[160:163], v[192:195], v[76:79]
	v_mfma_f32_16x16x32_bf16 v[72:75], v[136:139], v[200:203], v[72:75]
	v_mfma_f32_16x16x32_bf16 v[68:71], v[160:163], v[200:203], v[68:71]
	s_barrier
	s_setprio 0
	s_add_u32 s0, s30, 0xb0080
	s_addc_u32 s1, s31, 0
	s_add_i32 s26, s27, s17
	s_mov_b32 m0, s26
	s_nop 0
	global_load_lds_dwordx4 v26, s[0:1]
	s_add_i32 m0, s26, 0x2000
	s_nop 0
	global_load_lds_dwordx4 v144, s[0:1]
	v_add_u32_e32 v160, 0x10000, v222
	ds_read_b128 v[132:135], v160
	ds_read_b128 v[136:139], v160 offset:1024
	ds_read_b128 v[156:159], v160 offset:2048
	ds_read_b128 v[160:163], v160 offset:3072
	s_waitcnt vmcnt(10)
	s_setprio 1
	s_barrier
	v_mfma_f32_16x16x32_bf16 v[32:35], v[204:207], v[172:175], v[32:35]
	v_mfma_f32_16x16x32_bf16 v[28:31], v[212:215], v[172:175], v[28:31]
	v_mfma_f32_16x16x32_bf16 v[22:25], v[204:207], v[180:183], v[22:25]
	v_mfma_f32_16x16x32_bf16 v[18:21], v[212:215], v[180:183], v[18:21]
	v_mfma_f32_16x16x32_bf16 v[14:17], v[204:207], v[188:191], v[14:17]
	v_mfma_f32_16x16x32_bf16 v[10:13], v[212:215], v[188:191], v[10:13]
	v_mfma_f32_16x16x32_bf16 v[6:9], v[204:207], v[196:199], v[6:9]
	v_mfma_f32_16x16x32_bf16 v[2:5], v[212:215], v[196:199], v[2:5]
	v_mfma_f32_16x16x32_bf16 v[32:35], v[208:211], v[176:179], v[32:35]
	v_mfma_f32_16x16x32_bf16 v[28:31], v[216:219], v[176:179], v[28:31]
	v_mfma_f32_16x16x32_bf16 v[22:25], v[208:211], v[184:187], v[22:25]
	v_mfma_f32_16x16x32_bf16 v[18:21], v[216:219], v[184:187], v[18:21]
	v_mfma_f32_16x16x32_bf16 v[14:17], v[208:211], v[192:195], v[14:17]
	v_mfma_f32_16x16x32_bf16 v[10:13], v[216:219], v[192:195], v[10:13]
	v_mfma_f32_16x16x32_bf16 v[6:9], v[208:211], v[200:203], v[6:9]
	v_mfma_f32_16x16x32_bf16 v[2:5], v[216:219], v[200:203], v[2:5]
	s_barrier
	s_setprio 0
	s_add_i32 s81, s81, 2
	s_add_u32 s44, s44, 0x100
	s_addc_u32 s45, s45, 0
	s_cmp_gt_u32 s81, 41
	s_mov_b64 s[26:27], s[28:29]
	s_cbranch_scc0 .LBB0_1156
	s_waitcnt lgkmcnt(0)
	s_min_i32 s0, s24, 0x100
	s_ashr_i32 s0, s0, 5
	s_ashr_i32 s1, s0, 31
	s_add_i32 s26, s24, 0xffffff00
	s_cmpk_lt_i32 s24, 0x100
	s_cselect_b32 s26, s24, s26
	s_cselect_b32 s28, 0, s51
	s_cselect_b32 s29, 0, s50
	s_ashr_i32 s27, s26, 31
	s_lshl_b64 s[26:27], s[26:27], 19
	v_lshl_add_u64 v[132:133], s[26:27], 0, v[146:147]
	s_add_u32 s26, s20, s29
	v_lshl_or_b32 v166, s25, 8, v223
	s_addc_u32 s27, s21, s28
	s_ashr_i32 s25, s24, 31
	s_lshl_b64 s[28:29], s[24:25], 19
	v_lshl_add_u64 v[178:179], v[148:149], 0, s[28:29]
	s_lshl_b64 s[24:25], s[24:25], 10
	s_mul_i32 s28, s0, 0x9000
	v_ashrrev_i32_e32 v167, 31, v166
	s_mul_hi_i32 s29, s0, 0x9000
	s_add_u32 s28, s36, s28
	s_addc_u32 s29, s37, s29
	v_lshlrev_b64 v[180:181], 2, v[166:167]
	v_lshl_add_u64 v[156:157], s[28:29], 0, v[180:181]
	v_lshl_add_u64 v[168:169], v[132:133], 0, v[166:167]
	v_lshl_add_u64 v[182:183], v[132:133], 1, s[26:27]
	global_load_dwordx4 v[132:135], v[156:157], off offset:16
	global_load_dwordx4 v[136:139], v[156:157], off
	s_lshl_b64 s[0:1], s[0:1], 12
	s_add_u32 s28, s57, s0
	s_addc_u32 s29, s58, s1
	v_lshl_add_u64 v[180:181], s[28:29], 0, v[180:181]
	v_lshl_add_u64 v[196:197], v[168:169], 1, s[26:27]
	v_add_co_u32_e32 v210, vcc, s65, v196
	s_mov_b32 s1, 0x20000
	s_nop 0
	v_addc_co_u32_e32 v211, vcc, 0, v197, vcc
	v_add_co_u32_e32 v184, vcc, s1, v196
	s_mov_b32 s26, 0x30000
	s_nop 0
	v_addc_co_u32_e32 v185, vcc, 0, v197, vcc
	v_add_co_u32_e32 v188, vcc, s26, v196
	v_lshlrev_b64 v[166:167], 1, v[166:167]
	s_nop 0
	v_addc_co_u32_e32 v189, vcc, 0, v197, vcc
	v_lshl_add_u64 v[178:179], v[178:179], 0, v[166:167]
	v_lshl_add_u64 v[182:183], v[182:183], 0, v[166:167]
	s_mov_b32 s0, 0x8000
	s_mov_b32 s27, 0x80000
	s_mov_b32 s28, 0x90000
	s_waitcnt vmcnt(0)
	v_pk_mul_f32 v[172:173], v[134:135], 0.5 op_sel_hi:[1,0]
	v_pk_mul_f32 v[176:177], v[138:139], 0.5 op_sel_hi:[1,0]
	v_pk_mul_f32 v[174:175], v[136:137], 0.5 op_sel_hi:[1,0]
	v_pk_mul_f32 v[164:165], v[132:133], 0.5 op_sel_hi:[1,0]
	global_load_dwordx4 v[132:135], v[156:157], off offset:528
	global_load_dwordx4 v[136:139], v[156:157], off offset:512
	s_waitcnt vmcnt(0)
	v_pk_mul_f32 v[158:159], v[134:135], 0.5 op_sel_hi:[1,0]
	v_pk_mul_f32 v[162:163], v[138:139], 0.5 op_sel_hi:[1,0]
	v_pk_mul_f32 v[160:161], v[136:137], 0.5 op_sel_hi:[1,0]
	v_pk_mul_f32 v[156:157], v[132:133], 0.5 op_sel_hi:[1,0]
	global_load_dwordx4 v[132:135], v[180:181], off offset:16
	global_load_dwordx4 v[136:139], v[180:181], off
	global_load_dwordx4 v[190:193], v[196:197], off offset:2048
	global_load_dwordx4 v[198:201], v[210:211], off offset:2048
	global_load_dwordx4 v[202:205], v[184:185], off offset:2048
	global_load_dwordx4 v[206:209], v[188:189], off offset:2048
	s_waitcnt vmcnt(0)
	v_lshlrev_b32_e32 v166, 16, v190
	v_and_b32_e32 v167, 0xffff0000, v190
	v_lshlrev_b32_e32 v168, 16, v191
	v_and_b32_e32 v169, 0xffff0000, v191
	v_lshlrev_b32_e32 v186, 16, v192
	v_and_b32_e32 v187, 0xffff0000, v192
	v_lshlrev_b32_e32 v190, 16, v193
	v_and_b32_e32 v191, 0xffff0000, v193
	v_pk_fma_f32 v[130:131], v[130:131], v[176:177], v[168:169]
	v_pk_fma_f32 v[128:129], v[128:129], v[174:175], v[166:167]
	v_pk_fma_f32 v[126:127], v[126:127], v[172:173], v[190:191]
	v_pk_fma_f32 v[124:125], v[124:125], v[164:165], v[186:187]
	v_cvt_pk_bf16_f32 v190, v128, v129
	v_cvt_pk_bf16_f32 v191, v130, v131
	v_cvt_pk_bf16_f32 v192, v124, v125
	v_cvt_pk_bf16_f32 v193, v126, v127
	v_lshlrev_b32_e32 v130, 16, v190
	v_and_b32_e32 v131, 0xffff0000, v190
	v_lshlrev_b32_e32 v128, 16, v191
	v_and_b32_e32 v129, 0xffff0000, v191
	v_lshlrev_b32_e32 v126, 16, v192
	v_and_b32_e32 v127, 0xffff0000, v192
	v_lshlrev_b32_e32 v124, 16, v193
	v_and_b32_e32 v125, 0xffff0000, v193
	v_lshlrev_b32_e32 v212, 16, v200
	v_and_b32_e32 v213, 0xffff0000, v200
	v_lshlrev_b32_e32 v200, 16, v201
	v_and_b32_e32 v201, 0xffff0000, v201
	global_store_dwordx4 v[182:183], v[190:193], off offset:2048
	v_pk_mul_f32 v[166:167], v[138:139], v[128:129]
	v_pk_mul_f32 v[168:169], v[136:137], v[130:131]
	v_pk_mul_f32 v[186:187], v[134:135], v[124:125]
	v_pk_mul_f32 v[192:193], v[132:133], v[126:127]
	v_lshlrev_b32_e32 v194, 16, v198
	v_and_b32_e32 v195, 0xffff0000, v198
	v_lshlrev_b32_e32 v198, 16, v199
	v_and_b32_e32 v199, 0xffff0000, v199
	v_cvt_pk_bf16_f32 v190, v168, v169
	v_cvt_pk_bf16_f32 v191, v166, v167
	v_cvt_pk_bf16_f32 v192, v192, v193
	v_cvt_pk_bf16_f32 v193, v186, v187
	v_pk_fma_f32 v[118:119], v[118:119], v[172:173], v[200:201]
	v_pk_fma_f32 v[116:117], v[116:117], v[164:165], v[212:213]
	global_store_dwordx4 v[178:179], v[190:193], off
	v_pk_fma_f32 v[122:123], v[122:123], v[176:177], v[198:199]
	v_pk_fma_f32 v[120:121], v[120:121], v[174:175], v[194:195]
	v_cvt_pk_bf16_f32 v192, v116, v117
	v_cvt_pk_bf16_f32 v193, v118, v119
	v_add_co_u32_e32 v186, vcc, s65, v182
	v_cvt_pk_bf16_f32 v190, v120, v121
	v_cvt_pk_bf16_f32 v191, v122, v123
	v_addc_co_u32_e32 v187, vcc, 0, v183, vcc
	v_lshlrev_b32_e32 v118, 16, v192
	v_and_b32_e32 v119, 0xffff0000, v192
	v_lshlrev_b32_e32 v116, 16, v193
	v_and_b32_e32 v117, 0xffff0000, v193
	global_store_dwordx4 v[186:187], v[190:193], off offset:2048
	v_lshlrev_b32_e32 v122, 16, v190
	v_and_b32_e32 v123, 0xffff0000, v190
	v_lshlrev_b32_e32 v120, 16, v191
	v_and_b32_e32 v121, 0xffff0000, v191
	v_pk_mul_f32 v[190:191], v[134:135], v[116:117]
	v_pk_mul_f32 v[194:195], v[132:133], v[118:119]
	v_pk_mul_f32 v[166:167], v[138:139], v[120:121]
	v_pk_mul_f32 v[168:169], v[136:137], v[122:123]
	v_cvt_pk_bf16_f32 v194, v194, v195
	v_cvt_pk_bf16_f32 v195, v190, v191
	v_add_co_u32_e32 v190, vcc, s0, v178
	v_cvt_pk_bf16_f32 v192, v168, v169
	v_cvt_pk_bf16_f32 v193, v166, v167
	v_addc_co_u32_e32 v191, vcc, 0, v179, vcc
	global_store_dwordx4 v[190:191], v[192:195], off
	v_lshlrev_b32_e32 v198, 16, v204
	v_and_b32_e32 v199, 0xffff0000, v204
	v_add_co_u32_e32 v192, vcc, s27, v196
	v_lshlrev_b32_e32 v200, 16, v205
	s_nop 0
	v_addc_co_u32_e32 v193, vcc, 0, v197, vcc
	v_add_co_u32_e32 v194, vcc, s28, v196
	v_and_b32_e32 v201, 0xffff0000, v205
	global_load_dwordx4 v[212:215], v[192:193], off offset:2048
	v_addc_co_u32_e32 v195, vcc, 0, v197, vcc
	v_lshlrev_b32_e32 v166, 16, v202
	v_and_b32_e32 v167, 0xffff0000, v202
	v_lshlrev_b32_e32 v168, 16, v203
	v_and_b32_e32 v169, 0xffff0000, v203
	v_pk_fma_f32 v[110:111], v[110:111], v[172:173], v[200:201]
	v_pk_fma_f32 v[108:109], v[108:109], v[164:165], v[198:199]
	v_pk_fma_f32 v[114:115], v[114:115], v[176:177], v[168:169]
	v_pk_fma_f32 v[112:113], v[112:113], v[174:175], v[166:167]
	v_cvt_pk_bf16_f32 v202, v108, v109
	v_cvt_pk_bf16_f32 v203, v110, v111
	v_add_co_u32_e32 v198, vcc, s1, v182
	global_load_dwordx4 v[216:219], v[194:195], off offset:2048
	v_cvt_pk_bf16_f32 v200, v112, v113
	v_cvt_pk_bf16_f32 v201, v114, v115
	v_addc_co_u32_e32 v199, vcc, 0, v183, vcc
	v_lshlrev_b32_e32 v110, 16, v202
	v_and_b32_e32 v111, 0xffff0000, v202
	v_lshlrev_b32_e32 v108, 16, v203
	v_and_b32_e32 v109, 0xffff0000, v203
	global_store_dwordx4 v[198:199], v[200:203], off offset:2048
	v_lshlrev_b32_e32 v114, 16, v200
	v_and_b32_e32 v115, 0xffff0000, v200
	v_lshlrev_b32_e32 v112, 16, v201
	v_and_b32_e32 v113, 0xffff0000, v201
	v_pk_mul_f32 v[200:201], v[134:135], v[108:109]
	v_pk_mul_f32 v[204:205], v[132:133], v[110:111]
	v_lshlrev_b32_e32 v234, 16, v208
	v_and_b32_e32 v235, 0xffff0000, v208
	v_lshlrev_b32_e32 v208, 16, v209
	v_and_b32_e32 v209, 0xffff0000, v209
	v_pk_mul_f32 v[166:167], v[138:139], v[112:113]
	v_pk_mul_f32 v[168:169], v[136:137], v[114:115]
	v_cvt_pk_bf16_f32 v204, v204, v205
	v_cvt_pk_bf16_f32 v205, v200, v201
	v_add_co_u32_e32 v200, vcc, s65, v178
	v_lshlrev_b32_e32 v220, 16, v206
	v_and_b32_e32 v221, 0xffff0000, v206
	v_lshlrev_b32_e32 v206, 16, v207
	v_and_b32_e32 v207, 0xffff0000, v207
	v_cvt_pk_bf16_f32 v202, v168, v169
	v_cvt_pk_bf16_f32 v203, v166, v167
	v_addc_co_u32_e32 v201, vcc, 0, v179, vcc
	v_pk_fma_f32 v[102:103], v[102:103], v[172:173], v[208:209]
	v_pk_fma_f32 v[100:101], v[100:101], v[164:165], v[234:235]
	global_store_dwordx4 v[200:201], v[202:205], off
	v_pk_fma_f32 v[106:107], v[106:107], v[176:177], v[206:207]
	v_pk_fma_f32 v[104:105], v[104:105], v[174:175], v[220:221]
	v_cvt_pk_bf16_f32 v206, v100, v101
	v_cvt_pk_bf16_f32 v207, v102, v103
	v_add_co_u32_e32 v202, vcc, s26, v182
	v_cvt_pk_bf16_f32 v204, v104, v105
	v_cvt_pk_bf16_f32 v205, v106, v107
	v_addc_co_u32_e32 v203, vcc, 0, v183, vcc
	v_lshlrev_b32_e32 v102, 16, v206
	v_and_b32_e32 v103, 0xffff0000, v206
	v_lshlrev_b32_e32 v100, 16, v207
	v_and_b32_e32 v101, 0xffff0000, v207
	global_store_dwordx4 v[202:203], v[204:207], off offset:2048
	v_lshlrev_b32_e32 v106, 16, v204
	v_and_b32_e32 v107, 0xffff0000, v204
	v_lshlrev_b32_e32 v104, 16, v205
	v_and_b32_e32 v105, 0xffff0000, v205
	v_pk_mul_f32 v[204:205], v[134:135], v[100:101]
	v_pk_mul_f32 v[208:209], v[132:133], v[102:103]
	s_mov_b32 s0, 0x18000
	v_pk_mul_f32 v[166:167], v[138:139], v[104:105]
	v_pk_mul_f32 v[168:169], v[136:137], v[106:107]
	v_cvt_pk_bf16_f32 v208, v208, v209
	v_cvt_pk_bf16_f32 v209, v204, v205
	v_add_co_u32_e32 v204, vcc, s0, v178
	v_cvt_pk_bf16_f32 v206, v168, v169
	v_cvt_pk_bf16_f32 v207, v166, v167
	v_addc_co_u32_e32 v205, vcc, 0, v179, vcc
	global_store_dwordx4 v[204:205], v[206:209], off
	s_mov_b32 s0, 0xb0000
	s_waitcnt vmcnt(0)
	v_lshlrev_b32_e32 v166, 16, v212
	v_add_co_u32_e32 v206, vcc, s76, v196
	v_and_b32_e32 v167, 0xffff0000, v212
	s_nop 0
	v_addc_co_u32_e32 v207, vcc, 0, v197, vcc
	global_load_dwordx4 v[238:241], v[206:207], off offset:2048
	v_add_co_u32_e32 v208, vcc, s0, v196
	v_lshlrev_b32_e32 v168, 16, v213
	s_nop 0
	v_addc_co_u32_e32 v209, vcc, 0, v197, vcc
	global_load_dwordx4 v[242:245], v[208:209], off offset:2048
	v_and_b32_e32 v169, 0xffff0000, v213
	v_lshlrev_b32_e32 v212, 16, v214
	v_and_b32_e32 v213, 0xffff0000, v214
	v_lshlrev_b32_e32 v214, 16, v215
	v_and_b32_e32 v215, 0xffff0000, v215
	v_pk_fma_f32 v[94:95], v[94:95], v[172:173], v[214:215]
	v_pk_fma_f32 v[92:93], v[92:93], v[164:165], v[212:213]
	v_lshlrev_b32_e32 v220, 16, v216
	v_and_b32_e32 v221, 0xffff0000, v216
	v_lshlrev_b32_e32 v234, 16, v217
	v_and_b32_e32 v235, 0xffff0000, v217
	v_pk_fma_f32 v[98:99], v[98:99], v[176:177], v[168:169]
	v_pk_fma_f32 v[96:97], v[96:97], v[174:175], v[166:167]
	v_cvt_pk_bf16_f32 v216, v92, v93
	v_cvt_pk_bf16_f32 v217, v94, v95
	v_add_co_u32_e32 v212, vcc, s27, v182
	v_cvt_pk_bf16_f32 v214, v96, v97
	v_cvt_pk_bf16_f32 v215, v98, v99
	v_addc_co_u32_e32 v213, vcc, 0, v183, vcc
	v_lshlrev_b32_e32 v94, 16, v216
	v_and_b32_e32 v95, 0xffff0000, v216
	v_lshlrev_b32_e32 v92, 16, v217
	v_and_b32_e32 v93, 0xffff0000, v217
	v_lshlrev_b32_e32 v246, 16, v218
	v_and_b32_e32 v247, 0xffff0000, v218
	v_lshlrev_b32_e32 v248, 16, v219
	v_and_b32_e32 v249, 0xffff0000, v219
	global_store_dwordx4 v[212:213], v[214:217], off offset:2048
	v_lshlrev_b32_e32 v98, 16, v214
	v_and_b32_e32 v99, 0xffff0000, v214
	v_lshlrev_b32_e32 v96, 16, v215
	v_and_b32_e32 v97, 0xffff0000, v215
	v_pk_mul_f32 v[214:215], v[134:135], v[92:93]
	v_pk_mul_f32 v[218:219], v[132:133], v[94:95]
	s_mov_b32 s1, 0x40000
	v_pk_mul_f32 v[166:167], v[138:139], v[96:97]
	v_pk_mul_f32 v[168:169], v[136:137], v[98:99]
	v_cvt_pk_bf16_f32 v218, v218, v219
	v_cvt_pk_bf16_f32 v219, v214, v215
	v_add_co_u32_e32 v214, vcc, s1, v178
	v_cvt_pk_bf16_f32 v216, v168, v169
	v_cvt_pk_bf16_f32 v217, v166, v167
	v_addc_co_u32_e32 v215, vcc, 0, v179, vcc
	v_pk_fma_f32 v[86:87], v[86:87], v[172:173], v[248:249]
	global_store_dwordx4 v[214:215], v[216:219], off
	v_pk_fma_f32 v[90:91], v[90:91], v[176:177], v[234:235]
	v_pk_fma_f32 v[88:89], v[88:89], v[174:175], v[220:221]
	v_pk_fma_f32 v[84:85], v[84:85], v[164:165], v[246:247]
	v_cvt_pk_bf16_f32 v221, v86, v87
	v_add_co_u32_e32 v216, vcc, s28, v182
	v_cvt_pk_bf16_f32 v218, v88, v89
	v_cvt_pk_bf16_f32 v219, v90, v91
	v_cvt_pk_bf16_f32 v220, v84, v85
	v_addc_co_u32_e32 v217, vcc, 0, v183, vcc
	v_lshlrev_b32_e32 v84, 16, v221
	v_and_b32_e32 v85, 0xffff0000, v221
	global_store_dwordx4 v[216:217], v[218:221], off offset:2048
	v_lshlrev_b32_e32 v90, 16, v218
	v_and_b32_e32 v91, 0xffff0000, v218
	v_lshlrev_b32_e32 v88, 16, v219
	v_and_b32_e32 v89, 0xffff0000, v219
	v_lshlrev_b32_e32 v86, 16, v220
	v_and_b32_e32 v87, 0xffff0000, v220
	v_pk_mul_f32 v[218:219], v[134:135], v[84:85]
	s_mov_b32 s1, 0x48000
	v_pk_mul_f32 v[166:167], v[138:139], v[88:89]
	v_pk_mul_f32 v[168:169], v[136:137], v[90:91]
	v_pk_mul_f32 v[220:221], v[132:133], v[86:87]
	v_cvt_pk_bf16_f32 v249, v218, v219
	v_add_co_u32_e32 v218, vcc, s1, v178
	v_cvt_pk_bf16_f32 v246, v168, v169
	v_cvt_pk_bf16_f32 v247, v166, v167
	v_cvt_pk_bf16_f32 v248, v220, v221
	v_addc_co_u32_e32 v219, vcc, 0, v179, vcc
	global_store_dwordx4 v[218:219], v[246:249], off
	global_load_dwordx4 v[246:249], v[196:197], off offset:2304
	s_nop 0
	global_load_dwordx4 v[250:253], v[210:211], off offset:2304
	s_waitcnt vmcnt(0)
	v_lshlrev_b32_e32 v196, 16, v240
	v_and_b32_e32 v197, 0xffff0000, v240
	v_lshlrev_b32_e32 v210, 16, v241
	v_and_b32_e32 v211, 0xffff0000, v241
	v_lshlrev_b32_e32 v166, 16, v238
	v_and_b32_e32 v167, 0xffff0000, v238
	v_lshlrev_b32_e32 v168, 16, v239
	v_and_b32_e32 v169, 0xffff0000, v239
	v_pk_fma_f32 v[78:79], v[78:79], v[172:173], v[210:211]
	v_pk_fma_f32 v[76:77], v[76:77], v[164:165], v[196:197]
	v_pk_fma_f32 v[82:83], v[82:83], v[176:177], v[168:169]
	v_pk_fma_f32 v[80:81], v[80:81], v[174:175], v[166:167]
	v_cvt_pk_bf16_f32 v240, v76, v77
	v_cvt_pk_bf16_f32 v241, v78, v79
	v_add_co_u32_e32 v196, vcc, s76, v182
	v_cvt_pk_bf16_f32 v238, v80, v81
	v_cvt_pk_bf16_f32 v239, v82, v83
	v_addc_co_u32_e32 v197, vcc, 0, v183, vcc
	v_lshlrev_b32_e32 v78, 16, v240
	v_and_b32_e32 v79, 0xffff0000, v240
	v_lshlrev_b32_e32 v76, 16, v241
	v_and_b32_e32 v77, 0xffff0000, v241
	global_store_dwordx4 v[196:197], v[238:241], off offset:2048
	v_lshlrev_b32_e32 v80, 16, v239
	v_and_b32_e32 v81, 0xffff0000, v239
	v_pk_mul_f32 v[210:211], v[134:135], v[76:77]
	v_pk_mul_f32 v[240:241], v[132:133], v[78:79]
	v_lshlrev_b32_e32 v220, 16, v242
	v_and_b32_e32 v221, 0xffff0000, v242
	v_lshlrev_b32_e32 v234, 16, v243
	v_and_b32_e32 v235, 0xffff0000, v243
	v_lshlrev_b32_e32 v242, 16, v244
	v_and_b32_e32 v243, 0xffff0000, v244
	v_lshlrev_b32_e32 v244, 16, v245
	v_and_b32_e32 v245, 0xffff0000, v245
	v_pk_mul_f32 v[166:167], v[138:139], v[80:81]
	v_cvt_pk_bf16_f32 v240, v240, v241
	v_cvt_pk_bf16_f32 v241, v210, v211
	v_add_co_u32_e32 v210, vcc, s77, v178
	v_lshlrev_b32_e32 v82, 16, v238
	v_and_b32_e32 v83, 0xffff0000, v238
	v_cvt_pk_bf16_f32 v239, v166, v167
	v_addc_co_u32_e32 v211, vcc, 0, v179, vcc
	v_pk_fma_f32 v[74:75], v[74:75], v[176:177], v[234:235]
	v_pk_fma_f32 v[72:73], v[72:73], v[174:175], v[220:221]
	v_pk_fma_f32 v[166:167], v[70:71], v[172:173], v[244:245]
	v_pk_fma_f32 v[70:71], v[68:69], v[164:165], v[242:243]
	v_pk_mul_f32 v[168:169], v[136:137], v[82:83]
	v_cvt_pk_bf16_f32 v68, v72, v73
	v_cvt_pk_bf16_f32 v69, v74, v75
	v_cvt_pk_bf16_f32 v70, v70, v71
	v_cvt_pk_bf16_f32 v71, v166, v167
	v_add_co_u32_e32 v220, vcc, s0, v182
	v_cvt_pk_bf16_f32 v238, v168, v169
	s_nop 0
	v_addc_co_u32_e32 v221, vcc, 0, v183, vcc
	v_lshlrev_b32_e32 v176, 16, v68
	v_and_b32_e32 v177, 0xffff0000, v68
	v_lshlrev_b32_e32 v174, 16, v69
	v_and_b32_e32 v175, 0xffff0000, v69
	v_lshlrev_b32_e32 v172, 16, v70
	v_and_b32_e32 v173, 0xffff0000, v70
	v_lshlrev_b32_e32 v164, 16, v71
	v_and_b32_e32 v165, 0xffff0000, v71
	s_mov_b32 s0, 0x58000
	global_store_dwordx4 v[210:211], v[238:241], off
	global_store_dwordx4 v[220:221], v[68:71], off offset:2048
	v_pk_mul_f32 v[72:73], v[134:135], v[164:165]
	v_pk_mul_f32 v[74:75], v[132:133], v[172:173]
	v_pk_mul_f32 v[70:71], v[138:139], v[174:175]
	v_pk_mul_f32 v[68:69], v[136:137], v[176:177]
	v_add_co_u32_e32 v132, vcc, s0, v178
	v_cvt_pk_bf16_f32 v68, v68, v69
	v_cvt_pk_bf16_f32 v69, v70, v71
	v_cvt_pk_bf16_f32 v70, v74, v75
	v_cvt_pk_bf16_f32 v71, v72, v73
	v_addc_co_u32_e32 v133, vcc, 0, v179, vcc
	global_store_dwordx4 v[132:133], v[68:71], off
	global_load_dwordx4 v[134:137], v[184:185], off offset:2304
	global_load_dwordx4 v[238:241], v[188:189], off offset:2304
	s_nop 0
	global_load_dwordx4 v[68:71], v[180:181], off offset:528
	global_load_dwordx4 v[72:75], v[180:181], off offset:512
	v_lshlrev_b32_e32 v138, 16, v246
	v_and_b32_e32 v139, 0xffff0000, v246
	v_lshlrev_b32_e32 v166, 16, v247
	v_and_b32_e32 v167, 0xffff0000, v247
	v_lshlrev_b32_e32 v168, 16, v248
	v_and_b32_e32 v169, 0xffff0000, v248
	v_lshlrev_b32_e32 v180, 16, v249
	v_and_b32_e32 v181, 0xffff0000, v249
	v_pk_fma_f32 v[66:67], v[66:67], v[162:163], v[166:167]
	v_pk_fma_f32 v[64:65], v[64:65], v[160:161], v[138:139]
	v_pk_fma_f32 v[62:63], v[62:63], v[158:159], v[180:181]
	v_pk_fma_f32 v[60:61], v[60:61], v[156:157], v[168:169]
	v_cvt_pk_bf16_f32 v242, v64, v65
	v_cvt_pk_bf16_f32 v243, v66, v67
	v_cvt_pk_bf16_f32 v244, v60, v61
	v_cvt_pk_bf16_f32 v245, v62, v63
	v_lshlrev_b32_e32 v66, 16, v242
	v_and_b32_e32 v67, 0xffff0000, v242
	v_lshlrev_b32_e32 v64, 16, v243
	v_and_b32_e32 v65, 0xffff0000, v243
	v_lshlrev_b32_e32 v62, 16, v244
	v_and_b32_e32 v63, 0xffff0000, v244
	v_lshlrev_b32_e32 v60, 16, v245
	v_and_b32_e32 v61, 0xffff0000, v245
	v_lshlrev_b32_e32 v184, 16, v250
	v_and_b32_e32 v185, 0xffff0000, v250
	v_lshlrev_b32_e32 v188, 16, v251
	v_and_b32_e32 v189, 0xffff0000, v251
	v_lshlrev_b32_e32 v234, 16, v252
	v_and_b32_e32 v235, 0xffff0000, v252
	v_lshlrev_b32_e32 v246, 16, v253
	v_and_b32_e32 v247, 0xffff0000, v253
	global_store_dwordx4 v[182:183], v[242:245], off offset:2304
	v_pk_fma_f32 v[58:59], v[58:59], v[162:163], v[188:189]
	v_pk_fma_f32 v[56:57], v[56:57], v[160:161], v[184:185]
	v_pk_fma_f32 v[54:55], v[54:55], v[158:159], v[246:247]
	v_pk_fma_f32 v[52:53], v[52:53], v[156:157], v[234:235]
	s_waitcnt vmcnt(0)
	v_lshlrev_b32_e32 v188, 16, v240
	v_pk_mul_f32 v[168:169], v[70:71], v[60:61]
	v_pk_mul_f32 v[138:139], v[74:75], v[64:65]
	v_pk_mul_f32 v[166:167], v[72:73], v[66:67]
	v_pk_mul_f32 v[182:183], v[68:69], v[62:63]
	v_cvt_pk_bf16_f32 v180, v166, v167
	v_cvt_pk_bf16_f32 v181, v138, v139
	v_cvt_pk_bf16_f32 v182, v182, v183
	v_cvt_pk_bf16_f32 v183, v168, v169
	global_store_dwordx4 v[178:179], v[180:183], off offset:256
	v_cvt_pk_bf16_f32 v178, v56, v57
	v_cvt_pk_bf16_f32 v179, v58, v59
	v_cvt_pk_bf16_f32 v180, v52, v53
	v_cvt_pk_bf16_f32 v181, v54, v55
	v_lshlrev_b32_e32 v58, 16, v178
	v_and_b32_e32 v59, 0xffff0000, v178
	v_lshlrev_b32_e32 v56, 16, v179
	v_and_b32_e32 v57, 0xffff0000, v179
	v_lshlrev_b32_e32 v54, 16, v180
	v_and_b32_e32 v55, 0xffff0000, v180
	v_lshlrev_b32_e32 v52, 16, v181
	v_and_b32_e32 v53, 0xffff0000, v181
	global_store_dwordx4 v[186:187], v[178:181], off offset:2304
	v_pk_mul_f32 v[138:139], v[74:75], v[56:57]
	v_pk_mul_f32 v[166:167], v[72:73], v[58:59]
	v_pk_mul_f32 v[168:169], v[70:71], v[52:53]
	v_pk_mul_f32 v[180:181], v[68:69], v[54:55]
	v_cvt_pk_bf16_f32 v178, v166, v167
	v_cvt_pk_bf16_f32 v179, v138, v139
	v_cvt_pk_bf16_f32 v180, v180, v181
	v_cvt_pk_bf16_f32 v181, v168, v169
	v_lshlrev_b32_e32 v138, 16, v134
	v_and_b32_e32 v139, 0xffff0000, v134
	v_lshlrev_b32_e32 v134, 16, v135
	v_and_b32_e32 v135, 0xffff0000, v135
	v_lshlrev_b32_e32 v166, 16, v136
	v_and_b32_e32 v167, 0xffff0000, v136
	v_lshlrev_b32_e32 v136, 16, v137
	v_and_b32_e32 v137, 0xffff0000, v137
	global_store_dwordx4 v[190:191], v[178:181], off offset:256
	v_pk_fma_f32 v[50:51], v[50:51], v[162:163], v[134:135]
	v_pk_fma_f32 v[48:49], v[48:49], v[160:161], v[138:139]
	v_pk_fma_f32 v[46:47], v[46:47], v[158:159], v[136:137]
	v_pk_fma_f32 v[44:45], v[44:45], v[156:157], v[166:167]
	global_load_dwordx4 v[178:181], v[192:193], off offset:2304
	global_load_dwordx4 v[182:185], v[194:195], off offset:2304
	v_cvt_pk_bf16_f32 v134, v48, v49
	v_cvt_pk_bf16_f32 v135, v50, v51
	v_cvt_pk_bf16_f32 v136, v44, v45
	v_cvt_pk_bf16_f32 v137, v46, v47
	v_lshlrev_b32_e32 v50, 16, v134
	v_and_b32_e32 v51, 0xffff0000, v134
	v_lshlrev_b32_e32 v48, 16, v135
	v_and_b32_e32 v49, 0xffff0000, v135
	v_lshlrev_b32_e32 v46, 16, v136
	v_and_b32_e32 v47, 0xffff0000, v136
	v_lshlrev_b32_e32 v44, 16, v137
	v_and_b32_e32 v45, 0xffff0000, v137
	v_lshlrev_b32_e32 v168, 16, v238
	v_and_b32_e32 v169, 0xffff0000, v238
	v_lshlrev_b32_e32 v186, 16, v239
	v_and_b32_e32 v187, 0xffff0000, v239
	v_and_b32_e32 v189, 0xffff0000, v240
	v_lshlrev_b32_e32 v190, 16, v241
	v_and_b32_e32 v191, 0xffff0000, v241
	global_store_dwordx4 v[198:199], v[134:137], off offset:2304
	v_pk_mul_f32 v[138:139], v[70:71], v[44:45]
	v_pk_mul_f32 v[166:167], v[68:69], v[46:47]
	v_pk_mul_f32 v[136:137], v[74:75], v[48:49]
	v_pk_mul_f32 v[134:135], v[72:73], v[50:51]
	v_pk_fma_f32 v[42:43], v[42:43], v[162:163], v[186:187]
	v_cvt_pk_bf16_f32 v134, v134, v135
	v_cvt_pk_bf16_f32 v135, v136, v137
	v_cvt_pk_bf16_f32 v136, v166, v167
	v_cvt_pk_bf16_f32 v137, v138, v139
	v_pk_fma_f32 v[40:41], v[40:41], v[160:161], v[168:169]
	v_pk_fma_f32 v[38:39], v[38:39], v[158:159], v[190:191]
	v_pk_fma_f32 v[36:37], v[36:37], v[156:157], v[188:189]
	global_store_dwordx4 v[200:201], v[134:137], off offset:256
	v_mul_f32_e32 v67, v67, v67
	v_mul_f32_e32 v65, v65, v65
	v_cvt_pk_bf16_f32 v134, v40, v41
	v_cvt_pk_bf16_f32 v135, v42, v43
	v_cvt_pk_bf16_f32 v136, v36, v37
	v_cvt_pk_bf16_f32 v137, v38, v39
	v_lshlrev_b32_e32 v42, 16, v134
	v_and_b32_e32 v43, 0xffff0000, v134
	v_lshlrev_b32_e32 v40, 16, v135
	v_and_b32_e32 v41, 0xffff0000, v135
	v_lshlrev_b32_e32 v38, 16, v136
	v_and_b32_e32 v39, 0xffff0000, v136
	v_lshlrev_b32_e32 v36, 16, v137
	v_and_b32_e32 v37, 0xffff0000, v137
	global_store_dwordx4 v[202:203], v[134:137], off offset:2304
	v_pk_mul_f32 v[138:139], v[70:71], v[36:37]
	v_pk_mul_f32 v[166:167], v[68:69], v[38:39]
	v_pk_mul_f32 v[136:137], v[74:75], v[40:41]
	v_pk_mul_f32 v[134:135], v[72:73], v[42:43]
	v_fmac_f32_e32 v67, v66, v66
	v_cvt_pk_bf16_f32 v134, v134, v135
	v_cvt_pk_bf16_f32 v135, v136, v137
	v_cvt_pk_bf16_f32 v136, v166, v167
	v_cvt_pk_bf16_f32 v137, v138, v139
	global_store_dwordx4 v[204:205], v[134:137], off offset:256
	global_load_dwordx4 v[134:137], v[206:207], off offset:2304
	s_nop 0
	global_load_dwordx4 v[186:189], v[208:209], off offset:2304
	v_fmac_f32_e32 v65, v64, v64
	v_mul_f32_e32 v63, v63, v63
	v_mul_f32_e32 v61, v61, v61
	v_add_f32_e32 v64, v67, v65
	v_fmac_f32_e32 v63, v62, v62
	v_fmac_f32_e32 v61, v60, v60
	v_add_f32_e32 v60, v63, v61
	s_waitcnt vmcnt(0)
	v_lshlrev_b32_e32 v138, 16, v178
	v_and_b32_e32 v139, 0xffff0000, v178
	v_lshlrev_b32_e32 v166, 16, v179
	v_and_b32_e32 v167, 0xffff0000, v179
	v_lshlrev_b32_e32 v168, 16, v180
	v_and_b32_e32 v169, 0xffff0000, v180
	v_lshlrev_b32_e32 v178, 16, v181
	v_and_b32_e32 v179, 0xffff0000, v181
	v_pk_fma_f32 v[34:35], v[34:35], v[162:163], v[166:167]
	v_pk_fma_f32 v[32:33], v[32:33], v[160:161], v[138:139]
	v_pk_fma_f32 v[30:31], v[30:31], v[158:159], v[178:179]
	v_pk_fma_f32 v[28:29], v[28:29], v[156:157], v[168:169]
	v_cvt_pk_bf16_f32 v178, v32, v33
	v_cvt_pk_bf16_f32 v179, v34, v35
	v_cvt_pk_bf16_f32 v180, v28, v29
	v_cvt_pk_bf16_f32 v181, v30, v31
	v_lshlrev_b32_e32 v34, 16, v178
	v_and_b32_e32 v35, 0xffff0000, v178
	v_lshlrev_b32_e32 v32, 16, v179
	v_and_b32_e32 v33, 0xffff0000, v179
	v_lshlrev_b32_e32 v30, 16, v180
	v_and_b32_e32 v31, 0xffff0000, v180
	v_lshlrev_b32_e32 v28, 16, v181
	v_and_b32_e32 v29, 0xffff0000, v181
	v_lshlrev_b32_e32 v190, 16, v182
	v_and_b32_e32 v191, 0xffff0000, v182
	v_lshlrev_b32_e32 v182, 16, v183
	v_and_b32_e32 v183, 0xffff0000, v183
	global_store_dwordx4 v[212:213], v[178:181], off offset:2304
	v_pk_mul_f32 v[138:139], v[74:75], v[32:33]
	v_pk_mul_f32 v[166:167], v[72:73], v[34:35]
	v_pk_mul_f32 v[168:169], v[70:71], v[28:29]
	v_pk_mul_f32 v[180:181], v[68:69], v[30:31]
	v_cvt_pk_bf16_f32 v178, v166, v167
	v_cvt_pk_bf16_f32 v179, v138, v139
	v_cvt_pk_bf16_f32 v180, v180, v181
	v_cvt_pk_bf16_f32 v181, v168, v169
	v_pk_fma_f32 v[24:25], v[24:25], v[162:163], v[182:183]
	v_pk_fma_f32 v[22:23], v[22:23], v[160:161], v[190:191]
	v_lshlrev_b32_e32 v192, 16, v184
	v_and_b32_e32 v193, 0xffff0000, v184
	v_lshlrev_b32_e32 v184, 16, v185
	v_and_b32_e32 v185, 0xffff0000, v185
	global_store_dwordx4 v[214:215], v[178:181], off offset:256
	v_pk_fma_f32 v[20:21], v[20:21], v[158:159], v[184:185]
	v_pk_fma_f32 v[18:19], v[18:19], v[156:157], v[192:193]
	v_cvt_pk_bf16_f32 v178, v22, v23
	v_cvt_pk_bf16_f32 v179, v24, v25
	v_lshlrev_b32_e32 v24, 16, v178
	v_and_b32_e32 v25, 0xffff0000, v178
	v_lshlrev_b32_e32 v22, 16, v179
	v_and_b32_e32 v23, 0xffff0000, v179
	v_cvt_pk_bf16_f32 v180, v18, v19
	v_cvt_pk_bf16_f32 v181, v20, v21
	v_pk_mul_f32 v[138:139], v[74:75], v[22:23]
	v_pk_mul_f32 v[166:167], v[72:73], v[24:25]
	global_store_dwordx4 v[216:217], v[178:181], off offset:2304
	v_lshlrev_b32_e32 v20, 16, v180
	v_and_b32_e32 v21, 0xffff0000, v180
	v_cvt_pk_bf16_f32 v178, v166, v167
	v_cvt_pk_bf16_f32 v179, v138, v139
	v_lshlrev_b32_e32 v138, 16, v134
	v_and_b32_e32 v139, 0xffff0000, v134
	v_lshlrev_b32_e32 v134, 16, v135
	v_and_b32_e32 v135, 0xffff0000, v135
	v_lshlrev_b32_e32 v166, 16, v136
	v_and_b32_e32 v167, 0xffff0000, v136
	v_lshlrev_b32_e32 v136, 16, v137
	v_and_b32_e32 v137, 0xffff0000, v137
	v_lshlrev_b32_e32 v18, 16, v181
	v_and_b32_e32 v19, 0xffff0000, v181
	v_pk_fma_f32 v[16:17], v[16:17], v[162:163], v[134:135]
	v_pk_fma_f32 v[14:15], v[14:15], v[160:161], v[138:139]
	v_pk_fma_f32 v[12:13], v[12:13], v[158:159], v[136:137]
	v_pk_fma_f32 v[10:11], v[10:11], v[156:157], v[166:167]
	v_pk_mul_f32 v[168:169], v[70:71], v[18:19]
	v_pk_mul_f32 v[180:181], v[68:69], v[20:21]
	v_cvt_pk_bf16_f32 v134, v14, v15
	v_cvt_pk_bf16_f32 v135, v16, v17
	v_cvt_pk_bf16_f32 v136, v10, v11
	v_cvt_pk_bf16_f32 v137, v12, v13
	v_cvt_pk_bf16_f32 v180, v180, v181
	v_cvt_pk_bf16_f32 v181, v168, v169
	v_lshlrev_b32_e32 v16, 16, v134
	v_and_b32_e32 v17, 0xffff0000, v134
	v_lshlrev_b32_e32 v14, 16, v135
	v_and_b32_e32 v15, 0xffff0000, v135
	v_lshlrev_b32_e32 v12, 16, v136
	v_and_b32_e32 v13, 0xffff0000, v136
	v_lshlrev_b32_e32 v10, 16, v137
	v_and_b32_e32 v11, 0xffff0000, v137
	global_store_dwordx4 v[218:219], v[178:181], off offset:256
	v_lshlrev_b32_e32 v168, 16, v186
	v_and_b32_e32 v169, 0xffff0000, v186
	v_lshlrev_b32_e32 v178, 16, v187
	v_and_b32_e32 v179, 0xffff0000, v187
	v_lshlrev_b32_e32 v180, 16, v188
	v_and_b32_e32 v181, 0xffff0000, v188
	v_lshlrev_b32_e32 v182, 16, v189
	v_and_b32_e32 v183, 0xffff0000, v189
	global_store_dwordx4 v[196:197], v[134:137], off offset:2304
	v_pk_mul_f32 v[138:139], v[70:71], v[10:11]
	v_pk_mul_f32 v[166:167], v[68:69], v[12:13]
	v_pk_mul_f32 v[136:137], v[74:75], v[14:15]
	v_pk_mul_f32 v[134:135], v[72:73], v[16:17]
	v_pk_fma_f32 v[8:9], v[8:9], v[162:163], v[178:179]
	v_cvt_pk_bf16_f32 v134, v134, v135
	v_cvt_pk_bf16_f32 v135, v136, v137
	v_cvt_pk_bf16_f32 v136, v166, v167
	v_cvt_pk_bf16_f32 v137, v138, v139
	v_pk_fma_f32 v[6:7], v[6:7], v[160:161], v[168:169]
	v_pk_fma_f32 v[4:5], v[4:5], v[158:159], v[182:183]
	v_pk_fma_f32 v[2:3], v[2:3], v[156:157], v[180:181]
	global_store_dwordx4 v[210:211], v[134:137], off offset:256
	s_nop 1
	v_cvt_pk_bf16_f32 v134, v6, v7
	v_cvt_pk_bf16_f32 v135, v8, v9
	v_cvt_pk_bf16_f32 v136, v2, v3
	v_cvt_pk_bf16_f32 v137, v4, v5
	v_lshlrev_b32_e32 v8, 16, v134
	v_and_b32_e32 v9, 0xffff0000, v134
	v_lshlrev_b32_e32 v6, 16, v135
	v_and_b32_e32 v7, 0xffff0000, v135
	v_lshlrev_b32_e32 v4, 16, v136
	v_and_b32_e32 v5, 0xffff0000, v136
	v_lshlrev_b32_e32 v2, 16, v137
	v_and_b32_e32 v3, 0xffff0000, v137
	global_store_dwordx4 v[220:221], v[134:137], off offset:2304
	v_pk_mul_f32 v[74:75], v[74:75], v[6:7]
	v_pk_mul_f32 v[72:73], v[72:73], v[8:9]
	v_pk_mul_f32 v[134:135], v[70:71], v[2:3]
	v_pk_mul_f32 v[70:71], v[68:69], v[4:5]
	v_cvt_pk_bf16_f32 v68, v72, v73
	v_cvt_pk_bf16_f32 v69, v74, v75
	v_cvt_pk_bf16_f32 v70, v70, v71
	v_cvt_pk_bf16_f32 v71, v134, v135
	global_store_dwordx4 v[132:133], v[68:71], off offset:256
	v_xor_b32_e32 v72, 32, v227
	v_mul_f32_e32 v73, v129, v129
	v_and_b32_e32 v71, 64, v227
	v_xor_b32_e32 v70, 16, v227
	v_add_u32_e32 v71, 64, v71
	v_cmp_lt_i32_e32 vcc, v70, v71
	v_fmac_f32_e32 v73, v128, v128
	v_mul_f32_e32 v74, v125, v125
	v_cndmask_b32_e32 v70, v227, v70, vcc
	v_cmp_lt_i32_e32 vcc, v72, v71
	v_fmac_f32_e32 v74, v124, v124
	v_lshlrev_b32_e32 v70, 2, v70
	v_cndmask_b32_e32 v71, v227, v72, vcc
	v_mul_f32_e32 v72, v131, v131
	v_fmac_f32_e32 v72, v130, v130
	v_add_f32_e32 v72, v72, v73
	v_mul_f32_e32 v73, v127, v127
	v_fmac_f32_e32 v73, v126, v126
	v_add_f32_e32 v73, v73, v74
	v_add_f32_e32 v72, v72, v73
	v_add_f32_e32 v64, v72, v64
	v_add_f32_e32 v60, v60, v64
	ds_bpermute_b32 v61, v70, v60
	v_lshlrev_b32_e32 v71, 2, v71
	v_lshl_add_u64 v[68:69], v[150:151], 0, s[24:25]
	s_waitcnt lgkmcnt(0)
	v_add_f32_e32 v60, v60, v61
	ds_bpermute_b32 v61, v71, v60
	s_and_saveexec_b64 s[24:25], s[38:39]
	s_cbranch_execz .LBB0_1159
	s_waitcnt lgkmcnt(0)
	v_add_f32_e32 v60, v60, v61
	global_atomic_add_f32 v[68:69], v60, off
